# GEMM K-loops: mid-cluster s_setprio 0/1 pairs and already-satisfied post-barrier lgkmcnt waits deleted (3 issue slots per 32-MFMA cluster)
# speedup vs baseline: 1.0042x; 1.0042x over previous
; #define PG8_STAGE(bufoff, gbase, voff) do { _Pragma("unroll") for (int _i = 0; _i < 2; ++_i) \
;         __builtin_amdgcn_global_load_lds((const unsigned*)((const char*)(gbase) + (voff)[_i]), (LAS unsigned*)(lds + (bufoff) + ldsw + _i * 8192), 16, 0, 0); } while (0)
; #define PG8_STAGEB(bufoff, gbase, perm) do { _Pragma("unroll") for (int _i = 0; _i < 2; ++_i) \
;         __builtin_amdgcn_global_load_lds((const unsigned*)((const char*)(gbase) + ((BSEL && (perm)) ? voffBp[_i] : voffB[_i])), (LAS unsigned*)(lds + (bufoff) + ldsw + _i * 8192), 16, 0, 0); } while (0)
; #define PG8_LDA(dst, b, h) do { _Pragma("unroll") for (int m = 0; m < 4; ++m) _Pragma("unroll") for (int k = 0; k < 2; ++k) dst[m][k] = *(const LAS bf16x8*)(lds + PG8_SA(b, h) + aoff + m * 2048 + k * 1024); } while (0)
; #define PG8_LDB(dst, b, h) do { _Pragma("unroll") for (int n = 0; n < 2; ++n) _Pragma("unroll") for (int k = 0; k < 2; ++k) dst[n][k] = *(const LAS bf16x8*)(lds + PG8_SB(b, h) + boff + n * 2048 + k * 1024); } while (0)
; #define PG8_WAIT_V(n) asm volatile("s_waitcnt vmcnt(" #n ")" ::: "memory")
; #define PG8_WAIT_L(n) asm volatile("s_waitcnt lgkmcnt(" #n ")" ::: "memory")
; #define PG8_BAR __builtin_amdgcn_s_barrier()
; #define PG8_SCHED __builtin_amdgcn_sched_barrier(0)
; template <class Epi, bool BSEL = false>
; __device__ __forceinline__ void gemm_phase(LAS unsigned char* lds, const Gemm g, const Order& S, const Epi& E, const int tid) {
;     ...
;         for (int t = 0; t < nt; t += 2) {
;             const bool last = (t == nt - 2);
;             const char* a1 = cA + (size_t)(t + 1) * kstep;
;             const char* a2 = last ? nA : cA + (size_t)(t + 2) * kstep; const char* b2 = last ? nB : cB + (size_t)(t + 2) * kstep;
;             const char* a3 = a2 + kstep; const char* b3 = b2 + kstep;
;             const bool p2 = last ? nP : cP; const size_t h2 = last ? nhB : chB;
;             PG8_LDB(B0, 0, 0); PG8_LDB(B1, 0, 1); PG8_SCHED; PG8_LDA(At, 0, 0); PG8_STAGE(PG8_SA(1, 1), a1 + hstepA, voffA);
;             PG8_WAIT_V(8); PG8_WAIT_L(0); PG8_BAR; PG8_MMA(0, 0, At, B0); PG8_MMA(0, 1, At, B1); PG8_BAR; PG8_SCHED;
;             PG8_LDA(At, 0, 1); PG8_STAGEB(PG8_SB(0, 0), b2, p2); PG8_STAGEB(PG8_SB(0, 1), b2 + h2, p2); PG8_STAGE(PG8_SA(0, 0), a2, voffA);
;             PG8_WAIT_V(8); PG8_WAIT_L(0); PG8_BAR; PG8_MMA(1, 0, At, B0); PG8_MMA(1, 1, At, B1); PG8_BAR; PG8_SCHED;
.LBB0_324:
	v_add_u32_e32 v162, s45, v147
	v_add_u32_e32 v178, s46, v147
	s_add_u32 s2, s8, s38
	ds_read_b128 v[150:153], v162
	ds_read_b128 v[154:157], v162 offset:1024
	ds_read_b128 v[158:161], v162 offset:2048
	ds_read_b128 v[162:165], v162 offset:3072
	ds_read_b128 v[166:169], v178
	ds_read_b128 v[170:173], v178 offset:1024
	ds_read_b128 v[174:177], v178 offset:2048
	ds_read_b128 v[178:181], v178 offset:3072
	s_addc_u32 s3, s9, s39
	s_add_u32 s2, s2, 0x100
	s_addc_u32 s3, s3, 0
	s_add_u32 s57, s25, s38
	s_addc_u32 s58, s51, s39
	s_cmpk_eq_i32 s38, 0x700
	s_cselect_b32 s35, s52, s3
	s_cselect_b32 s34, s53, s2
	s_cselect_b32 s3, s54, s58
	s_cselect_b32 s2, s55, s57
	v_lshl_add_u64 v[198:199], v[142:143], 0, s[38:39]
	s_add_i32 m0, s7, 0xc000
	ds_read_b128 v[182:185], v149
	ds_read_b128 v[186:189], v149 offset:1024
	ds_read_b128 v[190:193], v149 offset:2048
	ds_read_b128 v[194:197], v149 offset:3072
	ds_read_b128 v[202:205], v149 offset:4096
	ds_read_b128 v[206:209], v149 offset:5120
	ds_read_b128 v[210:213], v149 offset:6144
	ds_read_b128 v[214:217], v149 offset:7168
	global_load_lds_dwordx4 v[198:199], off
	v_lshl_add_u64 v[198:199], v[144:145], 0, s[38:39]
	s_add_i32 m0, s7, 0xe000
	s_nop 0
	global_load_lds_dwordx4 v[198:199], off
	s_waitcnt vmcnt(8)
	s_waitcnt lgkmcnt(0)
	s_barrier
	s_setprio 1
	v_mfma_f32_16x16x32_bf16 v[124:127], v[150:153], v[182:185], v[124:127]
	v_mfma_f32_16x16x32_bf16 v[120:123], v[158:161], v[182:185], v[120:123]
	v_mfma_f32_16x16x32_bf16 v[116:119], v[150:153], v[190:193], v[116:119]
	v_mfma_f32_16x16x32_bf16 v[112:115], v[158:161], v[190:193], v[112:115]
	v_mfma_f32_16x16x32_bf16 v[108:111], v[150:153], v[202:205], v[108:111]
	v_mfma_f32_16x16x32_bf16 v[104:107], v[158:161], v[202:205], v[104:107]
	v_mfma_f32_16x16x32_bf16 v[100:103], v[150:153], v[210:213], v[100:103]
	v_mfma_f32_16x16x32_bf16 v[96:99], v[158:161], v[210:213], v[96:99]
	v_mfma_f32_16x16x32_bf16 v[124:127], v[154:157], v[186:189], v[124:127]
	v_mfma_f32_16x16x32_bf16 v[120:123], v[162:165], v[186:189], v[120:123]
	v_mfma_f32_16x16x32_bf16 v[116:119], v[154:157], v[194:197], v[116:119]
	v_mfma_f32_16x16x32_bf16 v[112:115], v[162:165], v[194:197], v[112:115]
	v_mfma_f32_16x16x32_bf16 v[108:111], v[154:157], v[206:209], v[108:111]
	v_mfma_f32_16x16x32_bf16 v[104:107], v[162:165], v[206:209], v[104:107]
	v_mfma_f32_16x16x32_bf16 v[100:103], v[154:157], v[214:217], v[100:103]
	v_mfma_f32_16x16x32_bf16 v[96:99], v[162:165], v[214:217], v[96:99]
	v_mfma_f32_16x16x32_bf16 v[92:95], v[166:169], v[182:185], v[92:95]
	v_mfma_f32_16x16x32_bf16 v[88:91], v[174:177], v[182:185], v[88:91]
	v_mfma_f32_16x16x32_bf16 v[84:87], v[166:169], v[190:193], v[84:87]
	v_mfma_f32_16x16x32_bf16 v[80:83], v[174:177], v[190:193], v[80:83]
	v_mfma_f32_16x16x32_bf16 v[76:79], v[166:169], v[202:205], v[76:79]
	v_mfma_f32_16x16x32_bf16 v[72:75], v[174:177], v[202:205], v[72:75]
	v_mfma_f32_16x16x32_bf16 v[68:71], v[166:169], v[210:213], v[68:71]
	v_mfma_f32_16x16x32_bf16 v[64:67], v[174:177], v[210:213], v[64:67]
	v_mfma_f32_16x16x32_bf16 v[92:95], v[170:173], v[186:189], v[92:95]
	v_mfma_f32_16x16x32_bf16 v[88:91], v[178:181], v[186:189], v[88:91]
	v_mfma_f32_16x16x32_bf16 v[84:87], v[170:173], v[194:197], v[84:87]
	v_mfma_f32_16x16x32_bf16 v[80:83], v[178:181], v[194:197], v[80:83]
	v_mfma_f32_16x16x32_bf16 v[76:79], v[170:173], v[206:209], v[76:79]
	v_mfma_f32_16x16x32_bf16 v[72:75], v[178:181], v[206:209], v[72:75]
	v_mfma_f32_16x16x32_bf16 v[68:71], v[170:173], v[214:217], v[68:71]
	v_mfma_f32_16x16x32_bf16 v[64:67], v[178:181], v[214:217], v[64:67]
	s_setprio 0
	s_barrier
	s_add_i32 s57, s45, s12
	v_lshl_add_u64 v[198:199], s[2:3], 0, v[132:133]
	s_mov_b32 m0, s57
	ds_read_b128 v[182:185], v149 offset:16384
	ds_read_b128 v[186:189], v149 offset:17408
	ds_read_b128 v[190:193], v149 offset:18432
	ds_read_b128 v[194:197], v149 offset:19456
	ds_read_b128 v[202:205], v149 offset:20480
	ds_read_b128 v[206:209], v149 offset:21504
	ds_read_b128 v[210:213], v149 offset:22528
	ds_read_b128 v[214:217], v149 offset:23552
	global_load_lds_dwordx4 v[198:199], off
	s_add_i32 m0, s57, 0x2000
	s_add_u32 s58, s2, 0x40000
	v_lshl_add_u64 v[218:219], s[2:3], 0, v[128:129]
	s_addc_u32 s59, s3, 0
	s_add_i32 s57, s46, s12
	global_load_lds_dwordx4 v[218:219], off
	v_lshl_add_u64 v[220:221], s[58:59], 0, v[132:133]
	s_mov_b32 m0, s57
	v_lshl_add_u64 v[222:223], s[34:35], 0, v[130:131]
	global_load_lds_dwordx4 v[220:221], off
	v_lshl_add_u64 v[220:221], s[58:59], 0, v[128:129]
	s_add_i32 m0, s57, 0x2000
	s_nop 0
	global_load_lds_dwordx4 v[220:221], off
	v_lshl_add_u64 v[220:221], s[34:35], 0, v[134:135]
	s_mov_b32 m0, s7
	s_nop 0
	global_load_lds_dwordx4 v[220:221], off
	s_mov_b32 m0, s15
	s_nop 0
	global_load_lds_dwordx4 v[222:223], off
	s_waitcnt vmcnt(8)
	s_waitcnt lgkmcnt(0)
	s_barrier
; #define PG8_STAGE(bufoff, gbase, voff) do { _Pragma("unroll") for (int _i = 0; _i < 2; ++_i) \
;         __builtin_amdgcn_global_load_lds((const unsigned*)((const char*)(gbase) + (voff)[_i]), (LAS unsigned*)(lds + (bufoff) + ldsw + _i * 8192), 16, 0, 0); } while (0)
; #define PG8_LDA(dst, b, h) do { _Pragma("unroll") for (int m = 0; m < 4; ++m) _Pragma("unroll") for (int k = 0; k < 2; ++k) dst[m][k] = *(const LAS bf16x8*)(lds + PG8_SA(b, h) + aoff + m * 2048 + k * 1024); } while (0)
; #define PG8_LDB(dst, b, h) do { _Pragma("unroll") for (int n = 0; n < 2; ++n) _Pragma("unroll") for (int k = 0; k < 2; ++k) dst[n][k] = *(const LAS bf16x8*)(lds + PG8_SB(b, h) + boff + n * 2048 + k * 1024); } while (0)
; #define PG8_MMA(ai, bj, At, Bt) do { __builtin_amdgcn_s_setprio(1); _Pragma("unroll") for (int m = 0; m < 4; ++m) _Pragma("unroll") for (int n = 0; n < 2; ++n) _Pragma("unroll") for (int k = 0; k < 2; ++k) \
;         acc[ai][bj][m][n] = __builtin_amdgcn_mfma_f32_16x16x32_bf16(Bt[n][k], At[m][k], acc[ai][bj][m][n], 0, 0, 0); __builtin_amdgcn_s_setprio(0); } while (0)
; #define PG8_WAIT_V(n) asm volatile("s_waitcnt vmcnt(" #n ")" ::: "memory")
; #define PG8_WAIT_L(n) asm volatile("s_waitcnt lgkmcnt(" #n ")" ::: "memory")
; #define PG8_BAR __builtin_amdgcn_s_barrier()
; #define PG8_SCHED __builtin_amdgcn_sched_barrier(0)
; template <class Epi, bool BSEL = false>
; __device__ __forceinline__ void gemm_phase(LAS unsigned char* lds, const Gemm g, const Order& S, const Epi& E, const int tid) {
;     ...
;             PG8_WAIT_V(8); PG8_WAIT_L(0); PG8_BAR; PG8_MMA(1, 0, At, B0); PG8_MMA(1, 1, At, B1); PG8_BAR; PG8_SCHED;
;             PG8_LDB(B0, 1, 0); PG8_LDB(B1, 1, 1); PG8_SCHED; PG8_LDA(At, 1, 0); PG8_STAGE(PG8_SA(0, 1), a2 + hstepA, voffA);
;             PG8_WAIT_V(8); PG8_WAIT_L(0); PG8_BAR; PG8_MMA(0, 0, At, B0); PG8_MMA(0, 1, At, B1); PG8_BAR; PG8_SCHED;
	s_setprio 1
	v_mfma_f32_16x16x32_bf16 v[60:63], v[150:153], v[182:185], v[60:63]
	v_mfma_f32_16x16x32_bf16 v[56:59], v[158:161], v[182:185], v[56:59]
	v_mfma_f32_16x16x32_bf16 v[52:55], v[150:153], v[190:193], v[52:55]
	v_mfma_f32_16x16x32_bf16 v[48:51], v[158:161], v[190:193], v[48:51]
	v_mfma_f32_16x16x32_bf16 v[44:47], v[150:153], v[202:205], v[44:47]
	v_mfma_f32_16x16x32_bf16 v[40:43], v[158:161], v[202:205], v[40:43]
	v_mfma_f32_16x16x32_bf16 v[36:39], v[150:153], v[210:213], v[36:39]
	v_mfma_f32_16x16x32_bf16 v[32:35], v[158:161], v[210:213], v[32:35]
	v_mfma_f32_16x16x32_bf16 v[60:63], v[154:157], v[186:189], v[60:63]
	v_mfma_f32_16x16x32_bf16 v[56:59], v[162:165], v[186:189], v[56:59]
	v_mfma_f32_16x16x32_bf16 v[52:55], v[154:157], v[194:197], v[52:55]
	v_mfma_f32_16x16x32_bf16 v[48:51], v[162:165], v[194:197], v[48:51]
	v_mfma_f32_16x16x32_bf16 v[44:47], v[154:157], v[206:209], v[44:47]
	v_mfma_f32_16x16x32_bf16 v[40:43], v[162:165], v[206:209], v[40:43]
	v_mfma_f32_16x16x32_bf16 v[36:39], v[154:157], v[214:217], v[36:39]
	v_mfma_f32_16x16x32_bf16 v[32:35], v[162:165], v[214:217], v[32:35]
	v_mfma_f32_16x16x32_bf16 v[28:31], v[166:169], v[182:185], v[28:31]
	v_mfma_f32_16x16x32_bf16 v[24:27], v[174:177], v[182:185], v[24:27]
	v_mfma_f32_16x16x32_bf16 v[20:23], v[166:169], v[190:193], v[20:23]
	v_mfma_f32_16x16x32_bf16 v[16:19], v[174:177], v[190:193], v[16:19]
	v_mfma_f32_16x16x32_bf16 v[12:15], v[166:169], v[202:205], v[12:15]
	v_mfma_f32_16x16x32_bf16 v[8:11], v[174:177], v[202:205], v[8:11]
	v_mfma_f32_16x16x32_bf16 v[4:7], v[166:169], v[210:213], v[4:7]
	v_mfma_f32_16x16x32_bf16 v[0:3], v[174:177], v[210:213], v[0:3]
	v_mfma_f32_16x16x32_bf16 v[28:31], v[170:173], v[186:189], v[28:31]
	v_mfma_f32_16x16x32_bf16 v[24:27], v[178:181], v[186:189], v[24:27]
	v_mfma_f32_16x16x32_bf16 v[20:23], v[170:173], v[194:197], v[20:23]
	v_mfma_f32_16x16x32_bf16 v[16:19], v[178:181], v[194:197], v[16:19]
	v_mfma_f32_16x16x32_bf16 v[12:15], v[170:173], v[206:209], v[12:15]
	v_mfma_f32_16x16x32_bf16 v[8:11], v[178:181], v[206:209], v[8:11]
	v_mfma_f32_16x16x32_bf16 v[4:7], v[170:173], v[214:217], v[4:7]
	v_mfma_f32_16x16x32_bf16 v[0:3], v[178:181], v[214:217], v[0:3]
	s_setprio 0
	s_barrier
	s_add_i32 s57, 0, 0x18000
	s_add_i32 s58, 0, 0x1c000
	v_add_u32_e32 v162, s57, v147
	v_add_u32_e32 v178, s58, v147
	ds_read_b128 v[150:153], v162
	ds_read_b128 v[154:157], v162 offset:1024
	ds_read_b128 v[158:161], v162 offset:2048
	ds_read_b128 v[162:165], v162 offset:3072
	ds_read_b128 v[166:169], v178
	ds_read_b128 v[170:173], v178 offset:1024
	ds_read_b128 v[174:177], v178 offset:2048
	ds_read_b128 v[178:181], v178 offset:3072
	s_add_u32 s34, s34, 0x40000
	s_addc_u32 s35, s35, 0
	s_mov_b32 m0, s40
	v_lshl_add_u64 v[224:225], s[34:35], 0, v[134:135]
	ds_read_b128 v[182:185], v149 offset:32768
	ds_read_b128 v[186:189], v149 offset:33792
	ds_read_b128 v[190:193], v149 offset:34816
	ds_read_b128 v[194:197], v149 offset:35840
	ds_read_b128 v[202:205], v149 offset:36864
	ds_read_b128 v[206:209], v149 offset:37888
	ds_read_b128 v[210:213], v149 offset:38912
	ds_read_b128 v[214:217], v149 offset:39936
	global_load_lds_dwordx4 v[224:225], off
	v_lshl_add_u64 v[224:225], s[34:35], 0, v[130:131]
	s_mov_b32 m0, s41
	s_nop 0
	global_load_lds_dwordx4 v[224:225], off
	s_waitcnt vmcnt(8)
	s_waitcnt lgkmcnt(0)
	s_barrier
	s_setprio 1
	v_mfma_f32_16x16x32_bf16 v[124:127], v[150:153], v[182:185], v[124:127]
	v_mfma_f32_16x16x32_bf16 v[120:123], v[158:161], v[182:185], v[120:123]
	v_mfma_f32_16x16x32_bf16 v[116:119], v[150:153], v[190:193], v[116:119]
	v_mfma_f32_16x16x32_bf16 v[112:115], v[158:161], v[190:193], v[112:115]
	v_mfma_f32_16x16x32_bf16 v[108:111], v[150:153], v[202:205], v[108:111]
	v_mfma_f32_16x16x32_bf16 v[104:107], v[158:161], v[202:205], v[104:107]
	v_mfma_f32_16x16x32_bf16 v[100:103], v[150:153], v[210:213], v[100:103]
	v_mfma_f32_16x16x32_bf16 v[96:99], v[158:161], v[210:213], v[96:99]
	v_mfma_f32_16x16x32_bf16 v[124:127], v[154:157], v[186:189], v[124:127]
	v_mfma_f32_16x16x32_bf16 v[120:123], v[162:165], v[186:189], v[120:123]
	v_mfma_f32_16x16x32_bf16 v[116:119], v[154:157], v[194:197], v[116:119]
	v_mfma_f32_16x16x32_bf16 v[112:115], v[162:165], v[194:197], v[112:115]
	v_mfma_f32_16x16x32_bf16 v[108:111], v[154:157], v[206:209], v[108:111]
	v_mfma_f32_16x16x32_bf16 v[104:107], v[162:165], v[206:209], v[104:107]
	v_mfma_f32_16x16x32_bf16 v[100:103], v[154:157], v[214:217], v[100:103]
	v_mfma_f32_16x16x32_bf16 v[96:99], v[162:165], v[214:217], v[96:99]
	v_mfma_f32_16x16x32_bf16 v[92:95], v[166:169], v[182:185], v[92:95]
	v_mfma_f32_16x16x32_bf16 v[88:91], v[174:177], v[182:185], v[88:91]
	v_mfma_f32_16x16x32_bf16 v[84:87], v[166:169], v[190:193], v[84:87]
	v_mfma_f32_16x16x32_bf16 v[80:83], v[174:177], v[190:193], v[80:83]
	v_mfma_f32_16x16x32_bf16 v[76:79], v[166:169], v[202:205], v[76:79]
	v_mfma_f32_16x16x32_bf16 v[72:75], v[174:177], v[202:205], v[72:75]
	v_mfma_f32_16x16x32_bf16 v[68:71], v[166:169], v[210:213], v[68:71]
	v_mfma_f32_16x16x32_bf16 v[64:67], v[174:177], v[210:213], v[64:67]
	v_mfma_f32_16x16x32_bf16 v[92:95], v[170:173], v[186:189], v[92:95]
	v_mfma_f32_16x16x32_bf16 v[88:91], v[178:181], v[186:189], v[88:91]
	v_mfma_f32_16x16x32_bf16 v[84:87], v[170:173], v[194:197], v[84:87]
	v_mfma_f32_16x16x32_bf16 v[80:83], v[178:181], v[194:197], v[80:83]
	v_mfma_f32_16x16x32_bf16 v[76:79], v[170:173], v[206:209], v[76:79]
	v_mfma_f32_16x16x32_bf16 v[72:75], v[178:181], v[206:209], v[72:75]
	v_mfma_f32_16x16x32_bf16 v[68:71], v[170:173], v[214:217], v[68:71]
	v_mfma_f32_16x16x32_bf16 v[64:67], v[178:181], v[214:217], v[64:67]
	s_setprio 0
	s_barrier
; #define PG8_STAGE(bufoff, gbase, voff) do { _Pragma("unroll") for (int _i = 0; _i < 2; ++_i) \
;         __builtin_amdgcn_global_load_lds((const unsigned*)((const char*)(gbase) + (voff)[_i]), (LAS unsigned*)(lds + (bufoff) + ldsw + _i * 8192), 16, 0, 0); } while (0)
; #define PG8_STAGEB(bufoff, gbase, perm) do { _Pragma("unroll") for (int _i = 0; _i < 2; ++_i) \
;         __builtin_amdgcn_global_load_lds((const unsigned*)((const char*)(gbase) + ((BSEL && (perm)) ? voffBp[_i] : voffB[_i])), (LAS unsigned*)(lds + (bufoff) + ldsw + _i * 8192), 16, 0, 0); } while (0)
; #define PG8_LDA(dst, b, h) do { _Pragma("unroll") for (int m = 0; m < 4; ++m) _Pragma("unroll") for (int k = 0; k < 2; ++k) dst[m][k] = *(const LAS bf16x8*)(lds + PG8_SA(b, h) + aoff + m * 2048 + k * 1024); } while (0)
; #define PG8_MMA(ai, bj, At, Bt) do { __builtin_amdgcn_s_setprio(1); _Pragma("unroll") for (int m = 0; m < 4; ++m) _Pragma("unroll") for (int n = 0; n < 2; ++n) _Pragma("unroll") for (int k = 0; k < 2; ++k) \
;         acc[ai][bj][m][n] = __builtin_amdgcn_mfma_f32_16x16x32_bf16(Bt[n][k], At[m][k], acc[ai][bj][m][n], 0, 0, 0); __builtin_amdgcn_s_setprio(0); } while (0)
; #define PG8_WAIT_V(n) asm volatile("s_waitcnt vmcnt(" #n ")" ::: "memory")
; #define PG8_WAIT_L(n) asm volatile("s_waitcnt lgkmcnt(" #n ")" ::: "memory")
; #define PG8_BAR __builtin_amdgcn_s_barrier()
; #define PG8_SCHED __builtin_amdgcn_sched_barrier(0)
; template <class Epi, bool BSEL = false>
; __device__ __forceinline__ void gemm_phase(LAS unsigned char* lds, const Gemm g, const Order& S, const Epi& E, const int tid) {
;     ...
;             PG8_WAIT_V(8); PG8_WAIT_L(0); PG8_BAR; PG8_MMA(0, 0, At, B0); PG8_MMA(0, 1, At, B1); PG8_BAR; PG8_SCHED;
;             PG8_LDA(At, 1, 1); PG8_STAGEB(PG8_SB(1, 0), b3, p2); PG8_STAGEB(PG8_SB(1, 1), b3 + h2, p2); PG8_STAGE(PG8_SA(1, 0), a3, voffA);
;             PG8_WAIT_V(8); PG8_WAIT_L(0); PG8_BAR; PG8_MMA(1, 0, At, B0); PG8_MMA(1, 1, At, B1); PG8_BAR; PG8_SCHED;
;         }
;         if constexpr (ALIGN_EPI) { if (wr == 0) PG8_BAR; }
	s_add_i32 s34, s57, s12
	v_lshl_add_u64 v[198:199], v[198:199], 0, s[20:21]
	s_mov_b32 m0, s34
	ds_read_b128 v[182:185], v149 offset:49152
	ds_read_b128 v[186:189], v149 offset:50176
	ds_read_b128 v[190:193], v149 offset:51200
	ds_read_b128 v[194:197], v149 offset:52224
	ds_read_b128 v[202:205], v149 offset:53248
	ds_read_b128 v[206:209], v149 offset:54272
	ds_read_b128 v[210:213], v149 offset:55296
	ds_read_b128 v[214:217], v149 offset:56320
	global_load_lds_dwordx4 v[198:199], off
	s_add_i32 m0, s34, 0x2000
	s_add_u32 s2, s2, 0x40080
	v_lshl_add_u64 v[198:199], v[218:219], 0, s[20:21]
	s_addc_u32 s3, s3, 0
	s_add_i32 s34, s58, s12
	global_load_lds_dwordx4 v[198:199], off
	v_lshl_add_u64 v[198:199], s[2:3], 0, v[132:133]
	s_mov_b32 m0, s34
	s_nop 0
	global_load_lds_dwordx4 v[198:199], off
	v_lshl_add_u64 v[198:199], s[2:3], 0, v[128:129]
	s_add_i32 m0, s34, 0x2000
	s_nop 0
	global_load_lds_dwordx4 v[198:199], off
	v_lshl_add_u64 v[198:199], v[220:221], 0, s[20:21]
	s_mov_b32 m0, s43
	s_nop 0
	global_load_lds_dwordx4 v[198:199], off
	v_lshl_add_u64 v[198:199], v[222:223], 0, s[20:21]
	s_mov_b32 m0, s44
	s_nop 0
	global_load_lds_dwordx4 v[198:199], off
	s_waitcnt vmcnt(8)
	s_waitcnt lgkmcnt(0)
	s_barrier
	s_setprio 1
	v_mfma_f32_16x16x32_bf16 v[60:63], v[150:153], v[182:185], v[60:63]
	v_mfma_f32_16x16x32_bf16 v[56:59], v[158:161], v[182:185], v[56:59]
	v_mfma_f32_16x16x32_bf16 v[52:55], v[150:153], v[190:193], v[52:55]
	v_mfma_f32_16x16x32_bf16 v[48:51], v[158:161], v[190:193], v[48:51]
	v_mfma_f32_16x16x32_bf16 v[44:47], v[150:153], v[202:205], v[44:47]
	v_mfma_f32_16x16x32_bf16 v[40:43], v[158:161], v[202:205], v[40:43]
	v_mfma_f32_16x16x32_bf16 v[36:39], v[150:153], v[210:213], v[36:39]
	v_mfma_f32_16x16x32_bf16 v[32:35], v[158:161], v[210:213], v[32:35]
	v_mfma_f32_16x16x32_bf16 v[60:63], v[154:157], v[186:189], v[60:63]
	v_mfma_f32_16x16x32_bf16 v[56:59], v[162:165], v[186:189], v[56:59]
	v_mfma_f32_16x16x32_bf16 v[52:55], v[154:157], v[194:197], v[52:55]
	v_mfma_f32_16x16x32_bf16 v[48:51], v[162:165], v[194:197], v[48:51]
	v_mfma_f32_16x16x32_bf16 v[44:47], v[154:157], v[206:209], v[44:47]
	v_mfma_f32_16x16x32_bf16 v[40:43], v[162:165], v[206:209], v[40:43]
	v_mfma_f32_16x16x32_bf16 v[36:39], v[154:157], v[214:217], v[36:39]
	v_mfma_f32_16x16x32_bf16 v[32:35], v[162:165], v[214:217], v[32:35]
	v_mfma_f32_16x16x32_bf16 v[28:31], v[166:169], v[182:185], v[28:31]
	v_mfma_f32_16x16x32_bf16 v[24:27], v[174:177], v[182:185], v[24:27]
	v_mfma_f32_16x16x32_bf16 v[20:23], v[166:169], v[190:193], v[20:23]
	v_mfma_f32_16x16x32_bf16 v[16:19], v[174:177], v[190:193], v[16:19]
	v_mfma_f32_16x16x32_bf16 v[12:15], v[166:169], v[202:205], v[12:15]
	v_mfma_f32_16x16x32_bf16 v[8:11], v[174:177], v[202:205], v[8:11]
	v_mfma_f32_16x16x32_bf16 v[4:7], v[166:169], v[210:213], v[4:7]
	v_mfma_f32_16x16x32_bf16 v[0:3], v[174:177], v[210:213], v[0:3]
	v_mfma_f32_16x16x32_bf16 v[28:31], v[170:173], v[186:189], v[28:31]
	v_mfma_f32_16x16x32_bf16 v[24:27], v[178:181], v[186:189], v[24:27]
	v_mfma_f32_16x16x32_bf16 v[20:23], v[170:173], v[194:197], v[20:23]
	v_mfma_f32_16x16x32_bf16 v[16:19], v[178:181], v[194:197], v[16:19]
	v_mfma_f32_16x16x32_bf16 v[12:15], v[170:173], v[206:209], v[12:15]
	v_mfma_f32_16x16x32_bf16 v[8:11], v[178:181], v[206:209], v[8:11]
	v_mfma_f32_16x16x32_bf16 v[4:7], v[170:173], v[214:217], v[4:7]
	v_mfma_f32_16x16x32_bf16 v[0:3], v[178:181], v[214:217], v[0:3]
	s_setprio 0
	s_barrier
	s_add_i32 s56, s56, 2
	s_add_u32 s38, s38, 0x100
	s_addc_u32 s39, s39, 0
	s_cmp_gt_u32 s56, 13
	s_cbranch_scc0 .LBB0_324
	s_and_b64 vcc, exec, s[22:23]
	s_cbranch_vccz .LBB0_327
	s_barrier

; #define PG8_STAGE(bufoff, gbase, voff) do { _Pragma("unroll") for (int _i = 0; _i < 2; ++_i) \
;         __builtin_amdgcn_global_load_lds((const unsigned*)((const char*)(gbase) + (voff)[_i]), (LAS unsigned*)(lds + (bufoff) + ldsw + _i * 8192), 16, 0, 0); } while (0)
; #define PG8_STAGEB(bufoff, gbase, perm) do { _Pragma("unroll") for (int _i = 0; _i < 2; ++_i) \
;         __builtin_amdgcn_global_load_lds((const unsigned*)((const char*)(gbase) + ((BSEL && (perm)) ? voffBp[_i] : voffB[_i])), (LAS unsigned*)(lds + (bufoff) + ldsw + _i * 8192), 16, 0, 0); } while (0)
; #define PG8_LDA(dst, b, h) do { _Pragma("unroll") for (int m = 0; m < 4; ++m) _Pragma("unroll") for (int k = 0; k < 2; ++k) dst[m][k] = *(const LAS bf16x8*)(lds + PG8_SA(b, h) + aoff + m * 2048 + k * 1024); } while (0)
; #define PG8_LDB(dst, b, h) do { _Pragma("unroll") for (int n = 0; n < 2; ++n) _Pragma("unroll") for (int k = 0; k < 2; ++k) dst[n][k] = *(const LAS bf16x8*)(lds + PG8_SB(b, h) + boff + n * 2048 + k * 1024); } while (0)
; #define PG8_MMA(ai, bj, At, Bt) do { __builtin_amdgcn_s_setprio(1); _Pragma("unroll") for (int m = 0; m < 4; ++m) _Pragma("unroll") for (int n = 0; n < 2; ++n) _Pragma("unroll") for (int k = 0; k < 2; ++k) \
;         acc[ai][bj][m][n] = __builtin_amdgcn_mfma_f32_16x16x32_bf16(Bt[n][k], At[m][k], acc[ai][bj][m][n], 0, 0, 0); __builtin_amdgcn_s_setprio(0); } while (0)
; #define PG8_WAIT_V(n) asm volatile("s_waitcnt vmcnt(" #n ")" ::: "memory")
; #define PG8_WAIT_L(n) asm volatile("s_waitcnt lgkmcnt(" #n ")" ::: "memory")
; #define PG8_BAR __builtin_amdgcn_s_barrier()
; #define PG8_SCHED __builtin_amdgcn_sched_barrier(0)
; template <class Epi, bool BSEL = false>
; __device__ __forceinline__ void gemm_phase(LAS unsigned char* lds, const Gemm g, const Order& S, const Epi& E, const int tid) {
;     ...
;             PG8_LDB(B0, 0, 0); PG8_LDB(B1, 0, 1); PG8_SCHED; PG8_LDA(At, 0, 0); PG8_STAGE(PG8_SA(1, 1), a1 + hstepA, voffA);
;             PG8_WAIT_V(8); PG8_WAIT_L(0); PG8_BAR; PG8_MMA(0, 0, At, B0); PG8_MMA(0, 1, At, B1); PG8_BAR; PG8_SCHED;
;             PG8_LDA(At, 0, 1); PG8_STAGEB(PG8_SB(0, 0), b2, p2); PG8_STAGEB(PG8_SB(0, 1), b2 + h2, p2); PG8_STAGE(PG8_SA(0, 0), a2, voffA);
;             PG8_WAIT_V(8); PG8_WAIT_L(0); PG8_BAR; PG8_MMA(1, 0, At, B0); PG8_MMA(1, 1, At, B1); PG8_BAR; PG8_SCHED;
.LBB0_417:
	v_add_u32_e32 v167, s55, v156
	v_add_u32_e32 v201, s56, v156
	ds_read_b128 v[140:143], v167
	ds_read_b128 v[144:147], v167 offset:1024
	ds_read_b128 v[148:151], v167 offset:2048
	ds_read_b128 v[152:155], v167 offset:3072
	ds_read_b128 v[168:171], v201
	ds_read_b128 v[172:175], v201 offset:1024
	ds_read_b128 v[190:193], v201 offset:2048
	ds_read_b128 v[194:197], v201 offset:3072
	s_and_b64 s[2:3], s[46:47], exec
	s_cselect_b32 s45, s41, s5
	s_cselect_b32 s44, s40, s4
	s_cselect_b32 s3, s43, s23
	s_cselect_b32 s2, s42, s22
	s_add_u32 s64, s4, 0xb0080
	s_addc_u32 s65, s5, 0
	s_add_i32 s68, s1, 0xc000
	v_lshl_add_u64 v[176:177], s[64:65], 0, v[130:131]
	s_mov_b32 m0, s68
	s_add_i32 s39, s1, 0xe000
	ds_read_b128 v[202:205], v166
	ds_read_b128 v[206:209], v166 offset:1024
	ds_read_b128 v[210:213], v166 offset:2048
	ds_read_b128 v[214:217], v166 offset:3072
	ds_read_b128 v[218:221], v166 offset:4096
	ds_read_b128 v[222:225], v166 offset:5120
	ds_read_b128 v[226:229], v166 offset:6144
	ds_read_b128 v[230:233], v166 offset:7168
	global_load_lds_dwordx4 v[176:177], off
	v_lshl_add_u64 v[176:177], s[64:65], 0, v[134:135]
	s_mov_b32 m0, s39
	s_nop 0
	global_load_lds_dwordx4 v[176:177], off
	s_waitcnt vmcnt(8)
	s_waitcnt lgkmcnt(0)
	s_barrier
	s_setprio 1
	v_mfma_f32_16x16x32_bf16 v[124:127], v[140:143], v[202:205], v[124:127]
	v_mfma_f32_16x16x32_bf16 v[120:123], v[148:151], v[202:205], v[120:123]
	v_mfma_f32_16x16x32_bf16 v[116:119], v[140:143], v[210:213], v[116:119]
	v_mfma_f32_16x16x32_bf16 v[112:115], v[148:151], v[210:213], v[112:115]
	v_mfma_f32_16x16x32_bf16 v[108:111], v[140:143], v[218:221], v[108:111]
	v_mfma_f32_16x16x32_bf16 v[104:107], v[148:151], v[218:221], v[104:107]
	v_mfma_f32_16x16x32_bf16 v[100:103], v[140:143], v[226:229], v[100:103]
	v_mfma_f32_16x16x32_bf16 v[96:99], v[148:151], v[226:229], v[96:99]
	v_mfma_f32_16x16x32_bf16 v[124:127], v[144:147], v[206:209], v[124:127]
	v_mfma_f32_16x16x32_bf16 v[120:123], v[152:155], v[206:209], v[120:123]
	v_mfma_f32_16x16x32_bf16 v[116:119], v[144:147], v[214:217], v[116:119]
	v_mfma_f32_16x16x32_bf16 v[112:115], v[152:155], v[214:217], v[112:115]
	v_mfma_f32_16x16x32_bf16 v[108:111], v[144:147], v[222:225], v[108:111]
	v_mfma_f32_16x16x32_bf16 v[104:107], v[152:155], v[222:225], v[104:107]
	v_mfma_f32_16x16x32_bf16 v[100:103], v[144:147], v[230:233], v[100:103]
	v_mfma_f32_16x16x32_bf16 v[96:99], v[152:155], v[230:233], v[96:99]
	v_mfma_f32_16x16x32_bf16 v[92:95], v[168:171], v[202:205], v[92:95]
	v_mfma_f32_16x16x32_bf16 v[88:91], v[190:193], v[202:205], v[88:91]
	v_mfma_f32_16x16x32_bf16 v[84:87], v[168:171], v[210:213], v[84:87]
	v_mfma_f32_16x16x32_bf16 v[80:83], v[190:193], v[210:213], v[80:83]
	v_mfma_f32_16x16x32_bf16 v[76:79], v[168:171], v[218:221], v[76:79]
	v_mfma_f32_16x16x32_bf16 v[72:75], v[190:193], v[218:221], v[72:75]
	v_mfma_f32_16x16x32_bf16 v[68:71], v[168:171], v[226:229], v[68:71]
	v_mfma_f32_16x16x32_bf16 v[64:67], v[190:193], v[226:229], v[64:67]
	v_mfma_f32_16x16x32_bf16 v[92:95], v[172:175], v[206:209], v[92:95]
	v_mfma_f32_16x16x32_bf16 v[88:91], v[194:197], v[206:209], v[88:91]
	v_mfma_f32_16x16x32_bf16 v[84:87], v[172:175], v[214:217], v[84:87]
	v_mfma_f32_16x16x32_bf16 v[80:83], v[194:197], v[214:217], v[80:83]
	v_mfma_f32_16x16x32_bf16 v[76:79], v[172:175], v[222:225], v[76:79]
	v_mfma_f32_16x16x32_bf16 v[72:75], v[194:197], v[222:225], v[72:75]
	v_mfma_f32_16x16x32_bf16 v[68:71], v[172:175], v[230:233], v[68:71]
	v_mfma_f32_16x16x32_bf16 v[64:67], v[194:197], v[230:233], v[64:67]
	s_setprio 0
	s_barrier
	v_lshl_add_u64 v[176:177], s[22:23], 0, v[132:133]
	s_add_i32 s66, s55, s20
	v_lshl_add_u64 v[198:199], v[176:177], 0, s[34:35]
	s_mov_b32 m0, s66
	s_add_i32 s63, s66, 0x2000
	ds_read_b128 v[202:205], v166 offset:16384
	ds_read_b128 v[206:209], v166 offset:17408
	ds_read_b128 v[210:213], v166 offset:18432
	ds_read_b128 v[214:217], v166 offset:19456
	ds_read_b128 v[218:221], v166 offset:20480
	ds_read_b128 v[222:225], v166 offset:21504
	ds_read_b128 v[226:229], v166 offset:22528
	ds_read_b128 v[230:233], v166 offset:23552
	global_load_lds_dwordx4 v[198:199], off
	v_lshl_add_u64 v[198:199], s[22:23], 0, v[136:137]
	s_add_u32 s70, s22, 0xb0100
	v_lshl_add_u64 v[234:235], v[198:199], 0, s[34:35]
	s_mov_b32 m0, s63
	s_addc_u32 s71, s23, 0
	s_add_i32 s64, s56, s20
	global_load_lds_dwordx4 v[234:235], off
	v_lshl_add_u64 v[234:235], s[70:71], 0, v[132:133]
	s_mov_b32 m0, s64
	s_add_i32 s65, s64, 0x2000
	global_load_lds_dwordx4 v[234:235], off
	v_lshl_add_u64 v[234:235], s[70:71], 0, v[136:137]
	s_mov_b32 m0, s65
	s_nop 0
	global_load_lds_dwordx4 v[234:235], off
	v_lshl_add_u64 v[234:235], s[4:5], 0, v[130:131]
	v_lshl_add_u64 v[236:237], v[234:235], 0, s[34:35]
	s_mov_b32 m0, s1
	s_nop 0
	global_load_lds_dwordx4 v[236:237], off
	v_lshl_add_u64 v[236:237], s[4:5], 0, v[134:135]
	v_lshl_add_u64 v[238:239], v[236:237], 0, s[34:35]
	s_mov_b32 m0, s49
	s_nop 0
	global_load_lds_dwordx4 v[238:239], off
	s_waitcnt vmcnt(8)
	s_waitcnt lgkmcnt(0)
	s_barrier
; #define PG8_STAGE(bufoff, gbase, voff) do { _Pragma("unroll") for (int _i = 0; _i < 2; ++_i) \
;         __builtin_amdgcn_global_load_lds((const unsigned*)((const char*)(gbase) + (voff)[_i]), (LAS unsigned*)(lds + (bufoff) + ldsw + _i * 8192), 16, 0, 0); } while (0)
; #define PG8_STAGEB(bufoff, gbase, perm) do { _Pragma("unroll") for (int _i = 0; _i < 2; ++_i) \
;         __builtin_amdgcn_global_load_lds((const unsigned*)((const char*)(gbase) + ((BSEL && (perm)) ? voffBp[_i] : voffB[_i])), (LAS unsigned*)(lds + (bufoff) + ldsw + _i * 8192), 16, 0, 0); } while (0)
; #define PG8_LDA(dst, b, h) do { _Pragma("unroll") for (int m = 0; m < 4; ++m) _Pragma("unroll") for (int k = 0; k < 2; ++k) dst[m][k] = *(const LAS bf16x8*)(lds + PG8_SA(b, h) + aoff + m * 2048 + k * 1024); } while (0)
; #define PG8_LDB(dst, b, h) do { _Pragma("unroll") for (int n = 0; n < 2; ++n) _Pragma("unroll") for (int k = 0; k < 2; ++k) dst[n][k] = *(const LAS bf16x8*)(lds + PG8_SB(b, h) + boff + n * 2048 + k * 1024); } while (0)
; #define PG8_WAIT_V(n) asm volatile("s_waitcnt vmcnt(" #n ")" ::: "memory")
; #define PG8_WAIT_L(n) asm volatile("s_waitcnt lgkmcnt(" #n ")" ::: "memory")
; template <class Epi, bool BSEL = false>
; __device__ __forceinline__ void gemm_phase(LAS unsigned char* lds, const Gemm g, const Order& S, const Epi& E, const int tid) {
;     ...
;             PG8_LDB(B0, 0, 0); PG8_LDB(B1, 0, 1); PG8_SCHED; PG8_LDA(At, 0, 0); PG8_STAGE(PG8_SA(1, 1), a1 + hstepA, voffA);
;             PG8_WAIT_V(8); PG8_WAIT_L(0); PG8_BAR; PG8_MMA(0, 0, At, B0); PG8_MMA(0, 1, At, B1); PG8_BAR; PG8_SCHED;
;             PG8_LDA(At, 0, 1); PG8_STAGEB(PG8_SB(0, 0), b2, p2); PG8_STAGEB(PG8_SB(0, 1), b2 + h2, p2); PG8_STAGE(PG8_SA(0, 0), a2, voffA);
;             PG8_WAIT_V(8); PG8_WAIT_L(0); PG8_BAR; PG8_MMA(1, 0, At, B0); PG8_MMA(1, 1, At, B1); PG8_BAR; PG8_SCHED;
;             PG8_LDB(B0, 1, 0); PG8_LDB(B1, 1, 1); PG8_SCHED; PG8_LDA(At, 1, 0); PG8_STAGE(PG8_SA(0, 1), a2 + hstepA, voffA);
;             PG8_WAIT_V(8); PG8_WAIT_L(0); PG8_BAR; PG8_MMA(0, 0, At, B0); PG8_MMA(0, 1, At, B1); PG8_BAR; PG8_SCHED;
;             PG8_LDA(At, 1, 1); PG8_STAGEB(PG8_SB(1, 0), b3, p2); PG8_STAGEB(PG8_SB(1, 1), b3 + h2, p2); PG8_STAGE(PG8_SA(1, 0), a3, voffA);
;             PG8_WAIT_V(8); PG8_WAIT_L(0); PG8_BAR; PG8_MMA(1, 0, At, B0); PG8_MMA(1, 1, At, B1); PG8_BAR; PG8_SCHED;
	s_setprio 1
	v_mfma_f32_16x16x32_bf16 v[60:63], v[140:143], v[202:205], v[60:63]
	v_mfma_f32_16x16x32_bf16 v[56:59], v[148:151], v[202:205], v[56:59]
	v_mfma_f32_16x16x32_bf16 v[52:55], v[140:143], v[210:213], v[52:55]
	v_mfma_f32_16x16x32_bf16 v[48:51], v[148:151], v[210:213], v[48:51]
	v_mfma_f32_16x16x32_bf16 v[44:47], v[140:143], v[218:221], v[44:47]
	v_mfma_f32_16x16x32_bf16 v[40:43], v[148:151], v[218:221], v[40:43]
	v_mfma_f32_16x16x32_bf16 v[36:39], v[140:143], v[226:229], v[36:39]
	v_mfma_f32_16x16x32_bf16 v[32:35], v[148:151], v[226:229], v[32:35]
	v_mfma_f32_16x16x32_bf16 v[60:63], v[144:147], v[206:209], v[60:63]
	v_mfma_f32_16x16x32_bf16 v[56:59], v[152:155], v[206:209], v[56:59]
	v_mfma_f32_16x16x32_bf16 v[52:55], v[144:147], v[214:217], v[52:55]
	v_mfma_f32_16x16x32_bf16 v[48:51], v[152:155], v[214:217], v[48:51]
	v_mfma_f32_16x16x32_bf16 v[44:47], v[144:147], v[222:225], v[44:47]
	v_mfma_f32_16x16x32_bf16 v[40:43], v[152:155], v[222:225], v[40:43]
	v_mfma_f32_16x16x32_bf16 v[36:39], v[144:147], v[230:233], v[36:39]
	v_mfma_f32_16x16x32_bf16 v[32:35], v[152:155], v[230:233], v[32:35]
	v_mfma_f32_16x16x32_bf16 v[28:31], v[168:171], v[202:205], v[28:31]
	v_mfma_f32_16x16x32_bf16 v[24:27], v[190:193], v[202:205], v[24:27]
	v_mfma_f32_16x16x32_bf16 v[20:23], v[168:171], v[210:213], v[20:23]
	v_mfma_f32_16x16x32_bf16 v[16:19], v[190:193], v[210:213], v[16:19]
	v_mfma_f32_16x16x32_bf16 v[12:15], v[168:171], v[218:221], v[12:15]
	v_mfma_f32_16x16x32_bf16 v[8:11], v[190:193], v[218:221], v[8:11]
	v_mfma_f32_16x16x32_bf16 v[4:7], v[168:171], v[226:229], v[4:7]
	v_mfma_f32_16x16x32_bf16 v[0:3], v[190:193], v[226:229], v[0:3]
	v_mfma_f32_16x16x32_bf16 v[28:31], v[172:175], v[206:209], v[28:31]
	v_mfma_f32_16x16x32_bf16 v[24:27], v[194:197], v[206:209], v[24:27]
	v_mfma_f32_16x16x32_bf16 v[20:23], v[172:175], v[214:217], v[20:23]
	v_mfma_f32_16x16x32_bf16 v[16:19], v[194:197], v[214:217], v[16:19]
	v_mfma_f32_16x16x32_bf16 v[12:15], v[172:175], v[222:225], v[12:15]
	v_mfma_f32_16x16x32_bf16 v[8:11], v[194:197], v[222:225], v[8:11]
	v_mfma_f32_16x16x32_bf16 v[4:7], v[172:175], v[230:233], v[4:7]
	v_mfma_f32_16x16x32_bf16 v[0:3], v[194:197], v[230:233], v[0:3]
	s_setprio 0
	s_barrier
	s_add_i32 s67, 0, 0x18000
	s_add_i32 s69, 0, 0x1c000
	v_add_u32_e32 v240, s67, v156
	v_add_u32_e32 v241, s69, v156
	ds_read_b128 v[140:143], v240
	ds_read_b128 v[144:147], v240 offset:1024
	ds_read_b128 v[148:151], v240 offset:2048
	ds_read_b128 v[152:155], v240 offset:3072
	ds_read_b128 v[168:171], v241
	ds_read_b128 v[172:175], v241 offset:1024
	ds_read_b128 v[190:193], v241 offset:2048
	ds_read_b128 v[194:197], v241 offset:3072
	s_add_u32 s70, s4, 0xb0100
	s_addc_u32 s71, s5, 0
	s_mov_b32 m0, s50
	v_lshl_add_u64 v[238:239], s[70:71], 0, v[130:131]
	ds_read_b128 v[202:205], v166 offset:32768
	ds_read_b128 v[206:209], v166 offset:33792
	ds_read_b128 v[210:213], v166 offset:34816
	ds_read_b128 v[214:217], v166 offset:35840
	ds_read_b128 v[218:221], v166 offset:36864
	ds_read_b128 v[222:225], v166 offset:37888
	ds_read_b128 v[226:229], v166 offset:38912
	ds_read_b128 v[230:233], v166 offset:39936
	global_load_lds_dwordx4 v[238:239], off
	v_lshl_add_u64 v[238:239], s[70:71], 0, v[134:135]
	s_mov_b32 m0, s51
	s_nop 0
	global_load_lds_dwordx4 v[238:239], off
	s_waitcnt vmcnt(8)
	s_waitcnt lgkmcnt(0)
	s_barrier
	s_setprio 1
	v_mfma_f32_16x16x32_bf16 v[124:127], v[140:143], v[202:205], v[124:127]
	v_mfma_f32_16x16x32_bf16 v[120:123], v[148:151], v[202:205], v[120:123]
	v_mfma_f32_16x16x32_bf16 v[116:119], v[140:143], v[210:213], v[116:119]
	v_mfma_f32_16x16x32_bf16 v[112:115], v[148:151], v[210:213], v[112:115]
	v_mfma_f32_16x16x32_bf16 v[108:111], v[140:143], v[218:221], v[108:111]
	v_mfma_f32_16x16x32_bf16 v[104:107], v[148:151], v[218:221], v[104:107]
	v_mfma_f32_16x16x32_bf16 v[100:103], v[140:143], v[226:229], v[100:103]
	v_mfma_f32_16x16x32_bf16 v[96:99], v[148:151], v[226:229], v[96:99]
	v_mfma_f32_16x16x32_bf16 v[124:127], v[144:147], v[206:209], v[124:127]
	v_mfma_f32_16x16x32_bf16 v[120:123], v[152:155], v[206:209], v[120:123]
	v_mfma_f32_16x16x32_bf16 v[116:119], v[144:147], v[214:217], v[116:119]
	v_mfma_f32_16x16x32_bf16 v[112:115], v[152:155], v[214:217], v[112:115]
	v_mfma_f32_16x16x32_bf16 v[108:111], v[144:147], v[222:225], v[108:111]
	v_mfma_f32_16x16x32_bf16 v[104:107], v[152:155], v[222:225], v[104:107]
	v_mfma_f32_16x16x32_bf16 v[100:103], v[144:147], v[230:233], v[100:103]
	v_mfma_f32_16x16x32_bf16 v[96:99], v[152:155], v[230:233], v[96:99]
	v_mfma_f32_16x16x32_bf16 v[92:95], v[168:171], v[202:205], v[92:95]
	v_mfma_f32_16x16x32_bf16 v[88:91], v[190:193], v[202:205], v[88:91]
	v_mfma_f32_16x16x32_bf16 v[84:87], v[168:171], v[210:213], v[84:87]
	v_mfma_f32_16x16x32_bf16 v[80:83], v[190:193], v[210:213], v[80:83]
	v_mfma_f32_16x16x32_bf16 v[76:79], v[168:171], v[218:221], v[76:79]
	v_mfma_f32_16x16x32_bf16 v[72:75], v[190:193], v[218:221], v[72:75]
	v_mfma_f32_16x16x32_bf16 v[68:71], v[168:171], v[226:229], v[68:71]
	v_mfma_f32_16x16x32_bf16 v[64:67], v[190:193], v[226:229], v[64:67]
	v_mfma_f32_16x16x32_bf16 v[92:95], v[172:175], v[206:209], v[92:95]
	v_mfma_f32_16x16x32_bf16 v[88:91], v[194:197], v[206:209], v[88:91]
	v_mfma_f32_16x16x32_bf16 v[84:87], v[172:175], v[214:217], v[84:87]
	v_mfma_f32_16x16x32_bf16 v[80:83], v[194:197], v[214:217], v[80:83]
	v_mfma_f32_16x16x32_bf16 v[76:79], v[172:175], v[222:225], v[76:79]
	v_mfma_f32_16x16x32_bf16 v[72:75], v[194:197], v[222:225], v[72:75]
	v_mfma_f32_16x16x32_bf16 v[68:71], v[172:175], v[230:233], v[68:71]
	v_mfma_f32_16x16x32_bf16 v[64:67], v[194:197], v[230:233], v[64:67]
	s_setprio 0
	s_barrier
; #define PG8_STAGE(bufoff, gbase, voff) do { _Pragma("unroll") for (int _i = 0; _i < 2; ++_i) \
;         __builtin_amdgcn_global_load_lds((const unsigned*)((const char*)(gbase) + (voff)[_i]), (LAS unsigned*)(lds + (bufoff) + ldsw + _i * 8192), 16, 0, 0); } while (0)
; #define PG8_STAGEB(bufoff, gbase, perm) do { _Pragma("unroll") for (int _i = 0; _i < 2; ++_i) \
;         __builtin_amdgcn_global_load_lds((const unsigned*)((const char*)(gbase) + ((BSEL && (perm)) ? voffBp[_i] : voffB[_i])), (LAS unsigned*)(lds + (bufoff) + ldsw + _i * 8192), 16, 0, 0); } while (0)
; #define PG8_LDA(dst, b, h) do { _Pragma("unroll") for (int m = 0; m < 4; ++m) _Pragma("unroll") for (int k = 0; k < 2; ++k) dst[m][k] = *(const LAS bf16x8*)(lds + PG8_SA(b, h) + aoff + m * 2048 + k * 1024); } while (0)
; #define PG8_LDB(dst, b, h) do { _Pragma("unroll") for (int n = 0; n < 2; ++n) _Pragma("unroll") for (int k = 0; k < 2; ++k) dst[n][k] = *(const LAS bf16x8*)(lds + PG8_SB(b, h) + boff + n * 2048 + k * 1024); } while (0)
; #define PG8_WAIT_V(n) asm volatile("s_waitcnt vmcnt(" #n ")" ::: "memory")
; #define PG8_WAIT_L(n) asm volatile("s_waitcnt lgkmcnt(" #n ")" ::: "memory")
; template <class Epi, bool BSEL = false>
; __device__ __forceinline__ void gemm_phase(LAS unsigned char* lds, const Gemm g, const Order& S, const Epi& E, const int tid) {
;     ...
;             PG8_LDB(B0, 0, 0); PG8_LDB(B1, 0, 1); PG8_SCHED; PG8_LDA(At, 0, 0); PG8_STAGE(PG8_SA(1, 1), a1 + hstepA, voffA);
;             PG8_WAIT_V(8); PG8_WAIT_L(0); PG8_BAR; PG8_MMA(0, 0, At, B0); PG8_MMA(0, 1, At, B1); PG8_BAR; PG8_SCHED;
;             PG8_LDA(At, 0, 1); PG8_STAGEB(PG8_SB(0, 0), b2, p2); PG8_STAGEB(PG8_SB(0, 1), b2 + h2, p2); PG8_STAGE(PG8_SA(0, 0), a2, voffA);
;             PG8_WAIT_V(8); PG8_WAIT_L(0); PG8_BAR; PG8_MMA(1, 0, At, B0); PG8_MMA(1, 1, At, B1); PG8_BAR; PG8_SCHED;
;             PG8_LDB(B0, 1, 0); PG8_LDB(B1, 1, 1); PG8_SCHED; PG8_LDA(At, 1, 0); PG8_STAGE(PG8_SA(0, 1), a2 + hstepA, voffA);
;             PG8_WAIT_V(8); PG8_WAIT_L(0); PG8_BAR; PG8_MMA(0, 0, At, B0); PG8_MMA(0, 1, At, B1); PG8_BAR; PG8_SCHED;
;             PG8_LDA(At, 1, 1); PG8_STAGEB(PG8_SB(1, 0), b3, p2); PG8_STAGEB(PG8_SB(1, 1), b3 + h2, p2); PG8_STAGE(PG8_SA(1, 0), a3, voffA);
;             PG8_WAIT_V(8); PG8_WAIT_L(0); PG8_BAR; PG8_MMA(1, 0, At, B0); PG8_MMA(1, 1, At, B1); PG8_BAR; PG8_SCHED;
	s_add_i32 s71, s67, s20
	s_add_i32 s67, s71, 0x2000
	v_lshl_add_u64 v[176:177], v[176:177], 0, s[36:37]
	s_mov_b32 m0, s71
	s_add_u32 s72, s22, 0xb0180
	ds_read_b128 v[202:205], v166 offset:49152
	ds_read_b128 v[206:209], v166 offset:50176
	ds_read_b128 v[210:213], v166 offset:51200
	ds_read_b128 v[214:217], v166 offset:52224
	ds_read_b128 v[218:221], v166 offset:53248
	ds_read_b128 v[222:225], v166 offset:54272
	ds_read_b128 v[226:229], v166 offset:55296
	ds_read_b128 v[230:233], v166 offset:56320
	global_load_lds_dwordx4 v[176:177], off
	v_lshl_add_u64 v[176:177], v[198:199], 0, s[36:37]
	s_mov_b32 m0, s67
	s_addc_u32 s73, s23, 0
	s_add_i32 s69, s69, s20
	global_load_lds_dwordx4 v[176:177], off
	v_lshl_add_u64 v[176:177], s[72:73], 0, v[132:133]
	s_mov_b32 m0, s69
	s_add_i32 s70, s69, 0x2000
	global_load_lds_dwordx4 v[176:177], off
	v_lshl_add_u64 v[176:177], s[72:73], 0, v[136:137]
	s_mov_b32 m0, s70
	s_nop 0
	global_load_lds_dwordx4 v[176:177], off
	v_lshl_add_u64 v[176:177], v[234:235], 0, s[36:37]
	s_mov_b32 m0, s53
	s_nop 0
	global_load_lds_dwordx4 v[176:177], off
	v_lshl_add_u64 v[176:177], v[236:237], 0, s[36:37]
	s_mov_b32 m0, s54
	s_nop 0
	global_load_lds_dwordx4 v[176:177], off
	s_waitcnt vmcnt(8)
	s_waitcnt lgkmcnt(0)
	s_barrier
	s_setprio 1
	v_mfma_f32_16x16x32_bf16 v[60:63], v[140:143], v[202:205], v[60:63]
	v_mfma_f32_16x16x32_bf16 v[56:59], v[148:151], v[202:205], v[56:59]
	v_mfma_f32_16x16x32_bf16 v[52:55], v[140:143], v[210:213], v[52:55]
	v_mfma_f32_16x16x32_bf16 v[48:51], v[148:151], v[210:213], v[48:51]
	v_mfma_f32_16x16x32_bf16 v[44:47], v[140:143], v[218:221], v[44:47]
	v_mfma_f32_16x16x32_bf16 v[40:43], v[148:151], v[218:221], v[40:43]
	v_mfma_f32_16x16x32_bf16 v[36:39], v[140:143], v[226:229], v[36:39]
	v_mfma_f32_16x16x32_bf16 v[32:35], v[148:151], v[226:229], v[32:35]
	v_mfma_f32_16x16x32_bf16 v[60:63], v[144:147], v[206:209], v[60:63]
	v_mfma_f32_16x16x32_bf16 v[56:59], v[152:155], v[206:209], v[56:59]
	v_mfma_f32_16x16x32_bf16 v[52:55], v[144:147], v[214:217], v[52:55]
	v_mfma_f32_16x16x32_bf16 v[48:51], v[152:155], v[214:217], v[48:51]
	v_mfma_f32_16x16x32_bf16 v[44:47], v[144:147], v[222:225], v[44:47]
	v_mfma_f32_16x16x32_bf16 v[40:43], v[152:155], v[222:225], v[40:43]
	v_mfma_f32_16x16x32_bf16 v[36:39], v[144:147], v[230:233], v[36:39]
	v_mfma_f32_16x16x32_bf16 v[32:35], v[152:155], v[230:233], v[32:35]
	v_mfma_f32_16x16x32_bf16 v[28:31], v[168:171], v[202:205], v[28:31]
	v_mfma_f32_16x16x32_bf16 v[24:27], v[190:193], v[202:205], v[24:27]
	v_mfma_f32_16x16x32_bf16 v[20:23], v[168:171], v[210:213], v[20:23]
	v_mfma_f32_16x16x32_bf16 v[16:19], v[190:193], v[210:213], v[16:19]
	v_mfma_f32_16x16x32_bf16 v[12:15], v[168:171], v[218:221], v[12:15]
	v_mfma_f32_16x16x32_bf16 v[8:11], v[190:193], v[218:221], v[8:11]
	v_mfma_f32_16x16x32_bf16 v[4:7], v[168:171], v[226:229], v[4:7]
	v_mfma_f32_16x16x32_bf16 v[0:3], v[190:193], v[226:229], v[0:3]
	v_mfma_f32_16x16x32_bf16 v[28:31], v[172:175], v[206:209], v[28:31]
	v_mfma_f32_16x16x32_bf16 v[24:27], v[194:197], v[206:209], v[24:27]
	v_mfma_f32_16x16x32_bf16 v[20:23], v[172:175], v[214:217], v[20:23]
	v_mfma_f32_16x16x32_bf16 v[16:19], v[194:197], v[214:217], v[16:19]
	v_mfma_f32_16x16x32_bf16 v[12:15], v[172:175], v[222:225], v[12:15]
	v_mfma_f32_16x16x32_bf16 v[8:11], v[194:197], v[222:225], v[8:11]
	v_mfma_f32_16x16x32_bf16 v[4:7], v[172:175], v[230:233], v[4:7]
	v_mfma_f32_16x16x32_bf16 v[0:3], v[194:197], v[230:233], v[0:3]
	s_setprio 0
	s_barrier
	ds_read_b128 v[140:143], v167
	ds_read_b128 v[144:147], v167 offset:1024
	ds_read_b128 v[148:151], v167 offset:2048
	ds_read_b128 v[152:155], v167 offset:3072
	ds_read_b128 v[168:171], v201
	ds_read_b128 v[172:175], v201 offset:1024
	ds_read_b128 v[190:193], v201 offset:2048
	ds_read_b128 v[194:197], v201 offset:3072
	s_add_u32 s72, s4, 0xb0180
	s_addc_u32 s73, s5, 0
	s_mov_b32 m0, s68
	v_lshl_add_u64 v[176:177], s[72:73], 0, v[130:131]
	ds_read_b128 v[202:205], v166
	ds_read_b128 v[206:209], v166 offset:1024
	ds_read_b128 v[210:213], v166 offset:2048
	ds_read_b128 v[214:217], v166 offset:3072
	ds_read_b128 v[218:221], v166 offset:4096
	ds_read_b128 v[222:225], v166 offset:5120
	ds_read_b128 v[226:229], v166 offset:6144
	ds_read_b128 v[230:233], v166 offset:7168
	global_load_lds_dwordx4 v[176:177], off
	v_lshl_add_u64 v[176:177], s[72:73], 0, v[134:135]
	s_mov_b32 m0, s39
	s_nop 0
	global_load_lds_dwordx4 v[176:177], off
	s_waitcnt vmcnt(8)
	s_waitcnt lgkmcnt(0)
	s_barrier
	s_setprio 1
	v_mfma_f32_16x16x32_bf16 v[124:127], v[140:143], v[202:205], v[124:127]
	v_mfma_f32_16x16x32_bf16 v[120:123], v[148:151], v[202:205], v[120:123]
	v_mfma_f32_16x16x32_bf16 v[116:119], v[140:143], v[210:213], v[116:119]
	v_mfma_f32_16x16x32_bf16 v[112:115], v[148:151], v[210:213], v[112:115]
	v_mfma_f32_16x16x32_bf16 v[108:111], v[140:143], v[218:221], v[108:111]
	v_mfma_f32_16x16x32_bf16 v[104:107], v[148:151], v[218:221], v[104:107]
	v_mfma_f32_16x16x32_bf16 v[100:103], v[140:143], v[226:229], v[100:103]
	v_mfma_f32_16x16x32_bf16 v[96:99], v[148:151], v[226:229], v[96:99]
	v_mfma_f32_16x16x32_bf16 v[124:127], v[144:147], v[206:209], v[124:127]
	v_mfma_f32_16x16x32_bf16 v[120:123], v[152:155], v[206:209], v[120:123]
	v_mfma_f32_16x16x32_bf16 v[116:119], v[144:147], v[214:217], v[116:119]
	v_mfma_f32_16x16x32_bf16 v[112:115], v[152:155], v[214:217], v[112:115]
	v_mfma_f32_16x16x32_bf16 v[108:111], v[144:147], v[222:225], v[108:111]
	v_mfma_f32_16x16x32_bf16 v[104:107], v[152:155], v[222:225], v[104:107]
	v_mfma_f32_16x16x32_bf16 v[100:103], v[144:147], v[230:233], v[100:103]
	v_mfma_f32_16x16x32_bf16 v[96:99], v[152:155], v[230:233], v[96:99]
	v_mfma_f32_16x16x32_bf16 v[92:95], v[168:171], v[202:205], v[92:95]
	v_mfma_f32_16x16x32_bf16 v[88:91], v[190:193], v[202:205], v[88:91]
	v_mfma_f32_16x16x32_bf16 v[84:87], v[168:171], v[210:213], v[84:87]
	v_mfma_f32_16x16x32_bf16 v[80:83], v[190:193], v[210:213], v[80:83]
	v_mfma_f32_16x16x32_bf16 v[76:79], v[168:171], v[218:221], v[76:79]
	v_mfma_f32_16x16x32_bf16 v[72:75], v[190:193], v[218:221], v[72:75]
	v_mfma_f32_16x16x32_bf16 v[68:71], v[168:171], v[226:229], v[68:71]
	v_mfma_f32_16x16x32_bf16 v[64:67], v[190:193], v[226:229], v[64:67]
	v_mfma_f32_16x16x32_bf16 v[92:95], v[172:175], v[206:209], v[92:95]
	v_mfma_f32_16x16x32_bf16 v[88:91], v[194:197], v[206:209], v[88:91]
	v_mfma_f32_16x16x32_bf16 v[84:87], v[172:175], v[214:217], v[84:87]
	v_mfma_f32_16x16x32_bf16 v[80:83], v[194:197], v[214:217], v[80:83]
	v_mfma_f32_16x16x32_bf16 v[76:79], v[172:175], v[222:225], v[76:79]
	v_mfma_f32_16x16x32_bf16 v[72:75], v[194:197], v[222:225], v[72:75]
	v_mfma_f32_16x16x32_bf16 v[68:71], v[172:175], v[230:233], v[68:71]
	v_mfma_f32_16x16x32_bf16 v[64:67], v[194:197], v[230:233], v[64:67]
	s_setprio 0
	s_barrier
; #define PG8_STAGE(bufoff, gbase, voff) do { _Pragma("unroll") for (int _i = 0; _i < 2; ++_i) \
;         __builtin_amdgcn_global_load_lds((const unsigned*)((const char*)(gbase) + (voff)[_i]), (LAS unsigned*)(lds + (bufoff) + ldsw + _i * 8192), 16, 0, 0); } while (0)
; #define PG8_STAGEB(bufoff, gbase, perm) do { _Pragma("unroll") for (int _i = 0; _i < 2; ++_i) \
;         __builtin_amdgcn_global_load_lds((const unsigned*)((const char*)(gbase) + ((BSEL && (perm)) ? voffBp[_i] : voffB[_i])), (LAS unsigned*)(lds + (bufoff) + ldsw + _i * 8192), 16, 0, 0); } while (0)
; #define PG8_LDA(dst, b, h) do { _Pragma("unroll") for (int m = 0; m < 4; ++m) _Pragma("unroll") for (int k = 0; k < 2; ++k) dst[m][k] = *(const LAS bf16x8*)(lds + PG8_SA(b, h) + aoff + m * 2048 + k * 1024); } while (0)
; #define PG8_LDB(dst, b, h) do { _Pragma("unroll") for (int n = 0; n < 2; ++n) _Pragma("unroll") for (int k = 0; k < 2; ++k) dst[n][k] = *(const LAS bf16x8*)(lds + PG8_SB(b, h) + boff + n * 2048 + k * 1024); } while (0)
; #define PG8_WAIT_V(n) asm volatile("s_waitcnt vmcnt(" #n ")" ::: "memory")
; #define PG8_WAIT_L(n) asm volatile("s_waitcnt lgkmcnt(" #n ")" ::: "memory")
; template <class Epi, bool BSEL = false>
; __device__ __forceinline__ void gemm_phase(LAS unsigned char* lds, const Gemm g, const Order& S, const Epi& E, const int tid) {
;     ...
;             PG8_LDB(B0, 0, 0); PG8_LDB(B1, 0, 1); PG8_SCHED; PG8_LDA(At, 0, 0); PG8_STAGE(PG8_SA(1, 1), a1 + hstepA, voffA);
;             PG8_WAIT_V(8); PG8_WAIT_L(0); PG8_BAR; PG8_MMA(0, 0, At, B0); PG8_MMA(0, 1, At, B1); PG8_BAR; PG8_SCHED;
;             PG8_LDA(At, 0, 1); PG8_STAGEB(PG8_SB(0, 0), b2, p2); PG8_STAGEB(PG8_SB(0, 1), b2 + h2, p2); PG8_STAGE(PG8_SA(0, 0), a2, voffA);
;             PG8_WAIT_V(8); PG8_WAIT_L(0); PG8_BAR; PG8_MMA(1, 0, At, B0); PG8_MMA(1, 1, At, B1); PG8_BAR; PG8_SCHED;
;             PG8_LDB(B0, 1, 0); PG8_LDB(B1, 1, 1); PG8_SCHED; PG8_LDA(At, 1, 0); PG8_STAGE(PG8_SA(0, 1), a2 + hstepA, voffA);
;             PG8_WAIT_V(8); PG8_WAIT_L(0); PG8_BAR; PG8_MMA(0, 0, At, B0); PG8_MMA(0, 1, At, B1); PG8_BAR; PG8_SCHED;
;             PG8_LDA(At, 1, 1); PG8_STAGEB(PG8_SB(1, 0), b3, p2); PG8_STAGEB(PG8_SB(1, 1), b3 + h2, p2); PG8_STAGE(PG8_SA(1, 0), a3, voffA);
;             PG8_WAIT_V(8); PG8_WAIT_L(0); PG8_BAR; PG8_MMA(1, 0, At, B0); PG8_MMA(1, 1, At, B1); PG8_BAR; PG8_SCHED;
	s_mov_b32 m0, s66
	v_lshl_add_u64 v[176:177], s[2:3], 0, v[132:133]
	s_add_u32 s72, s2, 0xb0000
	ds_read_b128 v[202:205], v166 offset:16384
	ds_read_b128 v[206:209], v166 offset:17408
	ds_read_b128 v[210:213], v166 offset:18432
	ds_read_b128 v[214:217], v166 offset:19456
	ds_read_b128 v[218:221], v166 offset:20480
	ds_read_b128 v[222:225], v166 offset:21504
	ds_read_b128 v[226:229], v166 offset:22528
	ds_read_b128 v[230:233], v166 offset:23552
	global_load_lds_dwordx4 v[176:177], off
	v_lshl_add_u64 v[198:199], s[2:3], 0, v[136:137]
	s_mov_b32 m0, s63
	s_addc_u32 s73, s3, 0
	global_load_lds_dwordx4 v[198:199], off
	v_lshl_add_u64 v[234:235], s[72:73], 0, v[132:133]
	s_mov_b32 m0, s64
	v_lshl_add_u64 v[236:237], s[44:45], 0, v[134:135]
	global_load_lds_dwordx4 v[234:235], off
	v_lshl_add_u64 v[234:235], s[72:73], 0, v[136:137]
	s_mov_b32 m0, s65
	s_nop 0
	global_load_lds_dwordx4 v[234:235], off
	v_lshl_add_u64 v[234:235], s[44:45], 0, v[130:131]
	s_mov_b32 m0, s1
	s_nop 0
	global_load_lds_dwordx4 v[234:235], off
	s_mov_b32 m0, s49
	s_nop 0
	global_load_lds_dwordx4 v[236:237], off
	s_waitcnt vmcnt(8)
	s_waitcnt lgkmcnt(0)
	s_barrier
	s_setprio 1
	v_mfma_f32_16x16x32_bf16 v[60:63], v[140:143], v[202:205], v[60:63]
	v_mfma_f32_16x16x32_bf16 v[56:59], v[148:151], v[202:205], v[56:59]
	v_mfma_f32_16x16x32_bf16 v[52:55], v[140:143], v[210:213], v[52:55]
	v_mfma_f32_16x16x32_bf16 v[48:51], v[148:151], v[210:213], v[48:51]
	v_mfma_f32_16x16x32_bf16 v[44:47], v[140:143], v[218:221], v[44:47]
	v_mfma_f32_16x16x32_bf16 v[40:43], v[148:151], v[218:221], v[40:43]
	v_mfma_f32_16x16x32_bf16 v[36:39], v[140:143], v[226:229], v[36:39]
	v_mfma_f32_16x16x32_bf16 v[32:35], v[148:151], v[226:229], v[32:35]
	v_mfma_f32_16x16x32_bf16 v[60:63], v[144:147], v[206:209], v[60:63]
	v_mfma_f32_16x16x32_bf16 v[56:59], v[152:155], v[206:209], v[56:59]
	v_mfma_f32_16x16x32_bf16 v[52:55], v[144:147], v[214:217], v[52:55]
	v_mfma_f32_16x16x32_bf16 v[48:51], v[152:155], v[214:217], v[48:51]
	v_mfma_f32_16x16x32_bf16 v[44:47], v[144:147], v[222:225], v[44:47]
	v_mfma_f32_16x16x32_bf16 v[40:43], v[152:155], v[222:225], v[40:43]
	v_mfma_f32_16x16x32_bf16 v[36:39], v[144:147], v[230:233], v[36:39]
	v_mfma_f32_16x16x32_bf16 v[32:35], v[152:155], v[230:233], v[32:35]
	v_mfma_f32_16x16x32_bf16 v[28:31], v[168:171], v[202:205], v[28:31]
	v_mfma_f32_16x16x32_bf16 v[24:27], v[190:193], v[202:205], v[24:27]
	v_mfma_f32_16x16x32_bf16 v[20:23], v[168:171], v[210:213], v[20:23]
	v_mfma_f32_16x16x32_bf16 v[16:19], v[190:193], v[210:213], v[16:19]
	v_mfma_f32_16x16x32_bf16 v[12:15], v[168:171], v[218:221], v[12:15]
	v_mfma_f32_16x16x32_bf16 v[8:11], v[190:193], v[218:221], v[8:11]
	v_mfma_f32_16x16x32_bf16 v[4:7], v[168:171], v[226:229], v[4:7]
	v_mfma_f32_16x16x32_bf16 v[0:3], v[190:193], v[226:229], v[0:3]
	v_mfma_f32_16x16x32_bf16 v[28:31], v[172:175], v[206:209], v[28:31]
	v_mfma_f32_16x16x32_bf16 v[24:27], v[194:197], v[206:209], v[24:27]
	v_mfma_f32_16x16x32_bf16 v[20:23], v[172:175], v[214:217], v[20:23]
	v_mfma_f32_16x16x32_bf16 v[16:19], v[194:197], v[214:217], v[16:19]
	v_mfma_f32_16x16x32_bf16 v[12:15], v[172:175], v[222:225], v[12:15]
	v_mfma_f32_16x16x32_bf16 v[8:11], v[194:197], v[222:225], v[8:11]
	v_mfma_f32_16x16x32_bf16 v[4:7], v[172:175], v[230:233], v[4:7]
	v_mfma_f32_16x16x32_bf16 v[0:3], v[194:197], v[230:233], v[0:3]
	s_setprio 0
	s_barrier
	ds_read_b128 v[140:143], v240
	ds_read_b128 v[144:147], v240 offset:1024
	ds_read_b128 v[148:151], v240 offset:2048
	ds_read_b128 v[152:155], v240 offset:3072
	ds_read_b128 v[168:171], v241
	ds_read_b128 v[172:175], v241 offset:1024
	ds_read_b128 v[190:193], v241 offset:2048
	ds_read_b128 v[194:197], v241 offset:3072
	s_add_u32 s44, s44, 0xb0000
	s_addc_u32 s45, s45, 0
	s_mov_b32 m0, s50
	v_lshl_add_u64 v[238:239], s[44:45], 0, v[130:131]
	ds_read_b128 v[202:205], v166 offset:32768
	ds_read_b128 v[206:209], v166 offset:33792
	ds_read_b128 v[210:213], v166 offset:34816
	ds_read_b128 v[214:217], v166 offset:35840
	ds_read_b128 v[218:221], v166 offset:36864
	ds_read_b128 v[222:225], v166 offset:37888
	ds_read_b128 v[226:229], v166 offset:38912
	ds_read_b128 v[230:233], v166 offset:39936
	global_load_lds_dwordx4 v[238:239], off
	v_lshl_add_u64 v[238:239], s[44:45], 0, v[134:135]
	s_mov_b32 m0, s51
	s_nop 0
	global_load_lds_dwordx4 v[238:239], off
	s_waitcnt vmcnt(8)
	s_waitcnt lgkmcnt(0)
	s_barrier
; #define PG8_STAGE(bufoff, gbase, voff) do { _Pragma("unroll") for (int _i = 0; _i < 2; ++_i) \
;         __builtin_amdgcn_global_load_lds((const unsigned*)((const char*)(gbase) + (voff)[_i]), (LAS unsigned*)(lds + (bufoff) + ldsw + _i * 8192), 16, 0, 0); } while (0)
; #define PG8_STAGEB(bufoff, gbase, perm) do { _Pragma("unroll") for (int _i = 0; _i < 2; ++_i) \
;         __builtin_amdgcn_global_load_lds((const unsigned*)((const char*)(gbase) + ((BSEL && (perm)) ? voffBp[_i] : voffB[_i])), (LAS unsigned*)(lds + (bufoff) + ldsw + _i * 8192), 16, 0, 0); } while (0)
; #define PG8_LDA(dst, b, h) do { _Pragma("unroll") for (int m = 0; m < 4; ++m) _Pragma("unroll") for (int k = 0; k < 2; ++k) dst[m][k] = *(const LAS bf16x8*)(lds + PG8_SA(b, h) + aoff + m * 2048 + k * 1024); } while (0)
; #define PG8_LDB(dst, b, h) do { _Pragma("unroll") for (int n = 0; n < 2; ++n) _Pragma("unroll") for (int k = 0; k < 2; ++k) dst[n][k] = *(const LAS bf16x8*)(lds + PG8_SB(b, h) + boff + n * 2048 + k * 1024); } while (0)
; #define PG8_WAIT_V(n) asm volatile("s_waitcnt vmcnt(" #n ")" ::: "memory")
; #define PG8_BAR __builtin_amdgcn_s_barrier()
; template <class Epi, bool BSEL = false>
; __device__ __forceinline__ void gemm_phase(LAS unsigned char* lds, const Gemm g, const Order& S, const Epi& E, const int tid) {
;     ...
;             PG8_LDB(B0, 0, 0); PG8_LDB(B1, 0, 1); PG8_SCHED; PG8_LDA(At, 0, 0); PG8_STAGE(PG8_SA(1, 1), a1 + hstepA, voffA);
;             PG8_WAIT_V(8); PG8_WAIT_L(0); PG8_BAR; PG8_MMA(0, 0, At, B0); PG8_MMA(0, 1, At, B1); PG8_BAR; PG8_SCHED;
;             PG8_LDA(At, 0, 1); PG8_STAGEB(PG8_SB(0, 0), b2, p2); PG8_STAGEB(PG8_SB(0, 1), b2 + h2, p2); PG8_STAGE(PG8_SA(0, 0), a2, voffA);
;             PG8_WAIT_V(8); PG8_WAIT_L(0); PG8_BAR; PG8_MMA(1, 0, At, B0); PG8_MMA(1, 1, At, B1); PG8_BAR; PG8_SCHED;
;             PG8_LDB(B0, 1, 0); PG8_LDB(B1, 1, 1); PG8_SCHED; PG8_LDA(At, 1, 0); PG8_STAGE(PG8_SA(0, 1), a2 + hstepA, voffA);
;             PG8_WAIT_V(8); PG8_WAIT_L(0); PG8_BAR; PG8_MMA(0, 0, At, B0); PG8_MMA(0, 1, At, B1); PG8_BAR; PG8_SCHED;
;             PG8_LDA(At, 1, 1); PG8_STAGEB(PG8_SB(1, 0), b3, p2); PG8_STAGEB(PG8_SB(1, 1), b3 + h2, p2); PG8_STAGE(PG8_SA(1, 0), a3, voffA);
;             PG8_WAIT_V(8); PG8_WAIT_L(0); PG8_BAR; PG8_MMA(1, 0, At, B0); PG8_MMA(1, 1, At, B1); PG8_BAR; PG8_SCHED;
;         }
;         if constexpr (ALIGN_EPI) { if (wr == 0) PG8_BAR; }
	s_setprio 1
	v_mfma_f32_16x16x32_bf16 v[124:127], v[140:143], v[202:205], v[124:127]
	v_mfma_f32_16x16x32_bf16 v[120:123], v[148:151], v[202:205], v[120:123]
	v_mfma_f32_16x16x32_bf16 v[116:119], v[140:143], v[210:213], v[116:119]
	v_mfma_f32_16x16x32_bf16 v[112:115], v[148:151], v[210:213], v[112:115]
	v_mfma_f32_16x16x32_bf16 v[108:111], v[140:143], v[218:221], v[108:111]
	v_mfma_f32_16x16x32_bf16 v[104:107], v[148:151], v[218:221], v[104:107]
	v_mfma_f32_16x16x32_bf16 v[100:103], v[140:143], v[226:229], v[100:103]
	v_mfma_f32_16x16x32_bf16 v[96:99], v[148:151], v[226:229], v[96:99]
	v_mfma_f32_16x16x32_bf16 v[124:127], v[144:147], v[206:209], v[124:127]
	v_mfma_f32_16x16x32_bf16 v[120:123], v[152:155], v[206:209], v[120:123]
	v_mfma_f32_16x16x32_bf16 v[116:119], v[144:147], v[214:217], v[116:119]
	v_mfma_f32_16x16x32_bf16 v[112:115], v[152:155], v[214:217], v[112:115]
	v_mfma_f32_16x16x32_bf16 v[108:111], v[144:147], v[222:225], v[108:111]
	v_mfma_f32_16x16x32_bf16 v[104:107], v[152:155], v[222:225], v[104:107]
	v_mfma_f32_16x16x32_bf16 v[100:103], v[144:147], v[230:233], v[100:103]
	v_mfma_f32_16x16x32_bf16 v[96:99], v[152:155], v[230:233], v[96:99]
	v_mfma_f32_16x16x32_bf16 v[92:95], v[168:171], v[202:205], v[92:95]
	v_mfma_f32_16x16x32_bf16 v[88:91], v[190:193], v[202:205], v[88:91]
	v_mfma_f32_16x16x32_bf16 v[84:87], v[168:171], v[210:213], v[84:87]
	v_mfma_f32_16x16x32_bf16 v[80:83], v[190:193], v[210:213], v[80:83]
	v_mfma_f32_16x16x32_bf16 v[76:79], v[168:171], v[218:221], v[76:79]
	v_mfma_f32_16x16x32_bf16 v[72:75], v[190:193], v[218:221], v[72:75]
	v_mfma_f32_16x16x32_bf16 v[68:71], v[168:171], v[226:229], v[68:71]
	v_mfma_f32_16x16x32_bf16 v[64:67], v[190:193], v[226:229], v[64:67]
	v_mfma_f32_16x16x32_bf16 v[92:95], v[172:175], v[206:209], v[92:95]
	v_mfma_f32_16x16x32_bf16 v[88:91], v[194:197], v[206:209], v[88:91]
	v_mfma_f32_16x16x32_bf16 v[84:87], v[172:175], v[214:217], v[84:87]
	v_mfma_f32_16x16x32_bf16 v[80:83], v[194:197], v[214:217], v[80:83]
	v_mfma_f32_16x16x32_bf16 v[76:79], v[172:175], v[222:225], v[76:79]
	v_mfma_f32_16x16x32_bf16 v[72:75], v[194:197], v[222:225], v[72:75]
	v_mfma_f32_16x16x32_bf16 v[68:71], v[172:175], v[230:233], v[68:71]
	v_mfma_f32_16x16x32_bf16 v[64:67], v[194:197], v[230:233], v[64:67]
	s_setprio 0
	s_barrier
	s_mov_b32 m0, s71
	v_lshl_add_u64 v[176:177], v[176:177], 0, s[26:27]
	s_add_u32 s2, s2, 0xb0080
	ds_read_b128 v[202:205], v166 offset:49152
	ds_read_b128 v[206:209], v166 offset:50176
	ds_read_b128 v[210:213], v166 offset:51200
	ds_read_b128 v[214:217], v166 offset:52224
	ds_read_b128 v[218:221], v166 offset:53248
	ds_read_b128 v[222:225], v166 offset:54272
	ds_read_b128 v[226:229], v166 offset:55296
	ds_read_b128 v[230:233], v166 offset:56320
	global_load_lds_dwordx4 v[176:177], off
	v_lshl_add_u64 v[176:177], v[198:199], 0, s[26:27]
	s_mov_b32 m0, s67
	s_addc_u32 s3, s3, 0
	global_load_lds_dwordx4 v[176:177], off
	v_lshl_add_u64 v[176:177], s[2:3], 0, v[132:133]
	s_mov_b32 m0, s69
	s_nop 0
	global_load_lds_dwordx4 v[176:177], off
	v_lshl_add_u64 v[176:177], s[2:3], 0, v[136:137]
	s_mov_b32 m0, s70
	s_nop 0
	global_load_lds_dwordx4 v[176:177], off
	v_lshl_add_u64 v[176:177], v[234:235], 0, s[26:27]
	s_mov_b32 m0, s53
	s_nop 0
	global_load_lds_dwordx4 v[176:177], off
	v_lshl_add_u64 v[176:177], v[236:237], 0, s[26:27]
	s_mov_b32 m0, s54
	s_nop 0
	global_load_lds_dwordx4 v[176:177], off
	s_waitcnt vmcnt(8)
	s_waitcnt lgkmcnt(0)
	s_barrier
	s_setprio 1
	v_mfma_f32_16x16x32_bf16 v[60:63], v[140:143], v[202:205], v[60:63]
	v_mfma_f32_16x16x32_bf16 v[56:59], v[148:151], v[202:205], v[56:59]
	v_mfma_f32_16x16x32_bf16 v[52:55], v[140:143], v[210:213], v[52:55]
	v_mfma_f32_16x16x32_bf16 v[48:51], v[148:151], v[210:213], v[48:51]
	v_mfma_f32_16x16x32_bf16 v[44:47], v[140:143], v[218:221], v[44:47]
	v_mfma_f32_16x16x32_bf16 v[40:43], v[148:151], v[218:221], v[40:43]
	v_mfma_f32_16x16x32_bf16 v[36:39], v[140:143], v[226:229], v[36:39]
	v_mfma_f32_16x16x32_bf16 v[32:35], v[148:151], v[226:229], v[32:35]
	v_mfma_f32_16x16x32_bf16 v[60:63], v[144:147], v[206:209], v[60:63]
	v_mfma_f32_16x16x32_bf16 v[56:59], v[152:155], v[206:209], v[56:59]
	v_mfma_f32_16x16x32_bf16 v[52:55], v[144:147], v[214:217], v[52:55]
	v_mfma_f32_16x16x32_bf16 v[48:51], v[152:155], v[214:217], v[48:51]
	v_mfma_f32_16x16x32_bf16 v[44:47], v[144:147], v[222:225], v[44:47]
	v_mfma_f32_16x16x32_bf16 v[40:43], v[152:155], v[222:225], v[40:43]
	v_mfma_f32_16x16x32_bf16 v[36:39], v[144:147], v[230:233], v[36:39]
	v_mfma_f32_16x16x32_bf16 v[32:35], v[152:155], v[230:233], v[32:35]
	v_mfma_f32_16x16x32_bf16 v[28:31], v[168:171], v[202:205], v[28:31]
	v_mfma_f32_16x16x32_bf16 v[24:27], v[190:193], v[202:205], v[24:27]
	v_mfma_f32_16x16x32_bf16 v[20:23], v[168:171], v[210:213], v[20:23]
	v_mfma_f32_16x16x32_bf16 v[16:19], v[190:193], v[210:213], v[16:19]
	v_mfma_f32_16x16x32_bf16 v[12:15], v[168:171], v[218:221], v[12:15]
	v_mfma_f32_16x16x32_bf16 v[8:11], v[190:193], v[218:221], v[8:11]
	v_mfma_f32_16x16x32_bf16 v[4:7], v[168:171], v[226:229], v[4:7]
	v_mfma_f32_16x16x32_bf16 v[0:3], v[190:193], v[226:229], v[0:3]
	v_mfma_f32_16x16x32_bf16 v[28:31], v[172:175], v[206:209], v[28:31]
	v_mfma_f32_16x16x32_bf16 v[24:27], v[194:197], v[206:209], v[24:27]
	v_mfma_f32_16x16x32_bf16 v[20:23], v[172:175], v[214:217], v[20:23]
	v_mfma_f32_16x16x32_bf16 v[16:19], v[194:197], v[214:217], v[16:19]
	v_mfma_f32_16x16x32_bf16 v[12:15], v[172:175], v[222:225], v[12:15]
	v_mfma_f32_16x16x32_bf16 v[8:11], v[194:197], v[222:225], v[8:11]
	v_mfma_f32_16x16x32_bf16 v[4:7], v[172:175], v[230:233], v[4:7]
	v_mfma_f32_16x16x32_bf16 v[0:3], v[194:197], v[230:233], v[0:3]
	s_setprio 0
	s_barrier
	s_andn2_b64 vcc, exec, s[28:29]
	s_cbranch_vccnz .LBB0_419
	s_barrier

; #define PG8_STAGE(bufoff, gbase, voff) do { _Pragma("unroll") for (int _i = 0; _i < 2; ++_i) \
;         __builtin_amdgcn_global_load_lds((const unsigned*)((const char*)(gbase) + (voff)[_i]), (LAS unsigned*)(lds + (bufoff) + ldsw + _i * 8192), 16, 0, 0); } while (0)
; #define PG8_LDA(dst, b, h) do { _Pragma("unroll") for (int m = 0; m < 4; ++m) _Pragma("unroll") for (int k = 0; k < 2; ++k) dst[m][k] = *(const LAS bf16x8*)(lds + PG8_SA(b, h) + aoff + m * 2048 + k * 1024); } while (0)
; #define PG8_LDB(dst, b, h) do { _Pragma("unroll") for (int n = 0; n < 2; ++n) _Pragma("unroll") for (int k = 0; k < 2; ++k) dst[n][k] = *(const LAS bf16x8*)(lds + PG8_SB(b, h) + boff + n * 2048 + k * 1024); } while (0)
; #define PG8_MMA(ai, bj, At, Bt) do { __builtin_amdgcn_s_setprio(1); _Pragma("unroll") for (int m = 0; m < 4; ++m) _Pragma("unroll") for (int n = 0; n < 2; ++n) _Pragma("unroll") for (int k = 0; k < 2; ++k) \
;         acc[ai][bj][m][n] = __builtin_amdgcn_mfma_f32_16x16x32_bf16(Bt[n][k], At[m][k], acc[ai][bj][m][n], 0, 0, 0); __builtin_amdgcn_s_setprio(0); } while (0)
; #define PG8_WAIT_V(n) asm volatile("s_waitcnt vmcnt(" #n ")" ::: "memory")
; #define PG8_WAIT_L(n) asm volatile("s_waitcnt lgkmcnt(" #n ")" ::: "memory")
; #define PG8_BAR __builtin_amdgcn_s_barrier()
; template <class Epi, bool BSEL = false>
; __device__ __forceinline__ void gemm_phase(LAS unsigned char* lds, const Gemm g, const Order& S, const Epi& E, const int tid) {
;     ...
;         const bool has_next = S.next(ui + 1, nxt);
;         const char* nA = has_next ? nxt.a : cA; const char* nB = has_next ? nxt.b : cB;
;         const bool nP = has_next ? (BSEL && nxt.kind == 3) : cP; const size_t nhB = nP ? hstepBp : hstepBn;
;         for (int t = 0; t < nt; t += 2) {
;             const bool last = (t == nt - 2);
;             const char* a1 = cA + (size_t)(t + 1) * kstep;
;             const char* a2 = last ? nA : cA + (size_t)(t + 2) * kstep; const char* b2 = last ? nB : cB + (size_t)(t + 2) * kstep;
;             const char* a3 = a2 + kstep; const char* b3 = b2 + kstep;
;             const bool p2 = last ? nP : cP; const size_t h2 = last ? nhB : chB;
;             PG8_LDB(B0, 0, 0); PG8_LDB(B1, 0, 1); PG8_SCHED; PG8_LDA(At, 0, 0); PG8_STAGE(PG8_SA(1, 1), a1 + hstepA, voffA);
;             PG8_WAIT_V(8); PG8_WAIT_L(0); PG8_BAR; PG8_MMA(0, 0, At, B0); PG8_MMA(0, 1, At, B1); PG8_BAR; PG8_SCHED;
.LBB0_440:
	v_add_u32_e32 v176, s46, v133
	ds_read_b128 v[164:167], v176
	ds_read_b128 v[168:171], v176 offset:1024
	ds_read_b128 v[172:175], v176 offset:2048
	ds_read_b128 v[192:195], v176 offset:3072
	v_add_u32_e32 v176, s47, v133
	s_add_u32 s36, s10, s2
	ds_read_b128 v[196:199], v176
	ds_read_b128 v[202:205], v176 offset:1024
	ds_read_b128 v[206:209], v176 offset:2048
	ds_read_b128 v[210:213], v176 offset:3072
	s_addc_u32 s37, s11, s3
	s_add_u32 s36, s36, 0x100
	s_addc_u32 s37, s37, 0
	s_add_u32 s58, s1, s2
	s_addc_u32 s59, s52, s3
	s_cmpk_eq_i32 s2, 0x1500
	s_cselect_b32 s41, s53, s37
	s_cselect_b32 s40, s54, s36
	s_cselect_b32 s37, s55, s59
	s_cselect_b32 s36, s56, s58
	v_lshl_add_u64 v[176:177], v[160:161], 0, s[2:3]
	s_add_i32 m0, s15, 0xc000
	ds_read_b128 v[214:217], v190
	ds_read_b128 v[218:221], v190 offset:1024
	ds_read_b128 v[222:225], v190 offset:2048
	ds_read_b128 v[226:229], v190 offset:3072
	ds_read_b128 v[230:233], v190 offset:4096
	ds_read_b128 v[234:237], v190 offset:5120
	ds_read_b128 v[238:241], v190 offset:6144
	ds_read_b128 v[242:245], v190 offset:7168
	global_load_lds_dwordx4 v[176:177], off
	v_lshl_add_u64 v[176:177], v[162:163], 0, s[2:3]
	s_add_i32 m0, s15, 0xe000
	s_nop 0
	global_load_lds_dwordx4 v[176:177], off
	s_waitcnt vmcnt(8)
	s_waitcnt lgkmcnt(0)
	s_barrier
	s_setprio 1
	v_mfma_f32_16x16x32_bf16 v[124:127], v[164:167], v[214:217], v[124:127]
	v_mfma_f32_16x16x32_bf16 v[120:123], v[172:175], v[214:217], v[120:123]
	v_mfma_f32_16x16x32_bf16 v[116:119], v[164:167], v[222:225], v[116:119]
	v_mfma_f32_16x16x32_bf16 v[112:115], v[172:175], v[222:225], v[112:115]
	v_mfma_f32_16x16x32_bf16 v[108:111], v[164:167], v[230:233], v[108:111]
	v_mfma_f32_16x16x32_bf16 v[104:107], v[172:175], v[230:233], v[104:107]
	v_mfma_f32_16x16x32_bf16 v[100:103], v[164:167], v[238:241], v[100:103]
	v_mfma_f32_16x16x32_bf16 v[96:99], v[172:175], v[238:241], v[96:99]
	v_mfma_f32_16x16x32_bf16 v[124:127], v[168:171], v[218:221], v[124:127]
	v_mfma_f32_16x16x32_bf16 v[120:123], v[192:195], v[218:221], v[120:123]
	v_mfma_f32_16x16x32_bf16 v[116:119], v[168:171], v[226:229], v[116:119]
	v_mfma_f32_16x16x32_bf16 v[112:115], v[192:195], v[226:229], v[112:115]
	v_mfma_f32_16x16x32_bf16 v[108:111], v[168:171], v[234:237], v[108:111]
	v_mfma_f32_16x16x32_bf16 v[104:107], v[192:195], v[234:237], v[104:107]
	v_mfma_f32_16x16x32_bf16 v[100:103], v[168:171], v[242:245], v[100:103]
	v_mfma_f32_16x16x32_bf16 v[96:99], v[192:195], v[242:245], v[96:99]
	v_mfma_f32_16x16x32_bf16 v[92:95], v[196:199], v[214:217], v[92:95]
	v_mfma_f32_16x16x32_bf16 v[88:91], v[206:209], v[214:217], v[88:91]
	v_mfma_f32_16x16x32_bf16 v[84:87], v[196:199], v[222:225], v[84:87]
	v_mfma_f32_16x16x32_bf16 v[80:83], v[206:209], v[222:225], v[80:83]
	v_mfma_f32_16x16x32_bf16 v[76:79], v[196:199], v[230:233], v[76:79]
	v_mfma_f32_16x16x32_bf16 v[72:75], v[206:209], v[230:233], v[72:75]
	v_mfma_f32_16x16x32_bf16 v[68:71], v[196:199], v[238:241], v[68:71]
	v_mfma_f32_16x16x32_bf16 v[64:67], v[206:209], v[238:241], v[64:67]
	v_mfma_f32_16x16x32_bf16 v[92:95], v[202:205], v[218:221], v[92:95]
	v_mfma_f32_16x16x32_bf16 v[88:91], v[210:213], v[218:221], v[88:91]
	v_mfma_f32_16x16x32_bf16 v[84:87], v[202:205], v[226:229], v[84:87]
	v_mfma_f32_16x16x32_bf16 v[80:83], v[210:213], v[226:229], v[80:83]
	v_mfma_f32_16x16x32_bf16 v[76:79], v[202:205], v[234:237], v[76:79]
	v_mfma_f32_16x16x32_bf16 v[72:75], v[210:213], v[234:237], v[72:75]
	v_mfma_f32_16x16x32_bf16 v[68:71], v[202:205], v[242:245], v[68:71]
	v_mfma_f32_16x16x32_bf16 v[64:67], v[210:213], v[242:245], v[64:67]
	s_setprio 0
	s_barrier
	s_add_i32 s58, s46, s14
	v_lshl_add_u64 v[176:177], s[36:37], 0, v[130:131]
	s_mov_b32 m0, s58
	ds_read_b128 v[214:217], v190 offset:16384
	ds_read_b128 v[218:221], v190 offset:17408
	ds_read_b128 v[222:225], v190 offset:18432
	ds_read_b128 v[226:229], v190 offset:19456
	ds_read_b128 v[230:233], v190 offset:20480
	ds_read_b128 v[234:237], v190 offset:21504
	ds_read_b128 v[238:241], v190 offset:22528
	ds_read_b128 v[242:245], v190 offset:23552
	global_load_lds_dwordx4 v[176:177], off
	s_add_i32 m0, s58, 0x2000
	s_add_u32 s58, s36, 0xb0000
	v_lshl_add_u64 v[246:247], s[36:37], 0, v[134:135]
	s_addc_u32 s59, s37, 0
	s_add_i32 s62, s47, s14
	global_load_lds_dwordx4 v[246:247], off
	v_lshl_add_u64 v[248:249], s[58:59], 0, v[130:131]
	s_mov_b32 m0, s62
	v_lshl_add_u64 v[250:251], s[40:41], 0, v[134:135]
	global_load_lds_dwordx4 v[248:249], off
	v_lshl_add_u64 v[248:249], s[58:59], 0, v[134:135]
	s_add_i32 m0, s62, 0x2000
	s_nop 0
	global_load_lds_dwordx4 v[248:249], off
	v_lshl_add_u64 v[248:249], s[40:41], 0, v[130:131]
	s_mov_b32 m0, s15
	s_nop 0
	global_load_lds_dwordx4 v[248:249], off
	s_mov_b32 m0, s20
	s_nop 0
	global_load_lds_dwordx4 v[250:251], off
	s_waitcnt vmcnt(8)
	s_waitcnt lgkmcnt(0)
	s_barrier
; #define PG8_STAGE(bufoff, gbase, voff) do { _Pragma("unroll") for (int _i = 0; _i < 2; ++_i) \
;         __builtin_amdgcn_global_load_lds((const unsigned*)((const char*)(gbase) + (voff)[_i]), (LAS unsigned*)(lds + (bufoff) + ldsw + _i * 8192), 16, 0, 0); } while (0)
; #define PG8_STAGEB(bufoff, gbase, perm) do { _Pragma("unroll") for (int _i = 0; _i < 2; ++_i) \
;         __builtin_amdgcn_global_load_lds((const unsigned*)((const char*)(gbase) + ((BSEL && (perm)) ? voffBp[_i] : voffB[_i])), (LAS unsigned*)(lds + (bufoff) + ldsw + _i * 8192), 16, 0, 0); } while (0)
; #define PG8_LDA(dst, b, h) do { _Pragma("unroll") for (int m = 0; m < 4; ++m) _Pragma("unroll") for (int k = 0; k < 2; ++k) dst[m][k] = *(const LAS bf16x8*)(lds + PG8_SA(b, h) + aoff + m * 2048 + k * 1024); } while (0)
; #define PG8_LDB(dst, b, h) do { _Pragma("unroll") for (int n = 0; n < 2; ++n) _Pragma("unroll") for (int k = 0; k < 2; ++k) dst[n][k] = *(const LAS bf16x8*)(lds + PG8_SB(b, h) + boff + n * 2048 + k * 1024); } while (0)
; #define PG8_WAIT_V(n) asm volatile("s_waitcnt vmcnt(" #n ")" ::: "memory")
; #define PG8_WAIT_L(n) asm volatile("s_waitcnt lgkmcnt(" #n ")" ::: "memory")
; template <class Epi, bool BSEL = false>
; __device__ __forceinline__ void gemm_phase(LAS unsigned char* lds, const Gemm g, const Order& S, const Epi& E, const int tid) {
;     ...
;             PG8_LDB(B0, 0, 0); PG8_LDB(B1, 0, 1); PG8_SCHED; PG8_LDA(At, 0, 0); PG8_STAGE(PG8_SA(1, 1), a1 + hstepA, voffA);
;             PG8_WAIT_V(8); PG8_WAIT_L(0); PG8_BAR; PG8_MMA(0, 0, At, B0); PG8_MMA(0, 1, At, B1); PG8_BAR; PG8_SCHED;
;             PG8_LDA(At, 0, 1); PG8_STAGEB(PG8_SB(0, 0), b2, p2); PG8_STAGEB(PG8_SB(0, 1), b2 + h2, p2); PG8_STAGE(PG8_SA(0, 0), a2, voffA);
;             PG8_WAIT_V(8); PG8_WAIT_L(0); PG8_BAR; PG8_MMA(1, 0, At, B0); PG8_MMA(1, 1, At, B1); PG8_BAR; PG8_SCHED;
;             PG8_LDB(B0, 1, 0); PG8_LDB(B1, 1, 1); PG8_SCHED; PG8_LDA(At, 1, 0); PG8_STAGE(PG8_SA(0, 1), a2 + hstepA, voffA);
;             PG8_WAIT_V(8); PG8_WAIT_L(0); PG8_BAR; PG8_MMA(0, 0, At, B0); PG8_MMA(0, 1, At, B1); PG8_BAR; PG8_SCHED;
;             PG8_LDA(At, 1, 1); PG8_STAGEB(PG8_SB(1, 0), b3, p2); PG8_STAGEB(PG8_SB(1, 1), b3 + h2, p2); PG8_STAGE(PG8_SA(1, 0), a3, voffA);
;             PG8_WAIT_V(8); PG8_WAIT_L(0); PG8_BAR; PG8_MMA(1, 0, At, B0); PG8_MMA(1, 1, At, B1); PG8_BAR; PG8_SCHED;
	s_setprio 1
	v_mfma_f32_16x16x32_bf16 v[60:63], v[164:167], v[214:217], v[60:63]
	v_mfma_f32_16x16x32_bf16 v[56:59], v[172:175], v[214:217], v[56:59]
	v_mfma_f32_16x16x32_bf16 v[52:55], v[164:167], v[222:225], v[52:55]
	v_mfma_f32_16x16x32_bf16 v[48:51], v[172:175], v[222:225], v[48:51]
	v_mfma_f32_16x16x32_bf16 v[44:47], v[164:167], v[230:233], v[44:47]
	v_mfma_f32_16x16x32_bf16 v[40:43], v[172:175], v[230:233], v[40:43]
	v_mfma_f32_16x16x32_bf16 v[36:39], v[164:167], v[238:241], v[36:39]
	v_mfma_f32_16x16x32_bf16 v[32:35], v[172:175], v[238:241], v[32:35]
	v_mfma_f32_16x16x32_bf16 v[60:63], v[168:171], v[218:221], v[60:63]
	v_mfma_f32_16x16x32_bf16 v[56:59], v[192:195], v[218:221], v[56:59]
	v_mfma_f32_16x16x32_bf16 v[52:55], v[168:171], v[226:229], v[52:55]
	v_mfma_f32_16x16x32_bf16 v[48:51], v[192:195], v[226:229], v[48:51]
	v_mfma_f32_16x16x32_bf16 v[44:47], v[168:171], v[234:237], v[44:47]
	v_mfma_f32_16x16x32_bf16 v[40:43], v[192:195], v[234:237], v[40:43]
	v_mfma_f32_16x16x32_bf16 v[36:39], v[168:171], v[242:245], v[36:39]
	v_mfma_f32_16x16x32_bf16 v[32:35], v[192:195], v[242:245], v[32:35]
	v_mfma_f32_16x16x32_bf16 v[28:31], v[196:199], v[214:217], v[28:31]
	v_mfma_f32_16x16x32_bf16 v[24:27], v[206:209], v[214:217], v[24:27]
	v_mfma_f32_16x16x32_bf16 v[20:23], v[196:199], v[222:225], v[20:23]
	v_mfma_f32_16x16x32_bf16 v[16:19], v[206:209], v[222:225], v[16:19]
	v_mfma_f32_16x16x32_bf16 v[12:15], v[196:199], v[230:233], v[12:15]
	v_mfma_f32_16x16x32_bf16 v[8:11], v[206:209], v[230:233], v[8:11]
	v_mfma_f32_16x16x32_bf16 v[4:7], v[196:199], v[238:241], v[4:7]
	v_mfma_f32_16x16x32_bf16 v[0:3], v[206:209], v[238:241], v[0:3]
	v_mfma_f32_16x16x32_bf16 v[28:31], v[202:205], v[218:221], v[28:31]
	v_mfma_f32_16x16x32_bf16 v[24:27], v[210:213], v[218:221], v[24:27]
	v_mfma_f32_16x16x32_bf16 v[20:23], v[202:205], v[226:229], v[20:23]
	v_mfma_f32_16x16x32_bf16 v[16:19], v[210:213], v[226:229], v[16:19]
	v_mfma_f32_16x16x32_bf16 v[12:15], v[202:205], v[234:237], v[12:15]
	v_mfma_f32_16x16x32_bf16 v[8:11], v[210:213], v[234:237], v[8:11]
	v_mfma_f32_16x16x32_bf16 v[4:7], v[202:205], v[242:245], v[4:7]
	v_mfma_f32_16x16x32_bf16 v[0:3], v[210:213], v[242:245], v[0:3]
	s_setprio 0
	s_barrier
	s_add_i32 s58, 0, 0x18000
	v_add_u32_e32 v191, s58, v133
	s_add_i32 s59, 0, 0x1c000
	ds_read_b128 v[164:167], v191
	ds_read_b128 v[168:171], v191 offset:1024
	ds_read_b128 v[172:175], v191 offset:2048
	ds_read_b128 v[192:195], v191 offset:3072
	v_add_u32_e32 v191, s59, v133
	ds_read_b128 v[196:199], v191
	ds_read_b128 v[202:205], v191 offset:1024
	ds_read_b128 v[206:209], v191 offset:2048
	ds_read_b128 v[210:213], v191 offset:3072
	s_add_u32 s40, s40, 0xb0000
	s_addc_u32 s41, s41, 0
	s_mov_b32 m0, s21
	v_lshl_add_u64 v[252:253], s[40:41], 0, v[130:131]
	ds_read_b128 v[214:217], v190 offset:32768
	ds_read_b128 v[218:221], v190 offset:33792
	ds_read_b128 v[222:225], v190 offset:34816
	ds_read_b128 v[226:229], v190 offset:35840
	ds_read_b128 v[230:233], v190 offset:36864
	ds_read_b128 v[234:237], v190 offset:37888
	ds_read_b128 v[238:241], v190 offset:38912
	ds_read_b128 v[242:245], v190 offset:39936
	global_load_lds_dwordx4 v[252:253], off
	v_lshl_add_u64 v[252:253], s[40:41], 0, v[134:135]
	s_mov_b32 m0, s42
	s_nop 0
	global_load_lds_dwordx4 v[252:253], off
	s_waitcnt vmcnt(8)
	s_waitcnt lgkmcnt(0)
	s_barrier
	s_setprio 1
	v_mfma_f32_16x16x32_bf16 v[124:127], v[164:167], v[214:217], v[124:127]
	v_mfma_f32_16x16x32_bf16 v[120:123], v[172:175], v[214:217], v[120:123]
	v_mfma_f32_16x16x32_bf16 v[116:119], v[164:167], v[222:225], v[116:119]
	v_mfma_f32_16x16x32_bf16 v[112:115], v[172:175], v[222:225], v[112:115]
	v_mfma_f32_16x16x32_bf16 v[108:111], v[164:167], v[230:233], v[108:111]
	v_mfma_f32_16x16x32_bf16 v[104:107], v[172:175], v[230:233], v[104:107]
	v_mfma_f32_16x16x32_bf16 v[100:103], v[164:167], v[238:241], v[100:103]
	v_mfma_f32_16x16x32_bf16 v[96:99], v[172:175], v[238:241], v[96:99]
	v_mfma_f32_16x16x32_bf16 v[124:127], v[168:171], v[218:221], v[124:127]
	v_mfma_f32_16x16x32_bf16 v[120:123], v[192:195], v[218:221], v[120:123]
	v_mfma_f32_16x16x32_bf16 v[116:119], v[168:171], v[226:229], v[116:119]
	v_mfma_f32_16x16x32_bf16 v[112:115], v[192:195], v[226:229], v[112:115]
	v_mfma_f32_16x16x32_bf16 v[108:111], v[168:171], v[234:237], v[108:111]
	v_mfma_f32_16x16x32_bf16 v[104:107], v[192:195], v[234:237], v[104:107]
	v_mfma_f32_16x16x32_bf16 v[100:103], v[168:171], v[242:245], v[100:103]
	v_mfma_f32_16x16x32_bf16 v[96:99], v[192:195], v[242:245], v[96:99]
	v_mfma_f32_16x16x32_bf16 v[92:95], v[196:199], v[214:217], v[92:95]
	v_mfma_f32_16x16x32_bf16 v[88:91], v[206:209], v[214:217], v[88:91]
	v_mfma_f32_16x16x32_bf16 v[84:87], v[196:199], v[222:225], v[84:87]
	v_mfma_f32_16x16x32_bf16 v[80:83], v[206:209], v[222:225], v[80:83]
	v_mfma_f32_16x16x32_bf16 v[76:79], v[196:199], v[230:233], v[76:79]
	v_mfma_f32_16x16x32_bf16 v[72:75], v[206:209], v[230:233], v[72:75]
	v_mfma_f32_16x16x32_bf16 v[68:71], v[196:199], v[238:241], v[68:71]
	v_mfma_f32_16x16x32_bf16 v[64:67], v[206:209], v[238:241], v[64:67]
	v_mfma_f32_16x16x32_bf16 v[92:95], v[202:205], v[218:221], v[92:95]
	v_mfma_f32_16x16x32_bf16 v[88:91], v[210:213], v[218:221], v[88:91]
	v_mfma_f32_16x16x32_bf16 v[84:87], v[202:205], v[226:229], v[84:87]
	v_mfma_f32_16x16x32_bf16 v[80:83], v[210:213], v[226:229], v[80:83]
	v_mfma_f32_16x16x32_bf16 v[76:79], v[202:205], v[234:237], v[76:79]
	v_mfma_f32_16x16x32_bf16 v[72:75], v[210:213], v[234:237], v[72:75]
	v_mfma_f32_16x16x32_bf16 v[68:71], v[202:205], v[242:245], v[68:71]
	v_mfma_f32_16x16x32_bf16 v[64:67], v[210:213], v[242:245], v[64:67]
	s_setprio 0
	s_barrier
; #define PG8_STAGE(bufoff, gbase, voff) do { _Pragma("unroll") for (int _i = 0; _i < 2; ++_i) \
;         __builtin_amdgcn_global_load_lds((const unsigned*)((const char*)(gbase) + (voff)[_i]), (LAS unsigned*)(lds + (bufoff) + ldsw + _i * 8192), 16, 0, 0); } while (0)
; #define PG8_STAGEB(bufoff, gbase, perm) do { _Pragma("unroll") for (int _i = 0; _i < 2; ++_i) \
;         __builtin_amdgcn_global_load_lds((const unsigned*)((const char*)(gbase) + ((BSEL && (perm)) ? voffBp[_i] : voffB[_i])), (LAS unsigned*)(lds + (bufoff) + ldsw + _i * 8192), 16, 0, 0); } while (0)
; #define PG8_LDA(dst, b, h) do { _Pragma("unroll") for (int m = 0; m < 4; ++m) _Pragma("unroll") for (int k = 0; k < 2; ++k) dst[m][k] = *(const LAS bf16x8*)(lds + PG8_SA(b, h) + aoff + m * 2048 + k * 1024); } while (0)
; #define PG8_LDB(dst, b, h) do { _Pragma("unroll") for (int n = 0; n < 2; ++n) _Pragma("unroll") for (int k = 0; k < 2; ++k) dst[n][k] = *(const LAS bf16x8*)(lds + PG8_SB(b, h) + boff + n * 2048 + k * 1024); } while (0)
; #define PG8_WAIT_V(n) asm volatile("s_waitcnt vmcnt(" #n ")" ::: "memory")
; #define PG8_BAR __builtin_amdgcn_s_barrier()
; template <class Epi, bool BSEL = false>
; __device__ __forceinline__ void gemm_phase(LAS unsigned char* lds, const Gemm g, const Order& S, const Epi& E, const int tid) {
;     ...
;             PG8_LDB(B0, 0, 0); PG8_LDB(B1, 0, 1); PG8_SCHED; PG8_LDA(At, 0, 0); PG8_STAGE(PG8_SA(1, 1), a1 + hstepA, voffA);
;             PG8_WAIT_V(8); PG8_WAIT_L(0); PG8_BAR; PG8_MMA(0, 0, At, B0); PG8_MMA(0, 1, At, B1); PG8_BAR; PG8_SCHED;
;             PG8_LDA(At, 0, 1); PG8_STAGEB(PG8_SB(0, 0), b2, p2); PG8_STAGEB(PG8_SB(0, 1), b2 + h2, p2); PG8_STAGE(PG8_SA(0, 0), a2, voffA);
;             PG8_WAIT_V(8); PG8_WAIT_L(0); PG8_BAR; PG8_MMA(1, 0, At, B0); PG8_MMA(1, 1, At, B1); PG8_BAR; PG8_SCHED;
;             PG8_LDB(B0, 1, 0); PG8_LDB(B1, 1, 1); PG8_SCHED; PG8_LDA(At, 1, 0); PG8_STAGE(PG8_SA(0, 1), a2 + hstepA, voffA);
;             PG8_WAIT_V(8); PG8_WAIT_L(0); PG8_BAR; PG8_MMA(0, 0, At, B0); PG8_MMA(0, 1, At, B1); PG8_BAR; PG8_SCHED;
;             PG8_LDA(At, 1, 1); PG8_STAGEB(PG8_SB(1, 0), b3, p2); PG8_STAGEB(PG8_SB(1, 1), b3 + h2, p2); PG8_STAGE(PG8_SA(1, 0), a3, voffA);
;             PG8_WAIT_V(8); PG8_WAIT_L(0); PG8_BAR; PG8_MMA(1, 0, At, B0); PG8_MMA(1, 1, At, B1); PG8_BAR; PG8_SCHED;
;         }
;         if constexpr (ALIGN_EPI) { if (wr == 0) PG8_BAR; }
	s_add_i32 s40, s58, s14
	v_lshl_add_u64 v[176:177], v[176:177], 0, s[24:25]
	s_mov_b32 m0, s40
	ds_read_b128 v[214:217], v190 offset:49152
	ds_read_b128 v[218:221], v190 offset:50176
	ds_read_b128 v[222:225], v190 offset:51200
	ds_read_b128 v[226:229], v190 offset:52224
	ds_read_b128 v[230:233], v190 offset:53248
	ds_read_b128 v[234:237], v190 offset:54272
	ds_read_b128 v[238:241], v190 offset:55296
	ds_read_b128 v[242:245], v190 offset:56320
	global_load_lds_dwordx4 v[176:177], off
	s_add_i32 m0, s40, 0x2000
	s_add_u32 s36, s36, 0xb0080
	v_lshl_add_u64 v[176:177], v[246:247], 0, s[24:25]
	s_addc_u32 s37, s37, 0
	s_add_i32 s40, s59, s14
	global_load_lds_dwordx4 v[176:177], off
	v_lshl_add_u64 v[176:177], s[36:37], 0, v[130:131]
	s_mov_b32 m0, s40
	s_nop 0
	global_load_lds_dwordx4 v[176:177], off
	v_lshl_add_u64 v[176:177], s[36:37], 0, v[134:135]
	s_add_i32 m0, s40, 0x2000
	s_nop 0
	global_load_lds_dwordx4 v[176:177], off
	v_lshl_add_u64 v[176:177], v[248:249], 0, s[24:25]
	s_mov_b32 m0, s44
	s_nop 0
	global_load_lds_dwordx4 v[176:177], off
	v_lshl_add_u64 v[176:177], v[250:251], 0, s[24:25]
	s_mov_b32 m0, s45
	s_nop 0
	global_load_lds_dwordx4 v[176:177], off
	s_waitcnt vmcnt(8)
	s_waitcnt lgkmcnt(0)
	s_barrier
	s_setprio 1
	v_mfma_f32_16x16x32_bf16 v[60:63], v[164:167], v[214:217], v[60:63]
	v_mfma_f32_16x16x32_bf16 v[56:59], v[172:175], v[214:217], v[56:59]
	v_mfma_f32_16x16x32_bf16 v[52:55], v[164:167], v[222:225], v[52:55]
	v_mfma_f32_16x16x32_bf16 v[48:51], v[172:175], v[222:225], v[48:51]
	v_mfma_f32_16x16x32_bf16 v[44:47], v[164:167], v[230:233], v[44:47]
	v_mfma_f32_16x16x32_bf16 v[40:43], v[172:175], v[230:233], v[40:43]
	v_mfma_f32_16x16x32_bf16 v[36:39], v[164:167], v[238:241], v[36:39]
	v_mfma_f32_16x16x32_bf16 v[32:35], v[172:175], v[238:241], v[32:35]
	v_mfma_f32_16x16x32_bf16 v[60:63], v[168:171], v[218:221], v[60:63]
	v_mfma_f32_16x16x32_bf16 v[56:59], v[192:195], v[218:221], v[56:59]
	v_mfma_f32_16x16x32_bf16 v[52:55], v[168:171], v[226:229], v[52:55]
	v_mfma_f32_16x16x32_bf16 v[48:51], v[192:195], v[226:229], v[48:51]
	v_mfma_f32_16x16x32_bf16 v[44:47], v[168:171], v[234:237], v[44:47]
	v_mfma_f32_16x16x32_bf16 v[40:43], v[192:195], v[234:237], v[40:43]
	v_mfma_f32_16x16x32_bf16 v[36:39], v[168:171], v[242:245], v[36:39]
	v_mfma_f32_16x16x32_bf16 v[32:35], v[192:195], v[242:245], v[32:35]
	v_mfma_f32_16x16x32_bf16 v[28:31], v[196:199], v[214:217], v[28:31]
	v_mfma_f32_16x16x32_bf16 v[24:27], v[206:209], v[214:217], v[24:27]
	v_mfma_f32_16x16x32_bf16 v[20:23], v[196:199], v[222:225], v[20:23]
	v_mfma_f32_16x16x32_bf16 v[16:19], v[206:209], v[222:225], v[16:19]
	v_mfma_f32_16x16x32_bf16 v[12:15], v[196:199], v[230:233], v[12:15]
	v_mfma_f32_16x16x32_bf16 v[8:11], v[206:209], v[230:233], v[8:11]
	v_mfma_f32_16x16x32_bf16 v[4:7], v[196:199], v[238:241], v[4:7]
	v_mfma_f32_16x16x32_bf16 v[0:3], v[206:209], v[238:241], v[0:3]
	v_mfma_f32_16x16x32_bf16 v[28:31], v[202:205], v[218:221], v[28:31]
	v_mfma_f32_16x16x32_bf16 v[24:27], v[210:213], v[218:221], v[24:27]
	v_mfma_f32_16x16x32_bf16 v[20:23], v[202:205], v[226:229], v[20:23]
	v_mfma_f32_16x16x32_bf16 v[16:19], v[210:213], v[226:229], v[16:19]
	v_mfma_f32_16x16x32_bf16 v[12:15], v[202:205], v[234:237], v[12:15]
	v_mfma_f32_16x16x32_bf16 v[8:11], v[210:213], v[234:237], v[8:11]
	v_mfma_f32_16x16x32_bf16 v[4:7], v[202:205], v[242:245], v[4:7]
	v_mfma_f32_16x16x32_bf16 v[0:3], v[210:213], v[242:245], v[0:3]
	s_setprio 0
	s_barrier
	s_add_i32 s57, s57, 2
	s_add_u32 s2, s2, 0x100
	s_addc_u32 s3, s3, 0
	s_cmp_gt_u32 s57, 41
	s_cbranch_scc0 .LBB0_440
	s_and_b64 vcc, exec, s[26:27]
	s_cbranch_vccz .LBB0_443
	s_barrier

; #define PG8_STAGE(bufoff, gbase, voff) do { _Pragma("unroll") for (int _i = 0; _i < 2; ++_i) \
;         __builtin_amdgcn_global_load_lds((const unsigned*)((const char*)(gbase) + (voff)[_i]), (LAS unsigned*)(lds + (bufoff) + ldsw + _i * 8192), 16, 0, 0); } while (0)
; #define PG8_LDA(dst, b, h) do { _Pragma("unroll") for (int m = 0; m < 4; ++m) _Pragma("unroll") for (int k = 0; k < 2; ++k) dst[m][k] = *(const LAS bf16x8*)(lds + PG8_SA(b, h) + aoff + m * 2048 + k * 1024); } while (0)
; #define PG8_LDB(dst, b, h) do { _Pragma("unroll") for (int n = 0; n < 2; ++n) _Pragma("unroll") for (int k = 0; k < 2; ++k) dst[n][k] = *(const LAS bf16x8*)(lds + PG8_SB(b, h) + boff + n * 2048 + k * 1024); } while (0)
; #define PG8_MMA(ai, bj, At, Bt) do { __builtin_amdgcn_s_setprio(1); _Pragma("unroll") for (int m = 0; m < 4; ++m) _Pragma("unroll") for (int n = 0; n < 2; ++n) _Pragma("unroll") for (int k = 0; k < 2; ++k) \
;         acc[ai][bj][m][n] = __builtin_amdgcn_mfma_f32_16x16x32_bf16(Bt[n][k], At[m][k], acc[ai][bj][m][n], 0, 0, 0); __builtin_amdgcn_s_setprio(0); } while (0)
; #define PG8_WAIT_V(n) asm volatile("s_waitcnt vmcnt(" #n ")" ::: "memory")
; #define PG8_WAIT_L(n) asm volatile("s_waitcnt lgkmcnt(" #n ")" ::: "memory")
; #define PG8_BAR __builtin_amdgcn_s_barrier()
; template <class Epi, bool BSEL = false>
; __device__ __forceinline__ void gemm_phase(LAS unsigned char* lds, const Gemm g, const Order& S, const Epi& E, const int tid) {
;     ...
;         const bool has_next = S.next(ui + 1, nxt);
;         const char* nA = has_next ? nxt.a : cA; const char* nB = has_next ? nxt.b : cB;
;         const bool nP = has_next ? (BSEL && nxt.kind == 3) : cP; const size_t nhB = nP ? hstepBp : hstepBn;
;         for (int t = 0; t < nt; t += 2) {
;             const bool last = (t == nt - 2);
;             const char* a1 = cA + (size_t)(t + 1) * kstep;
;             const char* a2 = last ? nA : cA + (size_t)(t + 2) * kstep; const char* b2 = last ? nB : cB + (size_t)(t + 2) * kstep;
;             const char* a3 = a2 + kstep; const char* b3 = b2 + kstep;
;             const bool p2 = last ? nP : cP; const size_t h2 = last ? nhB : chB;
;             PG8_LDB(B0, 0, 0); PG8_LDB(B1, 0, 1); PG8_SCHED; PG8_LDA(At, 0, 0); PG8_STAGE(PG8_SA(1, 1), a1 + hstepA, voffA);
;             PG8_WAIT_V(8); PG8_WAIT_L(0); PG8_BAR; PG8_MMA(0, 0, At, B0); PG8_MMA(0, 1, At, B1); PG8_BAR; PG8_SCHED;
.LBB0_472:
	v_add_u32_e32 v164, s52, v139
	v_add_u32_e32 v176, s53, v139
	s_add_u32 s46, s26, s44
	ds_read_b128 v[152:155], v164
	ds_read_b128 v[156:159], v164 offset:1024
	ds_read_b128 v[160:163], v164 offset:2048
	ds_read_b128 v[164:167], v164 offset:3072
	ds_read_b128 v[168:171], v176
	ds_read_b128 v[172:175], v176 offset:1024
	ds_read_b128 v[180:183], v176 offset:2048
	ds_read_b128 v[184:187], v176 offset:3072
	s_addc_u32 s47, s27, s45
	s_add_u32 s46, s46, 0x100
	s_addc_u32 s47, s47, 0
	s_add_u32 s65, s41, s44
	s_addc_u32 s66, s57, s45
	s_cmpk_eq_i32 s44, 0x1500
	s_cselect_b32 s49, s58, s47
	s_cselect_b32 s48, s59, s46
	s_cselect_b32 s47, s62, s66
	s_cselect_b32 s46, s63, s65
	v_lshl_add_u64 v[176:177], v[146:147], 0, s[44:45]
	s_add_i32 m0, s20, 0xc000
	ds_read_b128 v[188:191], v151
	ds_read_b128 v[192:195], v151 offset:1024
	ds_read_b128 v[196:199], v151 offset:2048
	ds_read_b128 v[202:205], v151 offset:3072
	ds_read_b128 v[206:209], v151 offset:4096
	ds_read_b128 v[210:213], v151 offset:5120
	ds_read_b128 v[214:217], v151 offset:6144
	ds_read_b128 v[218:221], v151 offset:7168
	global_load_lds_dwordx4 v[176:177], off
	v_lshl_add_u64 v[176:177], v[148:149], 0, s[44:45]
	s_add_i32 m0, s20, 0xe000
	s_nop 0
	global_load_lds_dwordx4 v[176:177], off
	s_waitcnt vmcnt(8)
	s_waitcnt lgkmcnt(0)
	s_barrier
	s_setprio 1
	v_mfma_f32_16x16x32_bf16 v[124:127], v[152:155], v[188:191], v[124:127]
	v_mfma_f32_16x16x32_bf16 v[120:123], v[160:163], v[188:191], v[120:123]
	v_mfma_f32_16x16x32_bf16 v[108:111], v[152:155], v[196:199], v[108:111]
	v_mfma_f32_16x16x32_bf16 v[104:107], v[160:163], v[196:199], v[104:107]
	v_mfma_f32_16x16x32_bf16 v[92:95], v[152:155], v[206:209], v[92:95]
	v_mfma_f32_16x16x32_bf16 v[88:91], v[160:163], v[206:209], v[88:91]
	v_mfma_f32_16x16x32_bf16 v[76:79], v[152:155], v[214:217], v[76:79]
	v_mfma_f32_16x16x32_bf16 v[72:75], v[160:163], v[214:217], v[72:75]
	v_mfma_f32_16x16x32_bf16 v[124:127], v[156:159], v[192:195], v[124:127]
	v_mfma_f32_16x16x32_bf16 v[120:123], v[164:167], v[192:195], v[120:123]
	v_mfma_f32_16x16x32_bf16 v[108:111], v[156:159], v[202:205], v[108:111]
	v_mfma_f32_16x16x32_bf16 v[104:107], v[164:167], v[202:205], v[104:107]
	v_mfma_f32_16x16x32_bf16 v[92:95], v[156:159], v[210:213], v[92:95]
	v_mfma_f32_16x16x32_bf16 v[88:91], v[164:167], v[210:213], v[88:91]
	v_mfma_f32_16x16x32_bf16 v[76:79], v[156:159], v[218:221], v[76:79]
	v_mfma_f32_16x16x32_bf16 v[72:75], v[164:167], v[218:221], v[72:75]
	v_mfma_f32_16x16x32_bf16 v[116:119], v[168:171], v[188:191], v[116:119]
	v_mfma_f32_16x16x32_bf16 v[112:115], v[180:183], v[188:191], v[112:115]
	v_mfma_f32_16x16x32_bf16 v[100:103], v[168:171], v[196:199], v[100:103]
	v_mfma_f32_16x16x32_bf16 v[96:99], v[180:183], v[196:199], v[96:99]
	v_mfma_f32_16x16x32_bf16 v[84:87], v[168:171], v[206:209], v[84:87]
	v_mfma_f32_16x16x32_bf16 v[80:83], v[180:183], v[206:209], v[80:83]
	v_mfma_f32_16x16x32_bf16 v[68:71], v[168:171], v[214:217], v[68:71]
	v_mfma_f32_16x16x32_bf16 v[64:67], v[180:183], v[214:217], v[64:67]
	v_mfma_f32_16x16x32_bf16 v[116:119], v[172:175], v[192:195], v[116:119]
	v_mfma_f32_16x16x32_bf16 v[112:115], v[184:187], v[192:195], v[112:115]
	v_mfma_f32_16x16x32_bf16 v[100:103], v[172:175], v[202:205], v[100:103]
	v_mfma_f32_16x16x32_bf16 v[96:99], v[184:187], v[202:205], v[96:99]
	v_mfma_f32_16x16x32_bf16 v[84:87], v[172:175], v[210:213], v[84:87]
	v_mfma_f32_16x16x32_bf16 v[80:83], v[184:187], v[210:213], v[80:83]
	v_mfma_f32_16x16x32_bf16 v[68:71], v[172:175], v[218:221], v[68:71]
	v_mfma_f32_16x16x32_bf16 v[64:67], v[184:187], v[218:221], v[64:67]
	s_setprio 0
	s_barrier
	s_add_i32 s65, s52, s15
	v_lshl_add_u64 v[176:177], s[46:47], 0, v[132:133]
	s_mov_b32 m0, s65
	ds_read_b128 v[188:191], v151 offset:16384
	ds_read_b128 v[192:195], v151 offset:17408
	ds_read_b128 v[196:199], v151 offset:18432
	ds_read_b128 v[202:205], v151 offset:19456
	ds_read_b128 v[206:209], v151 offset:20480
	ds_read_b128 v[210:213], v151 offset:21504
	ds_read_b128 v[214:217], v151 offset:22528
	ds_read_b128 v[218:221], v151 offset:23552
	global_load_lds_dwordx4 v[176:177], off
	s_add_i32 m0, s65, 0x2000
	s_add_u32 s66, s46, 0xb0000
	v_lshl_add_u64 v[222:223], s[46:47], 0, v[136:137]
	s_addc_u32 s67, s47, 0
	s_add_i32 s65, s53, s15
	global_load_lds_dwordx4 v[222:223], off
	v_lshl_add_u64 v[224:225], s[66:67], 0, v[132:133]
	s_mov_b32 m0, s65
	v_lshl_add_u64 v[226:227], s[48:49], 0, v[134:135]
	global_load_lds_dwordx4 v[224:225], off
	v_lshl_add_u64 v[224:225], s[66:67], 0, v[136:137]
	s_add_i32 m0, s65, 0x2000
	s_nop 0
	global_load_lds_dwordx4 v[224:225], off
	v_lshl_add_u64 v[224:225], s[48:49], 0, v[130:131]
	s_mov_b32 m0, s20
	s_nop 0
	global_load_lds_dwordx4 v[224:225], off
	s_mov_b32 m0, s21
	s_nop 0
	global_load_lds_dwordx4 v[226:227], off
	s_waitcnt vmcnt(8)
	s_waitcnt lgkmcnt(0)
	s_barrier
; #define PG8_STAGE(bufoff, gbase, voff) do { _Pragma("unroll") for (int _i = 0; _i < 2; ++_i) \
;         __builtin_amdgcn_global_load_lds((const unsigned*)((const char*)(gbase) + (voff)[_i]), (LAS unsigned*)(lds + (bufoff) + ldsw + _i * 8192), 16, 0, 0); } while (0)
; #define PG8_STAGEB(bufoff, gbase, perm) do { _Pragma("unroll") for (int _i = 0; _i < 2; ++_i) \
;         __builtin_amdgcn_global_load_lds((const unsigned*)((const char*)(gbase) + ((BSEL && (perm)) ? voffBp[_i] : voffB[_i])), (LAS unsigned*)(lds + (bufoff) + ldsw + _i * 8192), 16, 0, 0); } while (0)
; #define PG8_LDA(dst, b, h) do { _Pragma("unroll") for (int m = 0; m < 4; ++m) _Pragma("unroll") for (int k = 0; k < 2; ++k) dst[m][k] = *(const LAS bf16x8*)(lds + PG8_SA(b, h) + aoff + m * 2048 + k * 1024); } while (0)
; #define PG8_LDB(dst, b, h) do { _Pragma("unroll") for (int n = 0; n < 2; ++n) _Pragma("unroll") for (int k = 0; k < 2; ++k) dst[n][k] = *(const LAS bf16x8*)(lds + PG8_SB(b, h) + boff + n * 2048 + k * 1024); } while (0)
; #define PG8_WAIT_V(n) asm volatile("s_waitcnt vmcnt(" #n ")" ::: "memory")
; #define PG8_WAIT_L(n) asm volatile("s_waitcnt lgkmcnt(" #n ")" ::: "memory")
; template <class Epi, bool BSEL = false>
; __device__ __forceinline__ void gemm_phase(LAS unsigned char* lds, const Gemm g, const Order& S, const Epi& E, const int tid) {
;     ...
;             PG8_LDB(B0, 0, 0); PG8_LDB(B1, 0, 1); PG8_SCHED; PG8_LDA(At, 0, 0); PG8_STAGE(PG8_SA(1, 1), a1 + hstepA, voffA);
;             PG8_WAIT_V(8); PG8_WAIT_L(0); PG8_BAR; PG8_MMA(0, 0, At, B0); PG8_MMA(0, 1, At, B1); PG8_BAR; PG8_SCHED;
;             PG8_LDA(At, 0, 1); PG8_STAGEB(PG8_SB(0, 0), b2, p2); PG8_STAGEB(PG8_SB(0, 1), b2 + h2, p2); PG8_STAGE(PG8_SA(0, 0), a2, voffA);
;             PG8_WAIT_V(8); PG8_WAIT_L(0); PG8_BAR; PG8_MMA(1, 0, At, B0); PG8_MMA(1, 1, At, B1); PG8_BAR; PG8_SCHED;
;             PG8_LDB(B0, 1, 0); PG8_LDB(B1, 1, 1); PG8_SCHED; PG8_LDA(At, 1, 0); PG8_STAGE(PG8_SA(0, 1), a2 + hstepA, voffA);
;             PG8_WAIT_V(8); PG8_WAIT_L(0); PG8_BAR; PG8_MMA(0, 0, At, B0); PG8_MMA(0, 1, At, B1); PG8_BAR; PG8_SCHED;
;             PG8_LDA(At, 1, 1); PG8_STAGEB(PG8_SB(1, 0), b3, p2); PG8_STAGEB(PG8_SB(1, 1), b3 + h2, p2); PG8_STAGE(PG8_SA(1, 0), a3, voffA);
;             PG8_WAIT_V(8); PG8_WAIT_L(0); PG8_BAR; PG8_MMA(1, 0, At, B0); PG8_MMA(1, 1, At, B1); PG8_BAR; PG8_SCHED;
	s_setprio 1
	v_mfma_f32_16x16x32_bf16 v[60:63], v[152:155], v[188:191], v[60:63]
	v_mfma_f32_16x16x32_bf16 v[56:59], v[160:163], v[188:191], v[56:59]
	v_mfma_f32_16x16x32_bf16 v[44:47], v[152:155], v[196:199], v[44:47]
	v_mfma_f32_16x16x32_bf16 v[40:43], v[160:163], v[196:199], v[40:43]
	v_mfma_f32_16x16x32_bf16 v[28:31], v[152:155], v[206:209], v[28:31]
	v_mfma_f32_16x16x32_bf16 v[24:27], v[160:163], v[206:209], v[24:27]
	v_mfma_f32_16x16x32_bf16 v[12:15], v[152:155], v[214:217], v[12:15]
	v_mfma_f32_16x16x32_bf16 v[8:11], v[160:163], v[214:217], v[8:11]
	v_mfma_f32_16x16x32_bf16 v[60:63], v[156:159], v[192:195], v[60:63]
	v_mfma_f32_16x16x32_bf16 v[56:59], v[164:167], v[192:195], v[56:59]
	v_mfma_f32_16x16x32_bf16 v[44:47], v[156:159], v[202:205], v[44:47]
	v_mfma_f32_16x16x32_bf16 v[40:43], v[164:167], v[202:205], v[40:43]
	v_mfma_f32_16x16x32_bf16 v[28:31], v[156:159], v[210:213], v[28:31]
	v_mfma_f32_16x16x32_bf16 v[24:27], v[164:167], v[210:213], v[24:27]
	v_mfma_f32_16x16x32_bf16 v[12:15], v[156:159], v[218:221], v[12:15]
	v_mfma_f32_16x16x32_bf16 v[8:11], v[164:167], v[218:221], v[8:11]
	v_mfma_f32_16x16x32_bf16 v[52:55], v[168:171], v[188:191], v[52:55]
	v_mfma_f32_16x16x32_bf16 v[48:51], v[180:183], v[188:191], v[48:51]
	v_mfma_f32_16x16x32_bf16 v[36:39], v[168:171], v[196:199], v[36:39]
	v_mfma_f32_16x16x32_bf16 v[32:35], v[180:183], v[196:199], v[32:35]
	v_mfma_f32_16x16x32_bf16 v[20:23], v[168:171], v[206:209], v[20:23]
	v_mfma_f32_16x16x32_bf16 v[16:19], v[180:183], v[206:209], v[16:19]
	v_mfma_f32_16x16x32_bf16 v[4:7], v[168:171], v[214:217], v[4:7]
	v_mfma_f32_16x16x32_bf16 v[0:3], v[180:183], v[214:217], v[0:3]
	v_mfma_f32_16x16x32_bf16 v[52:55], v[172:175], v[192:195], v[52:55]
	v_mfma_f32_16x16x32_bf16 v[48:51], v[184:187], v[192:195], v[48:51]
	v_mfma_f32_16x16x32_bf16 v[36:39], v[172:175], v[202:205], v[36:39]
	v_mfma_f32_16x16x32_bf16 v[32:35], v[184:187], v[202:205], v[32:35]
	v_mfma_f32_16x16x32_bf16 v[20:23], v[172:175], v[210:213], v[20:23]
	v_mfma_f32_16x16x32_bf16 v[16:19], v[184:187], v[210:213], v[16:19]
	v_mfma_f32_16x16x32_bf16 v[4:7], v[172:175], v[218:221], v[4:7]
	v_mfma_f32_16x16x32_bf16 v[0:3], v[184:187], v[218:221], v[0:3]
	s_setprio 0
	s_barrier
	s_add_i32 s65, 0, 0x18000
	s_add_i32 s66, 0, 0x1c000
	v_add_u32_e32 v164, s65, v139
	v_add_u32_e32 v179, s66, v139
	ds_read_b128 v[152:155], v164
	ds_read_b128 v[156:159], v164 offset:1024
	ds_read_b128 v[160:163], v164 offset:2048
	ds_read_b128 v[164:167], v164 offset:3072
	ds_read_b128 v[168:171], v179
	ds_read_b128 v[172:175], v179 offset:1024
	ds_read_b128 v[180:183], v179 offset:2048
	ds_read_b128 v[184:187], v179 offset:3072
	s_add_u32 s48, s48, 0xb0000
	s_addc_u32 s49, s49, 0
	s_mov_b32 m0, s23
	v_lshl_add_u64 v[228:229], s[48:49], 0, v[130:131]
	ds_read_b128 v[188:191], v151 offset:32768
	ds_read_b128 v[192:195], v151 offset:33792
	ds_read_b128 v[196:199], v151 offset:34816
	ds_read_b128 v[202:205], v151 offset:35840
	ds_read_b128 v[206:209], v151 offset:36864
	ds_read_b128 v[210:213], v151 offset:37888
	ds_read_b128 v[214:217], v151 offset:38912
	ds_read_b128 v[218:221], v151 offset:39936
	global_load_lds_dwordx4 v[228:229], off
	v_lshl_add_u64 v[228:229], s[48:49], 0, v[134:135]
	s_mov_b32 m0, s25
	s_nop 0
	global_load_lds_dwordx4 v[228:229], off
	s_waitcnt vmcnt(8)
	s_waitcnt lgkmcnt(0)
	s_barrier
	s_setprio 1
	v_mfma_f32_16x16x32_bf16 v[124:127], v[152:155], v[188:191], v[124:127]
	v_mfma_f32_16x16x32_bf16 v[120:123], v[160:163], v[188:191], v[120:123]
	v_mfma_f32_16x16x32_bf16 v[108:111], v[152:155], v[196:199], v[108:111]
	v_mfma_f32_16x16x32_bf16 v[104:107], v[160:163], v[196:199], v[104:107]
	v_mfma_f32_16x16x32_bf16 v[92:95], v[152:155], v[206:209], v[92:95]
	v_mfma_f32_16x16x32_bf16 v[88:91], v[160:163], v[206:209], v[88:91]
	v_mfma_f32_16x16x32_bf16 v[76:79], v[152:155], v[214:217], v[76:79]
	v_mfma_f32_16x16x32_bf16 v[72:75], v[160:163], v[214:217], v[72:75]
	v_mfma_f32_16x16x32_bf16 v[124:127], v[156:159], v[192:195], v[124:127]
	v_mfma_f32_16x16x32_bf16 v[120:123], v[164:167], v[192:195], v[120:123]
	v_mfma_f32_16x16x32_bf16 v[108:111], v[156:159], v[202:205], v[108:111]
	v_mfma_f32_16x16x32_bf16 v[104:107], v[164:167], v[202:205], v[104:107]
	v_mfma_f32_16x16x32_bf16 v[92:95], v[156:159], v[210:213], v[92:95]
	v_mfma_f32_16x16x32_bf16 v[88:91], v[164:167], v[210:213], v[88:91]
	v_mfma_f32_16x16x32_bf16 v[76:79], v[156:159], v[218:221], v[76:79]
	v_mfma_f32_16x16x32_bf16 v[72:75], v[164:167], v[218:221], v[72:75]
	v_mfma_f32_16x16x32_bf16 v[116:119], v[168:171], v[188:191], v[116:119]
	v_mfma_f32_16x16x32_bf16 v[112:115], v[180:183], v[188:191], v[112:115]
	v_mfma_f32_16x16x32_bf16 v[100:103], v[168:171], v[196:199], v[100:103]
	v_mfma_f32_16x16x32_bf16 v[96:99], v[180:183], v[196:199], v[96:99]
	v_mfma_f32_16x16x32_bf16 v[84:87], v[168:171], v[206:209], v[84:87]
	v_mfma_f32_16x16x32_bf16 v[80:83], v[180:183], v[206:209], v[80:83]
	v_mfma_f32_16x16x32_bf16 v[68:71], v[168:171], v[214:217], v[68:71]
	v_mfma_f32_16x16x32_bf16 v[64:67], v[180:183], v[214:217], v[64:67]
	v_mfma_f32_16x16x32_bf16 v[116:119], v[172:175], v[192:195], v[116:119]
	v_mfma_f32_16x16x32_bf16 v[112:115], v[184:187], v[192:195], v[112:115]
	v_mfma_f32_16x16x32_bf16 v[100:103], v[172:175], v[202:205], v[100:103]
	v_mfma_f32_16x16x32_bf16 v[96:99], v[184:187], v[202:205], v[96:99]
	v_mfma_f32_16x16x32_bf16 v[84:87], v[172:175], v[210:213], v[84:87]
	v_mfma_f32_16x16x32_bf16 v[80:83], v[184:187], v[210:213], v[80:83]
	v_mfma_f32_16x16x32_bf16 v[68:71], v[172:175], v[218:221], v[68:71]
	v_mfma_f32_16x16x32_bf16 v[64:67], v[184:187], v[218:221], v[64:67]
	s_setprio 0
	s_barrier
; #define PG8_STAGE(bufoff, gbase, voff) do { _Pragma("unroll") for (int _i = 0; _i < 2; ++_i) \
;         __builtin_amdgcn_global_load_lds((const unsigned*)((const char*)(gbase) + (voff)[_i]), (LAS unsigned*)(lds + (bufoff) + ldsw + _i * 8192), 16, 0, 0); } while (0)
; #define PG8_STAGEB(bufoff, gbase, perm) do { _Pragma("unroll") for (int _i = 0; _i < 2; ++_i) \
;         __builtin_amdgcn_global_load_lds((const unsigned*)((const char*)(gbase) + ((BSEL && (perm)) ? voffBp[_i] : voffB[_i])), (LAS unsigned*)(lds + (bufoff) + ldsw + _i * 8192), 16, 0, 0); } while (0)
; #define PG8_LDA(dst, b, h) do { _Pragma("unroll") for (int m = 0; m < 4; ++m) _Pragma("unroll") for (int k = 0; k < 2; ++k) dst[m][k] = *(const LAS bf16x8*)(lds + PG8_SA(b, h) + aoff + m * 2048 + k * 1024); } while (0)
; #define PG8_LDB(dst, b, h) do { _Pragma("unroll") for (int n = 0; n < 2; ++n) _Pragma("unroll") for (int k = 0; k < 2; ++k) dst[n][k] = *(const LAS bf16x8*)(lds + PG8_SB(b, h) + boff + n * 2048 + k * 1024); } while (0)
; #define PG8_WAIT_V(n) asm volatile("s_waitcnt vmcnt(" #n ")" ::: "memory")
; #define PG8_BAR __builtin_amdgcn_s_barrier()
; template <class Epi, bool BSEL = false>
; __device__ __forceinline__ void gemm_phase(LAS unsigned char* lds, const Gemm g, const Order& S, const Epi& E, const int tid) {
;     ...
;             PG8_LDB(B0, 0, 0); PG8_LDB(B1, 0, 1); PG8_SCHED; PG8_LDA(At, 0, 0); PG8_STAGE(PG8_SA(1, 1), a1 + hstepA, voffA);
;             PG8_WAIT_V(8); PG8_WAIT_L(0); PG8_BAR; PG8_MMA(0, 0, At, B0); PG8_MMA(0, 1, At, B1); PG8_BAR; PG8_SCHED;
;             PG8_LDA(At, 0, 1); PG8_STAGEB(PG8_SB(0, 0), b2, p2); PG8_STAGEB(PG8_SB(0, 1), b2 + h2, p2); PG8_STAGE(PG8_SA(0, 0), a2, voffA);
;             PG8_WAIT_V(8); PG8_WAIT_L(0); PG8_BAR; PG8_MMA(1, 0, At, B0); PG8_MMA(1, 1, At, B1); PG8_BAR; PG8_SCHED;
;             PG8_LDB(B0, 1, 0); PG8_LDB(B1, 1, 1); PG8_SCHED; PG8_LDA(At, 1, 0); PG8_STAGE(PG8_SA(0, 1), a2 + hstepA, voffA);
;             PG8_WAIT_V(8); PG8_WAIT_L(0); PG8_BAR; PG8_MMA(0, 0, At, B0); PG8_MMA(0, 1, At, B1); PG8_BAR; PG8_SCHED;
;             PG8_LDA(At, 1, 1); PG8_STAGEB(PG8_SB(1, 0), b3, p2); PG8_STAGEB(PG8_SB(1, 1), b3 + h2, p2); PG8_STAGE(PG8_SA(1, 0), a3, voffA);
;             PG8_WAIT_V(8); PG8_WAIT_L(0); PG8_BAR; PG8_MMA(1, 0, At, B0); PG8_MMA(1, 1, At, B1); PG8_BAR; PG8_SCHED;
;         }
;         if constexpr (ALIGN_EPI) { if (wr == 0) PG8_BAR; }
	s_add_i32 s48, s65, s15
	v_lshl_add_u64 v[176:177], v[176:177], 0, s[30:31]
	s_mov_b32 m0, s48
	ds_read_b128 v[188:191], v151 offset:49152
	ds_read_b128 v[192:195], v151 offset:50176
	ds_read_b128 v[196:199], v151 offset:51200
	ds_read_b128 v[202:205], v151 offset:52224
	ds_read_b128 v[206:209], v151 offset:53248
	ds_read_b128 v[210:213], v151 offset:54272
	ds_read_b128 v[214:217], v151 offset:55296
	ds_read_b128 v[218:221], v151 offset:56320
	global_load_lds_dwordx4 v[176:177], off
	s_add_i32 m0, s48, 0x2000
	s_add_u32 s46, s46, 0xb0080
	v_lshl_add_u64 v[176:177], v[222:223], 0, s[30:31]
	s_addc_u32 s47, s47, 0
	s_add_i32 s48, s66, s15
	global_load_lds_dwordx4 v[176:177], off
	v_lshl_add_u64 v[176:177], s[46:47], 0, v[132:133]
	s_mov_b32 m0, s48
	s_nop 0
	global_load_lds_dwordx4 v[176:177], off
	v_lshl_add_u64 v[176:177], s[46:47], 0, v[136:137]
	s_add_i32 m0, s48, 0x2000
	s_nop 0
	global_load_lds_dwordx4 v[176:177], off
	v_lshl_add_u64 v[176:177], v[224:225], 0, s[30:31]
	s_mov_b32 m0, s50
	s_nop 0
	global_load_lds_dwordx4 v[176:177], off
	v_lshl_add_u64 v[176:177], v[226:227], 0, s[30:31]
	s_mov_b32 m0, s51
	s_nop 0
	global_load_lds_dwordx4 v[176:177], off
	s_waitcnt vmcnt(8)
	s_waitcnt lgkmcnt(0)
	s_barrier
	s_setprio 1
	v_mfma_f32_16x16x32_bf16 v[60:63], v[152:155], v[188:191], v[60:63]
	v_mfma_f32_16x16x32_bf16 v[56:59], v[160:163], v[188:191], v[56:59]
	v_mfma_f32_16x16x32_bf16 v[44:47], v[152:155], v[196:199], v[44:47]
	v_mfma_f32_16x16x32_bf16 v[40:43], v[160:163], v[196:199], v[40:43]
	v_mfma_f32_16x16x32_bf16 v[28:31], v[152:155], v[206:209], v[28:31]
	v_mfma_f32_16x16x32_bf16 v[24:27], v[160:163], v[206:209], v[24:27]
	v_mfma_f32_16x16x32_bf16 v[12:15], v[152:155], v[214:217], v[12:15]
	v_mfma_f32_16x16x32_bf16 v[8:11], v[160:163], v[214:217], v[8:11]
	v_mfma_f32_16x16x32_bf16 v[60:63], v[156:159], v[192:195], v[60:63]
	v_mfma_f32_16x16x32_bf16 v[56:59], v[164:167], v[192:195], v[56:59]
	v_mfma_f32_16x16x32_bf16 v[44:47], v[156:159], v[202:205], v[44:47]
	v_mfma_f32_16x16x32_bf16 v[40:43], v[164:167], v[202:205], v[40:43]
	v_mfma_f32_16x16x32_bf16 v[28:31], v[156:159], v[210:213], v[28:31]
	v_mfma_f32_16x16x32_bf16 v[24:27], v[164:167], v[210:213], v[24:27]
	v_mfma_f32_16x16x32_bf16 v[12:15], v[156:159], v[218:221], v[12:15]
	v_mfma_f32_16x16x32_bf16 v[8:11], v[164:167], v[218:221], v[8:11]
	v_mfma_f32_16x16x32_bf16 v[52:55], v[168:171], v[188:191], v[52:55]
	v_mfma_f32_16x16x32_bf16 v[48:51], v[180:183], v[188:191], v[48:51]
	v_mfma_f32_16x16x32_bf16 v[36:39], v[168:171], v[196:199], v[36:39]
	v_mfma_f32_16x16x32_bf16 v[32:35], v[180:183], v[196:199], v[32:35]
	v_mfma_f32_16x16x32_bf16 v[20:23], v[168:171], v[206:209], v[20:23]
	v_mfma_f32_16x16x32_bf16 v[16:19], v[180:183], v[206:209], v[16:19]
	v_mfma_f32_16x16x32_bf16 v[4:7], v[168:171], v[214:217], v[4:7]
	v_mfma_f32_16x16x32_bf16 v[0:3], v[180:183], v[214:217], v[0:3]
	v_mfma_f32_16x16x32_bf16 v[52:55], v[172:175], v[192:195], v[52:55]
	v_mfma_f32_16x16x32_bf16 v[48:51], v[184:187], v[192:195], v[48:51]
	v_mfma_f32_16x16x32_bf16 v[36:39], v[172:175], v[202:205], v[36:39]
	v_mfma_f32_16x16x32_bf16 v[32:35], v[184:187], v[202:205], v[32:35]
	v_mfma_f32_16x16x32_bf16 v[20:23], v[172:175], v[210:213], v[20:23]
	v_mfma_f32_16x16x32_bf16 v[16:19], v[184:187], v[210:213], v[16:19]
	v_mfma_f32_16x16x32_bf16 v[4:7], v[172:175], v[218:221], v[4:7]
	v_mfma_f32_16x16x32_bf16 v[0:3], v[184:187], v[218:221], v[0:3]
	s_setprio 0
	s_barrier
	s_add_i32 s64, s64, 2
	s_add_u32 s44, s44, 0x100
	s_addc_u32 s45, s45, 0
	s_cmp_gt_u32 s64, 41
	s_cbranch_scc0 .LBB0_472
	s_and_b64 vcc, exec, s[34:35]
	s_cbranch_vccz .LBB0_475
	s_barrier

; #define PG8_STAGE(bufoff, gbase, voff) do { _Pragma("unroll") for (int _i = 0; _i < 2; ++_i) \
;         __builtin_amdgcn_global_load_lds((const unsigned*)((const char*)(gbase) + (voff)[_i]), (LAS unsigned*)(lds + (bufoff) + ldsw + _i * 8192), 16, 0, 0); } while (0)
; #define PG8_STAGEB(bufoff, gbase, perm) do { _Pragma("unroll") for (int _i = 0; _i < 2; ++_i) \
;         __builtin_amdgcn_global_load_lds((const unsigned*)((const char*)(gbase) + ((BSEL && (perm)) ? voffBp[_i] : voffB[_i])), (LAS unsigned*)(lds + (bufoff) + ldsw + _i * 8192), 16, 0, 0); } while (0)
; #define PG8_LDA(dst, b, h) do { _Pragma("unroll") for (int m = 0; m < 4; ++m) _Pragma("unroll") for (int k = 0; k < 2; ++k) dst[m][k] = *(const LAS bf16x8*)(lds + PG8_SA(b, h) + aoff + m * 2048 + k * 1024); } while (0)
; #define PG8_LDB(dst, b, h) do { _Pragma("unroll") for (int n = 0; n < 2; ++n) _Pragma("unroll") for (int k = 0; k < 2; ++k) dst[n][k] = *(const LAS bf16x8*)(lds + PG8_SB(b, h) + boff + n * 2048 + k * 1024); } while (0)
; #define PG8_WAIT_V(n) asm volatile("s_waitcnt vmcnt(" #n ")" ::: "memory")
; #define PG8_BAR __builtin_amdgcn_s_barrier()
; template <class Epi, bool BSEL = false>
; __device__ __forceinline__ void gemm_phase(LAS unsigned char* lds, const Gemm g, const Order& S, const Epi& E, const int tid) {
;     ...
;         const bool has_next = S.next(ui + 1, nxt);
;         const char* nA = has_next ? nxt.a : cA; const char* nB = has_next ? nxt.b : cB;
;         const bool nP = has_next ? (BSEL && nxt.kind == 3) : cP; const size_t nhB = nP ? hstepBp : hstepBn;
;         for (int t = 0; t < nt; t += 2) {
;             const bool last = (t == nt - 2);
;             const char* a1 = cA + (size_t)(t + 1) * kstep;
;             const char* a2 = last ? nA : cA + (size_t)(t + 2) * kstep; const char* b2 = last ? nB : cB + (size_t)(t + 2) * kstep;
;             const char* a3 = a2 + kstep; const char* b3 = b2 + kstep;
;             const bool p2 = last ? nP : cP; const size_t h2 = last ? nhB : chB;
;             PG8_LDB(B0, 0, 0); PG8_LDB(B1, 0, 1); PG8_SCHED; PG8_LDA(At, 0, 0); PG8_STAGE(PG8_SA(1, 1), a1 + hstepA, voffA);
;             PG8_WAIT_V(8); PG8_WAIT_L(0); PG8_BAR; PG8_MMA(0, 0, At, B0); PG8_MMA(0, 1, At, B1); PG8_BAR; PG8_SCHED;
;             PG8_LDA(At, 0, 1); PG8_STAGEB(PG8_SB(0, 0), b2, p2); PG8_STAGEB(PG8_SB(0, 1), b2 + h2, p2); PG8_STAGE(PG8_SA(0, 0), a2, voffA);
.LBB0_670:
	s_add_u32 s2, s26, s62
	s_addc_u32 s3, s27, s63
	s_add_u32 s2, s2, 0x100
	s_addc_u32 s3, s3, 0
	s_add_u32 s44, s15, s62
	s_addc_u32 s45, s47, s63
	s_cmpk_eq_i32 s62, 0x700
	v_cndmask_b32_e64 v133, 0, 1, vcc
	s_cselect_b64 s[8:9], -1, 0
	v_cndmask_b32_e64 v133, v132, v133, s[8:9]
	v_and_b32_e32 v133, 1, v133
	v_cmp_eq_u32_e64 s[8:9], 1, v133
	v_add_u32_e32 v133, s94, v161
	ds_read_b128 v[134:137], v133
	ds_read_b128 v[138:141], v133 offset:1024
	ds_read_b128 v[178:181], v133 offset:2048
	ds_read_b128 v[182:185], v133 offset:3072
	v_add_u32_e32 v133, s96, v161
	ds_read_b128 v[186:189], v133
	ds_read_b128 v[190:193], v133 offset:1024
	ds_read_b128 v[194:197], v133 offset:2048
	ds_read_b128 v[202:205], v133 offset:3072
	s_cselect_b32 s3, s58, s3
	s_cselect_b32 s2, s59, s2
	s_cselect_b32 s45, s64, s45
	s_cselect_b32 s44, s65, s44
	s_cselect_b32 s93, 0, s51
	s_cselect_b32 s70, s28, s50
	v_lshl_add_u64 v[142:143], v[128:129], 0, s[62:63]
	s_add_i32 m0, s74, 0xc000
	ds_read_b128 v[206:209], v163
	ds_read_b128 v[210:213], v163 offset:1024
	ds_read_b128 v[214:217], v163 offset:2048
	ds_read_b128 v[218:221], v163 offset:3072
	ds_read_b128 v[222:225], v163 offset:4096
	ds_read_b128 v[226:229], v163 offset:5120
	ds_read_b128 v[230:233], v163 offset:6144
	ds_read_b128 v[234:237], v163 offset:7168
	global_load_lds_dwordx4 v[142:143], off
	v_lshl_add_u64 v[142:143], v[130:131], 0, s[62:63]
	s_add_i32 m0, s74, 0xe000
	s_nop 0
	global_load_lds_dwordx4 v[142:143], off
	s_waitcnt vmcnt(8)
	s_waitcnt lgkmcnt(0)
	s_barrier
	s_setprio 1
	v_mfma_f32_16x16x32_bf16 v[124:127], v[134:137], v[206:209], v[124:127]
	v_mfma_f32_16x16x32_bf16 v[120:123], v[178:181], v[206:209], v[120:123]
	v_mfma_f32_16x16x32_bf16 v[116:119], v[134:137], v[214:217], v[116:119]
	v_mfma_f32_16x16x32_bf16 v[112:115], v[178:181], v[214:217], v[112:115]
	v_mfma_f32_16x16x32_bf16 v[108:111], v[134:137], v[222:225], v[108:111]
	v_mfma_f32_16x16x32_bf16 v[104:107], v[178:181], v[222:225], v[104:107]
	v_mfma_f32_16x16x32_bf16 v[100:103], v[134:137], v[230:233], v[100:103]
	v_mfma_f32_16x16x32_bf16 v[96:99], v[178:181], v[230:233], v[96:99]
	v_mfma_f32_16x16x32_bf16 v[124:127], v[138:141], v[210:213], v[124:127]
	v_mfma_f32_16x16x32_bf16 v[120:123], v[182:185], v[210:213], v[120:123]
	v_mfma_f32_16x16x32_bf16 v[116:119], v[138:141], v[218:221], v[116:119]
	v_mfma_f32_16x16x32_bf16 v[112:115], v[182:185], v[218:221], v[112:115]
	v_mfma_f32_16x16x32_bf16 v[108:111], v[138:141], v[226:229], v[108:111]
	v_mfma_f32_16x16x32_bf16 v[104:107], v[182:185], v[226:229], v[104:107]
	v_mfma_f32_16x16x32_bf16 v[100:103], v[138:141], v[234:237], v[100:103]
	v_mfma_f32_16x16x32_bf16 v[96:99], v[182:185], v[234:237], v[96:99]
	v_mfma_f32_16x16x32_bf16 v[92:95], v[186:189], v[206:209], v[92:95]
	v_mfma_f32_16x16x32_bf16 v[88:91], v[194:197], v[206:209], v[88:91]
	v_mfma_f32_16x16x32_bf16 v[84:87], v[186:189], v[214:217], v[84:87]
	v_mfma_f32_16x16x32_bf16 v[80:83], v[194:197], v[214:217], v[80:83]
	v_mfma_f32_16x16x32_bf16 v[76:79], v[186:189], v[222:225], v[76:79]
	v_mfma_f32_16x16x32_bf16 v[72:75], v[194:197], v[222:225], v[72:75]
	v_mfma_f32_16x16x32_bf16 v[68:71], v[186:189], v[230:233], v[68:71]
	v_mfma_f32_16x16x32_bf16 v[64:67], v[194:197], v[230:233], v[64:67]
	v_mfma_f32_16x16x32_bf16 v[92:95], v[190:193], v[210:213], v[92:95]
	v_mfma_f32_16x16x32_bf16 v[88:91], v[202:205], v[210:213], v[88:91]
	v_mfma_f32_16x16x32_bf16 v[84:87], v[190:193], v[218:221], v[84:87]
	v_mfma_f32_16x16x32_bf16 v[80:83], v[202:205], v[218:221], v[80:83]
	v_mfma_f32_16x16x32_bf16 v[76:79], v[190:193], v[226:229], v[76:79]
	v_mfma_f32_16x16x32_bf16 v[72:75], v[202:205], v[226:229], v[72:75]
	v_mfma_f32_16x16x32_bf16 v[68:71], v[190:193], v[234:237], v[68:71]
	v_mfma_f32_16x16x32_bf16 v[64:67], v[202:205], v[234:237], v[64:67]
	s_setprio 0
	s_barrier
	s_add_i32 s71, s94, s25
	v_cndmask_b32_e64 v148, v151, v153, s[8:9]
	s_mov_b32 m0, s71
	ds_read_b128 v[206:209], v163 offset:16384
	ds_read_b128 v[210:213], v163 offset:17408
	ds_read_b128 v[214:217], v163 offset:18432
	ds_read_b128 v[218:221], v163 offset:19456
	ds_read_b128 v[222:225], v163 offset:20480
	ds_read_b128 v[226:229], v163 offset:21504
	ds_read_b128 v[230:233], v163 offset:22528
	ds_read_b128 v[234:237], v163 offset:23552
	global_load_lds_dwordx4 v148, s[44:45]
	s_add_i32 m0, s71, 0x2000
	v_cndmask_b32_e64 v198, v155, v157, s[8:9]
	v_mov_b32_e32 v199, v149
	s_add_u32 s8, s44, s70
	v_lshl_add_u64 v[142:143], s[44:45], 0, v[148:149]
	v_lshl_add_u64 v[238:239], s[44:45], 0, v[198:199]
	global_load_lds_dwordx4 v198, s[44:45]
	s_addc_u32 s9, s45, s93
	s_add_i32 s44, s96, s25
	s_mov_b32 m0, s44
	v_lshl_add_u64 v[242:243], s[8:9], 0, v[198:199]
	global_load_lds_dwordx4 v148, s[8:9]
	s_add_i32 m0, s44, 0x2000
	v_lshl_add_u64 v[244:245], s[2:3], 0, v[146:147]
	global_load_lds_dwordx4 v198, s[8:9]
	v_lshl_add_u64 v[198:199], s[2:3], 0, v[144:145]
	s_mov_b32 m0, s74
	v_lshl_add_u64 v[240:241], s[8:9], 0, v[148:149]
	global_load_lds_dwordx4 v[198:199], off
	s_mov_b32 m0, s76
	s_nop 0
	global_load_lds_dwordx4 v[244:245], off
	s_waitcnt vmcnt(8)
	s_waitcnt lgkmcnt(0)
	s_barrier
; #define PG8_STAGE(bufoff, gbase, voff) do { _Pragma("unroll") for (int _i = 0; _i < 2; ++_i) \
;         __builtin_amdgcn_global_load_lds((const unsigned*)((const char*)(gbase) + (voff)[_i]), (LAS unsigned*)(lds + (bufoff) + ldsw + _i * 8192), 16, 0, 0); } while (0)
; #define PG8_STAGEB(bufoff, gbase, perm) do { _Pragma("unroll") for (int _i = 0; _i < 2; ++_i) \
;         __builtin_amdgcn_global_load_lds((const unsigned*)((const char*)(gbase) + ((BSEL && (perm)) ? voffBp[_i] : voffB[_i])), (LAS unsigned*)(lds + (bufoff) + ldsw + _i * 8192), 16, 0, 0); } while (0)
; #define PG8_LDA(dst, b, h) do { _Pragma("unroll") for (int m = 0; m < 4; ++m) _Pragma("unroll") for (int k = 0; k < 2; ++k) dst[m][k] = *(const LAS bf16x8*)(lds + PG8_SA(b, h) + aoff + m * 2048 + k * 1024); } while (0)
; #define PG8_LDB(dst, b, h) do { _Pragma("unroll") for (int n = 0; n < 2; ++n) _Pragma("unroll") for (int k = 0; k < 2; ++k) dst[n][k] = *(const LAS bf16x8*)(lds + PG8_SB(b, h) + boff + n * 2048 + k * 1024); } while (0)
; #define PG8_WAIT_V(n) asm volatile("s_waitcnt vmcnt(" #n ")" ::: "memory")
; #define PG8_WAIT_L(n) asm volatile("s_waitcnt lgkmcnt(" #n ")" ::: "memory")
; template <class Epi, bool BSEL = false>
; __device__ __forceinline__ void gemm_phase(LAS unsigned char* lds, const Gemm g, const Order& S, const Epi& E, const int tid) {
;     ...
;             PG8_LDB(B0, 0, 0); PG8_LDB(B1, 0, 1); PG8_SCHED; PG8_LDA(At, 0, 0); PG8_STAGE(PG8_SA(1, 1), a1 + hstepA, voffA);
;             PG8_WAIT_V(8); PG8_WAIT_L(0); PG8_BAR; PG8_MMA(0, 0, At, B0); PG8_MMA(0, 1, At, B1); PG8_BAR; PG8_SCHED;
;             PG8_LDA(At, 0, 1); PG8_STAGEB(PG8_SB(0, 0), b2, p2); PG8_STAGEB(PG8_SB(0, 1), b2 + h2, p2); PG8_STAGE(PG8_SA(0, 0), a2, voffA);
;             PG8_WAIT_V(8); PG8_WAIT_L(0); PG8_BAR; PG8_MMA(1, 0, At, B0); PG8_MMA(1, 1, At, B1); PG8_BAR; PG8_SCHED;
;             PG8_LDB(B0, 1, 0); PG8_LDB(B1, 1, 1); PG8_SCHED; PG8_LDA(At, 1, 0); PG8_STAGE(PG8_SA(0, 1), a2 + hstepA, voffA);
;             PG8_WAIT_V(8); PG8_WAIT_L(0); PG8_BAR; PG8_MMA(0, 0, At, B0); PG8_MMA(0, 1, At, B1); PG8_BAR; PG8_SCHED;
;             PG8_LDA(At, 1, 1); PG8_STAGEB(PG8_SB(1, 0), b3, p2); PG8_STAGEB(PG8_SB(1, 1), b3 + h2, p2); PG8_STAGE(PG8_SA(1, 0), a3, voffA);
;             PG8_WAIT_V(8); PG8_WAIT_L(0); PG8_BAR; PG8_MMA(1, 0, At, B0); PG8_MMA(1, 1, At, B1); PG8_BAR; PG8_SCHED;
	s_setprio 1
	v_mfma_f32_16x16x32_bf16 v[60:63], v[134:137], v[206:209], v[60:63]
	v_mfma_f32_16x16x32_bf16 v[56:59], v[178:181], v[206:209], v[56:59]
	v_mfma_f32_16x16x32_bf16 v[52:55], v[134:137], v[214:217], v[52:55]
	v_mfma_f32_16x16x32_bf16 v[48:51], v[178:181], v[214:217], v[48:51]
	v_mfma_f32_16x16x32_bf16 v[44:47], v[134:137], v[222:225], v[44:47]
	v_mfma_f32_16x16x32_bf16 v[40:43], v[178:181], v[222:225], v[40:43]
	v_mfma_f32_16x16x32_bf16 v[36:39], v[134:137], v[230:233], v[36:39]
	v_mfma_f32_16x16x32_bf16 v[32:35], v[178:181], v[230:233], v[32:35]
	v_mfma_f32_16x16x32_bf16 v[60:63], v[138:141], v[210:213], v[60:63]
	v_mfma_f32_16x16x32_bf16 v[56:59], v[182:185], v[210:213], v[56:59]
	v_mfma_f32_16x16x32_bf16 v[52:55], v[138:141], v[218:221], v[52:55]
	v_mfma_f32_16x16x32_bf16 v[48:51], v[182:185], v[218:221], v[48:51]
	v_mfma_f32_16x16x32_bf16 v[44:47], v[138:141], v[226:229], v[44:47]
	v_mfma_f32_16x16x32_bf16 v[40:43], v[182:185], v[226:229], v[40:43]
	v_mfma_f32_16x16x32_bf16 v[36:39], v[138:141], v[234:237], v[36:39]
	v_mfma_f32_16x16x32_bf16 v[32:35], v[182:185], v[234:237], v[32:35]
	v_mfma_f32_16x16x32_bf16 v[28:31], v[186:189], v[206:209], v[28:31]
	v_mfma_f32_16x16x32_bf16 v[24:27], v[194:197], v[206:209], v[24:27]
	v_mfma_f32_16x16x32_bf16 v[20:23], v[186:189], v[214:217], v[20:23]
	v_mfma_f32_16x16x32_bf16 v[16:19], v[194:197], v[214:217], v[16:19]
	v_mfma_f32_16x16x32_bf16 v[12:15], v[186:189], v[222:225], v[12:15]
	v_mfma_f32_16x16x32_bf16 v[8:11], v[194:197], v[222:225], v[8:11]
	v_mfma_f32_16x16x32_bf16 v[4:7], v[186:189], v[230:233], v[4:7]
	v_mfma_f32_16x16x32_bf16 v[0:3], v[194:197], v[230:233], v[0:3]
	v_mfma_f32_16x16x32_bf16 v[28:31], v[190:193], v[210:213], v[28:31]
	v_mfma_f32_16x16x32_bf16 v[24:27], v[202:205], v[210:213], v[24:27]
	v_mfma_f32_16x16x32_bf16 v[20:23], v[190:193], v[218:221], v[20:23]
	v_mfma_f32_16x16x32_bf16 v[16:19], v[202:205], v[218:221], v[16:19]
	v_mfma_f32_16x16x32_bf16 v[12:15], v[190:193], v[226:229], v[12:15]
	v_mfma_f32_16x16x32_bf16 v[8:11], v[202:205], v[226:229], v[8:11]
	v_mfma_f32_16x16x32_bf16 v[4:7], v[190:193], v[234:237], v[4:7]
	v_mfma_f32_16x16x32_bf16 v[0:3], v[202:205], v[234:237], v[0:3]
	s_setprio 0
	s_barrier
	s_add_i32 s8, 0, 0x18000
	v_add_u32_e32 v133, s8, v161
	s_add_i32 s9, 0, 0x1c000
	ds_read_b128 v[134:137], v133
	ds_read_b128 v[138:141], v133 offset:1024
	ds_read_b128 v[178:181], v133 offset:2048
	ds_read_b128 v[182:185], v133 offset:3072
	v_add_u32_e32 v133, s9, v161
	ds_read_b128 v[186:189], v133
	ds_read_b128 v[190:193], v133 offset:1024
	ds_read_b128 v[194:197], v133 offset:2048
	ds_read_b128 v[202:205], v133 offset:3072
	s_add_u32 s2, s2, 0x40000
	s_addc_u32 s3, s3, 0
	s_mov_b32 m0, s77
	v_lshl_add_u64 v[246:247], s[2:3], 0, v[144:145]
	ds_read_b128 v[206:209], v163 offset:32768
	ds_read_b128 v[210:213], v163 offset:33792
	ds_read_b128 v[214:217], v163 offset:34816
	ds_read_b128 v[218:221], v163 offset:35840
	ds_read_b128 v[222:225], v163 offset:36864
	ds_read_b128 v[226:229], v163 offset:37888
	ds_read_b128 v[230:233], v163 offset:38912
	ds_read_b128 v[234:237], v163 offset:39936
	global_load_lds_dwordx4 v[246:247], off
	v_lshl_add_u64 v[246:247], s[2:3], 0, v[146:147]
	s_mov_b32 m0, s78
	s_nop 0
	global_load_lds_dwordx4 v[246:247], off
	s_waitcnt vmcnt(8)
	s_waitcnt lgkmcnt(0)
	s_barrier
	s_setprio 1
	v_mfma_f32_16x16x32_bf16 v[124:127], v[134:137], v[206:209], v[124:127]
	v_mfma_f32_16x16x32_bf16 v[120:123], v[178:181], v[206:209], v[120:123]
	v_mfma_f32_16x16x32_bf16 v[116:119], v[134:137], v[214:217], v[116:119]
	v_mfma_f32_16x16x32_bf16 v[112:115], v[178:181], v[214:217], v[112:115]
	v_mfma_f32_16x16x32_bf16 v[108:111], v[134:137], v[222:225], v[108:111]
	v_mfma_f32_16x16x32_bf16 v[104:107], v[178:181], v[222:225], v[104:107]
	v_mfma_f32_16x16x32_bf16 v[100:103], v[134:137], v[230:233], v[100:103]
	v_mfma_f32_16x16x32_bf16 v[96:99], v[178:181], v[230:233], v[96:99]
	v_mfma_f32_16x16x32_bf16 v[124:127], v[138:141], v[210:213], v[124:127]
	v_mfma_f32_16x16x32_bf16 v[120:123], v[182:185], v[210:213], v[120:123]
	v_mfma_f32_16x16x32_bf16 v[116:119], v[138:141], v[218:221], v[116:119]
	v_mfma_f32_16x16x32_bf16 v[112:115], v[182:185], v[218:221], v[112:115]
	v_mfma_f32_16x16x32_bf16 v[108:111], v[138:141], v[226:229], v[108:111]
	v_mfma_f32_16x16x32_bf16 v[104:107], v[182:185], v[226:229], v[104:107]
	v_mfma_f32_16x16x32_bf16 v[100:103], v[138:141], v[234:237], v[100:103]
	v_mfma_f32_16x16x32_bf16 v[96:99], v[182:185], v[234:237], v[96:99]
	v_mfma_f32_16x16x32_bf16 v[92:95], v[186:189], v[206:209], v[92:95]
	v_mfma_f32_16x16x32_bf16 v[88:91], v[194:197], v[206:209], v[88:91]
	v_mfma_f32_16x16x32_bf16 v[84:87], v[186:189], v[214:217], v[84:87]
	v_mfma_f32_16x16x32_bf16 v[80:83], v[194:197], v[214:217], v[80:83]
	v_mfma_f32_16x16x32_bf16 v[76:79], v[186:189], v[222:225], v[76:79]
	v_mfma_f32_16x16x32_bf16 v[72:75], v[194:197], v[222:225], v[72:75]
	v_mfma_f32_16x16x32_bf16 v[68:71], v[186:189], v[230:233], v[68:71]
	v_mfma_f32_16x16x32_bf16 v[64:67], v[194:197], v[230:233], v[64:67]
	v_mfma_f32_16x16x32_bf16 v[92:95], v[190:193], v[210:213], v[92:95]
	v_mfma_f32_16x16x32_bf16 v[88:91], v[202:205], v[210:213], v[88:91]
	v_mfma_f32_16x16x32_bf16 v[84:87], v[190:193], v[218:221], v[84:87]
	v_mfma_f32_16x16x32_bf16 v[80:83], v[202:205], v[218:221], v[80:83]
	v_mfma_f32_16x16x32_bf16 v[76:79], v[190:193], v[226:229], v[76:79]
	v_mfma_f32_16x16x32_bf16 v[72:75], v[202:205], v[226:229], v[72:75]
	v_mfma_f32_16x16x32_bf16 v[68:71], v[190:193], v[234:237], v[68:71]
	v_mfma_f32_16x16x32_bf16 v[64:67], v[202:205], v[234:237], v[64:67]
	s_setprio 0
	s_barrier
; #define PG8_STAGE(bufoff, gbase, voff) do { _Pragma("unroll") for (int _i = 0; _i < 2; ++_i) \
;         __builtin_amdgcn_global_load_lds((const unsigned*)((const char*)(gbase) + (voff)[_i]), (LAS unsigned*)(lds + (bufoff) + ldsw + _i * 8192), 16, 0, 0); } while (0)
; #define PG8_STAGEB(bufoff, gbase, perm) do { _Pragma("unroll") for (int _i = 0; _i < 2; ++_i) \
;         __builtin_amdgcn_global_load_lds((const unsigned*)((const char*)(gbase) + ((BSEL && (perm)) ? voffBp[_i] : voffB[_i])), (LAS unsigned*)(lds + (bufoff) + ldsw + _i * 8192), 16, 0, 0); } while (0)
; #define PG8_LDA(dst, b, h) do { _Pragma("unroll") for (int m = 0; m < 4; ++m) _Pragma("unroll") for (int k = 0; k < 2; ++k) dst[m][k] = *(const LAS bf16x8*)(lds + PG8_SA(b, h) + aoff + m * 2048 + k * 1024); } while (0)
; #define PG8_WAIT_V(n) asm volatile("s_waitcnt vmcnt(" #n ")" ::: "memory")
; #define PG8_WAIT_L(n) asm volatile("s_waitcnt lgkmcnt(" #n ")" ::: "memory")
; template <class Epi, bool BSEL = false>
; __device__ __forceinline__ void gemm_phase(LAS unsigned char* lds, const Gemm g, const Order& S, const Epi& E, const int tid) {
;     ...
;             PG8_LDB(B0, 0, 0); PG8_LDB(B1, 0, 1); PG8_SCHED; PG8_LDA(At, 0, 0); PG8_STAGE(PG8_SA(1, 1), a1 + hstepA, voffA);
;             PG8_WAIT_V(8); PG8_WAIT_L(0); PG8_BAR; PG8_MMA(0, 0, At, B0); PG8_MMA(0, 1, At, B1); PG8_BAR; PG8_SCHED;
;             PG8_LDA(At, 0, 1); PG8_STAGEB(PG8_SB(0, 0), b2, p2); PG8_STAGEB(PG8_SB(0, 1), b2 + h2, p2); PG8_STAGE(PG8_SA(0, 0), a2, voffA);
;             PG8_WAIT_V(8); PG8_WAIT_L(0); PG8_BAR; PG8_MMA(1, 0, At, B0); PG8_MMA(1, 1, At, B1); PG8_BAR; PG8_SCHED;
;             PG8_LDB(B0, 1, 0); PG8_LDB(B1, 1, 1); PG8_SCHED; PG8_LDA(At, 1, 0); PG8_STAGE(PG8_SA(0, 1), a2 + hstepA, voffA);
;             PG8_WAIT_V(8); PG8_WAIT_L(0); PG8_BAR; PG8_MMA(0, 0, At, B0); PG8_MMA(0, 1, At, B1); PG8_BAR; PG8_SCHED;
;             PG8_LDA(At, 1, 1); PG8_STAGEB(PG8_SB(1, 0), b3, p2); PG8_STAGEB(PG8_SB(1, 1), b3 + h2, p2); PG8_STAGE(PG8_SA(1, 0), a3, voffA);
;             PG8_WAIT_V(8); PG8_WAIT_L(0); PG8_BAR; PG8_MMA(1, 0, At, B0); PG8_MMA(1, 1, At, B1); PG8_BAR; PG8_SCHED;
;         }
;         if constexpr (ALIGN_EPI) { if (wr == 0) PG8_BAR; }
;     __device__ __forceinline__ void operator()(const f32x4 (&acc)[2][2][4][2], const Unit& u, int wr, int wc, int fr, int fq) const {
;         if (u.kind <= 1) {
	s_add_i32 s2, s8, s25
	v_lshl_add_u64 v[142:143], v[142:143], 0, s[36:37]
	s_mov_b32 m0, s2
	ds_read_b128 v[206:209], v163 offset:49152
	ds_read_b128 v[210:213], v163 offset:50176
	ds_read_b128 v[214:217], v163 offset:51200
	ds_read_b128 v[218:221], v163 offset:52224
	ds_read_b128 v[222:225], v163 offset:53248
	ds_read_b128 v[226:229], v163 offset:54272
	ds_read_b128 v[230:233], v163 offset:55296
	ds_read_b128 v[234:237], v163 offset:56320
	global_load_lds_dwordx4 v[142:143], off
	v_lshl_add_u64 v[142:143], v[238:239], 0, s[36:37]
	s_add_i32 m0, s2, 0x2000
	s_add_i32 s2, s9, s25
	global_load_lds_dwordx4 v[142:143], off
	v_lshl_add_u64 v[142:143], v[240:241], 0, s[36:37]
	s_mov_b32 m0, s2
	s_nop 0
	global_load_lds_dwordx4 v[142:143], off
	v_lshl_add_u64 v[142:143], v[242:243], 0, s[36:37]
	s_add_i32 m0, s2, 0x2000
	s_nop 0
	global_load_lds_dwordx4 v[142:143], off
	v_lshl_add_u64 v[142:143], v[198:199], 0, s[36:37]
	s_mov_b32 m0, s89
	s_nop 0
	global_load_lds_dwordx4 v[142:143], off
	v_lshl_add_u64 v[142:143], v[244:245], 0, s[36:37]
	s_mov_b32 m0, s90
	s_nop 0
	global_load_lds_dwordx4 v[142:143], off
	s_waitcnt vmcnt(8)
	s_waitcnt lgkmcnt(0)
	s_barrier
	s_setprio 1
	v_mfma_f32_16x16x32_bf16 v[60:63], v[134:137], v[206:209], v[60:63]
	v_mfma_f32_16x16x32_bf16 v[56:59], v[178:181], v[206:209], v[56:59]
	v_mfma_f32_16x16x32_bf16 v[52:55], v[134:137], v[214:217], v[52:55]
	v_mfma_f32_16x16x32_bf16 v[48:51], v[178:181], v[214:217], v[48:51]
	v_mfma_f32_16x16x32_bf16 v[44:47], v[134:137], v[222:225], v[44:47]
	v_mfma_f32_16x16x32_bf16 v[40:43], v[178:181], v[222:225], v[40:43]
	v_mfma_f32_16x16x32_bf16 v[36:39], v[134:137], v[230:233], v[36:39]
	v_mfma_f32_16x16x32_bf16 v[32:35], v[178:181], v[230:233], v[32:35]
	v_mfma_f32_16x16x32_bf16 v[60:63], v[138:141], v[210:213], v[60:63]
	v_mfma_f32_16x16x32_bf16 v[56:59], v[182:185], v[210:213], v[56:59]
	v_mfma_f32_16x16x32_bf16 v[52:55], v[138:141], v[218:221], v[52:55]
	v_mfma_f32_16x16x32_bf16 v[48:51], v[182:185], v[218:221], v[48:51]
	v_mfma_f32_16x16x32_bf16 v[44:47], v[138:141], v[226:229], v[44:47]
	v_mfma_f32_16x16x32_bf16 v[40:43], v[182:185], v[226:229], v[40:43]
	v_mfma_f32_16x16x32_bf16 v[36:39], v[138:141], v[234:237], v[36:39]
	v_mfma_f32_16x16x32_bf16 v[32:35], v[182:185], v[234:237], v[32:35]
	v_mfma_f32_16x16x32_bf16 v[28:31], v[186:189], v[206:209], v[28:31]
	v_mfma_f32_16x16x32_bf16 v[24:27], v[194:197], v[206:209], v[24:27]
	v_mfma_f32_16x16x32_bf16 v[20:23], v[186:189], v[214:217], v[20:23]
	v_mfma_f32_16x16x32_bf16 v[16:19], v[194:197], v[214:217], v[16:19]
	v_mfma_f32_16x16x32_bf16 v[12:15], v[186:189], v[222:225], v[12:15]
	v_mfma_f32_16x16x32_bf16 v[8:11], v[194:197], v[222:225], v[8:11]
	v_mfma_f32_16x16x32_bf16 v[4:7], v[186:189], v[230:233], v[4:7]
	v_mfma_f32_16x16x32_bf16 v[0:3], v[194:197], v[230:233], v[0:3]
	v_mfma_f32_16x16x32_bf16 v[28:31], v[190:193], v[210:213], v[28:31]
	v_mfma_f32_16x16x32_bf16 v[24:27], v[202:205], v[210:213], v[24:27]
	v_mfma_f32_16x16x32_bf16 v[20:23], v[190:193], v[218:221], v[20:23]
	v_mfma_f32_16x16x32_bf16 v[16:19], v[202:205], v[218:221], v[16:19]
	v_mfma_f32_16x16x32_bf16 v[12:15], v[190:193], v[226:229], v[12:15]
	v_mfma_f32_16x16x32_bf16 v[8:11], v[202:205], v[226:229], v[8:11]
	v_mfma_f32_16x16x32_bf16 v[4:7], v[190:193], v[234:237], v[4:7]
	v_mfma_f32_16x16x32_bf16 v[0:3], v[202:205], v[234:237], v[0:3]
	s_setprio 0
	s_barrier
	s_add_i32 s95, s95, 2
	s_add_u32 s62, s62, 0x100
	s_addc_u32 s63, s63, 0
	s_cmp_gt_u32 s95, 13
	s_cbranch_scc0 .LBB0_670
	s_and_b64 vcc, exec, s[38:39]
	s_cbranch_vccz .LBB0_696
	s_barrier
	s_cmp_gt_i32 s73, 1
	s_mov_b64 s[2:3], -1
	s_cbranch_scc1 .LBB0_697

; #define PG8_STAGE(bufoff, gbase, voff) do { _Pragma("unroll") for (int _i = 0; _i < 2; ++_i) \
;         __builtin_amdgcn_global_load_lds((const unsigned*)((const char*)(gbase) + (voff)[_i]), (LAS unsigned*)(lds + (bufoff) + ldsw + _i * 8192), 16, 0, 0); } while (0)
; #define PG8_LDA(dst, b, h) do { _Pragma("unroll") for (int m = 0; m < 4; ++m) _Pragma("unroll") for (int k = 0; k < 2; ++k) dst[m][k] = *(const LAS bf16x8*)(lds + PG8_SA(b, h) + aoff + m * 2048 + k * 1024); } while (0)
; #define PG8_LDB(dst, b, h) do { _Pragma("unroll") for (int n = 0; n < 2; ++n) _Pragma("unroll") for (int k = 0; k < 2; ++k) dst[n][k] = *(const LAS bf16x8*)(lds + PG8_SB(b, h) + boff + n * 2048 + k * 1024); } while (0)
; #define PG8_MMA(ai, bj, At, Bt) do { __builtin_amdgcn_s_setprio(1); _Pragma("unroll") for (int m = 0; m < 4; ++m) _Pragma("unroll") for (int n = 0; n < 2; ++n) _Pragma("unroll") for (int k = 0; k < 2; ++k) \
;         acc[ai][bj][m][n] = __builtin_amdgcn_mfma_f32_16x16x32_bf16(Bt[n][k], At[m][k], acc[ai][bj][m][n], 0, 0, 0); __builtin_amdgcn_s_setprio(0); } while (0)
; #define PG8_WAIT_V(n) asm volatile("s_waitcnt vmcnt(" #n ")" ::: "memory")
; #define PG8_WAIT_L(n) asm volatile("s_waitcnt lgkmcnt(" #n ")" ::: "memory")
; #define PG8_BAR __builtin_amdgcn_s_barrier()
; template <class Epi, bool BSEL = false>
; __device__ __forceinline__ void gemm_phase(LAS unsigned char* lds, const Gemm g, const Order& S, const Epi& E, const int tid) {
;     ...
;         const bool has_next = S.next(ui + 1, nxt);
;         const char* nA = has_next ? nxt.a : cA; const char* nB = has_next ? nxt.b : cB;
;         const bool nP = has_next ? (BSEL && nxt.kind == 3) : cP; const size_t nhB = nP ? hstepBp : hstepBn;
;         for (int t = 0; t < nt; t += 2) {
;             const bool last = (t == nt - 2);
;             const char* a1 = cA + (size_t)(t + 1) * kstep;
;             const char* a2 = last ? nA : cA + (size_t)(t + 2) * kstep; const char* b2 = last ? nB : cB + (size_t)(t + 2) * kstep;
;             const char* a3 = a2 + kstep; const char* b3 = b2 + kstep;
;             const bool p2 = last ? nP : cP; const size_t h2 = last ? nhB : chB;
;             PG8_LDB(B0, 0, 0); PG8_LDB(B1, 0, 1); PG8_SCHED; PG8_LDA(At, 0, 0); PG8_STAGE(PG8_SA(1, 1), a1 + hstepA, voffA);
;             PG8_WAIT_V(8); PG8_WAIT_L(0); PG8_BAR; PG8_MMA(0, 0, At, B0); PG8_MMA(0, 1, At, B1); PG8_BAR; PG8_SCHED;
.LBB0_826:
	s_xor_b64 s[38:39], s[40:41], -1
	v_add_u32_e32 v145, s53, v139
	s_and_b64 s[2:3], s[40:41], exec
	ds_read_b128 v[146:149], v145
	ds_read_b128 v[150:153], v145 offset:1024
	ds_read_b128 v[154:157], v145 offset:2048
	ds_read_b128 v[158:161], v145 offset:3072
	v_add_u32_e32 v145, s54, v139
	s_cselect_b32 s45, s1, s1
	s_cselect_b32 s44, s0, s0
	s_add_u32 s58, s0, 0x8080
	ds_read_b128 v[162:165], v145
	ds_read_b128 v[166:169], v145 offset:1024
	ds_read_b128 v[170:173], v145 offset:2048
	ds_read_b128 v[174:177], v145 offset:3072
	s_addc_u32 s59, s1, 0
	s_add_u32 s42, s44, 0x8000
	s_addc_u32 s43, s45, 0
	s_and_b64 s[2:3], s[40:41], exec
	s_cselect_b32 s2, s36, s4
	s_cselect_b32 s3, s37, s5
	s_add_u32 s60, s2, 0x8000
	s_addc_u32 s61, s3, 0
	v_lshl_add_u64 v[198:199], s[58:59], 0, v[128:129]
	s_add_i32 m0, s20, 0xc000
	ds_read_b128 v[178:181], v144
	ds_read_b128 v[182:185], v144 offset:1024
	ds_read_b128 v[186:189], v144 offset:2048
	ds_read_b128 v[190:193], v144 offset:3072
	ds_read_b128 v[194:197], v144 offset:4096
	ds_read_b128 v[202:205], v144 offset:5120
	ds_read_b128 v[206:209], v144 offset:6144
	ds_read_b128 v[210:213], v144 offset:7168
	global_load_lds_dwordx4 v[198:199], off
	v_lshl_add_u64 v[198:199], s[58:59], 0, v[132:133]
	s_add_i32 m0, s20, 0xe000
	s_nop 0
	global_load_lds_dwordx4 v[198:199], off
	s_waitcnt vmcnt(8)
	s_waitcnt lgkmcnt(0)
	s_barrier
	s_setprio 1
	v_mfma_f32_16x16x32_bf16 v[124:127], v[146:149], v[178:181], v[124:127]
	v_mfma_f32_16x16x32_bf16 v[120:123], v[154:157], v[178:181], v[120:123]
	v_mfma_f32_16x16x32_bf16 v[116:119], v[146:149], v[186:189], v[116:119]
	v_mfma_f32_16x16x32_bf16 v[112:115], v[154:157], v[186:189], v[112:115]
	v_mfma_f32_16x16x32_bf16 v[108:111], v[146:149], v[194:197], v[108:111]
	v_mfma_f32_16x16x32_bf16 v[104:107], v[154:157], v[194:197], v[104:107]
	v_mfma_f32_16x16x32_bf16 v[100:103], v[146:149], v[206:209], v[100:103]
	v_mfma_f32_16x16x32_bf16 v[96:99], v[154:157], v[206:209], v[96:99]
	v_mfma_f32_16x16x32_bf16 v[124:127], v[150:153], v[182:185], v[124:127]
	v_mfma_f32_16x16x32_bf16 v[120:123], v[158:161], v[182:185], v[120:123]
	v_mfma_f32_16x16x32_bf16 v[116:119], v[150:153], v[190:193], v[116:119]
	v_mfma_f32_16x16x32_bf16 v[112:115], v[158:161], v[190:193], v[112:115]
	v_mfma_f32_16x16x32_bf16 v[108:111], v[150:153], v[202:205], v[108:111]
	v_mfma_f32_16x16x32_bf16 v[104:107], v[158:161], v[202:205], v[104:107]
	v_mfma_f32_16x16x32_bf16 v[100:103], v[150:153], v[210:213], v[100:103]
	v_mfma_f32_16x16x32_bf16 v[96:99], v[158:161], v[210:213], v[96:99]
	v_mfma_f32_16x16x32_bf16 v[92:95], v[162:165], v[178:181], v[92:95]
	v_mfma_f32_16x16x32_bf16 v[88:91], v[170:173], v[178:181], v[88:91]
	v_mfma_f32_16x16x32_bf16 v[84:87], v[162:165], v[186:189], v[84:87]
	v_mfma_f32_16x16x32_bf16 v[80:83], v[170:173], v[186:189], v[80:83]
	v_mfma_f32_16x16x32_bf16 v[76:79], v[162:165], v[194:197], v[76:79]
	v_mfma_f32_16x16x32_bf16 v[72:75], v[170:173], v[194:197], v[72:75]
	v_mfma_f32_16x16x32_bf16 v[68:71], v[162:165], v[206:209], v[68:71]
	v_mfma_f32_16x16x32_bf16 v[64:67], v[170:173], v[206:209], v[64:67]
	v_mfma_f32_16x16x32_bf16 v[92:95], v[166:169], v[182:185], v[92:95]
	v_mfma_f32_16x16x32_bf16 v[88:91], v[174:177], v[182:185], v[88:91]
	v_mfma_f32_16x16x32_bf16 v[84:87], v[166:169], v[190:193], v[84:87]
	v_mfma_f32_16x16x32_bf16 v[80:83], v[174:177], v[190:193], v[80:83]
	v_mfma_f32_16x16x32_bf16 v[76:79], v[166:169], v[202:205], v[76:79]
	v_mfma_f32_16x16x32_bf16 v[72:75], v[174:177], v[202:205], v[72:75]
	v_mfma_f32_16x16x32_bf16 v[68:71], v[166:169], v[210:213], v[68:71]
	v_mfma_f32_16x16x32_bf16 v[64:67], v[174:177], v[210:213], v[64:67]
	s_setprio 0
	s_barrier
	s_add_i32 s35, s53, s15
	v_lshl_add_u64 v[198:199], s[2:3], 0, v[130:131]
	s_mov_b32 m0, s35
	ds_read_b128 v[178:181], v144 offset:16384
	ds_read_b128 v[182:185], v144 offset:17408
	ds_read_b128 v[186:189], v144 offset:18432
	ds_read_b128 v[190:193], v144 offset:19456
	ds_read_b128 v[194:197], v144 offset:20480
	ds_read_b128 v[202:205], v144 offset:21504
	ds_read_b128 v[206:209], v144 offset:22528
	ds_read_b128 v[210:213], v144 offset:23552
	global_load_lds_dwordx4 v[198:199], off
	v_lshl_add_u64 v[214:215], s[2:3], 0, v[134:135]
	s_add_i32 m0, s35, 0x2000
	s_add_i32 s35, s54, s15
	global_load_lds_dwordx4 v[214:215], off
	v_lshl_add_u64 v[216:217], s[60:61], 0, v[130:131]
	s_mov_b32 m0, s35
	v_lshl_add_u64 v[218:219], s[44:45], 0, v[132:133]
	global_load_lds_dwordx4 v[216:217], off
	v_lshl_add_u64 v[216:217], s[60:61], 0, v[134:135]
	s_add_i32 m0, s35, 0x2000
	s_nop 0
	global_load_lds_dwordx4 v[216:217], off
	v_lshl_add_u64 v[216:217], s[44:45], 0, v[128:129]
	s_mov_b32 m0, s20
	s_nop 0
	global_load_lds_dwordx4 v[216:217], off
	s_mov_b32 m0, s21
	s_nop 0
	global_load_lds_dwordx4 v[218:219], off
	s_waitcnt vmcnt(8)
	s_waitcnt lgkmcnt(0)
	s_barrier
; #define PG8_STAGE(bufoff, gbase, voff) do { _Pragma("unroll") for (int _i = 0; _i < 2; ++_i) \
;         __builtin_amdgcn_global_load_lds((const unsigned*)((const char*)(gbase) + (voff)[_i]), (LAS unsigned*)(lds + (bufoff) + ldsw + _i * 8192), 16, 0, 0); } while (0)
; #define PG8_STAGEB(bufoff, gbase, perm) do { _Pragma("unroll") for (int _i = 0; _i < 2; ++_i) \
;         __builtin_amdgcn_global_load_lds((const unsigned*)((const char*)(gbase) + ((BSEL && (perm)) ? voffBp[_i] : voffB[_i])), (LAS unsigned*)(lds + (bufoff) + ldsw + _i * 8192), 16, 0, 0); } while (0)
; #define PG8_LDA(dst, b, h) do { _Pragma("unroll") for (int m = 0; m < 4; ++m) _Pragma("unroll") for (int k = 0; k < 2; ++k) dst[m][k] = *(const LAS bf16x8*)(lds + PG8_SA(b, h) + aoff + m * 2048 + k * 1024); } while (0)
; #define PG8_LDB(dst, b, h) do { _Pragma("unroll") for (int n = 0; n < 2; ++n) _Pragma("unroll") for (int k = 0; k < 2; ++k) dst[n][k] = *(const LAS bf16x8*)(lds + PG8_SB(b, h) + boff + n * 2048 + k * 1024); } while (0)
; #define PG8_MMA(ai, bj, At, Bt) do { __builtin_amdgcn_s_setprio(1); _Pragma("unroll") for (int m = 0; m < 4; ++m) _Pragma("unroll") for (int n = 0; n < 2; ++n) _Pragma("unroll") for (int k = 0; k < 2; ++k) \
;         acc[ai][bj][m][n] = __builtin_amdgcn_mfma_f32_16x16x32_bf16(Bt[n][k], At[m][k], acc[ai][bj][m][n], 0, 0, 0); __builtin_amdgcn_s_setprio(0); } while (0)
; #define PG8_BAR __builtin_amdgcn_s_barrier()
; template <class Epi, bool BSEL = false>
; __device__ __forceinline__ void gemm_phase(LAS unsigned char* lds, const Gemm g, const Order& S, const Epi& E, const int tid) {
;     ...
;             PG8_LDA(At, 0, 1); PG8_STAGEB(PG8_SB(0, 0), b2, p2); PG8_STAGEB(PG8_SB(0, 1), b2 + h2, p2); PG8_STAGE(PG8_SA(0, 0), a2, voffA);
;             PG8_WAIT_V(8); PG8_WAIT_L(0); PG8_BAR; PG8_MMA(1, 0, At, B0); PG8_MMA(1, 1, At, B1); PG8_BAR; PG8_SCHED;
;             PG8_LDB(B0, 1, 0); PG8_LDB(B1, 1, 1); PG8_SCHED; PG8_LDA(At, 1, 0); PG8_STAGE(PG8_SA(0, 1), a2 + hstepA, voffA);
;             PG8_WAIT_V(8); PG8_WAIT_L(0); PG8_BAR; PG8_MMA(0, 0, At, B0); PG8_MMA(0, 1, At, B1); PG8_BAR; PG8_SCHED;
;             PG8_LDA(At, 1, 1); PG8_STAGEB(PG8_SB(1, 0), b3, p2); PG8_STAGEB(PG8_SB(1, 1), b3 + h2, p2); PG8_STAGE(PG8_SA(1, 0), a3, voffA);
;             PG8_WAIT_V(8); PG8_WAIT_L(0); PG8_BAR; PG8_MMA(1, 0, At, B0); PG8_MMA(1, 1, At, B1); PG8_BAR; PG8_SCHED;
	s_setprio 1
	v_mfma_f32_16x16x32_bf16 v[60:63], v[146:149], v[178:181], v[60:63]
	v_mfma_f32_16x16x32_bf16 v[56:59], v[154:157], v[178:181], v[56:59]
	v_mfma_f32_16x16x32_bf16 v[52:55], v[146:149], v[186:189], v[52:55]
	v_mfma_f32_16x16x32_bf16 v[48:51], v[154:157], v[186:189], v[48:51]
	v_mfma_f32_16x16x32_bf16 v[44:47], v[146:149], v[194:197], v[44:47]
	v_mfma_f32_16x16x32_bf16 v[40:43], v[154:157], v[194:197], v[40:43]
	v_mfma_f32_16x16x32_bf16 v[36:39], v[146:149], v[206:209], v[36:39]
	v_mfma_f32_16x16x32_bf16 v[32:35], v[154:157], v[206:209], v[32:35]
	v_mfma_f32_16x16x32_bf16 v[60:63], v[150:153], v[182:185], v[60:63]
	v_mfma_f32_16x16x32_bf16 v[56:59], v[158:161], v[182:185], v[56:59]
	v_mfma_f32_16x16x32_bf16 v[52:55], v[150:153], v[190:193], v[52:55]
	v_mfma_f32_16x16x32_bf16 v[48:51], v[158:161], v[190:193], v[48:51]
	v_mfma_f32_16x16x32_bf16 v[44:47], v[150:153], v[202:205], v[44:47]
	v_mfma_f32_16x16x32_bf16 v[40:43], v[158:161], v[202:205], v[40:43]
	v_mfma_f32_16x16x32_bf16 v[36:39], v[150:153], v[210:213], v[36:39]
	v_mfma_f32_16x16x32_bf16 v[32:35], v[158:161], v[210:213], v[32:35]
	v_mfma_f32_16x16x32_bf16 v[28:31], v[162:165], v[178:181], v[28:31]
	v_mfma_f32_16x16x32_bf16 v[24:27], v[170:173], v[178:181], v[24:27]
	v_mfma_f32_16x16x32_bf16 v[20:23], v[162:165], v[186:189], v[20:23]
	v_mfma_f32_16x16x32_bf16 v[16:19], v[170:173], v[186:189], v[16:19]
	v_mfma_f32_16x16x32_bf16 v[12:15], v[162:165], v[194:197], v[12:15]
	v_mfma_f32_16x16x32_bf16 v[8:11], v[170:173], v[194:197], v[8:11]
	v_mfma_f32_16x16x32_bf16 v[4:7], v[162:165], v[206:209], v[4:7]
	v_mfma_f32_16x16x32_bf16 v[0:3], v[170:173], v[206:209], v[0:3]
	v_mfma_f32_16x16x32_bf16 v[28:31], v[166:169], v[182:185], v[28:31]
	v_mfma_f32_16x16x32_bf16 v[24:27], v[174:177], v[182:185], v[24:27]
	v_mfma_f32_16x16x32_bf16 v[20:23], v[166:169], v[190:193], v[20:23]
	v_mfma_f32_16x16x32_bf16 v[16:19], v[174:177], v[190:193], v[16:19]
	v_mfma_f32_16x16x32_bf16 v[12:15], v[166:169], v[202:205], v[12:15]
	v_mfma_f32_16x16x32_bf16 v[8:11], v[174:177], v[202:205], v[8:11]
	v_mfma_f32_16x16x32_bf16 v[4:7], v[166:169], v[210:213], v[4:7]
	v_mfma_f32_16x16x32_bf16 v[0:3], v[174:177], v[210:213], v[0:3]
	s_setprio 0
	s_barrier
	s_add_i32 s35, 0, 0x18000
	v_add_u32_e32 v145, s35, v139
	s_add_i32 s44, 0, 0x1c000
	ds_read_b128 v[146:149], v145
	ds_read_b128 v[150:153], v145 offset:1024
	ds_read_b128 v[154:157], v145 offset:2048
	ds_read_b128 v[158:161], v145 offset:3072
	v_add_u32_e32 v145, s44, v139
	ds_read_b128 v[162:165], v145
	ds_read_b128 v[166:169], v145 offset:1024
	ds_read_b128 v[170:173], v145 offset:2048
	ds_read_b128 v[174:177], v145 offset:3072
	s_mov_b32 m0, s46
	v_lshl_add_u64 v[220:221], s[42:43], 0, v[128:129]
	ds_read_b128 v[178:181], v144 offset:32768
	ds_read_b128 v[182:185], v144 offset:33792
	ds_read_b128 v[186:189], v144 offset:34816
	ds_read_b128 v[190:193], v144 offset:35840
	ds_read_b128 v[194:197], v144 offset:36864
	ds_read_b128 v[202:205], v144 offset:37888
	ds_read_b128 v[206:209], v144 offset:38912
	ds_read_b128 v[210:213], v144 offset:39936
	global_load_lds_dwordx4 v[220:221], off
	v_lshl_add_u64 v[220:221], s[42:43], 0, v[132:133]
	s_mov_b32 m0, s47
	s_nop 0
	global_load_lds_dwordx4 v[220:221], off
	s_waitcnt vmcnt(8)
	s_waitcnt lgkmcnt(0)
	s_barrier
	s_setprio 1
	v_mfma_f32_16x16x32_bf16 v[124:127], v[146:149], v[178:181], v[124:127]
	v_mfma_f32_16x16x32_bf16 v[120:123], v[154:157], v[178:181], v[120:123]
	v_mfma_f32_16x16x32_bf16 v[116:119], v[146:149], v[186:189], v[116:119]
	v_mfma_f32_16x16x32_bf16 v[112:115], v[154:157], v[186:189], v[112:115]
	v_mfma_f32_16x16x32_bf16 v[108:111], v[146:149], v[194:197], v[108:111]
	v_mfma_f32_16x16x32_bf16 v[104:107], v[154:157], v[194:197], v[104:107]
	v_mfma_f32_16x16x32_bf16 v[100:103], v[146:149], v[206:209], v[100:103]
	v_mfma_f32_16x16x32_bf16 v[96:99], v[154:157], v[206:209], v[96:99]
	v_mfma_f32_16x16x32_bf16 v[124:127], v[150:153], v[182:185], v[124:127]
	v_mfma_f32_16x16x32_bf16 v[120:123], v[158:161], v[182:185], v[120:123]
	v_mfma_f32_16x16x32_bf16 v[116:119], v[150:153], v[190:193], v[116:119]
	v_mfma_f32_16x16x32_bf16 v[112:115], v[158:161], v[190:193], v[112:115]
	v_mfma_f32_16x16x32_bf16 v[108:111], v[150:153], v[202:205], v[108:111]
	v_mfma_f32_16x16x32_bf16 v[104:107], v[158:161], v[202:205], v[104:107]
	v_mfma_f32_16x16x32_bf16 v[100:103], v[150:153], v[210:213], v[100:103]
	v_mfma_f32_16x16x32_bf16 v[96:99], v[158:161], v[210:213], v[96:99]
	v_mfma_f32_16x16x32_bf16 v[92:95], v[162:165], v[178:181], v[92:95]
	v_mfma_f32_16x16x32_bf16 v[88:91], v[170:173], v[178:181], v[88:91]
	v_mfma_f32_16x16x32_bf16 v[84:87], v[162:165], v[186:189], v[84:87]
	v_mfma_f32_16x16x32_bf16 v[80:83], v[170:173], v[186:189], v[80:83]
	v_mfma_f32_16x16x32_bf16 v[76:79], v[162:165], v[194:197], v[76:79]
	v_mfma_f32_16x16x32_bf16 v[72:75], v[170:173], v[194:197], v[72:75]
	v_mfma_f32_16x16x32_bf16 v[68:71], v[162:165], v[206:209], v[68:71]
	v_mfma_f32_16x16x32_bf16 v[64:67], v[170:173], v[206:209], v[64:67]
	v_mfma_f32_16x16x32_bf16 v[92:95], v[166:169], v[182:185], v[92:95]
	v_mfma_f32_16x16x32_bf16 v[88:91], v[174:177], v[182:185], v[88:91]
	v_mfma_f32_16x16x32_bf16 v[84:87], v[166:169], v[190:193], v[84:87]
	v_mfma_f32_16x16x32_bf16 v[80:83], v[174:177], v[190:193], v[80:83]
	v_mfma_f32_16x16x32_bf16 v[76:79], v[166:169], v[202:205], v[76:79]
	v_mfma_f32_16x16x32_bf16 v[72:75], v[174:177], v[202:205], v[72:75]
	v_mfma_f32_16x16x32_bf16 v[68:71], v[166:169], v[210:213], v[68:71]
	v_mfma_f32_16x16x32_bf16 v[64:67], v[174:177], v[210:213], v[64:67]
	s_setprio 0
	s_barrier
; #define PG8_STAGE(bufoff, gbase, voff) do { _Pragma("unroll") for (int _i = 0; _i < 2; ++_i) \
;         __builtin_amdgcn_global_load_lds((const unsigned*)((const char*)(gbase) + (voff)[_i]), (LAS unsigned*)(lds + (bufoff) + ldsw + _i * 8192), 16, 0, 0); } while (0)
; #define PG8_STAGEB(bufoff, gbase, perm) do { _Pragma("unroll") for (int _i = 0; _i < 2; ++_i) \
;         __builtin_amdgcn_global_load_lds((const unsigned*)((const char*)(gbase) + ((BSEL && (perm)) ? voffBp[_i] : voffB[_i])), (LAS unsigned*)(lds + (bufoff) + ldsw + _i * 8192), 16, 0, 0); } while (0)
; #define PG8_WAIT_V(n) asm volatile("s_waitcnt vmcnt(" #n ")" ::: "memory")
; template <class Epi, bool BSEL = false>
; __device__ __forceinline__ void gemm_phase(LAS unsigned char* lds, const Gemm g, const Order& S, const Epi& E, const int tid) {
;     ...
;             PG8_WAIT_V(8); PG8_WAIT_L(0); PG8_BAR; PG8_MMA(0, 0, At, B0); PG8_MMA(0, 1, At, B1); PG8_BAR; PG8_SCHED;
;             PG8_LDA(At, 1, 1); PG8_STAGEB(PG8_SB(1, 0), b3, p2); PG8_STAGEB(PG8_SB(1, 1), b3 + h2, p2); PG8_STAGE(PG8_SA(1, 0), a3, voffA);
;             PG8_WAIT_V(8); PG8_WAIT_L(0); PG8_BAR; PG8_MMA(1, 0, At, B0); PG8_MMA(1, 1, At, B1); PG8_BAR; PG8_SCHED;
;         }
;         if constexpr (ALIGN_EPI) { if (wr == 0) PG8_BAR; }
;     __device__ __forceinline__ void operator()(const f32x4 (&acc)[2][2][4][2], const Unit& u, int wr, int wc, int fr, int fq) const {
;         if (wr != 0) return;
;         const __amdgpu_buffer_rsrc_t rsrc = __builtin_amdgcn_make_buffer_rsrc(YT, 0, 65536 * 128 * 2, 0x00020000);
; #pragma unroll
;         for (int m = 0; m < 4; ++m) { const int k1 = 16 * m + fr;
; #pragma unroll
;             for (int bj = 0; bj < 2; ++bj) { const int col = 4 * u.pn + 2 * bj + (wc >> 1), b = col >> 8, ch = col & 255;
;                 const int n2 = 32 * (wc & 1) + 8 * fq;
;                 const unsigned rowo = (unsigned)((((size_t)(b * 64 + k1) * 256 + ch) * 128 + n2) * 2);
;                 int kk = k1; asm volatile("" : "+v"(kk));
;                 f32x4 pr[2], pi[2];
; #pragma unroll
;                 for (int n = 0; n < 2; ++n) { const f32x4 yr = acc[0][bj][m][n], yi = acc[1][bj][m][n];
; #pragma unroll
;                     for (int i = 0; i < 4; ++i) { const f32x2 cs = TW[(n2 + 4 * n + i) * kk]; pr[n][i] = yr[i] * cs.x + yi[i] * cs.y; pi[n][i] = yi[i] * cs.x - yr[i] * cs.y; } }
	s_add_i32 s35, s35, s15
	v_lshl_add_u64 v[198:199], v[198:199], 0, s[28:29]
	s_mov_b32 m0, s35
	ds_read_b128 v[178:181], v144 offset:49152
	ds_read_b128 v[182:185], v144 offset:50176
	ds_read_b128 v[186:189], v144 offset:51200
	ds_read_b128 v[190:193], v144 offset:52224
	ds_read_b128 v[194:197], v144 offset:53248
	ds_read_b128 v[202:205], v144 offset:54272
	ds_read_b128 v[206:209], v144 offset:55296
	ds_read_b128 v[210:213], v144 offset:56320
	global_load_lds_dwordx4 v[198:199], off
	s_add_i32 m0, s35, 0x2000
	s_add_u32 s2, s2, 0x8080
	v_lshl_add_u64 v[198:199], v[214:215], 0, s[28:29]
	s_addc_u32 s3, s3, 0
	s_add_i32 s35, s44, s15
	global_load_lds_dwordx4 v[198:199], off
	v_lshl_add_u64 v[198:199], s[2:3], 0, v[130:131]
	s_mov_b32 m0, s35
	s_nop 0
	global_load_lds_dwordx4 v[198:199], off
	v_lshl_add_u64 v[198:199], s[2:3], 0, v[134:135]
	s_add_i32 m0, s35, 0x2000
	s_nop 0
	global_load_lds_dwordx4 v[198:199], off
	v_lshl_add_u64 v[198:199], v[216:217], 0, s[28:29]
	s_mov_b32 m0, s49
	s_nop 0
	global_load_lds_dwordx4 v[198:199], off
	v_lshl_add_u64 v[198:199], v[218:219], 0, s[28:29]
	s_mov_b32 m0, s51
	s_nop 0
	global_load_lds_dwordx4 v[198:199], off
	s_waitcnt vmcnt(8)
	s_waitcnt lgkmcnt(0)
	s_barrier
	s_setprio 1
	v_mfma_f32_16x16x32_bf16 v[60:63], v[146:149], v[178:181], v[60:63]
	v_mfma_f32_16x16x32_bf16 v[56:59], v[154:157], v[178:181], v[56:59]
	v_mfma_f32_16x16x32_bf16 v[52:55], v[146:149], v[186:189], v[52:55]
	v_mfma_f32_16x16x32_bf16 v[48:51], v[154:157], v[186:189], v[48:51]
	v_mfma_f32_16x16x32_bf16 v[44:47], v[146:149], v[194:197], v[44:47]
	v_mfma_f32_16x16x32_bf16 v[40:43], v[154:157], v[194:197], v[40:43]
	v_mfma_f32_16x16x32_bf16 v[36:39], v[146:149], v[206:209], v[36:39]
	v_mfma_f32_16x16x32_bf16 v[32:35], v[154:157], v[206:209], v[32:35]
	v_mfma_f32_16x16x32_bf16 v[60:63], v[150:153], v[182:185], v[60:63]
	v_mfma_f32_16x16x32_bf16 v[56:59], v[158:161], v[182:185], v[56:59]
	v_mfma_f32_16x16x32_bf16 v[52:55], v[150:153], v[190:193], v[52:55]
	v_mfma_f32_16x16x32_bf16 v[48:51], v[158:161], v[190:193], v[48:51]
	v_mfma_f32_16x16x32_bf16 v[44:47], v[150:153], v[202:205], v[44:47]
	v_mfma_f32_16x16x32_bf16 v[40:43], v[158:161], v[202:205], v[40:43]
	v_mfma_f32_16x16x32_bf16 v[36:39], v[150:153], v[210:213], v[36:39]
	v_mfma_f32_16x16x32_bf16 v[32:35], v[158:161], v[210:213], v[32:35]
	v_mfma_f32_16x16x32_bf16 v[28:31], v[162:165], v[178:181], v[28:31]
	v_mfma_f32_16x16x32_bf16 v[24:27], v[170:173], v[178:181], v[24:27]
	v_mfma_f32_16x16x32_bf16 v[20:23], v[162:165], v[186:189], v[20:23]
	v_mfma_f32_16x16x32_bf16 v[16:19], v[170:173], v[186:189], v[16:19]
	v_mfma_f32_16x16x32_bf16 v[12:15], v[162:165], v[194:197], v[12:15]
	v_mfma_f32_16x16x32_bf16 v[8:11], v[170:173], v[194:197], v[8:11]
	v_mfma_f32_16x16x32_bf16 v[4:7], v[162:165], v[206:209], v[4:7]
	v_mfma_f32_16x16x32_bf16 v[0:3], v[170:173], v[206:209], v[0:3]
	v_mfma_f32_16x16x32_bf16 v[28:31], v[166:169], v[182:185], v[28:31]
	v_mfma_f32_16x16x32_bf16 v[24:27], v[174:177], v[182:185], v[24:27]
	v_mfma_f32_16x16x32_bf16 v[20:23], v[166:169], v[190:193], v[20:23]
	v_mfma_f32_16x16x32_bf16 v[16:19], v[174:177], v[190:193], v[16:19]
	v_mfma_f32_16x16x32_bf16 v[12:15], v[166:169], v[202:205], v[12:15]
	v_mfma_f32_16x16x32_bf16 v[8:11], v[174:177], v[202:205], v[8:11]
	v_mfma_f32_16x16x32_bf16 v[4:7], v[166:169], v[210:213], v[4:7]
	v_mfma_f32_16x16x32_bf16 v[0:3], v[174:177], v[210:213], v[0:3]
	s_setprio 0
	s_barrier
	s_andn2_b64 vcc, exec, s[30:31]
	s_cbranch_vccnz .LBB0_828
	v_mov_b32_e32 v145, v138
	s_barrier
	v_mov_b32_e32 v162, v124
	v_mul_lo_u32 v146, v145, v140
	v_ashrrev_i32_e32 v147, 31, v146
	v_lshl_add_u64 v[148:149], v[146:147], 3, s[26:27]
	v_add_u32_e32 v146, v146, v145
	v_ashrrev_i32_e32 v147, 31, v146
	v_lshl_add_u64 v[150:151], v[146:147], 3, s[26:27]
	v_add_u32_e32 v146, v146, v145
	v_ashrrev_i32_e32 v147, 31, v146
	v_lshl_add_u64 v[152:153], v[146:147], 3, s[26:27]
	v_add_u32_e32 v146, v146, v145
	v_ashrrev_i32_e32 v147, 31, v146
	v_lshl_add_u64 v[154:155], v[146:147], 3, s[26:27]
	v_add_u32_e32 v146, v146, v145
	global_load_dwordx2 v[148:149], v[148:149], off
	v_ashrrev_i32_e32 v147, 31, v146
	global_load_dwordx2 v[150:151], v[150:151], off
	v_lshl_add_u64 v[156:157], v[146:147], 3, s[26:27]
	v_add_u32_e32 v146, v146, v145
	global_load_dwordx2 v[152:153], v[152:153], off
	v_ashrrev_i32_e32 v147, 31, v146
	global_load_dwordx2 v[154:155], v[154:155], off
	v_lshl_add_u64 v[158:159], v[146:147], 3, s[26:27]
	v_add_u32_e32 v146, v146, v145
	global_load_dwordx2 v[156:157], v[156:157], off
	v_ashrrev_i32_e32 v147, 31, v146
	global_load_dwordx2 v[158:159], v[158:159], off
	v_lshl_add_u64 v[160:161], v[146:147], 3, s[26:27]
	global_load_dwordx2 v[160:161], v[160:161], off
	v_add_u32_e32 v146, v146, v145
	v_ashrrev_i32_e32 v147, 31, v146
	v_lshl_add_u64 v[146:147], v[146:147], 3, s[26:27]
	global_load_dwordx2 v[146:147], v[146:147], off
	v_mov_b32_e32 v163, v60
	v_mov_b32_e32 v164, v60
	v_mov_b32_e32 v165, v124
	v_mov_b32_e32 v166, v125
	v_mov_b32_e32 v167, v61
	v_mov_b32_e32 v168, v61
	v_mov_b32_e32 v169, v125
	v_mov_b32_e32 v170, v126
	v_mov_b32_e32 v171, v62
	v_mov_b32_e32 v172, v62
	v_mov_b32_e32 v173, v126
	v_mov_b32_e32 v174, v127
	v_mov_b32_e32 v175, v63
	v_mov_b32_e32 v176, v63
	v_mov_b32_e32 v177, v127
	v_mov_b32_e32 v178, v120
	v_mov_b32_e32 v179, v56
	v_mov_b32_e32 v180, v56
	v_mov_b32_e32 v181, v120
	v_mov_b32_e32 v182, v121
	v_mov_b32_e32 v183, v57
	v_mov_b32_e32 v184, v57
	v_mov_b32_e32 v185, v121
	v_mov_b32_e32 v186, v122
	v_mov_b32_e32 v187, v58
	s_lshl_b32 s3, s48, 2
	s_and_b32 s2, s48, 0xffc0
	s_and_b32 s3, s3, 0xfc
	v_or_b32_e32 v145, s2, v138
	s_or_b32 s3, s3, s52
	v_lshl_or_b32 v145, v145, 15, v140
	s_lshl_b32 s35, s3, 7
	v_or_b32_e32 v188, s35, v145
	s_or_b32 s3, s35, 0x100
	v_or_b32_e32 v145, s3, v145
	v_lshlrev_b32_e32 v145, 1, v145
	s_waitcnt vmcnt(0)
; __device__ __forceinline__ unsigned cvt_pk_bf16(float lo, float hi) { unsigned r; asm volatile("v_cvt_pk_bf16_f32 %0, %1, %2" : "=v"(r) : "v"(lo), "v"(hi)); return r; }
;     __device__ __forceinline__ void operator()(const f32x4 (&acc)[2][2][4][2], const Unit& u, int wr, int wc, int fr, int fq) const {
;     ...
;         for (int m = 0; m < 4; ++m) { const int k1 = 16 * m + fr;
; #pragma unroll
;             for (int bj = 0; bj < 2; ++bj) { const int col = 4 * u.pn + 2 * bj + (wc >> 1), b = col >> 8, ch = col & 255;
;                 const int n2 = 32 * (wc & 1) + 8 * fq;
;                 const unsigned rowo = (unsigned)((((size_t)(b * 64 + k1) * 256 + ch) * 128 + n2) * 2);
;                 int kk = k1; asm volatile("" : "+v"(kk));
;                 f32x4 pr[2], pi[2];
; #pragma unroll
;                 for (int n = 0; n < 2; ++n) { const f32x4 yr = acc[0][bj][m][n], yi = acc[1][bj][m][n];
; #pragma unroll
;                     for (int i = 0; i < 4; ++i) { const f32x2 cs = TW[(n2 + 4 * n + i) * kk]; pr[n][i] = yr[i] * cs.x + yi[i] * cs.y; pi[n][i] = yi[i] * cs.x - yr[i] * cs.y; } }
;                 u32x4 w; w.x = cvt_pk_bf16(pr[0][0], pr[0][1]); w.y = cvt_pk_bf16(pr[0][2], pr[0][3]); w.z = cvt_pk_bf16(pr[1][0], pr[1][1]); w.w = cvt_pk_bf16(pr[1][2], pr[1][3]);
;                 __builtin_amdgcn_raw_buffer_store_b128(w, rsrc, rowo, 0, 16);
;                 w.x = cvt_pk_bf16(pi[0][0], pi[0][1]); w.y = cvt_pk_bf16(pi[0][2], pi[0][3]); w.z = cvt_pk_bf16(pi[1][0], pi[1][1]); w.w = cvt_pk_bf16(pi[1][2], pi[1][3]);
;                 __builtin_amdgcn_raw_buffer_store_b128(w, rsrc, rowo + 128, 0, 16);
;                 asm volatile("" ::: "memory"); } }
	v_pk_mul_f32 v[162:163], v[162:163], v[148:149]
	v_pk_mul_f32 v[148:149], v[164:165], v[148:149]
	v_add_f32_e32 v162, v162, v163
	v_sub_f32_e32 v163, v148, v149
	v_pk_mul_f32 v[148:149], v[166:167], v[150:151]
	v_pk_mul_f32 v[150:151], v[168:169], v[150:151]
	v_add_f32_e32 v164, v148, v149
	v_pk_mul_f32 v[148:149], v[170:171], v[152:153]
	v_sub_f32_e32 v165, v150, v151
	v_pk_mul_f32 v[150:151], v[172:173], v[152:153]
	v_add_f32_e32 v152, v148, v149
	v_pk_mul_f32 v[148:149], v[174:175], v[154:155]
	v_sub_f32_e32 v153, v150, v151
	v_pk_mul_f32 v[150:151], v[176:177], v[154:155]
	v_add_f32_e32 v154, v148, v149
	v_pk_mul_f32 v[148:149], v[178:179], v[156:157]
	v_sub_f32_e32 v155, v150, v151
	v_pk_mul_f32 v[150:151], v[180:181], v[156:157]
	v_add_f32_e32 v156, v148, v149
	v_pk_mul_f32 v[148:149], v[182:183], v[158:159]
	v_sub_f32_e32 v157, v150, v151
	v_pk_mul_f32 v[150:151], v[184:185], v[158:159]
	v_add_f32_e32 v158, v148, v149
	v_pk_mul_f32 v[148:149], v[186:187], v[160:161]
	v_sub_f32_e32 v150, v150, v151
	v_add_f32_e32 v151, v148, v149
	v_mov_b32_e32 v148, v58
	v_mov_b32_e32 v149, v122
	v_pk_mul_f32 v[148:149], v[148:149], v[160:161]
	v_lshlrev_b32_e32 v166, 1, v188
	v_sub_f32_e32 v159, v148, v149
	v_mov_b32_e32 v148, v123
	v_mov_b32_e32 v149, v59
	v_pk_mul_f32 v[148:149], v[148:149], v[146:147]
	v_mov_b32_e32 v167, v29
	v_add_f32_e32 v160, v148, v149
	v_mov_b32_e32 v148, v59
	v_mov_b32_e32 v149, v123
	v_pk_mul_f32 v[146:147], v[148:149], v[146:147]
	v_mov_b32_e32 v168, v29
	v_sub_f32_e32 v161, v146, v147
	v_cvt_pk_bf16_f32 v146, v162, v164
	v_cvt_pk_bf16_f32 v147, v152, v154
	v_cvt_pk_bf16_f32 v148, v156, v158
	v_cvt_pk_bf16_f32 v149, v151, v160
	buffer_store_dwordx4 v[146:149], v166, s[8:11], 0 offen sc1
	v_mov_b32_e32 v162, v138
	v_mov_b32_e32 v164, v28
	v_cvt_pk_bf16_f32 v146, v163, v165
	v_cvt_pk_bf16_f32 v147, v153, v155
	v_cvt_pk_bf16_f32 v148, v157, v150
	v_cvt_pk_bf16_f32 v149, v159, v161
	buffer_store_dwordx4 v[146:149], v166, s[8:11], 0 offen offset:128 sc1
	v_mov_b32_e32 v163, v28
	v_mov_b32_e32 v165, v92
	v_mul_lo_u32 v146, v162, v140
	v_ashrrev_i32_e32 v147, 31, v146
	v_lshl_add_u64 v[148:149], v[146:147], 3, s[26:27]
	v_add_u32_e32 v146, v146, v162
	v_ashrrev_i32_e32 v147, 31, v146
	v_lshl_add_u64 v[150:151], v[146:147], 3, s[26:27]
	v_add_u32_e32 v146, v146, v162
	v_ashrrev_i32_e32 v147, 31, v146
	global_load_dwordx2 v[148:149], v[148:149], off
	v_lshl_add_u64 v[152:153], v[146:147], 3, s[26:27]
	v_add_u32_e32 v146, v146, v162
	global_load_dwordx2 v[150:151], v[150:151], off
	v_ashrrev_i32_e32 v147, 31, v146
	global_load_dwordx2 v[152:153], v[152:153], off
	v_lshl_add_u64 v[154:155], v[146:147], 3, s[26:27]
	v_add_u32_e32 v146, v146, v162
	global_load_dwordx2 v[154:155], v[154:155], off
	v_ashrrev_i32_e32 v147, 31, v146
	v_lshl_add_u64 v[156:157], v[146:147], 3, s[26:27]
	global_load_dwordx2 v[156:157], v[156:157], off
	v_add_u32_e32 v146, v146, v162
	v_ashrrev_i32_e32 v147, 31, v146
	v_lshl_add_u64 v[158:159], v[146:147], 3, s[26:27]
	global_load_dwordx2 v[158:159], v[158:159], off
	v_add_u32_e32 v146, v146, v162
	v_ashrrev_i32_e32 v147, 31, v146
	v_lshl_add_u64 v[160:161], v[146:147], 3, s[26:27]
	global_load_dwordx2 v[160:161], v[160:161], off
	v_add_u32_e32 v146, v146, v162
	v_ashrrev_i32_e32 v147, 31, v146
	v_lshl_add_u64 v[146:147], v[146:147], 3, s[26:27]
	global_load_dwordx2 v[146:147], v[146:147], off
	v_mov_b32_e32 v162, v92
	v_mov_b32_e32 v166, v93
	v_mov_b32_e32 v169, v93
	v_mov_b32_e32 v170, v94
	v_mov_b32_e32 v171, v30
	v_mov_b32_e32 v172, v30
	v_mov_b32_e32 v173, v94
	v_mov_b32_e32 v174, v95
	v_mov_b32_e32 v175, v31
	v_mov_b32_e32 v176, v31
	v_mov_b32_e32 v177, v95
	s_waitcnt vmcnt(7)
	v_pk_mul_f32 v[162:163], v[162:163], v[148:149]
	v_pk_mul_f32 v[148:149], v[164:165], v[148:149]
	v_add_f32_e32 v162, v162, v163
	v_sub_f32_e32 v163, v148, v149
	s_waitcnt vmcnt(6)
	v_pk_mul_f32 v[148:149], v[166:167], v[150:151]
	v_pk_mul_f32 v[150:151], v[168:169], v[150:151]
	v_add_f32_e32 v164, v148, v149
	s_waitcnt vmcnt(5)
	v_pk_mul_f32 v[148:149], v[170:171], v[152:153]
	v_sub_f32_e32 v165, v150, v151
	v_pk_mul_f32 v[150:151], v[172:173], v[152:153]
	v_add_f32_e32 v152, v148, v149
	s_waitcnt vmcnt(4)
	v_pk_mul_f32 v[148:149], v[174:175], v[154:155]
	v_sub_f32_e32 v153, v150, v151
	v_pk_mul_f32 v[150:151], v[176:177], v[154:155]
	v_add_f32_e32 v154, v148, v149
	v_mov_b32_e32 v148, v88
	v_mov_b32_e32 v149, v24
	s_waitcnt vmcnt(3)
	v_pk_mul_f32 v[148:149], v[148:149], v[156:157]
	v_sub_f32_e32 v150, v150, v151
	v_add_f32_e32 v151, v148, v149
	v_mov_b32_e32 v148, v24
	v_mov_b32_e32 v149, v88
	v_pk_mul_f32 v[148:149], v[148:149], v[156:157]
	v_mov_b32_e32 v166, v117
	v_sub_f32_e32 v155, v148, v149
	v_mov_b32_e32 v148, v89
	v_mov_b32_e32 v149, v25
	s_waitcnt vmcnt(2)
	v_pk_mul_f32 v[148:149], v[148:149], v[158:159]
	v_mov_b32_e32 v167, v53
	v_add_f32_e32 v156, v148, v149
	v_mov_b32_e32 v148, v25
	v_mov_b32_e32 v149, v89
	v_pk_mul_f32 v[148:149], v[148:149], v[158:159]
	s_nop 0
	v_sub_f32_e32 v157, v148, v149
	v_mov_b32_e32 v148, v90
	v_mov_b32_e32 v149, v26
	s_waitcnt vmcnt(1)
	v_pk_mul_f32 v[148:149], v[148:149], v[160:161]
	s_nop 0
	v_add_f32_e32 v158, v148, v149
	v_mov_b32_e32 v148, v26
	v_mov_b32_e32 v149, v90
	v_pk_mul_f32 v[148:149], v[148:149], v[160:161]
	s_nop 0
	v_sub_f32_e32 v159, v148, v149
	v_mov_b32_e32 v148, v91
	v_mov_b32_e32 v149, v27
	s_waitcnt vmcnt(0)
; __device__ __forceinline__ unsigned cvt_pk_bf16(float lo, float hi) { unsigned r; asm volatile("v_cvt_pk_bf16_f32 %0, %1, %2" : "=v"(r) : "v"(lo), "v"(hi)); return r; }
;     __device__ __forceinline__ void operator()(const f32x4 (&acc)[2][2][4][2], const Unit& u, int wr, int wc, int fr, int fq) const {
;     ...
;         for (int m = 0; m < 4; ++m) { const int k1 = 16 * m + fr;
; #pragma unroll
;             for (int bj = 0; bj < 2; ++bj) { const int col = 4 * u.pn + 2 * bj + (wc >> 1), b = col >> 8, ch = col & 255;
;                 const int n2 = 32 * (wc & 1) + 8 * fq;
;                 const unsigned rowo = (unsigned)((((size_t)(b * 64 + k1) * 256 + ch) * 128 + n2) * 2);
;                 int kk = k1; asm volatile("" : "+v"(kk));
;                 f32x4 pr[2], pi[2];
; #pragma unroll
;                 for (int n = 0; n < 2; ++n) { const f32x4 yr = acc[0][bj][m][n], yi = acc[1][bj][m][n];
; #pragma unroll
;                     for (int i = 0; i < 4; ++i) { const f32x2 cs = TW[(n2 + 4 * n + i) * kk]; pr[n][i] = yr[i] * cs.x + yi[i] * cs.y; pi[n][i] = yi[i] * cs.x - yr[i] * cs.y; } }
;                 u32x4 w; w.x = cvt_pk_bf16(pr[0][0], pr[0][1]); w.y = cvt_pk_bf16(pr[0][2], pr[0][3]); w.z = cvt_pk_bf16(pr[1][0], pr[1][1]); w.w = cvt_pk_bf16(pr[1][2], pr[1][3]);
;                 __builtin_amdgcn_raw_buffer_store_b128(w, rsrc, rowo, 0, 16);
;                 w.x = cvt_pk_bf16(pi[0][0], pi[0][1]); w.y = cvt_pk_bf16(pi[0][2], pi[0][3]); w.z = cvt_pk_bf16(pi[1][0], pi[1][1]); w.w = cvt_pk_bf16(pi[1][2], pi[1][3]);
;                 __builtin_amdgcn_raw_buffer_store_b128(w, rsrc, rowo + 128, 0, 16);
;                 asm volatile("" ::: "memory"); } }
	v_pk_mul_f32 v[148:149], v[148:149], v[146:147]
	s_nop 0
	v_add_f32_e32 v160, v148, v149
	v_mov_b32_e32 v148, v27
	v_mov_b32_e32 v149, v91
	v_pk_mul_f32 v[146:147], v[148:149], v[146:147]
	s_nop 0
	v_sub_f32_e32 v161, v146, v147
	v_cvt_pk_bf16_f32 v146, v162, v164
	v_cvt_pk_bf16_f32 v147, v152, v154
	v_cvt_pk_bf16_f32 v148, v151, v156
	v_cvt_pk_bf16_f32 v149, v158, v160
	buffer_store_dwordx4 v[146:149], v145, s[8:11], 0 offen sc1
	v_mov_b32_e32 v162, v116
	v_mov_b32_e32 v164, v52
	v_cvt_pk_bf16_f32 v146, v163, v165
	v_cvt_pk_bf16_f32 v147, v153, v150
	v_cvt_pk_bf16_f32 v148, v155, v157
	v_cvt_pk_bf16_f32 v149, v159, v161
	buffer_store_dwordx4 v[146:149], v145, s[8:11], 0 offen offset:128 sc1
	v_mov_b32_e32 v145, v141
	v_mov_b32_e32 v163, v52
	v_mul_lo_u32 v146, v145, v140
	v_ashrrev_i32_e32 v147, 31, v146
	v_lshl_add_u64 v[148:149], v[146:147], 3, s[26:27]
	v_add_u32_e32 v146, v146, v145
	v_ashrrev_i32_e32 v147, 31, v146
	global_load_dwordx2 v[148:149], v[148:149], off
	v_lshl_add_u64 v[150:151], v[146:147], 3, s[26:27]
	global_load_dwordx2 v[150:151], v[150:151], off
	v_add_u32_e32 v146, v146, v145
	v_ashrrev_i32_e32 v147, 31, v146
	v_lshl_add_u64 v[152:153], v[146:147], 3, s[26:27]
	global_load_dwordx2 v[152:153], v[152:153], off
	v_add_u32_e32 v146, v146, v145
	v_ashrrev_i32_e32 v147, 31, v146
	v_lshl_add_u64 v[154:155], v[146:147], 3, s[26:27]
	global_load_dwordx2 v[154:155], v[154:155], off
	v_add_u32_e32 v146, v146, v145
	v_ashrrev_i32_e32 v147, 31, v146
	v_lshl_add_u64 v[156:157], v[146:147], 3, s[26:27]
	global_load_dwordx2 v[156:157], v[156:157], off
	v_add_u32_e32 v146, v146, v145
	v_ashrrev_i32_e32 v147, 31, v146
	v_lshl_add_u64 v[158:159], v[146:147], 3, s[26:27]
	global_load_dwordx2 v[158:159], v[158:159], off
	v_add_u32_e32 v146, v146, v145
	v_ashrrev_i32_e32 v147, 31, v146
	v_lshl_add_u64 v[160:161], v[146:147], 3, s[26:27]
	global_load_dwordx2 v[160:161], v[160:161], off
	v_add_u32_e32 v146, v146, v145
	v_ashrrev_i32_e32 v147, 31, v146
	v_lshl_add_u64 v[146:147], v[146:147], 3, s[26:27]
	global_load_dwordx2 v[146:147], v[146:147], off
	v_mov_b32_e32 v165, v116
	v_or_b32_e32 v145, s2, v141
	v_lshl_or_b32 v145, v145, 15, v140
	v_or_b32_e32 v168, s35, v145
	v_or_b32_e32 v145, s3, v145
	v_lshlrev_b32_e32 v145, 1, v145
	s_waitcnt vmcnt(7)
	v_pk_mul_f32 v[162:163], v[162:163], v[148:149]
	v_pk_mul_f32 v[148:149], v[164:165], v[148:149]
	v_add_f32_e32 v162, v162, v163
	v_sub_f32_e32 v163, v148, v149
	s_waitcnt vmcnt(6)
	v_pk_mul_f32 v[148:149], v[166:167], v[150:151]
	v_lshlrev_b32_e32 v166, 1, v168
	v_add_f32_e32 v164, v148, v149
	v_mov_b32_e32 v148, v53
	v_mov_b32_e32 v149, v117
	v_pk_mul_f32 v[148:149], v[148:149], v[150:151]
	s_nop 0
	v_sub_f32_e32 v150, v148, v149
	v_mov_b32_e32 v148, v118
	v_mov_b32_e32 v149, v54
	s_waitcnt vmcnt(5)
	v_pk_mul_f32 v[148:149], v[148:149], v[152:153]
	s_nop 0
	v_add_f32_e32 v151, v148, v149
	v_mov_b32_e32 v148, v54
	v_mov_b32_e32 v149, v118
	v_pk_mul_f32 v[148:149], v[148:149], v[152:153]
	s_nop 0
	v_sub_f32_e32 v152, v148, v149
	v_mov_b32_e32 v148, v119
	v_mov_b32_e32 v149, v55
	s_waitcnt vmcnt(4)
	v_pk_mul_f32 v[148:149], v[148:149], v[154:155]
	s_nop 0
	v_add_f32_e32 v153, v148, v149
	v_mov_b32_e32 v148, v55
	v_mov_b32_e32 v149, v119
	v_pk_mul_f32 v[148:149], v[148:149], v[154:155]
	s_nop 0
	v_sub_f32_e32 v154, v148, v149
	v_mov_b32_e32 v148, v112
	v_mov_b32_e32 v149, v48
	s_waitcnt vmcnt(3)
	v_pk_mul_f32 v[148:149], v[148:149], v[156:157]
	s_nop 0
	v_add_f32_e32 v155, v148, v149
	v_mov_b32_e32 v148, v48
	v_mov_b32_e32 v149, v112
	v_pk_mul_f32 v[148:149], v[148:149], v[156:157]
	s_nop 0
	v_sub_f32_e32 v156, v148, v149
	v_mov_b32_e32 v148, v113
	v_mov_b32_e32 v149, v49
	s_waitcnt vmcnt(2)
	v_pk_mul_f32 v[148:149], v[148:149], v[158:159]
	s_nop 0
	v_add_f32_e32 v157, v148, v149
	v_mov_b32_e32 v148, v49
	v_mov_b32_e32 v149, v113
	v_pk_mul_f32 v[148:149], v[148:149], v[158:159]
	s_nop 0
	v_sub_f32_e32 v158, v148, v149
	v_mov_b32_e32 v148, v114
	v_mov_b32_e32 v149, v50
	s_waitcnt vmcnt(1)
	v_pk_mul_f32 v[148:149], v[148:149], v[160:161]
	s_nop 0
	v_add_f32_e32 v159, v148, v149
	v_mov_b32_e32 v148, v50
	v_mov_b32_e32 v149, v114
	v_pk_mul_f32 v[148:149], v[148:149], v[160:161]
	s_nop 0
	v_sub_f32_e32 v160, v148, v149
	v_mov_b32_e32 v148, v115
	v_mov_b32_e32 v149, v51
	s_waitcnt vmcnt(0)
	v_pk_mul_f32 v[148:149], v[148:149], v[146:147]
	s_nop 0
	v_add_f32_e32 v161, v148, v149
	v_mov_b32_e32 v148, v51
	v_mov_b32_e32 v149, v115
	v_pk_mul_f32 v[146:147], v[148:149], v[146:147]
	s_nop 0
	v_sub_f32_e32 v165, v146, v147
	v_cvt_pk_bf16_f32 v146, v162, v164
	v_cvt_pk_bf16_f32 v147, v151, v153
	v_cvt_pk_bf16_f32 v148, v155, v157
	v_cvt_pk_bf16_f32 v149, v159, v161
	buffer_store_dwordx4 v[146:149], v166, s[8:11], 0 offen sc1
	v_mov_b32_e32 v162, v141
	s_nop 0
	v_cvt_pk_bf16_f32 v146, v163, v150
	v_cvt_pk_bf16_f32 v147, v152, v154
	v_cvt_pk_bf16_f32 v148, v156, v158
	v_cvt_pk_bf16_f32 v149, v160, v165
	buffer_store_dwordx4 v[146:149], v166, s[8:11], 0 offen offset:128 sc1
	v_mov_b32_e32 v163, v20
	s_nop 0
	v_mul_lo_u32 v146, v162, v140
	v_ashrrev_i32_e32 v147, 31, v146
	v_lshl_add_u64 v[148:149], v[146:147], 3, s[26:27]
	global_load_dwordx2 v[148:149], v[148:149], off
	v_add_u32_e32 v146, v146, v162
	v_ashrrev_i32_e32 v147, 31, v146
	v_lshl_add_u64 v[150:151], v[146:147], 3, s[26:27]
	global_load_dwordx2 v[150:151], v[150:151], off
	v_add_u32_e32 v146, v146, v162
	v_ashrrev_i32_e32 v147, 31, v146
	v_lshl_add_u64 v[152:153], v[146:147], 3, s[26:27]
	global_load_dwordx2 v[152:153], v[152:153], off
	v_add_u32_e32 v146, v146, v162
	v_ashrrev_i32_e32 v147, 31, v146
	v_lshl_add_u64 v[154:155], v[146:147], 3, s[26:27]
	global_load_dwordx2 v[154:155], v[154:155], off
	v_add_u32_e32 v146, v146, v162
	v_ashrrev_i32_e32 v147, 31, v146
	v_lshl_add_u64 v[156:157], v[146:147], 3, s[26:27]
	global_load_dwordx2 v[156:157], v[156:157], off
	v_add_u32_e32 v146, v146, v162
	v_ashrrev_i32_e32 v147, 31, v146
	v_lshl_add_u64 v[158:159], v[146:147], 3, s[26:27]
	global_load_dwordx2 v[158:159], v[158:159], off
	v_add_u32_e32 v146, v146, v162
	v_ashrrev_i32_e32 v147, 31, v146
	v_lshl_add_u64 v[160:161], v[146:147], 3, s[26:27]
	global_load_dwordx2 v[160:161], v[160:161], off
	v_add_u32_e32 v146, v146, v162
	v_ashrrev_i32_e32 v147, 31, v146
	v_lshl_add_u64 v[146:147], v[146:147], 3, s[26:27]
	global_load_dwordx2 v[146:147], v[146:147], off
	v_mov_b32_e32 v162, v84
	s_waitcnt vmcnt(7)
; __device__ __forceinline__ unsigned cvt_pk_bf16(float lo, float hi) { unsigned r; asm volatile("v_cvt_pk_bf16_f32 %0, %1, %2" : "=v"(r) : "v"(lo), "v"(hi)); return r; }
;     __device__ __forceinline__ void operator()(const f32x4 (&acc)[2][2][4][2], const Unit& u, int wr, int wc, int fr, int fq) const {
;     ...
;         for (int m = 0; m < 4; ++m) { const int k1 = 16 * m + fr;
; #pragma unroll
;             for (int bj = 0; bj < 2; ++bj) { const int col = 4 * u.pn + 2 * bj + (wc >> 1), b = col >> 8, ch = col & 255;
;                 const int n2 = 32 * (wc & 1) + 8 * fq;
;                 const unsigned rowo = (unsigned)((((size_t)(b * 64 + k1) * 256 + ch) * 128 + n2) * 2);
;                 int kk = k1; asm volatile("" : "+v"(kk));
;                 f32x4 pr[2], pi[2];
; #pragma unroll
;                 for (int n = 0; n < 2; ++n) { const f32x4 yr = acc[0][bj][m][n], yi = acc[1][bj][m][n];
; #pragma unroll
;                     for (int i = 0; i < 4; ++i) { const f32x2 cs = TW[(n2 + 4 * n + i) * kk]; pr[n][i] = yr[i] * cs.x + yi[i] * cs.y; pi[n][i] = yi[i] * cs.x - yr[i] * cs.y; } }
;                 u32x4 w; w.x = cvt_pk_bf16(pr[0][0], pr[0][1]); w.y = cvt_pk_bf16(pr[0][2], pr[0][3]); w.z = cvt_pk_bf16(pr[1][0], pr[1][1]); w.w = cvt_pk_bf16(pr[1][2], pr[1][3]);
;                 __builtin_amdgcn_raw_buffer_store_b128(w, rsrc, rowo, 0, 16);
;                 w.x = cvt_pk_bf16(pi[0][0], pi[0][1]); w.y = cvt_pk_bf16(pi[0][2], pi[0][3]); w.z = cvt_pk_bf16(pi[1][0], pi[1][1]); w.w = cvt_pk_bf16(pi[1][2], pi[1][3]);
;                 __builtin_amdgcn_raw_buffer_store_b128(w, rsrc, rowo + 128, 0, 16);
;                 asm volatile("" ::: "memory"); } }
	v_pk_mul_f32 v[162:163], v[162:163], v[148:149]
	s_nop 0
	v_add_f32_e32 v164, v162, v163
	v_mov_b32_e32 v162, v20
	v_mov_b32_e32 v163, v84
	v_pk_mul_f32 v[148:149], v[162:163], v[148:149]
	s_nop 0
	v_sub_f32_e32 v162, v148, v149
	v_mov_b32_e32 v148, v85
	v_mov_b32_e32 v149, v21
	s_waitcnt vmcnt(6)
	v_pk_mul_f32 v[148:149], v[148:149], v[150:151]
	s_nop 0
	v_add_f32_e32 v163, v148, v149
	v_mov_b32_e32 v148, v21
	v_mov_b32_e32 v149, v85
	v_pk_mul_f32 v[148:149], v[148:149], v[150:151]
	s_nop 0
	v_sub_f32_e32 v150, v148, v149
	v_mov_b32_e32 v148, v86
	v_mov_b32_e32 v149, v22
	s_waitcnt vmcnt(5)
	v_pk_mul_f32 v[148:149], v[148:149], v[152:153]
	s_nop 0
	v_add_f32_e32 v151, v148, v149
	v_mov_b32_e32 v148, v22
	v_mov_b32_e32 v149, v86
	v_pk_mul_f32 v[148:149], v[148:149], v[152:153]
	s_nop 0
	v_sub_f32_e32 v152, v148, v149
	v_mov_b32_e32 v148, v87
	v_mov_b32_e32 v149, v23
	s_waitcnt vmcnt(4)
	v_pk_mul_f32 v[148:149], v[148:149], v[154:155]
	s_nop 0
	v_add_f32_e32 v153, v148, v149
	v_mov_b32_e32 v148, v23
	v_mov_b32_e32 v149, v87
	v_pk_mul_f32 v[148:149], v[148:149], v[154:155]
	s_nop 0
	v_sub_f32_e32 v154, v148, v149
	v_mov_b32_e32 v148, v80
	v_mov_b32_e32 v149, v16
	s_waitcnt vmcnt(3)
	v_pk_mul_f32 v[148:149], v[148:149], v[156:157]
	s_nop 0
	v_add_f32_e32 v155, v148, v149
	v_mov_b32_e32 v148, v16
	v_mov_b32_e32 v149, v80
	v_pk_mul_f32 v[148:149], v[148:149], v[156:157]
	s_nop 0
	v_sub_f32_e32 v156, v148, v149
	v_mov_b32_e32 v148, v81
	v_mov_b32_e32 v149, v17
	s_waitcnt vmcnt(2)
	v_pk_mul_f32 v[148:149], v[148:149], v[158:159]
	s_nop 0
	v_add_f32_e32 v157, v148, v149
	v_mov_b32_e32 v148, v17
	v_mov_b32_e32 v149, v81
	v_pk_mul_f32 v[148:149], v[148:149], v[158:159]
	s_nop 0
	v_sub_f32_e32 v158, v148, v149
	v_mov_b32_e32 v148, v82
	v_mov_b32_e32 v149, v18
	s_waitcnt vmcnt(1)
	v_pk_mul_f32 v[148:149], v[148:149], v[160:161]
	s_nop 0
	v_add_f32_e32 v159, v148, v149
	v_mov_b32_e32 v148, v18
	v_mov_b32_e32 v149, v82
	v_pk_mul_f32 v[148:149], v[148:149], v[160:161]
	s_nop 0
	v_sub_f32_e32 v160, v148, v149
	v_mov_b32_e32 v148, v83
	v_mov_b32_e32 v149, v19
	s_waitcnt vmcnt(0)
	v_pk_mul_f32 v[148:149], v[148:149], v[146:147]
	s_nop 0
	v_add_f32_e32 v161, v148, v149
	v_mov_b32_e32 v148, v19
	v_mov_b32_e32 v149, v83
	v_pk_mul_f32 v[146:147], v[148:149], v[146:147]
	s_nop 0
	v_sub_f32_e32 v165, v146, v147
	v_cvt_pk_bf16_f32 v146, v164, v163
	v_cvt_pk_bf16_f32 v147, v151, v153
	v_cvt_pk_bf16_f32 v148, v155, v157
	v_cvt_pk_bf16_f32 v149, v159, v161
	buffer_store_dwordx4 v[146:149], v145, s[8:11], 0 offen sc1
	v_mov_b32_e32 v163, v44
	s_nop 0
	v_cvt_pk_bf16_f32 v146, v162, v150
	v_cvt_pk_bf16_f32 v147, v152, v154
	v_cvt_pk_bf16_f32 v148, v156, v158
	v_cvt_pk_bf16_f32 v149, v160, v165
	buffer_store_dwordx4 v[146:149], v145, s[8:11], 0 offen offset:128 sc1
	v_mov_b32_e32 v145, v142
	v_mov_b32_e32 v162, v108
	v_mul_lo_u32 v146, v145, v140
	v_ashrrev_i32_e32 v147, 31, v146
	v_lshl_add_u64 v[148:149], v[146:147], 3, s[26:27]
	global_load_dwordx2 v[148:149], v[148:149], off
	v_add_u32_e32 v146, v146, v145
	v_ashrrev_i32_e32 v147, 31, v146
	v_lshl_add_u64 v[150:151], v[146:147], 3, s[26:27]
	global_load_dwordx2 v[150:151], v[150:151], off
	v_add_u32_e32 v146, v146, v145
	v_ashrrev_i32_e32 v147, 31, v146
	v_lshl_add_u64 v[152:153], v[146:147], 3, s[26:27]
	global_load_dwordx2 v[152:153], v[152:153], off
	v_add_u32_e32 v146, v146, v145
	v_ashrrev_i32_e32 v147, 31, v146
	v_lshl_add_u64 v[154:155], v[146:147], 3, s[26:27]
	global_load_dwordx2 v[154:155], v[154:155], off
	v_add_u32_e32 v146, v146, v145
	v_ashrrev_i32_e32 v147, 31, v146
	v_lshl_add_u64 v[156:157], v[146:147], 3, s[26:27]
	global_load_dwordx2 v[156:157], v[156:157], off
	v_add_u32_e32 v146, v146, v145
	v_ashrrev_i32_e32 v147, 31, v146
	v_lshl_add_u64 v[158:159], v[146:147], 3, s[26:27]
	global_load_dwordx2 v[158:159], v[158:159], off
	v_add_u32_e32 v146, v146, v145
	v_ashrrev_i32_e32 v147, 31, v146
	v_lshl_add_u64 v[160:161], v[146:147], 3, s[26:27]
	global_load_dwordx2 v[160:161], v[160:161], off
	v_add_u32_e32 v146, v146, v145
	v_ashrrev_i32_e32 v147, 31, v146
	v_lshl_add_u64 v[146:147], v[146:147], 3, s[26:27]
	global_load_dwordx2 v[146:147], v[146:147], off
	v_or_b32_e32 v145, s2, v142
	v_lshl_or_b32 v145, v145, 15, v140
	v_or_b32_e32 v164, s35, v145
	v_lshlrev_b32_e32 v164, 1, v164
	v_or_b32_e32 v145, s3, v145
	v_lshlrev_b32_e32 v145, 1, v145
	s_waitcnt vmcnt(7)
	v_pk_mul_f32 v[162:163], v[162:163], v[148:149]
	s_nop 0
	v_add_f32_e32 v165, v162, v163
	v_mov_b32_e32 v162, v44
	v_mov_b32_e32 v163, v108
	v_pk_mul_f32 v[148:149], v[162:163], v[148:149]
	s_nop 0
	v_sub_f32_e32 v162, v148, v149
	v_mov_b32_e32 v148, v109
	v_mov_b32_e32 v149, v45
	s_waitcnt vmcnt(6)
	v_pk_mul_f32 v[148:149], v[148:149], v[150:151]
	s_nop 0
	v_add_f32_e32 v163, v148, v149
	v_mov_b32_e32 v148, v45
	v_mov_b32_e32 v149, v109
	v_pk_mul_f32 v[148:149], v[148:149], v[150:151]
	s_nop 0
	v_sub_f32_e32 v150, v148, v149
	v_mov_b32_e32 v148, v110
	v_mov_b32_e32 v149, v46
	s_waitcnt vmcnt(5)
	v_pk_mul_f32 v[148:149], v[148:149], v[152:153]
	s_nop 0
	v_add_f32_e32 v151, v148, v149
	v_mov_b32_e32 v148, v46
	v_mov_b32_e32 v149, v110
	v_pk_mul_f32 v[148:149], v[148:149], v[152:153]
	s_nop 0
	v_sub_f32_e32 v152, v148, v149
	v_mov_b32_e32 v148, v111
	v_mov_b32_e32 v149, v47
	s_waitcnt vmcnt(4)
	v_pk_mul_f32 v[148:149], v[148:149], v[154:155]
	s_nop 0
	v_add_f32_e32 v153, v148, v149
	v_mov_b32_e32 v148, v47
	v_mov_b32_e32 v149, v111
	v_pk_mul_f32 v[148:149], v[148:149], v[154:155]
	s_nop 0
	v_sub_f32_e32 v154, v148, v149
	v_mov_b32_e32 v148, v104
	v_mov_b32_e32 v149, v40
	s_waitcnt vmcnt(3)
; __device__ __forceinline__ unsigned cvt_pk_bf16(float lo, float hi) { unsigned r; asm volatile("v_cvt_pk_bf16_f32 %0, %1, %2" : "=v"(r) : "v"(lo), "v"(hi)); return r; }
;     __device__ __forceinline__ void operator()(const f32x4 (&acc)[2][2][4][2], const Unit& u, int wr, int wc, int fr, int fq) const {
;     ...
;         for (int m = 0; m < 4; ++m) { const int k1 = 16 * m + fr;
; #pragma unroll
;             for (int bj = 0; bj < 2; ++bj) { const int col = 4 * u.pn + 2 * bj + (wc >> 1), b = col >> 8, ch = col & 255;
;                 const int n2 = 32 * (wc & 1) + 8 * fq;
;                 const unsigned rowo = (unsigned)((((size_t)(b * 64 + k1) * 256 + ch) * 128 + n2) * 2);
;                 int kk = k1; asm volatile("" : "+v"(kk));
;                 f32x4 pr[2], pi[2];
; #pragma unroll
;                 for (int n = 0; n < 2; ++n) { const f32x4 yr = acc[0][bj][m][n], yi = acc[1][bj][m][n];
; #pragma unroll
;                     for (int i = 0; i < 4; ++i) { const f32x2 cs = TW[(n2 + 4 * n + i) * kk]; pr[n][i] = yr[i] * cs.x + yi[i] * cs.y; pi[n][i] = yi[i] * cs.x - yr[i] * cs.y; } }
;                 u32x4 w; w.x = cvt_pk_bf16(pr[0][0], pr[0][1]); w.y = cvt_pk_bf16(pr[0][2], pr[0][3]); w.z = cvt_pk_bf16(pr[1][0], pr[1][1]); w.w = cvt_pk_bf16(pr[1][2], pr[1][3]);
;                 __builtin_amdgcn_raw_buffer_store_b128(w, rsrc, rowo, 0, 16);
;                 w.x = cvt_pk_bf16(pi[0][0], pi[0][1]); w.y = cvt_pk_bf16(pi[0][2], pi[0][3]); w.z = cvt_pk_bf16(pi[1][0], pi[1][1]); w.w = cvt_pk_bf16(pi[1][2], pi[1][3]);
;                 __builtin_amdgcn_raw_buffer_store_b128(w, rsrc, rowo + 128, 0, 16);
;                 asm volatile("" ::: "memory"); } }
	v_pk_mul_f32 v[148:149], v[148:149], v[156:157]
	s_nop 0
	v_add_f32_e32 v155, v148, v149
	v_mov_b32_e32 v148, v40
	v_mov_b32_e32 v149, v104
	v_pk_mul_f32 v[148:149], v[148:149], v[156:157]
	s_nop 0
	v_sub_f32_e32 v156, v148, v149
	v_mov_b32_e32 v148, v105
	v_mov_b32_e32 v149, v41
	s_waitcnt vmcnt(2)
	v_pk_mul_f32 v[148:149], v[148:149], v[158:159]
	s_nop 0
	v_add_f32_e32 v157, v148, v149
	v_mov_b32_e32 v148, v41
	v_mov_b32_e32 v149, v105
	v_pk_mul_f32 v[148:149], v[148:149], v[158:159]
	s_nop 0
	v_sub_f32_e32 v158, v148, v149
	v_mov_b32_e32 v148, v106
	v_mov_b32_e32 v149, v42
	s_waitcnt vmcnt(1)
	v_pk_mul_f32 v[148:149], v[148:149], v[160:161]
	s_nop 0
	v_add_f32_e32 v159, v148, v149
	v_mov_b32_e32 v148, v42
	v_mov_b32_e32 v149, v106
	v_pk_mul_f32 v[148:149], v[148:149], v[160:161]
	s_nop 0
	v_sub_f32_e32 v160, v148, v149
	v_mov_b32_e32 v148, v107
	v_mov_b32_e32 v149, v43
	s_waitcnt vmcnt(0)
	v_pk_mul_f32 v[148:149], v[148:149], v[146:147]
	s_nop 0
	v_add_f32_e32 v161, v148, v149
	v_mov_b32_e32 v148, v43
	v_mov_b32_e32 v149, v107
	v_pk_mul_f32 v[146:147], v[148:149], v[146:147]
	s_nop 0
	v_sub_f32_e32 v166, v146, v147
	v_cvt_pk_bf16_f32 v146, v165, v163
	v_cvt_pk_bf16_f32 v147, v151, v153
	v_cvt_pk_bf16_f32 v148, v155, v157
	v_cvt_pk_bf16_f32 v149, v159, v161
	buffer_store_dwordx4 v[146:149], v164, s[8:11], 0 offen sc1
	v_mov_b32_e32 v163, v12
	s_nop 0
	v_cvt_pk_bf16_f32 v146, v162, v150
	v_cvt_pk_bf16_f32 v147, v152, v154
	v_cvt_pk_bf16_f32 v148, v156, v158
	v_cvt_pk_bf16_f32 v149, v160, v166
	buffer_store_dwordx4 v[146:149], v164, s[8:11], 0 offen offset:128 sc1
	v_mov_b32_e32 v162, v142
	s_nop 0
	v_mul_lo_u32 v146, v162, v140
	v_ashrrev_i32_e32 v147, 31, v146
	v_lshl_add_u64 v[148:149], v[146:147], 3, s[26:27]
	global_load_dwordx2 v[148:149], v[148:149], off
	v_add_u32_e32 v146, v146, v162
	v_ashrrev_i32_e32 v147, 31, v146
	v_lshl_add_u64 v[150:151], v[146:147], 3, s[26:27]
	global_load_dwordx2 v[150:151], v[150:151], off
	v_add_u32_e32 v146, v146, v162
	v_ashrrev_i32_e32 v147, 31, v146
	v_lshl_add_u64 v[152:153], v[146:147], 3, s[26:27]
	global_load_dwordx2 v[152:153], v[152:153], off
	v_add_u32_e32 v146, v146, v162
	v_ashrrev_i32_e32 v147, 31, v146
	v_lshl_add_u64 v[154:155], v[146:147], 3, s[26:27]
	global_load_dwordx2 v[154:155], v[154:155], off
	v_add_u32_e32 v146, v146, v162
	v_ashrrev_i32_e32 v147, 31, v146
	v_lshl_add_u64 v[156:157], v[146:147], 3, s[26:27]
	global_load_dwordx2 v[156:157], v[156:157], off
	v_add_u32_e32 v146, v146, v162
	v_ashrrev_i32_e32 v147, 31, v146
	v_lshl_add_u64 v[158:159], v[146:147], 3, s[26:27]
	global_load_dwordx2 v[158:159], v[158:159], off
	v_add_u32_e32 v146, v146, v162
	v_ashrrev_i32_e32 v147, 31, v146
	v_lshl_add_u64 v[160:161], v[146:147], 3, s[26:27]
	global_load_dwordx2 v[160:161], v[160:161], off
	v_add_u32_e32 v146, v146, v162
	v_ashrrev_i32_e32 v147, 31, v146
	v_lshl_add_u64 v[146:147], v[146:147], 3, s[26:27]
	global_load_dwordx2 v[146:147], v[146:147], off
	v_mov_b32_e32 v162, v76
	s_waitcnt vmcnt(7)
	v_pk_mul_f32 v[162:163], v[162:163], v[148:149]
	s_nop 0
	v_add_f32_e32 v164, v162, v163
	v_mov_b32_e32 v162, v12
	v_mov_b32_e32 v163, v76
	v_pk_mul_f32 v[148:149], v[162:163], v[148:149]
	s_nop 0
	v_sub_f32_e32 v162, v148, v149
	v_mov_b32_e32 v148, v77
	v_mov_b32_e32 v149, v13
	s_waitcnt vmcnt(6)
	v_pk_mul_f32 v[148:149], v[148:149], v[150:151]
	s_nop 0
	v_add_f32_e32 v163, v148, v149
	v_mov_b32_e32 v148, v13
	v_mov_b32_e32 v149, v77
	v_pk_mul_f32 v[148:149], v[148:149], v[150:151]
	s_nop 0
	v_sub_f32_e32 v150, v148, v149
	v_mov_b32_e32 v148, v78
	v_mov_b32_e32 v149, v14
	s_waitcnt vmcnt(5)
	v_pk_mul_f32 v[148:149], v[148:149], v[152:153]
	s_nop 0
	v_add_f32_e32 v151, v148, v149
	v_mov_b32_e32 v148, v14
	v_mov_b32_e32 v149, v78
	v_pk_mul_f32 v[148:149], v[148:149], v[152:153]
	s_nop 0
	v_sub_f32_e32 v152, v148, v149
	v_mov_b32_e32 v148, v79
	v_mov_b32_e32 v149, v15
	s_waitcnt vmcnt(4)
	v_pk_mul_f32 v[148:149], v[148:149], v[154:155]
	s_nop 0
	v_add_f32_e32 v153, v148, v149
	v_mov_b32_e32 v148, v15
	v_mov_b32_e32 v149, v79
	v_pk_mul_f32 v[148:149], v[148:149], v[154:155]
	s_nop 0
	v_sub_f32_e32 v154, v148, v149
	v_mov_b32_e32 v148, v72
	v_mov_b32_e32 v149, v8
	s_waitcnt vmcnt(3)
	v_pk_mul_f32 v[148:149], v[148:149], v[156:157]
	s_nop 0
	v_add_f32_e32 v155, v148, v149
	v_mov_b32_e32 v148, v8
	v_mov_b32_e32 v149, v72
	v_pk_mul_f32 v[148:149], v[148:149], v[156:157]
	s_nop 0
	v_sub_f32_e32 v156, v148, v149
	v_mov_b32_e32 v148, v73
	v_mov_b32_e32 v149, v9
	s_waitcnt vmcnt(2)
	v_pk_mul_f32 v[148:149], v[148:149], v[158:159]
	s_nop 0
	v_add_f32_e32 v157, v148, v149
	v_mov_b32_e32 v148, v9
	v_mov_b32_e32 v149, v73
	v_pk_mul_f32 v[148:149], v[148:149], v[158:159]
	s_nop 0
	v_sub_f32_e32 v158, v148, v149
	v_mov_b32_e32 v148, v74
	v_mov_b32_e32 v149, v10
	s_waitcnt vmcnt(1)
	v_pk_mul_f32 v[148:149], v[148:149], v[160:161]
	s_nop 0
	v_add_f32_e32 v159, v148, v149
	v_mov_b32_e32 v148, v10
	v_mov_b32_e32 v149, v74
	v_pk_mul_f32 v[148:149], v[148:149], v[160:161]
	s_nop 0
	v_sub_f32_e32 v160, v148, v149
	v_mov_b32_e32 v148, v75
	v_mov_b32_e32 v149, v11
	s_waitcnt vmcnt(0)
; __device__ __forceinline__ unsigned cvt_pk_bf16(float lo, float hi) { unsigned r; asm volatile("v_cvt_pk_bf16_f32 %0, %1, %2" : "=v"(r) : "v"(lo), "v"(hi)); return r; }
;     __device__ __forceinline__ void operator()(const f32x4 (&acc)[2][2][4][2], const Unit& u, int wr, int wc, int fr, int fq) const {
;     ...
;         for (int m = 0; m < 4; ++m) { const int k1 = 16 * m + fr;
; #pragma unroll
;             for (int bj = 0; bj < 2; ++bj) { const int col = 4 * u.pn + 2 * bj + (wc >> 1), b = col >> 8, ch = col & 255;
;                 const int n2 = 32 * (wc & 1) + 8 * fq;
;                 const unsigned rowo = (unsigned)((((size_t)(b * 64 + k1) * 256 + ch) * 128 + n2) * 2);
;                 int kk = k1; asm volatile("" : "+v"(kk));
;                 f32x4 pr[2], pi[2];
; #pragma unroll
;                 for (int n = 0; n < 2; ++n) { const f32x4 yr = acc[0][bj][m][n], yi = acc[1][bj][m][n];
; #pragma unroll
;                     for (int i = 0; i < 4; ++i) { const f32x2 cs = TW[(n2 + 4 * n + i) * kk]; pr[n][i] = yr[i] * cs.x + yi[i] * cs.y; pi[n][i] = yi[i] * cs.x - yr[i] * cs.y; } }
;                 u32x4 w; w.x = cvt_pk_bf16(pr[0][0], pr[0][1]); w.y = cvt_pk_bf16(pr[0][2], pr[0][3]); w.z = cvt_pk_bf16(pr[1][0], pr[1][1]); w.w = cvt_pk_bf16(pr[1][2], pr[1][3]);
;                 __builtin_amdgcn_raw_buffer_store_b128(w, rsrc, rowo, 0, 16);
;                 w.x = cvt_pk_bf16(pi[0][0], pi[0][1]); w.y = cvt_pk_bf16(pi[0][2], pi[0][3]); w.z = cvt_pk_bf16(pi[1][0], pi[1][1]); w.w = cvt_pk_bf16(pi[1][2], pi[1][3]);
;                 __builtin_amdgcn_raw_buffer_store_b128(w, rsrc, rowo + 128, 0, 16);
;                 asm volatile("" ::: "memory"); } }
	v_pk_mul_f32 v[148:149], v[148:149], v[146:147]
	s_nop 0
	v_add_f32_e32 v161, v148, v149
	v_mov_b32_e32 v148, v11
	v_mov_b32_e32 v149, v75
	v_pk_mul_f32 v[146:147], v[148:149], v[146:147]
	s_nop 0
	v_sub_f32_e32 v165, v146, v147
	v_cvt_pk_bf16_f32 v146, v164, v163
	v_cvt_pk_bf16_f32 v147, v151, v153
	v_cvt_pk_bf16_f32 v148, v155, v157
	v_cvt_pk_bf16_f32 v149, v159, v161
	buffer_store_dwordx4 v[146:149], v145, s[8:11], 0 offen sc1
	v_mov_b32_e32 v163, v36
	s_nop 0
	v_cvt_pk_bf16_f32 v146, v162, v150
	v_cvt_pk_bf16_f32 v147, v152, v154
	v_cvt_pk_bf16_f32 v148, v156, v158
	v_cvt_pk_bf16_f32 v149, v160, v165
	buffer_store_dwordx4 v[146:149], v145, s[8:11], 0 offen offset:128 sc1
	v_mov_b32_e32 v145, v143
	v_mov_b32_e32 v162, v100
	v_mul_lo_u32 v146, v145, v140
	v_ashrrev_i32_e32 v147, 31, v146
	v_lshl_add_u64 v[148:149], v[146:147], 3, s[26:27]
	global_load_dwordx2 v[148:149], v[148:149], off
	v_add_u32_e32 v146, v146, v145
	v_ashrrev_i32_e32 v147, 31, v146
	v_lshl_add_u64 v[150:151], v[146:147], 3, s[26:27]
	global_load_dwordx2 v[150:151], v[150:151], off
	v_add_u32_e32 v146, v146, v145
	v_ashrrev_i32_e32 v147, 31, v146
	v_lshl_add_u64 v[152:153], v[146:147], 3, s[26:27]
	global_load_dwordx2 v[152:153], v[152:153], off
	v_add_u32_e32 v146, v146, v145
	v_ashrrev_i32_e32 v147, 31, v146
	v_lshl_add_u64 v[154:155], v[146:147], 3, s[26:27]
	global_load_dwordx2 v[154:155], v[154:155], off
	v_add_u32_e32 v146, v146, v145
	v_ashrrev_i32_e32 v147, 31, v146
	v_lshl_add_u64 v[156:157], v[146:147], 3, s[26:27]
	global_load_dwordx2 v[156:157], v[156:157], off
	v_add_u32_e32 v146, v146, v145
	v_ashrrev_i32_e32 v147, 31, v146
	v_lshl_add_u64 v[158:159], v[146:147], 3, s[26:27]
	global_load_dwordx2 v[158:159], v[158:159], off
	v_add_u32_e32 v146, v146, v145
	v_ashrrev_i32_e32 v147, 31, v146
	v_lshl_add_u64 v[160:161], v[146:147], 3, s[26:27]
	global_load_dwordx2 v[160:161], v[160:161], off
	v_add_u32_e32 v146, v146, v145
	v_ashrrev_i32_e32 v147, 31, v146
	v_lshl_add_u64 v[146:147], v[146:147], 3, s[26:27]
	global_load_dwordx2 v[146:147], v[146:147], off
	v_or_b32_e32 v145, s2, v143
	v_lshl_or_b32 v145, v145, 15, v140
	v_or_b32_e32 v164, s35, v145
	v_lshlrev_b32_e32 v164, 1, v164
	v_or_b32_e32 v145, s3, v145
	v_lshlrev_b32_e32 v145, 1, v145
	s_waitcnt vmcnt(7)
	v_pk_mul_f32 v[162:163], v[162:163], v[148:149]
	s_nop 0
	v_add_f32_e32 v165, v162, v163
	v_mov_b32_e32 v162, v36
	v_mov_b32_e32 v163, v100
	v_pk_mul_f32 v[148:149], v[162:163], v[148:149]
	s_nop 0
	v_sub_f32_e32 v162, v148, v149
	v_mov_b32_e32 v148, v101
	v_mov_b32_e32 v149, v37
	s_waitcnt vmcnt(6)
	v_pk_mul_f32 v[148:149], v[148:149], v[150:151]
	s_nop 0
	v_add_f32_e32 v163, v148, v149
	v_mov_b32_e32 v148, v37
	v_mov_b32_e32 v149, v101
	v_pk_mul_f32 v[148:149], v[148:149], v[150:151]
	s_nop 0
	v_sub_f32_e32 v150, v148, v149
	v_mov_b32_e32 v148, v102
	v_mov_b32_e32 v149, v38
	s_waitcnt vmcnt(5)
	v_pk_mul_f32 v[148:149], v[148:149], v[152:153]
	s_nop 0
	v_add_f32_e32 v151, v148, v149
	v_mov_b32_e32 v148, v38
	v_mov_b32_e32 v149, v102
	v_pk_mul_f32 v[148:149], v[148:149], v[152:153]
	s_nop 0
	v_sub_f32_e32 v152, v148, v149
	v_mov_b32_e32 v148, v103
	v_mov_b32_e32 v149, v39
	s_waitcnt vmcnt(4)
	v_pk_mul_f32 v[148:149], v[148:149], v[154:155]
	s_nop 0
	v_add_f32_e32 v153, v148, v149
	v_mov_b32_e32 v148, v39
	v_mov_b32_e32 v149, v103
	v_pk_mul_f32 v[148:149], v[148:149], v[154:155]
	s_nop 0
	v_sub_f32_e32 v154, v148, v149
	v_mov_b32_e32 v148, v96
	v_mov_b32_e32 v149, v32
	s_waitcnt vmcnt(3)
	v_pk_mul_f32 v[148:149], v[148:149], v[156:157]
	s_nop 0
	v_add_f32_e32 v155, v148, v149
	v_mov_b32_e32 v148, v32
	v_mov_b32_e32 v149, v96
	v_pk_mul_f32 v[148:149], v[148:149], v[156:157]
	s_nop 0
	v_sub_f32_e32 v156, v148, v149
	v_mov_b32_e32 v148, v97
	v_mov_b32_e32 v149, v33
	s_waitcnt vmcnt(2)
	v_pk_mul_f32 v[148:149], v[148:149], v[158:159]
	s_nop 0
	v_add_f32_e32 v157, v148, v149
	v_mov_b32_e32 v148, v33
	v_mov_b32_e32 v149, v97
	v_pk_mul_f32 v[148:149], v[148:149], v[158:159]
	s_nop 0
	v_sub_f32_e32 v158, v148, v149
	v_mov_b32_e32 v148, v98
	v_mov_b32_e32 v149, v34
	s_waitcnt vmcnt(1)
	v_pk_mul_f32 v[148:149], v[148:149], v[160:161]
	s_nop 0
	v_add_f32_e32 v159, v148, v149
	v_mov_b32_e32 v148, v34
	v_mov_b32_e32 v149, v98
	v_pk_mul_f32 v[148:149], v[148:149], v[160:161]
	s_nop 0
	v_sub_f32_e32 v160, v148, v149
	v_mov_b32_e32 v148, v99
	v_mov_b32_e32 v149, v35
	s_waitcnt vmcnt(0)
; __device__ __forceinline__ unsigned cvt_pk_bf16(float lo, float hi) { unsigned r; asm volatile("v_cvt_pk_bf16_f32 %0, %1, %2" : "=v"(r) : "v"(lo), "v"(hi)); return r; }
; template <class Epi, bool BSEL = false>
; __device__ __forceinline__ void gemm_phase(LAS unsigned char* lds, const Gemm g, const Order& S, const Epi& E, const int tid) {
;     ...
;         if (!has_next) break;
;     __device__ __forceinline__ void operator()(const f32x4 (&acc)[2][2][4][2], const Unit& u, int wr, int wc, int fr, int fq) const {
;     ...
;         for (int m = 0; m < 4; ++m) { const int k1 = 16 * m + fr;
; #pragma unroll
;             for (int bj = 0; bj < 2; ++bj) { const int col = 4 * u.pn + 2 * bj + (wc >> 1), b = col >> 8, ch = col & 255;
;                 const int n2 = 32 * (wc & 1) + 8 * fq;
;                 const unsigned rowo = (unsigned)((((size_t)(b * 64 + k1) * 256 + ch) * 128 + n2) * 2);
;                 int kk = k1; asm volatile("" : "+v"(kk));
;                 f32x4 pr[2], pi[2];
; #pragma unroll
;                 for (int n = 0; n < 2; ++n) { const f32x4 yr = acc[0][bj][m][n], yi = acc[1][bj][m][n];
; #pragma unroll
;                     for (int i = 0; i < 4; ++i) { const f32x2 cs = TW[(n2 + 4 * n + i) * kk]; pr[n][i] = yr[i] * cs.x + yi[i] * cs.y; pi[n][i] = yi[i] * cs.x - yr[i] * cs.y; } }
;                 u32x4 w; w.x = cvt_pk_bf16(pr[0][0], pr[0][1]); w.y = cvt_pk_bf16(pr[0][2], pr[0][3]); w.z = cvt_pk_bf16(pr[1][0], pr[1][1]); w.w = cvt_pk_bf16(pr[1][2], pr[1][3]);
;                 __builtin_amdgcn_raw_buffer_store_b128(w, rsrc, rowo, 0, 16);
;                 w.x = cvt_pk_bf16(pi[0][0], pi[0][1]); w.y = cvt_pk_bf16(pi[0][2], pi[0][3]); w.z = cvt_pk_bf16(pi[1][0], pi[1][1]); w.w = cvt_pk_bf16(pi[1][2], pi[1][3]);
;                 __builtin_amdgcn_raw_buffer_store_b128(w, rsrc, rowo + 128, 0, 16);
;                 asm volatile("" ::: "memory"); } }
	v_pk_mul_f32 v[148:149], v[148:149], v[146:147]
	s_nop 0
	v_add_f32_e32 v161, v148, v149
	v_mov_b32_e32 v148, v35
	v_mov_b32_e32 v149, v99
	v_pk_mul_f32 v[146:147], v[148:149], v[146:147]
	s_nop 0
	v_sub_f32_e32 v166, v146, v147
	v_cvt_pk_bf16_f32 v146, v165, v163
	v_cvt_pk_bf16_f32 v147, v151, v153
	v_cvt_pk_bf16_f32 v148, v155, v157
	v_cvt_pk_bf16_f32 v149, v159, v161
	buffer_store_dwordx4 v[146:149], v164, s[8:11], 0 offen sc1
	v_mov_b32_e32 v163, v4
	s_nop 0
	v_cvt_pk_bf16_f32 v146, v162, v150
	v_cvt_pk_bf16_f32 v147, v152, v154
	v_cvt_pk_bf16_f32 v148, v156, v158
	v_cvt_pk_bf16_f32 v149, v160, v166
	buffer_store_dwordx4 v[146:149], v164, s[8:11], 0 offen offset:128 sc1
	v_mov_b32_e32 v162, v143
	s_nop 0
	v_mul_lo_u32 v146, v162, v140
	v_ashrrev_i32_e32 v147, 31, v146
	v_lshl_add_u64 v[148:149], v[146:147], 3, s[26:27]
	global_load_dwordx2 v[148:149], v[148:149], off
	v_add_u32_e32 v146, v146, v162
	v_ashrrev_i32_e32 v147, 31, v146
	v_lshl_add_u64 v[150:151], v[146:147], 3, s[26:27]
	global_load_dwordx2 v[150:151], v[150:151], off
	v_add_u32_e32 v146, v146, v162
	v_ashrrev_i32_e32 v147, 31, v146
	v_lshl_add_u64 v[152:153], v[146:147], 3, s[26:27]
	global_load_dwordx2 v[152:153], v[152:153], off
	v_add_u32_e32 v146, v146, v162
	v_ashrrev_i32_e32 v147, 31, v146
	v_lshl_add_u64 v[154:155], v[146:147], 3, s[26:27]
	global_load_dwordx2 v[154:155], v[154:155], off
	v_add_u32_e32 v146, v146, v162
	v_ashrrev_i32_e32 v147, 31, v146
	v_lshl_add_u64 v[156:157], v[146:147], 3, s[26:27]
	global_load_dwordx2 v[156:157], v[156:157], off
	v_add_u32_e32 v146, v146, v162
	v_ashrrev_i32_e32 v147, 31, v146
	v_lshl_add_u64 v[158:159], v[146:147], 3, s[26:27]
	global_load_dwordx2 v[158:159], v[158:159], off
	v_add_u32_e32 v146, v146, v162
	v_ashrrev_i32_e32 v147, 31, v146
	v_lshl_add_u64 v[160:161], v[146:147], 3, s[26:27]
	global_load_dwordx2 v[160:161], v[160:161], off
	v_add_u32_e32 v146, v146, v162
	v_ashrrev_i32_e32 v147, 31, v146
	v_lshl_add_u64 v[146:147], v[146:147], 3, s[26:27]
	global_load_dwordx2 v[146:147], v[146:147], off
	v_mov_b32_e32 v162, v68
	s_waitcnt vmcnt(7)
	v_pk_mul_f32 v[162:163], v[162:163], v[148:149]
	s_nop 0
	v_add_f32_e32 v164, v162, v163
	v_mov_b32_e32 v162, v4
	v_mov_b32_e32 v163, v68
	v_pk_mul_f32 v[148:149], v[162:163], v[148:149]
	s_nop 0
	v_sub_f32_e32 v162, v148, v149
	v_mov_b32_e32 v148, v69
	v_mov_b32_e32 v149, v5
	s_waitcnt vmcnt(6)
	v_pk_mul_f32 v[148:149], v[148:149], v[150:151]
	s_nop 0
	v_add_f32_e32 v163, v148, v149
	v_mov_b32_e32 v148, v5
	v_mov_b32_e32 v149, v69
	v_pk_mul_f32 v[148:149], v[148:149], v[150:151]
	s_nop 0
	v_sub_f32_e32 v150, v148, v149
	v_mov_b32_e32 v148, v70
	v_mov_b32_e32 v149, v6
	s_waitcnt vmcnt(5)
	v_pk_mul_f32 v[148:149], v[148:149], v[152:153]
	s_nop 0
	v_add_f32_e32 v151, v148, v149
	v_mov_b32_e32 v148, v6
	v_mov_b32_e32 v149, v70
	v_pk_mul_f32 v[148:149], v[148:149], v[152:153]
	s_nop 0
	v_sub_f32_e32 v152, v148, v149
	v_mov_b32_e32 v148, v71
	v_mov_b32_e32 v149, v7
	s_waitcnt vmcnt(4)
	v_pk_mul_f32 v[148:149], v[148:149], v[154:155]
	s_nop 0
	v_add_f32_e32 v153, v148, v149
	v_mov_b32_e32 v148, v7
	v_mov_b32_e32 v149, v71
	v_pk_mul_f32 v[148:149], v[148:149], v[154:155]
	s_nop 0
	v_sub_f32_e32 v154, v148, v149
	v_mov_b32_e32 v148, v64
	v_mov_b32_e32 v149, v0
	s_waitcnt vmcnt(3)
	v_pk_mul_f32 v[148:149], v[148:149], v[156:157]
	s_nop 0
	v_add_f32_e32 v155, v148, v149
	v_mov_b32_e32 v148, v0
	v_mov_b32_e32 v149, v64
	v_pk_mul_f32 v[148:149], v[148:149], v[156:157]
	s_nop 0
	v_sub_f32_e32 v156, v148, v149
	v_mov_b32_e32 v148, v65
	v_mov_b32_e32 v149, v1
	s_waitcnt vmcnt(2)
	v_pk_mul_f32 v[148:149], v[148:149], v[158:159]
	s_nop 0
	v_add_f32_e32 v157, v148, v149
	v_mov_b32_e32 v148, v1
	v_mov_b32_e32 v149, v65
	v_pk_mul_f32 v[148:149], v[148:149], v[158:159]
	s_nop 0
	v_sub_f32_e32 v158, v148, v149
	v_mov_b32_e32 v148, v66
	v_mov_b32_e32 v149, v2
	s_waitcnt vmcnt(1)
	v_pk_mul_f32 v[148:149], v[148:149], v[160:161]
	s_nop 0
	v_add_f32_e32 v159, v148, v149
	v_mov_b32_e32 v148, v2
	v_mov_b32_e32 v149, v66
	v_pk_mul_f32 v[148:149], v[148:149], v[160:161]
	s_nop 0
	v_sub_f32_e32 v160, v148, v149
	v_mov_b32_e32 v148, v67
	v_mov_b32_e32 v149, v3
	s_waitcnt vmcnt(0)
	v_pk_mul_f32 v[148:149], v[148:149], v[146:147]
	s_nop 0
	v_add_f32_e32 v161, v148, v149
	v_mov_b32_e32 v148, v3
	v_mov_b32_e32 v149, v67
	v_pk_mul_f32 v[146:147], v[148:149], v[146:147]
	s_nop 0
	v_sub_f32_e32 v165, v146, v147
	v_cvt_pk_bf16_f32 v146, v164, v163
	v_cvt_pk_bf16_f32 v147, v151, v153
	v_cvt_pk_bf16_f32 v148, v155, v157
	v_cvt_pk_bf16_f32 v149, v159, v161
	buffer_store_dwordx4 v[146:149], v145, s[8:11], 0 offen sc1
	s_nop 1
	v_cvt_pk_bf16_f32 v146, v162, v150
	v_cvt_pk_bf16_f32 v147, v152, v154
	v_cvt_pk_bf16_f32 v148, v156, v158
	v_cvt_pk_bf16_f32 v149, v160, v165
	buffer_store_dwordx4 v[146:149], v145, s[8:11], 0 offen offset:128 sc1
	s_andn2_b64 vcc, exec, s[40:41]
	s_cbranch_vccnz .LBB0_820
	s_branch .LBB0_829

; #define PG8_STAGE(bufoff, gbase, voff) do { _Pragma("unroll") for (int _i = 0; _i < 2; ++_i) \
;         __builtin_amdgcn_global_load_lds((const unsigned*)((const char*)(gbase) + (voff)[_i]), (LAS unsigned*)(lds + (bufoff) + ldsw + _i * 8192), 16, 0, 0); } while (0)
; #define PG8_LDA(dst, b, h) do { _Pragma("unroll") for (int m = 0; m < 4; ++m) _Pragma("unroll") for (int k = 0; k < 2; ++k) dst[m][k] = *(const LAS bf16x8*)(lds + PG8_SA(b, h) + aoff + m * 2048 + k * 1024); } while (0)
; template <class Epi, bool BSEL = false>
; __device__ __forceinline__ void gemm_phase(LAS unsigned char* lds, const Gemm g, const Order& S, const Epi& E, const int tid) {
;     ...
;         const bool has_next = S.next(ui + 1, nxt);
;         const char* nA = has_next ? nxt.a : cA; const char* nB = has_next ? nxt.b : cB;
;         const bool nP = has_next ? (BSEL && nxt.kind == 3) : cP; const size_t nhB = nP ? hstepBp : hstepBn;
;         for (int t = 0; t < nt; t += 2) {
;             const bool last = (t == nt - 2);
;             const char* a1 = cA + (size_t)(t + 1) * kstep;
;             const char* a2 = last ? nA : cA + (size_t)(t + 2) * kstep; const char* b2 = last ? nB : cB + (size_t)(t + 2) * kstep;
;             const char* a3 = a2 + kstep; const char* b3 = b2 + kstep;
;             const bool p2 = last ? nP : cP; const size_t h2 = last ? nhB : chB;
;             PG8_LDB(B0, 0, 0); PG8_LDB(B1, 0, 1); PG8_SCHED; PG8_LDA(At, 0, 0); PG8_STAGE(PG8_SA(1, 1), a1 + hstepA, voffA);
;             PG8_WAIT_V(8); PG8_WAIT_L(0); PG8_BAR; PG8_MMA(0, 0, At, B0); PG8_MMA(0, 1, At, B1); PG8_BAR; PG8_SCHED;
;             PG8_LDA(At, 0, 1); PG8_STAGEB(PG8_SB(0, 0), b2, p2); PG8_STAGEB(PG8_SB(0, 1), b2 + h2, p2); PG8_STAGE(PG8_SA(0, 0), a2, voffA);
;             PG8_WAIT_V(8); PG8_WAIT_L(0); PG8_BAR; PG8_MMA(1, 0, At, B0); PG8_MMA(1, 1, At, B1); PG8_BAR; PG8_SCHED;
;             PG8_LDB(B0, 1, 0); PG8_LDB(B1, 1, 1); PG8_SCHED; PG8_LDA(At, 1, 0); PG8_STAGE(PG8_SA(0, 1), a2 + hstepA, voffA);
;             PG8_WAIT_V(8); PG8_WAIT_L(0); PG8_BAR; PG8_MMA(0, 0, At, B0); PG8_MMA(0, 1, At, B1); PG8_BAR; PG8_SCHED;
;             PG8_LDA(At, 1, 1); PG8_STAGEB(PG8_SB(1, 0), b3, p2); PG8_STAGEB(PG8_SB(1, 1), b3 + h2, p2); PG8_STAGE(PG8_SA(1, 0), a3, voffA);
;             PG8_WAIT_V(8); PG8_WAIT_L(0); PG8_BAR; PG8_MMA(1, 0, At, B0); PG8_MMA(1, 1, At, B1); PG8_BAR; PG8_SCHED;
.LBB0_998:
	s_xor_b64 s[2:3], s[34:35], -1
	v_add_u32_e32 v79, s44, v77
	s_and_b64 s[36:37], s[34:35], exec
	ds_read_b128 v[80:83], v79
	ds_read_b128 v[84:87], v79 offset:1024
	ds_read_b128 v[88:91], v79 offset:2048
	ds_read_b128 v[92:95], v79 offset:3072
	v_add_u32_e32 v79, s45, v77
	s_cselect_b32 s41, s1, s1
	s_cselect_b32 s40, s0, s0
	s_add_u32 s48, s0, 0x8080
	ds_read_b128 v[96:99], v79
	ds_read_b128 v[100:103], v79 offset:1024
	ds_read_b128 v[104:107], v79 offset:2048
	ds_read_b128 v[108:111], v79 offset:3072
	s_addc_u32 s49, s1, 0
	s_add_u32 s38, s40, 0x8000
	s_addc_u32 s39, s41, 0
	s_and_b64 s[36:37], s[34:35], exec
	s_cselect_b32 s36, s30, s4
	s_cselect_b32 s37, s31, s5
	s_add_u32 s52, s36, 0x8000
	s_addc_u32 s53, s37, 0
	v_lshl_add_u64 v[144:145], s[48:49], 0, v[64:65]
	s_add_i32 m0, s13, 0xc000
	ds_read_b128 v[112:115], v78
	ds_read_b128 v[116:119], v78 offset:1024
	ds_read_b128 v[120:123], v78 offset:2048
	ds_read_b128 v[124:127], v78 offset:3072
	ds_read_b128 v[128:131], v78 offset:4096
	ds_read_b128 v[132:135], v78 offset:5120
	ds_read_b128 v[136:139], v78 offset:6144
	ds_read_b128 v[140:143], v78 offset:7168
	global_load_lds_dwordx4 v[144:145], off
	v_lshl_add_u64 v[144:145], s[48:49], 0, v[68:69]
	s_add_i32 m0, s13, 0xe000
	s_nop 0
	global_load_lds_dwordx4 v[144:145], off
	s_waitcnt vmcnt(8)
	s_waitcnt lgkmcnt(0)
	s_barrier
	s_setprio 1
	v_mfma_f32_16x16x32_bf16 v[60:63], v[80:83], v[112:115], v[60:63]
	v_mfma_f32_16x16x32_bf16 v[56:59], v[88:91], v[112:115], v[56:59]
	v_mfma_f32_16x16x32_bf16 v[52:55], v[80:83], v[120:123], v[52:55]
	v_mfma_f32_16x16x32_bf16 v[48:51], v[88:91], v[120:123], v[48:51]
	v_mfma_f32_16x16x32_bf16 v[44:47], v[80:83], v[128:131], v[44:47]
	v_mfma_f32_16x16x32_bf16 v[40:43], v[88:91], v[128:131], v[40:43]
	v_mfma_f32_16x16x32_bf16 v[36:39], v[80:83], v[136:139], v[36:39]
	v_mfma_f32_16x16x32_bf16 v[32:35], v[88:91], v[136:139], v[32:35]
	v_mfma_f32_16x16x32_bf16 v[60:63], v[84:87], v[116:119], v[60:63]
	v_mfma_f32_16x16x32_bf16 v[56:59], v[92:95], v[116:119], v[56:59]
	v_mfma_f32_16x16x32_bf16 v[52:55], v[84:87], v[124:127], v[52:55]
	v_mfma_f32_16x16x32_bf16 v[48:51], v[92:95], v[124:127], v[48:51]
	v_mfma_f32_16x16x32_bf16 v[44:47], v[84:87], v[132:135], v[44:47]
	v_mfma_f32_16x16x32_bf16 v[40:43], v[92:95], v[132:135], v[40:43]
	v_mfma_f32_16x16x32_bf16 v[36:39], v[84:87], v[140:143], v[36:39]
	v_mfma_f32_16x16x32_bf16 v[32:35], v[92:95], v[140:143], v[32:35]
	v_mfma_f32_16x16x32_bf16 v[28:31], v[96:99], v[112:115], v[28:31]
	v_mfma_f32_16x16x32_bf16 v[24:27], v[104:107], v[112:115], v[24:27]
	v_mfma_f32_16x16x32_bf16 v[20:23], v[96:99], v[120:123], v[20:23]
	v_mfma_f32_16x16x32_bf16 v[16:19], v[104:107], v[120:123], v[16:19]
	v_mfma_f32_16x16x32_bf16 v[12:15], v[96:99], v[128:131], v[12:15]
	v_mfma_f32_16x16x32_bf16 v[8:11], v[104:107], v[128:131], v[8:11]
	v_mfma_f32_16x16x32_bf16 v[4:7], v[96:99], v[136:139], v[4:7]
	v_mfma_f32_16x16x32_bf16 v[0:3], v[104:107], v[136:139], v[0:3]
	v_mfma_f32_16x16x32_bf16 v[28:31], v[100:103], v[116:119], v[28:31]
	v_mfma_f32_16x16x32_bf16 v[24:27], v[108:111], v[116:119], v[24:27]
	v_mfma_f32_16x16x32_bf16 v[20:23], v[100:103], v[124:127], v[20:23]
	v_mfma_f32_16x16x32_bf16 v[16:19], v[108:111], v[124:127], v[16:19]
	v_mfma_f32_16x16x32_bf16 v[12:15], v[100:103], v[132:135], v[12:15]
	v_mfma_f32_16x16x32_bf16 v[8:11], v[108:111], v[132:135], v[8:11]
	v_mfma_f32_16x16x32_bf16 v[4:7], v[100:103], v[140:143], v[4:7]
	v_mfma_f32_16x16x32_bf16 v[0:3], v[108:111], v[140:143], v[0:3]
	s_setprio 0
	s_barrier
	s_add_i32 s29, s44, s12
	v_lshl_add_u64 v[144:145], s[36:37], 0, v[66:67]
	s_mov_b32 m0, s29
	v_lshl_add_u64 v[146:147], s[36:37], 0, v[70:71]
	global_load_lds_dwordx4 v[144:145], off
	s_add_i32 m0, s29, 0x2000
	s_add_i32 s29, s45, s12
	global_load_lds_dwordx4 v[146:147], off
	v_lshl_add_u64 v[80:81], s[52:53], 0, v[66:67]
	s_mov_b32 m0, s29
	v_lshl_add_u64 v[148:149], s[40:41], 0, v[64:65]
	global_load_lds_dwordx4 v[80:81], off
	v_lshl_add_u64 v[80:81], s[52:53], 0, v[70:71]
	s_add_i32 m0, s29, 0x2000
	v_lshl_add_u64 v[150:151], s[40:41], 0, v[68:69]
	global_load_lds_dwordx4 v[80:81], off
	s_mov_b32 m0, s13
	s_nop 0
	global_load_lds_dwordx4 v[148:149], off
	s_mov_b32 m0, s14
	s_nop 0
	global_load_lds_dwordx4 v[150:151], off
	s_waitcnt vmcnt(8)
	s_waitcnt lgkmcnt(0)
	s_barrier
	s_setprio 1
	s_setprio 0
	s_setprio 1
	s_setprio 0
	s_barrier
	s_add_i32 s29, 0, 0x18000
	v_add_u32_e32 v79, s29, v77
	s_add_i32 s40, 0, 0x1c000
	ds_read_b128 v[80:83], v79
	ds_read_b128 v[84:87], v79 offset:1024
	ds_read_b128 v[88:91], v79 offset:2048
	ds_read_b128 v[92:95], v79 offset:3072
	v_add_u32_e32 v79, s40, v77
	ds_read_b128 v[96:99], v79
	ds_read_b128 v[100:103], v79 offset:1024
	ds_read_b128 v[104:107], v79 offset:2048
	ds_read_b128 v[108:111], v79 offset:3072
	s_mov_b32 m0, s15
	v_lshl_add_u64 v[152:153], s[38:39], 0, v[64:65]
	ds_read_b128 v[112:115], v78 offset:32768
	ds_read_b128 v[116:119], v78 offset:33792
	ds_read_b128 v[120:123], v78 offset:34816
	ds_read_b128 v[124:127], v78 offset:35840
	ds_read_b128 v[128:131], v78 offset:36864
	ds_read_b128 v[132:135], v78 offset:37888
	ds_read_b128 v[136:139], v78 offset:38912
	ds_read_b128 v[140:143], v78 offset:39936
	global_load_lds_dwordx4 v[152:153], off
	v_lshl_add_u64 v[152:153], s[38:39], 0, v[68:69]
	s_mov_b32 m0, s20
	s_nop 0
	global_load_lds_dwordx4 v[152:153], off
	s_waitcnt vmcnt(8)
	s_waitcnt lgkmcnt(0)
	s_barrier
; __device__ __forceinline__ unsigned cvt_pk_bf16(float lo, float hi) { unsigned r; asm volatile("v_cvt_pk_bf16_f32 %0, %1, %2" : "=v"(r) : "v"(lo), "v"(hi)); return r; }
; #define PG8_STAGE(bufoff, gbase, voff) do { _Pragma("unroll") for (int _i = 0; _i < 2; ++_i) \
;         __builtin_amdgcn_global_load_lds((const unsigned*)((const char*)(gbase) + (voff)[_i]), (LAS unsigned*)(lds + (bufoff) + ldsw + _i * 8192), 16, 0, 0); } while (0)
; #define PG8_STAGEB(bufoff, gbase, perm) do { _Pragma("unroll") for (int _i = 0; _i < 2; ++_i) \
;         __builtin_amdgcn_global_load_lds((const unsigned*)((const char*)(gbase) + ((BSEL && (perm)) ? voffBp[_i] : voffB[_i])), (LAS unsigned*)(lds + (bufoff) + ldsw + _i * 8192), 16, 0, 0); } while (0)
; #define PG8_LDA(dst, b, h) do { _Pragma("unroll") for (int m = 0; m < 4; ++m) _Pragma("unroll") for (int k = 0; k < 2; ++k) dst[m][k] = *(const LAS bf16x8*)(lds + PG8_SA(b, h) + aoff + m * 2048 + k * 1024); } while (0)
; #define PG8_WAIT_V(n) asm volatile("s_waitcnt vmcnt(" #n ")" ::: "memory")
; template <class Epi, bool BSEL = false>
; __device__ __forceinline__ void gemm_phase(LAS unsigned char* lds, const Gemm g, const Order& S, const Epi& E, const int tid) {
;     ...
;             PG8_WAIT_V(8); PG8_WAIT_L(0); PG8_BAR; PG8_MMA(0, 0, At, B0); PG8_MMA(0, 1, At, B1); PG8_BAR; PG8_SCHED;
;             PG8_LDA(At, 1, 1); PG8_STAGEB(PG8_SB(1, 0), b3, p2); PG8_STAGEB(PG8_SB(1, 1), b3 + h2, p2); PG8_STAGE(PG8_SA(1, 0), a3, voffA);
;             PG8_WAIT_V(8); PG8_WAIT_L(0); PG8_BAR; PG8_MMA(1, 0, At, B0); PG8_MMA(1, 1, At, B1); PG8_BAR; PG8_SCHED;
;         }
;         if constexpr (ALIGN_EPI) { if (wr == 0) PG8_BAR; }
;     __device__ __forceinline__ void operator()(const f32x4 (&acc)[2][2][4][2], const Unit& u, int wr, int wc, int fr, int fq) const {
;     ...
;         const float sc = 1.0f / 512.0f; const int b = u.pn >> 6, k1 = u.pn & 63;
; #pragma unroll
;         for (int m = 0; m < 4; ++m) { const int k2 = 16 * m + fr; bf16_t* rowp = AO + (size_t)(b * SEQ + 64 * k2 + k1) * DM + DQK + wc * 32 + 8 * fq;
; #pragma unroll
;             for (int bj = 0; bj < 2; ++bj) { const f32x4 v0 = acc[0][bj][m][0] * sc, v1 = acc[0][bj][m][1] * sc;
;                 u32x4 w; w.x = cvt_pk_bf16(v0[0], v0[1]); w.y = cvt_pk_bf16(v0[2], v0[3]); w.z = cvt_pk_bf16(v1[0], v1[1]); w.w = cvt_pk_bf16(v1[2], v1[3]);
;                 *(u32x4*)(rowp + bj * HALF) = w; } }
	s_setprio 1
	v_mfma_f32_16x16x32_bf16 v[60:63], v[80:83], v[112:115], v[60:63]
	v_mfma_f32_16x16x32_bf16 v[56:59], v[88:91], v[112:115], v[56:59]
	v_mfma_f32_16x16x32_bf16 v[52:55], v[80:83], v[120:123], v[52:55]
	v_mfma_f32_16x16x32_bf16 v[48:51], v[88:91], v[120:123], v[48:51]
	v_mfma_f32_16x16x32_bf16 v[44:47], v[80:83], v[128:131], v[44:47]
	v_mfma_f32_16x16x32_bf16 v[40:43], v[88:91], v[128:131], v[40:43]
	v_mfma_f32_16x16x32_bf16 v[36:39], v[80:83], v[136:139], v[36:39]
	v_mfma_f32_16x16x32_bf16 v[32:35], v[88:91], v[136:139], v[32:35]
	v_mfma_f32_16x16x32_bf16 v[60:63], v[84:87], v[116:119], v[60:63]
	v_mfma_f32_16x16x32_bf16 v[56:59], v[92:95], v[116:119], v[56:59]
	v_mfma_f32_16x16x32_bf16 v[52:55], v[84:87], v[124:127], v[52:55]
	v_mfma_f32_16x16x32_bf16 v[48:51], v[92:95], v[124:127], v[48:51]
	v_mfma_f32_16x16x32_bf16 v[44:47], v[84:87], v[132:135], v[44:47]
	v_mfma_f32_16x16x32_bf16 v[40:43], v[92:95], v[132:135], v[40:43]
	v_mfma_f32_16x16x32_bf16 v[36:39], v[84:87], v[140:143], v[36:39]
	v_mfma_f32_16x16x32_bf16 v[32:35], v[92:95], v[140:143], v[32:35]
	v_mfma_f32_16x16x32_bf16 v[28:31], v[96:99], v[112:115], v[28:31]
	v_mfma_f32_16x16x32_bf16 v[24:27], v[104:107], v[112:115], v[24:27]
	v_mfma_f32_16x16x32_bf16 v[20:23], v[96:99], v[120:123], v[20:23]
	v_mfma_f32_16x16x32_bf16 v[16:19], v[104:107], v[120:123], v[16:19]
	v_mfma_f32_16x16x32_bf16 v[12:15], v[96:99], v[128:131], v[12:15]
	v_mfma_f32_16x16x32_bf16 v[8:11], v[104:107], v[128:131], v[8:11]
	v_mfma_f32_16x16x32_bf16 v[4:7], v[96:99], v[136:139], v[4:7]
	v_mfma_f32_16x16x32_bf16 v[0:3], v[104:107], v[136:139], v[0:3]
	v_mfma_f32_16x16x32_bf16 v[28:31], v[100:103], v[116:119], v[28:31]
	v_mfma_f32_16x16x32_bf16 v[24:27], v[108:111], v[116:119], v[24:27]
	v_mfma_f32_16x16x32_bf16 v[20:23], v[100:103], v[124:127], v[20:23]
	v_mfma_f32_16x16x32_bf16 v[16:19], v[108:111], v[124:127], v[16:19]
	v_mfma_f32_16x16x32_bf16 v[12:15], v[100:103], v[132:135], v[12:15]
	v_mfma_f32_16x16x32_bf16 v[8:11], v[108:111], v[132:135], v[8:11]
	v_mfma_f32_16x16x32_bf16 v[4:7], v[100:103], v[140:143], v[4:7]
	v_mfma_f32_16x16x32_bf16 v[0:3], v[108:111], v[140:143], v[0:3]
	s_setprio 0
	s_barrier
	s_add_i32 s29, s29, s12
	v_lshl_add_u64 v[80:81], v[144:145], 0, s[10:11]
	s_mov_b32 m0, s29
	s_nop 0
	global_load_lds_dwordx4 v[80:81], off
	s_add_i32 m0, s29, 0x2000
	s_add_u32 s36, s36, 0x8080
	v_lshl_add_u64 v[80:81], v[146:147], 0, s[10:11]
	s_addc_u32 s37, s37, 0
	s_add_i32 s29, s40, s12
	global_load_lds_dwordx4 v[80:81], off
	v_lshl_add_u64 v[80:81], s[36:37], 0, v[66:67]
	s_mov_b32 m0, s29
	s_nop 0
	global_load_lds_dwordx4 v[80:81], off
	v_lshl_add_u64 v[80:81], s[36:37], 0, v[70:71]
	s_add_i32 m0, s29, 0x2000
	s_nop 0
	global_load_lds_dwordx4 v[80:81], off
	v_lshl_add_u64 v[80:81], v[148:149], 0, s[10:11]
	s_mov_b32 m0, s27
	s_nop 0
	global_load_lds_dwordx4 v[80:81], off
	v_lshl_add_u64 v[80:81], v[150:151], 0, s[10:11]
	s_mov_b32 m0, s42
	s_nop 0
	global_load_lds_dwordx4 v[80:81], off
	s_waitcnt vmcnt(8)
	s_waitcnt lgkmcnt(0)
	s_barrier
	s_setprio 1
	s_setprio 0
	s_setprio 1
	s_setprio 0
	s_barrier
	s_andn2_b64 vcc, exec, s[24:25]
	s_cbranch_vccnz .LBB0_1000
	s_and_b32 s36, s21, 0x3ffffc0
	s_and_b32 s29, s21, 63
	v_or_b32_e32 v79, s36, v76
	v_lshl_or_b32 v84, v79, 6, s29
	v_ashrrev_i32_e32 v85, 31, v84
	v_lshlrev_b64 v[80:81], 11, v[84:85]
	v_lshl_add_u64 v[86:87], v[72:73], 0, v[80:81]
	v_pk_mul_f32 v[80:81], v[60:61], s[26:27] op_sel_hi:[1,0]
	s_barrier
; __device__ __forceinline__ unsigned cvt_pk_bf16(float lo, float hi) { unsigned r; asm volatile("v_cvt_pk_bf16_f32 %0, %1, %2" : "=v"(r) : "v"(lo), "v"(hi)); return r; }
;     __device__ __forceinline__ void operator()(const f32x4 (&acc)[2][2][4][2], const Unit& u, int wr, int wc, int fr, int fq) const {
;     ...
;         const float sc = 1.0f / 512.0f; const int b = u.pn >> 6, k1 = u.pn & 63;
; #pragma unroll
;         for (int m = 0; m < 4; ++m) { const int k2 = 16 * m + fr; bf16_t* rowp = AO + (size_t)(b * SEQ + 64 * k2 + k1) * DM + DQK + wc * 32 + 8 * fq;
; #pragma unroll
;             for (int bj = 0; bj < 2; ++bj) { const f32x4 v0 = acc[0][bj][m][0] * sc, v1 = acc[0][bj][m][1] * sc;
;                 u32x4 w; w.x = cvt_pk_bf16(v0[0], v0[1]); w.y = cvt_pk_bf16(v0[2], v0[3]); w.z = cvt_pk_bf16(v1[0], v1[1]); w.w = cvt_pk_bf16(v1[2], v1[3]);
;                 *(u32x4*)(rowp + bj * HALF) = w; } }
	v_pk_mul_f32 v[82:83], v[62:63], s[26:27] op_sel_hi:[1,0]
	v_cvt_pk_bf16_f32 v80, v80, v81
	v_pk_mul_f32 v[88:89], v[58:59], s[26:27] op_sel_hi:[1,0]
	v_cvt_pk_bf16_f32 v81, v82, v83
	v_pk_mul_f32 v[90:91], v[56:57], s[26:27] op_sel_hi:[1,0]
	s_nop 0
	v_cvt_pk_bf16_f32 v82, v90, v91
	v_cvt_pk_bf16_f32 v83, v88, v89
	global_store_dwordx4 v[86:87], v[80:83], off offset:1536
	v_pk_mul_f32 v[88:89], v[26:27], s[26:27] op_sel_hi:[1,0]
	v_pk_mul_f32 v[90:91], v[24:25], s[26:27] op_sel_hi:[1,0]
	v_pk_mul_f32 v[80:81], v[28:29], s[26:27] op_sel_hi:[1,0]
	v_pk_mul_f32 v[82:83], v[30:31], s[26:27] op_sel_hi:[1,0]
	v_cvt_pk_bf16_f32 v80, v80, v81
	s_nop 0
	v_cvt_pk_bf16_f32 v81, v82, v83
	v_cvt_pk_bf16_f32 v82, v90, v91
	v_cvt_pk_bf16_f32 v83, v88, v89
	global_store_dwordx4 v[86:87], v[80:83], off offset:1792
	v_pk_mul_f32 v[88:89], v[50:51], s[26:27] op_sel_hi:[1,0]
	v_pk_mul_f32 v[90:91], v[48:49], s[26:27] op_sel_hi:[1,0]
	v_or_b32_e32 v80, 0x400, v84
	v_ashrrev_i32_e32 v81, 31, v80
	v_lshlrev_b64 v[80:81], 11, v[80:81]
	v_lshl_add_u64 v[86:87], v[72:73], 0, v[80:81]
	v_pk_mul_f32 v[80:81], v[52:53], s[26:27] op_sel_hi:[1,0]
	v_pk_mul_f32 v[82:83], v[54:55], s[26:27] op_sel_hi:[1,0]
	v_cvt_pk_bf16_f32 v80, v80, v81
	s_nop 0
	v_cvt_pk_bf16_f32 v81, v82, v83
	v_cvt_pk_bf16_f32 v82, v90, v91
	v_cvt_pk_bf16_f32 v83, v88, v89
	global_store_dwordx4 v[86:87], v[80:83], off offset:1536
	v_pk_mul_f32 v[88:89], v[18:19], s[26:27] op_sel_hi:[1,0]
	v_pk_mul_f32 v[90:91], v[16:17], s[26:27] op_sel_hi:[1,0]
	v_pk_mul_f32 v[80:81], v[20:21], s[26:27] op_sel_hi:[1,0]
	v_pk_mul_f32 v[82:83], v[22:23], s[26:27] op_sel_hi:[1,0]
	v_cvt_pk_bf16_f32 v80, v80, v81
	s_nop 0
	v_cvt_pk_bf16_f32 v81, v82, v83
	v_cvt_pk_bf16_f32 v82, v90, v91
	v_cvt_pk_bf16_f32 v83, v88, v89
	global_store_dwordx4 v[86:87], v[80:83], off offset:1792
	v_pk_mul_f32 v[88:89], v[42:43], s[26:27] op_sel_hi:[1,0]
	v_pk_mul_f32 v[90:91], v[40:41], s[26:27] op_sel_hi:[1,0]
	v_or_b32_e32 v80, 0x800, v84
	v_ashrrev_i32_e32 v81, 31, v80
	v_lshlrev_b64 v[80:81], 11, v[80:81]
	v_lshl_add_u64 v[86:87], v[72:73], 0, v[80:81]
	v_pk_mul_f32 v[80:81], v[44:45], s[26:27] op_sel_hi:[1,0]
	v_pk_mul_f32 v[82:83], v[46:47], s[26:27] op_sel_hi:[1,0]
	v_cvt_pk_bf16_f32 v80, v80, v81
	s_nop 0
	v_cvt_pk_bf16_f32 v81, v82, v83
	v_cvt_pk_bf16_f32 v82, v90, v91
	v_cvt_pk_bf16_f32 v83, v88, v89
	global_store_dwordx4 v[86:87], v[80:83], off offset:1536
	v_pk_mul_f32 v[88:89], v[10:11], s[26:27] op_sel_hi:[1,0]
	v_pk_mul_f32 v[90:91], v[8:9], s[26:27] op_sel_hi:[1,0]
	v_pk_mul_f32 v[80:81], v[12:13], s[26:27] op_sel_hi:[1,0]
	v_pk_mul_f32 v[82:83], v[14:15], s[26:27] op_sel_hi:[1,0]
	v_cvt_pk_bf16_f32 v80, v80, v81
	s_nop 0
	v_cvt_pk_bf16_f32 v81, v82, v83
	v_cvt_pk_bf16_f32 v82, v90, v91
	v_cvt_pk_bf16_f32 v83, v88, v89
	global_store_dwordx4 v[86:87], v[80:83], off offset:1792
	v_pk_mul_f32 v[86:87], v[34:35], s[26:27] op_sel_hi:[1,0]
	v_pk_mul_f32 v[88:89], v[32:33], s[26:27] op_sel_hi:[1,0]
	v_or_b32_e32 v80, 0xc00, v84
	v_ashrrev_i32_e32 v81, 31, v80
	v_lshlrev_b64 v[80:81], 11, v[80:81]
	v_lshl_add_u64 v[84:85], v[72:73], 0, v[80:81]
	v_pk_mul_f32 v[82:83], v[38:39], s[26:27] op_sel_hi:[1,0]
	v_pk_mul_f32 v[80:81], v[36:37], s[26:27] op_sel_hi:[1,0]
	s_nop 0
	v_cvt_pk_bf16_f32 v80, v80, v81
	v_cvt_pk_bf16_f32 v81, v82, v83
	v_cvt_pk_bf16_f32 v82, v88, v89
	v_cvt_pk_bf16_f32 v83, v86, v87
	global_store_dwordx4 v[84:85], v[80:83], off offset:1536
	v_pk_mul_f32 v[86:87], v[2:3], s[26:27] op_sel_hi:[1,0]
	v_pk_mul_f32 v[88:89], v[0:1], s[26:27] op_sel_hi:[1,0]
	v_pk_mul_f32 v[82:83], v[6:7], s[26:27] op_sel_hi:[1,0]
	v_pk_mul_f32 v[80:81], v[4:5], s[26:27] op_sel_hi:[1,0]
	s_nop 0
	v_cvt_pk_bf16_f32 v80, v80, v81
	v_cvt_pk_bf16_f32 v81, v82, v83
	v_cvt_pk_bf16_f32 v82, v88, v89
	v_cvt_pk_bf16_f32 v83, v86, v87
	global_store_dwordx4 v[84:85], v[80:83], off offset:1792
	s_andn2_b64 vcc, exec, s[34:35]
	s_cbranch_vccnz .LBB0_990
	s_branch .LBB0_1001

; #define PG8_STAGE(bufoff, gbase, voff) do { _Pragma("unroll") for (int _i = 0; _i < 2; ++_i) \
;         __builtin_amdgcn_global_load_lds((const unsigned*)((const char*)(gbase) + (voff)[_i]), (LAS unsigned*)(lds + (bufoff) + ldsw + _i * 8192), 16, 0, 0); } while (0)
; #define PG8_STAGEB(bufoff, gbase, perm) do { _Pragma("unroll") for (int _i = 0; _i < 2; ++_i) \
;         __builtin_amdgcn_global_load_lds((const unsigned*)((const char*)(gbase) + ((BSEL && (perm)) ? voffBp[_i] : voffB[_i])), (LAS unsigned*)(lds + (bufoff) + ldsw + _i * 8192), 16, 0, 0); } while (0)
; #define PG8_LDA(dst, b, h) do { _Pragma("unroll") for (int m = 0; m < 4; ++m) _Pragma("unroll") for (int k = 0; k < 2; ++k) dst[m][k] = *(const LAS bf16x8*)(lds + PG8_SA(b, h) + aoff + m * 2048 + k * 1024); } while (0)
; #define PG8_LDB(dst, b, h) do { _Pragma("unroll") for (int n = 0; n < 2; ++n) _Pragma("unroll") for (int k = 0; k < 2; ++k) dst[n][k] = *(const LAS bf16x8*)(lds + PG8_SB(b, h) + boff + n * 2048 + k * 1024); } while (0)
; #define PG8_WAIT_V(n) asm volatile("s_waitcnt vmcnt(" #n ")" ::: "memory")
; #define PG8_WAIT_L(n) asm volatile("s_waitcnt lgkmcnt(" #n ")" ::: "memory")
; #define PG8_BAR __builtin_amdgcn_s_barrier()
; #define PG8_SCHED __builtin_amdgcn_sched_barrier(0)
; template <class Epi, bool BSEL = false>
; __device__ __forceinline__ void gemm_phase(LAS unsigned char* lds, const Gemm g, const Order& S, const Epi& E, const int tid) {
;     ...
;         for (int t = 0; t < nt; t += 2) {
;             const bool last = (t == nt - 2);
;             const char* a1 = cA + (size_t)(t + 1) * kstep;
;             const char* a2 = last ? nA : cA + (size_t)(t + 2) * kstep; const char* b2 = last ? nB : cB + (size_t)(t + 2) * kstep;
;             const char* a3 = a2 + kstep; const char* b3 = b2 + kstep;
;             const bool p2 = last ? nP : cP; const size_t h2 = last ? nhB : chB;
;             PG8_LDB(B0, 0, 0); PG8_LDB(B1, 0, 1); PG8_SCHED; PG8_LDA(At, 0, 0); PG8_STAGE(PG8_SA(1, 1), a1 + hstepA, voffA);
;             PG8_WAIT_V(8); PG8_WAIT_L(0); PG8_BAR; PG8_MMA(0, 0, At, B0); PG8_MMA(0, 1, At, B1); PG8_BAR; PG8_SCHED;
;             PG8_LDA(At, 0, 1); PG8_STAGEB(PG8_SB(0, 0), b2, p2); PG8_STAGEB(PG8_SB(0, 1), b2 + h2, p2); PG8_STAGE(PG8_SA(0, 0), a2, voffA);
;             PG8_WAIT_V(8); PG8_WAIT_L(0); PG8_BAR; PG8_MMA(1, 0, At, B0); PG8_MMA(1, 1, At, B1); PG8_BAR; PG8_SCHED;
.LBB0_1072:
	v_add_u32_e32 v172, s47, v145
	ds_read_b128 v[132:135], v172
	ds_read_b128 v[136:139], v172 offset:1024
	ds_read_b128 v[140:143], v172 offset:2048
	ds_read_b128 v[176:179], v172 offset:3072
	v_add_u32_e32 v172, s48, v145
	s_add_u32 s34, s6, s2
	ds_read_b128 v[180:183], v172
	ds_read_b128 v[184:187], v172 offset:1024
	ds_read_b128 v[188:191], v172 offset:2048
	ds_read_b128 v[192:195], v172 offset:3072
	s_addc_u32 s35, s7, s3
	s_add_u32 s34, s34, 0x100
	s_addc_u32 s35, s35, 0
	s_add_u32 s57, s1, s2
	s_addc_u32 s58, s25, s3
	s_cmpk_eq_i32 s2, 0x700
	s_cselect_b32 s39, s52, s35
	s_cselect_b32 s38, s53, s34
	s_cselect_b32 s35, s54, s58
	s_cselect_b32 s34, s55, s57
	v_lshl_add_u64 v[172:173], v[128:129], 0, s[2:3]
	s_add_i32 m0, s20, 0xc000
	ds_read_b128 v[196:199], v175
	ds_read_b128 v[202:205], v175 offset:1024
	ds_read_b128 v[206:209], v175 offset:2048
	ds_read_b128 v[210:213], v175 offset:3072
	ds_read_b128 v[214:217], v175 offset:4096
	ds_read_b128 v[218:221], v175 offset:5120
	ds_read_b128 v[222:225], v175 offset:6144
	ds_read_b128 v[226:229], v175 offset:7168
	global_load_lds_dwordx4 v[172:173], off
	v_lshl_add_u64 v[172:173], v[130:131], 0, s[2:3]
	s_add_i32 m0, s20, 0xe000
	s_nop 0
	global_load_lds_dwordx4 v[172:173], off
	s_waitcnt vmcnt(8)
	s_waitcnt lgkmcnt(0)
	s_barrier
	s_setprio 1
	v_mfma_f32_16x16x32_bf16 v[124:127], v[132:135], v[196:199], v[124:127]
	v_mfma_f32_16x16x32_bf16 v[120:123], v[140:143], v[196:199], v[120:123]
	v_mfma_f32_16x16x32_bf16 v[116:119], v[132:135], v[206:209], v[116:119]
	v_mfma_f32_16x16x32_bf16 v[112:115], v[140:143], v[206:209], v[112:115]
	v_mfma_f32_16x16x32_bf16 v[108:111], v[132:135], v[214:217], v[108:111]
	v_mfma_f32_16x16x32_bf16 v[104:107], v[140:143], v[214:217], v[104:107]
	v_mfma_f32_16x16x32_bf16 v[100:103], v[132:135], v[222:225], v[100:103]
	v_mfma_f32_16x16x32_bf16 v[96:99], v[140:143], v[222:225], v[96:99]
	v_mfma_f32_16x16x32_bf16 v[124:127], v[136:139], v[202:205], v[124:127]
	v_mfma_f32_16x16x32_bf16 v[120:123], v[176:179], v[202:205], v[120:123]
	v_mfma_f32_16x16x32_bf16 v[116:119], v[136:139], v[210:213], v[116:119]
	v_mfma_f32_16x16x32_bf16 v[112:115], v[176:179], v[210:213], v[112:115]
	v_mfma_f32_16x16x32_bf16 v[108:111], v[136:139], v[218:221], v[108:111]
	v_mfma_f32_16x16x32_bf16 v[104:107], v[176:179], v[218:221], v[104:107]
	v_mfma_f32_16x16x32_bf16 v[100:103], v[136:139], v[226:229], v[100:103]
	v_mfma_f32_16x16x32_bf16 v[96:99], v[176:179], v[226:229], v[96:99]
	v_mfma_f32_16x16x32_bf16 v[92:95], v[180:183], v[196:199], v[92:95]
	v_mfma_f32_16x16x32_bf16 v[88:91], v[188:191], v[196:199], v[88:91]
	v_mfma_f32_16x16x32_bf16 v[84:87], v[180:183], v[206:209], v[84:87]
	v_mfma_f32_16x16x32_bf16 v[80:83], v[188:191], v[206:209], v[80:83]
	v_mfma_f32_16x16x32_bf16 v[76:79], v[180:183], v[214:217], v[76:79]
	v_mfma_f32_16x16x32_bf16 v[72:75], v[188:191], v[214:217], v[72:75]
	v_mfma_f32_16x16x32_bf16 v[68:71], v[180:183], v[222:225], v[68:71]
	v_mfma_f32_16x16x32_bf16 v[64:67], v[188:191], v[222:225], v[64:67]
	v_mfma_f32_16x16x32_bf16 v[92:95], v[184:187], v[202:205], v[92:95]
	v_mfma_f32_16x16x32_bf16 v[88:91], v[192:195], v[202:205], v[88:91]
	v_mfma_f32_16x16x32_bf16 v[84:87], v[184:187], v[210:213], v[84:87]
	v_mfma_f32_16x16x32_bf16 v[80:83], v[192:195], v[210:213], v[80:83]
	v_mfma_f32_16x16x32_bf16 v[76:79], v[184:187], v[218:221], v[76:79]
	v_mfma_f32_16x16x32_bf16 v[72:75], v[192:195], v[218:221], v[72:75]
	v_mfma_f32_16x16x32_bf16 v[68:71], v[184:187], v[226:229], v[68:71]
	v_mfma_f32_16x16x32_bf16 v[64:67], v[192:195], v[226:229], v[64:67]
	s_setprio 0
	s_barrier
	s_add_i32 s57, s47, s15
	v_lshl_add_u64 v[172:173], s[34:35], 0, v[146:147]
	s_mov_b32 m0, s57
	ds_read_b128 v[196:199], v175 offset:16384
	ds_read_b128 v[202:205], v175 offset:17408
	ds_read_b128 v[206:209], v175 offset:18432
	ds_read_b128 v[210:213], v175 offset:19456
	ds_read_b128 v[214:217], v175 offset:20480
	ds_read_b128 v[218:221], v175 offset:21504
	ds_read_b128 v[222:225], v175 offset:22528
	ds_read_b128 v[226:229], v175 offset:23552
	global_load_lds_dwordx4 v[172:173], off
	s_add_i32 m0, s57, 0x2000
	s_add_u32 s58, s34, 0x40000
	v_lshl_add_u64 v[230:231], s[34:35], 0, v[148:149]
	s_addc_u32 s59, s35, 0
	s_add_i32 s57, s48, s15
	global_load_lds_dwordx4 v[230:231], off
	v_lshl_add_u64 v[232:233], s[58:59], 0, v[146:147]
	s_mov_b32 m0, s57
	v_lshl_add_u64 v[234:235], s[38:39], 0, v[148:149]
	global_load_lds_dwordx4 v[232:233], off
	v_lshl_add_u64 v[232:233], s[58:59], 0, v[148:149]
	s_add_i32 m0, s57, 0x2000
	s_nop 0
	global_load_lds_dwordx4 v[232:233], off
	v_lshl_add_u64 v[232:233], s[38:39], 0, v[146:147]
	s_mov_b32 m0, s20
	s_nop 0
	global_load_lds_dwordx4 v[232:233], off
	s_mov_b32 m0, s21
	s_nop 0
	global_load_lds_dwordx4 v[234:235], off
	s_waitcnt vmcnt(8)
	s_waitcnt lgkmcnt(0)
	s_barrier
; #define PG8_STAGE(bufoff, gbase, voff) do { _Pragma("unroll") for (int _i = 0; _i < 2; ++_i) \
;         __builtin_amdgcn_global_load_lds((const unsigned*)((const char*)(gbase) + (voff)[_i]), (LAS unsigned*)(lds + (bufoff) + ldsw + _i * 8192), 16, 0, 0); } while (0)
; #define PG8_LDA(dst, b, h) do { _Pragma("unroll") for (int m = 0; m < 4; ++m) _Pragma("unroll") for (int k = 0; k < 2; ++k) dst[m][k] = *(const LAS bf16x8*)(lds + PG8_SA(b, h) + aoff + m * 2048 + k * 1024); } while (0)
; #define PG8_LDB(dst, b, h) do { _Pragma("unroll") for (int n = 0; n < 2; ++n) _Pragma("unroll") for (int k = 0; k < 2; ++k) dst[n][k] = *(const LAS bf16x8*)(lds + PG8_SB(b, h) + boff + n * 2048 + k * 1024); } while (0)
; #define PG8_MMA(ai, bj, At, Bt) do { __builtin_amdgcn_s_setprio(1); _Pragma("unroll") for (int m = 0; m < 4; ++m) _Pragma("unroll") for (int n = 0; n < 2; ++n) _Pragma("unroll") for (int k = 0; k < 2; ++k) \
;         acc[ai][bj][m][n] = __builtin_amdgcn_mfma_f32_16x16x32_bf16(Bt[n][k], At[m][k], acc[ai][bj][m][n], 0, 0, 0); __builtin_amdgcn_s_setprio(0); } while (0)
; #define PG8_WAIT_V(n) asm volatile("s_waitcnt vmcnt(" #n ")" ::: "memory")
; #define PG8_WAIT_L(n) asm volatile("s_waitcnt lgkmcnt(" #n ")" ::: "memory")
; #define PG8_BAR __builtin_amdgcn_s_barrier()
; #define PG8_SCHED __builtin_amdgcn_sched_barrier(0)
; template <class Epi, bool BSEL = false>
; __device__ __forceinline__ void gemm_phase(LAS unsigned char* lds, const Gemm g, const Order& S, const Epi& E, const int tid) {
;     ...
;             PG8_WAIT_V(8); PG8_WAIT_L(0); PG8_BAR; PG8_MMA(1, 0, At, B0); PG8_MMA(1, 1, At, B1); PG8_BAR; PG8_SCHED;
;             PG8_LDB(B0, 1, 0); PG8_LDB(B1, 1, 1); PG8_SCHED; PG8_LDA(At, 1, 0); PG8_STAGE(PG8_SA(0, 1), a2 + hstepA, voffA);
;             PG8_WAIT_V(8); PG8_WAIT_L(0); PG8_BAR; PG8_MMA(0, 0, At, B0); PG8_MMA(0, 1, At, B1); PG8_BAR; PG8_SCHED;
	s_setprio 1
	v_mfma_f32_16x16x32_bf16 v[60:63], v[132:135], v[196:199], v[60:63]
	v_mfma_f32_16x16x32_bf16 v[56:59], v[140:143], v[196:199], v[56:59]
	v_mfma_f32_16x16x32_bf16 v[52:55], v[132:135], v[206:209], v[52:55]
	v_mfma_f32_16x16x32_bf16 v[48:51], v[140:143], v[206:209], v[48:51]
	v_mfma_f32_16x16x32_bf16 v[44:47], v[132:135], v[214:217], v[44:47]
	v_mfma_f32_16x16x32_bf16 v[40:43], v[140:143], v[214:217], v[40:43]
	v_mfma_f32_16x16x32_bf16 v[36:39], v[132:135], v[222:225], v[36:39]
	v_mfma_f32_16x16x32_bf16 v[32:35], v[140:143], v[222:225], v[32:35]
	v_mfma_f32_16x16x32_bf16 v[60:63], v[136:139], v[202:205], v[60:63]
	v_mfma_f32_16x16x32_bf16 v[56:59], v[176:179], v[202:205], v[56:59]
	v_mfma_f32_16x16x32_bf16 v[52:55], v[136:139], v[210:213], v[52:55]
	v_mfma_f32_16x16x32_bf16 v[48:51], v[176:179], v[210:213], v[48:51]
	v_mfma_f32_16x16x32_bf16 v[44:47], v[136:139], v[218:221], v[44:47]
	v_mfma_f32_16x16x32_bf16 v[40:43], v[176:179], v[218:221], v[40:43]
	v_mfma_f32_16x16x32_bf16 v[36:39], v[136:139], v[226:229], v[36:39]
	v_mfma_f32_16x16x32_bf16 v[32:35], v[176:179], v[226:229], v[32:35]
	v_mfma_f32_16x16x32_bf16 v[28:31], v[180:183], v[196:199], v[28:31]
	v_mfma_f32_16x16x32_bf16 v[24:27], v[188:191], v[196:199], v[24:27]
	v_mfma_f32_16x16x32_bf16 v[20:23], v[180:183], v[206:209], v[20:23]
	v_mfma_f32_16x16x32_bf16 v[16:19], v[188:191], v[206:209], v[16:19]
	v_mfma_f32_16x16x32_bf16 v[12:15], v[180:183], v[214:217], v[12:15]
	v_mfma_f32_16x16x32_bf16 v[8:11], v[188:191], v[214:217], v[8:11]
	v_mfma_f32_16x16x32_bf16 v[4:7], v[180:183], v[222:225], v[4:7]
	v_mfma_f32_16x16x32_bf16 v[0:3], v[188:191], v[222:225], v[0:3]
	v_mfma_f32_16x16x32_bf16 v[28:31], v[184:187], v[202:205], v[28:31]
	v_mfma_f32_16x16x32_bf16 v[24:27], v[192:195], v[202:205], v[24:27]
	v_mfma_f32_16x16x32_bf16 v[20:23], v[184:187], v[210:213], v[20:23]
	v_mfma_f32_16x16x32_bf16 v[16:19], v[192:195], v[210:213], v[16:19]
	v_mfma_f32_16x16x32_bf16 v[12:15], v[184:187], v[218:221], v[12:15]
	v_mfma_f32_16x16x32_bf16 v[8:11], v[192:195], v[218:221], v[8:11]
	v_mfma_f32_16x16x32_bf16 v[4:7], v[184:187], v[226:229], v[4:7]
	v_mfma_f32_16x16x32_bf16 v[0:3], v[192:195], v[226:229], v[0:3]
	s_setprio 0
	s_barrier
	s_add_i32 s57, 0, 0x18000
	s_add_i32 s58, 0, 0x1c000
	v_add_u32_e32 v176, s57, v145
	v_add_u32_e32 v192, s58, v145
	ds_read_b128 v[132:135], v176
	ds_read_b128 v[136:139], v176 offset:1024
	ds_read_b128 v[140:143], v176 offset:2048
	ds_read_b128 v[176:179], v176 offset:3072
	ds_read_b128 v[180:183], v192
	ds_read_b128 v[184:187], v192 offset:1024
	ds_read_b128 v[188:191], v192 offset:2048
	ds_read_b128 v[192:195], v192 offset:3072
	s_add_u32 s38, s38, 0x40000
	s_addc_u32 s39, s39, 0
	s_mov_b32 m0, s40
	v_lshl_add_u64 v[236:237], s[38:39], 0, v[146:147]
	ds_read_b128 v[196:199], v175 offset:32768
	ds_read_b128 v[202:205], v175 offset:33792
	ds_read_b128 v[206:209], v175 offset:34816
	ds_read_b128 v[210:213], v175 offset:35840
	ds_read_b128 v[214:217], v175 offset:36864
	ds_read_b128 v[218:221], v175 offset:37888
	ds_read_b128 v[222:225], v175 offset:38912
	ds_read_b128 v[226:229], v175 offset:39936
	global_load_lds_dwordx4 v[236:237], off
	v_lshl_add_u64 v[236:237], s[38:39], 0, v[148:149]
	s_mov_b32 m0, s41
	s_nop 0
	global_load_lds_dwordx4 v[236:237], off
	s_waitcnt vmcnt(8)
	s_waitcnt lgkmcnt(0)
	s_barrier
	s_setprio 1
	v_mfma_f32_16x16x32_bf16 v[124:127], v[132:135], v[196:199], v[124:127]
	v_mfma_f32_16x16x32_bf16 v[120:123], v[140:143], v[196:199], v[120:123]
	v_mfma_f32_16x16x32_bf16 v[116:119], v[132:135], v[206:209], v[116:119]
	v_mfma_f32_16x16x32_bf16 v[112:115], v[140:143], v[206:209], v[112:115]
	v_mfma_f32_16x16x32_bf16 v[108:111], v[132:135], v[214:217], v[108:111]
	v_mfma_f32_16x16x32_bf16 v[104:107], v[140:143], v[214:217], v[104:107]
	v_mfma_f32_16x16x32_bf16 v[100:103], v[132:135], v[222:225], v[100:103]
	v_mfma_f32_16x16x32_bf16 v[96:99], v[140:143], v[222:225], v[96:99]
	v_mfma_f32_16x16x32_bf16 v[124:127], v[136:139], v[202:205], v[124:127]
	v_mfma_f32_16x16x32_bf16 v[120:123], v[176:179], v[202:205], v[120:123]
	v_mfma_f32_16x16x32_bf16 v[116:119], v[136:139], v[210:213], v[116:119]
	v_mfma_f32_16x16x32_bf16 v[112:115], v[176:179], v[210:213], v[112:115]
	v_mfma_f32_16x16x32_bf16 v[108:111], v[136:139], v[218:221], v[108:111]
	v_mfma_f32_16x16x32_bf16 v[104:107], v[176:179], v[218:221], v[104:107]
	v_mfma_f32_16x16x32_bf16 v[100:103], v[136:139], v[226:229], v[100:103]
	v_mfma_f32_16x16x32_bf16 v[96:99], v[176:179], v[226:229], v[96:99]
	v_mfma_f32_16x16x32_bf16 v[92:95], v[180:183], v[196:199], v[92:95]
	v_mfma_f32_16x16x32_bf16 v[88:91], v[188:191], v[196:199], v[88:91]
	v_mfma_f32_16x16x32_bf16 v[84:87], v[180:183], v[206:209], v[84:87]
	v_mfma_f32_16x16x32_bf16 v[80:83], v[188:191], v[206:209], v[80:83]
	v_mfma_f32_16x16x32_bf16 v[76:79], v[180:183], v[214:217], v[76:79]
	v_mfma_f32_16x16x32_bf16 v[72:75], v[188:191], v[214:217], v[72:75]
	v_mfma_f32_16x16x32_bf16 v[68:71], v[180:183], v[222:225], v[68:71]
	v_mfma_f32_16x16x32_bf16 v[64:67], v[188:191], v[222:225], v[64:67]
	v_mfma_f32_16x16x32_bf16 v[92:95], v[184:187], v[202:205], v[92:95]
	v_mfma_f32_16x16x32_bf16 v[88:91], v[192:195], v[202:205], v[88:91]
	v_mfma_f32_16x16x32_bf16 v[84:87], v[184:187], v[210:213], v[84:87]
	v_mfma_f32_16x16x32_bf16 v[80:83], v[192:195], v[210:213], v[80:83]
	v_mfma_f32_16x16x32_bf16 v[76:79], v[184:187], v[218:221], v[76:79]
	v_mfma_f32_16x16x32_bf16 v[72:75], v[192:195], v[218:221], v[72:75]
	v_mfma_f32_16x16x32_bf16 v[68:71], v[184:187], v[226:229], v[68:71]
	v_mfma_f32_16x16x32_bf16 v[64:67], v[192:195], v[226:229], v[64:67]
	s_setprio 0
	s_barrier
; #define PG8_STAGE(bufoff, gbase, voff) do { _Pragma("unroll") for (int _i = 0; _i < 2; ++_i) \
;         __builtin_amdgcn_global_load_lds((const unsigned*)((const char*)(gbase) + (voff)[_i]), (LAS unsigned*)(lds + (bufoff) + ldsw + _i * 8192), 16, 0, 0); } while (0)
; #define PG8_STAGEB(bufoff, gbase, perm) do { _Pragma("unroll") for (int _i = 0; _i < 2; ++_i) \
;         __builtin_amdgcn_global_load_lds((const unsigned*)((const char*)(gbase) + ((BSEL && (perm)) ? voffBp[_i] : voffB[_i])), (LAS unsigned*)(lds + (bufoff) + ldsw + _i * 8192), 16, 0, 0); } while (0)
; #define PG8_LDA(dst, b, h) do { _Pragma("unroll") for (int m = 0; m < 4; ++m) _Pragma("unroll") for (int k = 0; k < 2; ++k) dst[m][k] = *(const LAS bf16x8*)(lds + PG8_SA(b, h) + aoff + m * 2048 + k * 1024); } while (0)
; #define PG8_MMA(ai, bj, At, Bt) do { __builtin_amdgcn_s_setprio(1); _Pragma("unroll") for (int m = 0; m < 4; ++m) _Pragma("unroll") for (int n = 0; n < 2; ++n) _Pragma("unroll") for (int k = 0; k < 2; ++k) \
;         acc[ai][bj][m][n] = __builtin_amdgcn_mfma_f32_16x16x32_bf16(Bt[n][k], At[m][k], acc[ai][bj][m][n], 0, 0, 0); __builtin_amdgcn_s_setprio(0); } while (0)
; #define PG8_WAIT_V(n) asm volatile("s_waitcnt vmcnt(" #n ")" ::: "memory")
; #define PG8_WAIT_L(n) asm volatile("s_waitcnt lgkmcnt(" #n ")" ::: "memory")
; #define PG8_BAR __builtin_amdgcn_s_barrier()
; #define PG8_SCHED __builtin_amdgcn_sched_barrier(0)
; template <class Epi, bool BSEL = false>
; __device__ __forceinline__ void gemm_phase(LAS unsigned char* lds, const Gemm g, const Order& S, const Epi& E, const int tid) {
;     ...
;             PG8_LDA(At, 1, 1); PG8_STAGEB(PG8_SB(1, 0), b3, p2); PG8_STAGEB(PG8_SB(1, 1), b3 + h2, p2); PG8_STAGE(PG8_SA(1, 0), a3, voffA);
;             PG8_WAIT_V(8); PG8_WAIT_L(0); PG8_BAR; PG8_MMA(1, 0, At, B0); PG8_MMA(1, 1, At, B1); PG8_BAR; PG8_SCHED;
;         }
;         if constexpr (ALIGN_EPI) { if (wr == 0) PG8_BAR; }
	s_add_i32 s38, s57, s15
	v_lshl_add_u64 v[172:173], v[172:173], 0, s[10:11]
	s_mov_b32 m0, s38
	ds_read_b128 v[196:199], v175 offset:49152
	ds_read_b128 v[202:205], v175 offset:50176
	ds_read_b128 v[206:209], v175 offset:51200
	ds_read_b128 v[210:213], v175 offset:52224
	ds_read_b128 v[214:217], v175 offset:53248
	ds_read_b128 v[218:221], v175 offset:54272
	ds_read_b128 v[222:225], v175 offset:55296
	ds_read_b128 v[226:229], v175 offset:56320
	global_load_lds_dwordx4 v[172:173], off
	s_add_i32 m0, s38, 0x2000
	s_add_u32 s34, s34, 0x40080
	v_lshl_add_u64 v[172:173], v[230:231], 0, s[10:11]
	s_addc_u32 s35, s35, 0
	s_add_i32 s38, s58, s15
	global_load_lds_dwordx4 v[172:173], off
	v_lshl_add_u64 v[172:173], s[34:35], 0, v[146:147]
	s_mov_b32 m0, s38
	s_nop 0
	global_load_lds_dwordx4 v[172:173], off
	v_lshl_add_u64 v[172:173], s[34:35], 0, v[148:149]
	s_add_i32 m0, s38, 0x2000
	s_nop 0
	global_load_lds_dwordx4 v[172:173], off
	v_lshl_add_u64 v[172:173], v[232:233], 0, s[10:11]
	s_mov_b32 m0, s45
	s_nop 0
	global_load_lds_dwordx4 v[172:173], off
	v_lshl_add_u64 v[172:173], v[234:235], 0, s[10:11]
	s_mov_b32 m0, s46
	s_nop 0
	global_load_lds_dwordx4 v[172:173], off
	s_waitcnt vmcnt(8)
	s_waitcnt lgkmcnt(0)
	s_barrier
	s_setprio 1
	v_mfma_f32_16x16x32_bf16 v[60:63], v[132:135], v[196:199], v[60:63]
	v_mfma_f32_16x16x32_bf16 v[56:59], v[140:143], v[196:199], v[56:59]
	v_mfma_f32_16x16x32_bf16 v[52:55], v[132:135], v[206:209], v[52:55]
	v_mfma_f32_16x16x32_bf16 v[48:51], v[140:143], v[206:209], v[48:51]
	v_mfma_f32_16x16x32_bf16 v[44:47], v[132:135], v[214:217], v[44:47]
	v_mfma_f32_16x16x32_bf16 v[40:43], v[140:143], v[214:217], v[40:43]
	v_mfma_f32_16x16x32_bf16 v[36:39], v[132:135], v[222:225], v[36:39]
	v_mfma_f32_16x16x32_bf16 v[32:35], v[140:143], v[222:225], v[32:35]
	v_mfma_f32_16x16x32_bf16 v[60:63], v[136:139], v[202:205], v[60:63]
	v_mfma_f32_16x16x32_bf16 v[56:59], v[176:179], v[202:205], v[56:59]
	v_mfma_f32_16x16x32_bf16 v[52:55], v[136:139], v[210:213], v[52:55]
	v_mfma_f32_16x16x32_bf16 v[48:51], v[176:179], v[210:213], v[48:51]
	v_mfma_f32_16x16x32_bf16 v[44:47], v[136:139], v[218:221], v[44:47]
	v_mfma_f32_16x16x32_bf16 v[40:43], v[176:179], v[218:221], v[40:43]
	v_mfma_f32_16x16x32_bf16 v[36:39], v[136:139], v[226:229], v[36:39]
	v_mfma_f32_16x16x32_bf16 v[32:35], v[176:179], v[226:229], v[32:35]
	v_mfma_f32_16x16x32_bf16 v[28:31], v[180:183], v[196:199], v[28:31]
	v_mfma_f32_16x16x32_bf16 v[24:27], v[188:191], v[196:199], v[24:27]
	v_mfma_f32_16x16x32_bf16 v[20:23], v[180:183], v[206:209], v[20:23]
	v_mfma_f32_16x16x32_bf16 v[16:19], v[188:191], v[206:209], v[16:19]
	v_mfma_f32_16x16x32_bf16 v[12:15], v[180:183], v[214:217], v[12:15]
	v_mfma_f32_16x16x32_bf16 v[8:11], v[188:191], v[214:217], v[8:11]
	v_mfma_f32_16x16x32_bf16 v[4:7], v[180:183], v[222:225], v[4:7]
	v_mfma_f32_16x16x32_bf16 v[0:3], v[188:191], v[222:225], v[0:3]
	v_mfma_f32_16x16x32_bf16 v[28:31], v[184:187], v[202:205], v[28:31]
	v_mfma_f32_16x16x32_bf16 v[24:27], v[192:195], v[202:205], v[24:27]
	v_mfma_f32_16x16x32_bf16 v[20:23], v[184:187], v[210:213], v[20:23]
	v_mfma_f32_16x16x32_bf16 v[16:19], v[192:195], v[210:213], v[16:19]
	v_mfma_f32_16x16x32_bf16 v[12:15], v[184:187], v[218:221], v[12:15]
	v_mfma_f32_16x16x32_bf16 v[8:11], v[192:195], v[218:221], v[8:11]
	v_mfma_f32_16x16x32_bf16 v[4:7], v[184:187], v[226:229], v[4:7]
	v_mfma_f32_16x16x32_bf16 v[0:3], v[192:195], v[226:229], v[0:3]
	s_setprio 0
	s_barrier
	s_add_i32 s56, s56, 2
	s_add_u32 s2, s2, 0x100
	s_addc_u32 s3, s3, 0
	s_cmp_gt_u32 s56, 13
	s_cbranch_scc0 .LBB0_1072
	s_and_b64 vcc, exec, s[22:23]
	s_cbranch_vccz .LBB0_1075
	s_barrier

; #define PG8_STAGE(bufoff, gbase, voff) do { _Pragma("unroll") for (int _i = 0; _i < 2; ++_i) \
;         __builtin_amdgcn_global_load_lds((const unsigned*)((const char*)(gbase) + (voff)[_i]), (LAS unsigned*)(lds + (bufoff) + ldsw + _i * 8192), 16, 0, 0); } while (0)
; #define PG8_STAGEB(bufoff, gbase, perm) do { _Pragma("unroll") for (int _i = 0; _i < 2; ++_i) \
;         __builtin_amdgcn_global_load_lds((const unsigned*)((const char*)(gbase) + ((BSEL && (perm)) ? voffBp[_i] : voffB[_i])), (LAS unsigned*)(lds + (bufoff) + ldsw + _i * 8192), 16, 0, 0); } while (0)
; #define PG8_LDA(dst, b, h) do { _Pragma("unroll") for (int m = 0; m < 4; ++m) _Pragma("unroll") for (int k = 0; k < 2; ++k) dst[m][k] = *(const LAS bf16x8*)(lds + PG8_SA(b, h) + aoff + m * 2048 + k * 1024); } while (0)
; #define PG8_LDB(dst, b, h) do { _Pragma("unroll") for (int n = 0; n < 2; ++n) _Pragma("unroll") for (int k = 0; k < 2; ++k) dst[n][k] = *(const LAS bf16x8*)(lds + PG8_SB(b, h) + boff + n * 2048 + k * 1024); } while (0)
; #define PG8_WAIT_V(n) asm volatile("s_waitcnt vmcnt(" #n ")" ::: "memory")
; #define PG8_WAIT_L(n) asm volatile("s_waitcnt lgkmcnt(" #n ")" ::: "memory")
; #define PG8_BAR __builtin_amdgcn_s_barrier()
; #define PG8_SCHED __builtin_amdgcn_sched_barrier(0)
; template <class Epi, bool BSEL = false>
; __device__ __forceinline__ void gemm_phase(LAS unsigned char* lds, const Gemm g, const Order& S, const Epi& E, const int tid) {
;     ...
;         for (int t = 0; t < nt; t += 2) {
;             const bool last = (t == nt - 2);
;             const char* a1 = cA + (size_t)(t + 1) * kstep;
;             const char* a2 = last ? nA : cA + (size_t)(t + 2) * kstep; const char* b2 = last ? nB : cB + (size_t)(t + 2) * kstep;
;             const char* a3 = a2 + kstep; const char* b3 = b2 + kstep;
;             const bool p2 = last ? nP : cP; const size_t h2 = last ? nhB : chB;
;             PG8_LDB(B0, 0, 0); PG8_LDB(B1, 0, 1); PG8_SCHED; PG8_LDA(At, 0, 0); PG8_STAGE(PG8_SA(1, 1), a1 + hstepA, voffA);
;             PG8_WAIT_V(8); PG8_WAIT_L(0); PG8_BAR; PG8_MMA(0, 0, At, B0); PG8_MMA(0, 1, At, B1); PG8_BAR; PG8_SCHED;
;             PG8_LDA(At, 0, 1); PG8_STAGEB(PG8_SB(0, 0), b2, p2); PG8_STAGEB(PG8_SB(0, 1), b2 + h2, p2); PG8_STAGE(PG8_SA(0, 0), a2, voffA);
;             PG8_WAIT_V(8); PG8_WAIT_L(0); PG8_BAR; PG8_MMA(1, 0, At, B0); PG8_MMA(1, 1, At, B1); PG8_BAR; PG8_SCHED;
.LBB0_1101:
	v_add_u32_e32 v164, s47, v129
	v_add_u32_e32 v180, s48, v129
	s_add_u32 s40, s8, s38
	ds_read_b128 v[152:155], v164
	ds_read_b128 v[156:159], v164 offset:1024
	ds_read_b128 v[160:163], v164 offset:2048
	ds_read_b128 v[164:167], v164 offset:3072
	ds_read_b128 v[168:171], v180
	ds_read_b128 v[172:175], v180 offset:1024
	ds_read_b128 v[176:179], v180 offset:2048
	ds_read_b128 v[180:183], v180 offset:3072
	s_addc_u32 s41, s9, s39
	s_add_u32 s40, s40, 0x100
	s_addc_u32 s41, s41, 0
	s_add_u32 s56, s27, s38
	s_addc_u32 s57, s35, s39
	s_cmpk_eq_i32 s38, 0x700
	s_cselect_b32 s43, s51, s41
	s_cselect_b32 s42, s52, s40
	s_cselect_b32 s41, s53, s57
	s_cselect_b32 s40, s54, s56
	v_lshl_add_u64 v[188:189], v[146:147], 0, s[38:39]
	s_add_i32 m0, s7, 0xc000
	ds_read_b128 v[184:187], v151
	ds_read_b128 v[192:195], v151 offset:1024
	ds_read_b128 v[196:199], v151 offset:2048
	ds_read_b128 v[202:205], v151 offset:3072
	ds_read_b128 v[206:209], v151 offset:4096
	ds_read_b128 v[210:213], v151 offset:5120
	ds_read_b128 v[214:217], v151 offset:6144
	ds_read_b128 v[218:221], v151 offset:7168
	global_load_lds_dwordx4 v[188:189], off
	v_lshl_add_u64 v[188:189], v[148:149], 0, s[38:39]
	s_add_i32 m0, s7, 0xe000
	s_nop 0
	global_load_lds_dwordx4 v[188:189], off
	s_waitcnt vmcnt(8)
	s_waitcnt lgkmcnt(0)
	s_barrier
	s_setprio 1
	v_mfma_f32_16x16x32_bf16 v[124:127], v[152:155], v[184:187], v[124:127]
	v_mfma_f32_16x16x32_bf16 v[120:123], v[160:163], v[184:187], v[120:123]
	v_mfma_f32_16x16x32_bf16 v[108:111], v[152:155], v[196:199], v[108:111]
	v_mfma_f32_16x16x32_bf16 v[104:107], v[160:163], v[196:199], v[104:107]
	v_mfma_f32_16x16x32_bf16 v[92:95], v[152:155], v[206:209], v[92:95]
	v_mfma_f32_16x16x32_bf16 v[88:91], v[160:163], v[206:209], v[88:91]
	v_mfma_f32_16x16x32_bf16 v[76:79], v[152:155], v[214:217], v[76:79]
	v_mfma_f32_16x16x32_bf16 v[72:75], v[160:163], v[214:217], v[72:75]
	v_mfma_f32_16x16x32_bf16 v[124:127], v[156:159], v[192:195], v[124:127]
	v_mfma_f32_16x16x32_bf16 v[120:123], v[164:167], v[192:195], v[120:123]
	v_mfma_f32_16x16x32_bf16 v[108:111], v[156:159], v[202:205], v[108:111]
	v_mfma_f32_16x16x32_bf16 v[104:107], v[164:167], v[202:205], v[104:107]
	v_mfma_f32_16x16x32_bf16 v[92:95], v[156:159], v[210:213], v[92:95]
	v_mfma_f32_16x16x32_bf16 v[88:91], v[164:167], v[210:213], v[88:91]
	v_mfma_f32_16x16x32_bf16 v[76:79], v[156:159], v[218:221], v[76:79]
	v_mfma_f32_16x16x32_bf16 v[72:75], v[164:167], v[218:221], v[72:75]
	v_mfma_f32_16x16x32_bf16 v[116:119], v[168:171], v[184:187], v[116:119]
	v_mfma_f32_16x16x32_bf16 v[112:115], v[176:179], v[184:187], v[112:115]
	v_mfma_f32_16x16x32_bf16 v[100:103], v[168:171], v[196:199], v[100:103]
	v_mfma_f32_16x16x32_bf16 v[96:99], v[176:179], v[196:199], v[96:99]
	v_mfma_f32_16x16x32_bf16 v[84:87], v[168:171], v[206:209], v[84:87]
	v_mfma_f32_16x16x32_bf16 v[80:83], v[176:179], v[206:209], v[80:83]
	v_mfma_f32_16x16x32_bf16 v[68:71], v[168:171], v[214:217], v[68:71]
	v_mfma_f32_16x16x32_bf16 v[64:67], v[176:179], v[214:217], v[64:67]
	v_mfma_f32_16x16x32_bf16 v[116:119], v[172:175], v[192:195], v[116:119]
	v_mfma_f32_16x16x32_bf16 v[112:115], v[180:183], v[192:195], v[112:115]
	v_mfma_f32_16x16x32_bf16 v[100:103], v[172:175], v[202:205], v[100:103]
	v_mfma_f32_16x16x32_bf16 v[96:99], v[180:183], v[202:205], v[96:99]
	v_mfma_f32_16x16x32_bf16 v[84:87], v[172:175], v[210:213], v[84:87]
	v_mfma_f32_16x16x32_bf16 v[80:83], v[180:183], v[210:213], v[80:83]
	v_mfma_f32_16x16x32_bf16 v[68:71], v[172:175], v[218:221], v[68:71]
	v_mfma_f32_16x16x32_bf16 v[64:67], v[180:183], v[218:221], v[64:67]
	s_setprio 0
	s_barrier
	s_add_i32 s56, s47, s15
	v_lshl_add_u64 v[188:189], s[40:41], 0, v[132:133]
	s_mov_b32 m0, s56
	ds_read_b128 v[184:187], v151 offset:16384
	ds_read_b128 v[192:195], v151 offset:17408
	ds_read_b128 v[196:199], v151 offset:18432
	ds_read_b128 v[202:205], v151 offset:19456
	ds_read_b128 v[206:209], v151 offset:20480
	ds_read_b128 v[210:213], v151 offset:21504
	ds_read_b128 v[214:217], v151 offset:22528
	ds_read_b128 v[218:221], v151 offset:23552
	global_load_lds_dwordx4 v[188:189], off
	s_add_i32 m0, s56, 0x2000
	s_add_u32 s56, s40, 0x40000
	v_lshl_add_u64 v[222:223], s[40:41], 0, v[136:137]
	s_addc_u32 s57, s41, 0
	s_add_i32 s58, s48, s15
	global_load_lds_dwordx4 v[222:223], off
	v_lshl_add_u64 v[224:225], s[56:57], 0, v[132:133]
	s_mov_b32 m0, s58
	v_lshl_add_u64 v[226:227], s[42:43], 0, v[134:135]
	global_load_lds_dwordx4 v[224:225], off
	v_lshl_add_u64 v[224:225], s[56:57], 0, v[136:137]
	s_add_i32 m0, s58, 0x2000
	s_nop 0
	global_load_lds_dwordx4 v[224:225], off
	v_lshl_add_u64 v[224:225], s[42:43], 0, v[130:131]
	s_mov_b32 m0, s7
	s_nop 0
	global_load_lds_dwordx4 v[224:225], off
	s_mov_b32 m0, s20
	s_nop 0
	global_load_lds_dwordx4 v[226:227], off
	s_waitcnt vmcnt(8)
	s_waitcnt lgkmcnt(0)
	s_barrier
; #define PG8_STAGE(bufoff, gbase, voff) do { _Pragma("unroll") for (int _i = 0; _i < 2; ++_i) \
;         __builtin_amdgcn_global_load_lds((const unsigned*)((const char*)(gbase) + (voff)[_i]), (LAS unsigned*)(lds + (bufoff) + ldsw + _i * 8192), 16, 0, 0); } while (0)
; #define PG8_LDA(dst, b, h) do { _Pragma("unroll") for (int m = 0; m < 4; ++m) _Pragma("unroll") for (int k = 0; k < 2; ++k) dst[m][k] = *(const LAS bf16x8*)(lds + PG8_SA(b, h) + aoff + m * 2048 + k * 1024); } while (0)
; #define PG8_LDB(dst, b, h) do { _Pragma("unroll") for (int n = 0; n < 2; ++n) _Pragma("unroll") for (int k = 0; k < 2; ++k) dst[n][k] = *(const LAS bf16x8*)(lds + PG8_SB(b, h) + boff + n * 2048 + k * 1024); } while (0)
; #define PG8_MMA(ai, bj, At, Bt) do { __builtin_amdgcn_s_setprio(1); _Pragma("unroll") for (int m = 0; m < 4; ++m) _Pragma("unroll") for (int n = 0; n < 2; ++n) _Pragma("unroll") for (int k = 0; k < 2; ++k) \
;         acc[ai][bj][m][n] = __builtin_amdgcn_mfma_f32_16x16x32_bf16(Bt[n][k], At[m][k], acc[ai][bj][m][n], 0, 0, 0); __builtin_amdgcn_s_setprio(0); } while (0)
; #define PG8_WAIT_V(n) asm volatile("s_waitcnt vmcnt(" #n ")" ::: "memory")
; #define PG8_WAIT_L(n) asm volatile("s_waitcnt lgkmcnt(" #n ")" ::: "memory")
; #define PG8_BAR __builtin_amdgcn_s_barrier()
; #define PG8_SCHED __builtin_amdgcn_sched_barrier(0)
; template <class Epi, bool BSEL = false>
; __device__ __forceinline__ void gemm_phase(LAS unsigned char* lds, const Gemm g, const Order& S, const Epi& E, const int tid) {
;     ...
;             PG8_WAIT_V(8); PG8_WAIT_L(0); PG8_BAR; PG8_MMA(1, 0, At, B0); PG8_MMA(1, 1, At, B1); PG8_BAR; PG8_SCHED;
;             PG8_LDB(B0, 1, 0); PG8_LDB(B1, 1, 1); PG8_SCHED; PG8_LDA(At, 1, 0); PG8_STAGE(PG8_SA(0, 1), a2 + hstepA, voffA);
;             PG8_WAIT_V(8); PG8_WAIT_L(0); PG8_BAR; PG8_MMA(0, 0, At, B0); PG8_MMA(0, 1, At, B1); PG8_BAR; PG8_SCHED;
	s_setprio 1
	v_mfma_f32_16x16x32_bf16 v[60:63], v[152:155], v[184:187], v[60:63]
	v_mfma_f32_16x16x32_bf16 v[56:59], v[160:163], v[184:187], v[56:59]
	v_mfma_f32_16x16x32_bf16 v[44:47], v[152:155], v[196:199], v[44:47]
	v_mfma_f32_16x16x32_bf16 v[40:43], v[160:163], v[196:199], v[40:43]
	v_mfma_f32_16x16x32_bf16 v[28:31], v[152:155], v[206:209], v[28:31]
	v_mfma_f32_16x16x32_bf16 v[24:27], v[160:163], v[206:209], v[24:27]
	v_mfma_f32_16x16x32_bf16 v[12:15], v[152:155], v[214:217], v[12:15]
	v_mfma_f32_16x16x32_bf16 v[8:11], v[160:163], v[214:217], v[8:11]
	v_mfma_f32_16x16x32_bf16 v[60:63], v[156:159], v[192:195], v[60:63]
	v_mfma_f32_16x16x32_bf16 v[56:59], v[164:167], v[192:195], v[56:59]
	v_mfma_f32_16x16x32_bf16 v[44:47], v[156:159], v[202:205], v[44:47]
	v_mfma_f32_16x16x32_bf16 v[40:43], v[164:167], v[202:205], v[40:43]
	v_mfma_f32_16x16x32_bf16 v[28:31], v[156:159], v[210:213], v[28:31]
	v_mfma_f32_16x16x32_bf16 v[24:27], v[164:167], v[210:213], v[24:27]
	v_mfma_f32_16x16x32_bf16 v[12:15], v[156:159], v[218:221], v[12:15]
	v_mfma_f32_16x16x32_bf16 v[8:11], v[164:167], v[218:221], v[8:11]
	v_mfma_f32_16x16x32_bf16 v[52:55], v[168:171], v[184:187], v[52:55]
	v_mfma_f32_16x16x32_bf16 v[48:51], v[176:179], v[184:187], v[48:51]
	v_mfma_f32_16x16x32_bf16 v[36:39], v[168:171], v[196:199], v[36:39]
	v_mfma_f32_16x16x32_bf16 v[32:35], v[176:179], v[196:199], v[32:35]
	v_mfma_f32_16x16x32_bf16 v[20:23], v[168:171], v[206:209], v[20:23]
	v_mfma_f32_16x16x32_bf16 v[16:19], v[176:179], v[206:209], v[16:19]
	v_mfma_f32_16x16x32_bf16 v[4:7], v[168:171], v[214:217], v[4:7]
	v_mfma_f32_16x16x32_bf16 v[0:3], v[176:179], v[214:217], v[0:3]
	v_mfma_f32_16x16x32_bf16 v[52:55], v[172:175], v[192:195], v[52:55]
	v_mfma_f32_16x16x32_bf16 v[48:51], v[180:183], v[192:195], v[48:51]
	v_mfma_f32_16x16x32_bf16 v[36:39], v[172:175], v[202:205], v[36:39]
	v_mfma_f32_16x16x32_bf16 v[32:35], v[180:183], v[202:205], v[32:35]
	v_mfma_f32_16x16x32_bf16 v[20:23], v[172:175], v[210:213], v[20:23]
	v_mfma_f32_16x16x32_bf16 v[16:19], v[180:183], v[210:213], v[16:19]
	v_mfma_f32_16x16x32_bf16 v[4:7], v[172:175], v[218:221], v[4:7]
	v_mfma_f32_16x16x32_bf16 v[0:3], v[180:183], v[218:221], v[0:3]
	s_setprio 0
	s_barrier
	s_add_i32 s56, 0, 0x18000
	s_add_i32 s57, 0, 0x1c000
	v_add_u32_e32 v164, s56, v129
	v_add_u32_e32 v180, s57, v129
	ds_read_b128 v[152:155], v164
	ds_read_b128 v[156:159], v164 offset:1024
	ds_read_b128 v[160:163], v164 offset:2048
	ds_read_b128 v[164:167], v164 offset:3072
	ds_read_b128 v[168:171], v180
	ds_read_b128 v[172:175], v180 offset:1024
	ds_read_b128 v[176:179], v180 offset:2048
	ds_read_b128 v[180:183], v180 offset:3072
	s_add_u32 s42, s42, 0x40000
	s_addc_u32 s43, s43, 0
	s_mov_b32 m0, s21
	v_lshl_add_u64 v[228:229], s[42:43], 0, v[130:131]
	ds_read_b128 v[184:187], v151 offset:32768
	ds_read_b128 v[192:195], v151 offset:33792
	ds_read_b128 v[196:199], v151 offset:34816
	ds_read_b128 v[202:205], v151 offset:35840
	ds_read_b128 v[206:209], v151 offset:36864
	ds_read_b128 v[210:213], v151 offset:37888
	ds_read_b128 v[214:217], v151 offset:38912
	ds_read_b128 v[218:221], v151 offset:39936
	global_load_lds_dwordx4 v[228:229], off
	v_lshl_add_u64 v[228:229], s[42:43], 0, v[134:135]
	s_mov_b32 m0, s44
	s_nop 0
	global_load_lds_dwordx4 v[228:229], off
	s_waitcnt vmcnt(8)
	s_waitcnt lgkmcnt(0)
	s_barrier
	s_setprio 1
	v_mfma_f32_16x16x32_bf16 v[124:127], v[152:155], v[184:187], v[124:127]
	v_mfma_f32_16x16x32_bf16 v[120:123], v[160:163], v[184:187], v[120:123]
	v_mfma_f32_16x16x32_bf16 v[108:111], v[152:155], v[196:199], v[108:111]
	v_mfma_f32_16x16x32_bf16 v[104:107], v[160:163], v[196:199], v[104:107]
	v_mfma_f32_16x16x32_bf16 v[92:95], v[152:155], v[206:209], v[92:95]
	v_mfma_f32_16x16x32_bf16 v[88:91], v[160:163], v[206:209], v[88:91]
	v_mfma_f32_16x16x32_bf16 v[76:79], v[152:155], v[214:217], v[76:79]
	v_mfma_f32_16x16x32_bf16 v[72:75], v[160:163], v[214:217], v[72:75]
	v_mfma_f32_16x16x32_bf16 v[124:127], v[156:159], v[192:195], v[124:127]
	v_mfma_f32_16x16x32_bf16 v[120:123], v[164:167], v[192:195], v[120:123]
	v_mfma_f32_16x16x32_bf16 v[108:111], v[156:159], v[202:205], v[108:111]
	v_mfma_f32_16x16x32_bf16 v[104:107], v[164:167], v[202:205], v[104:107]
	v_mfma_f32_16x16x32_bf16 v[92:95], v[156:159], v[210:213], v[92:95]
	v_mfma_f32_16x16x32_bf16 v[88:91], v[164:167], v[210:213], v[88:91]
	v_mfma_f32_16x16x32_bf16 v[76:79], v[156:159], v[218:221], v[76:79]
	v_mfma_f32_16x16x32_bf16 v[72:75], v[164:167], v[218:221], v[72:75]
	v_mfma_f32_16x16x32_bf16 v[116:119], v[168:171], v[184:187], v[116:119]
	v_mfma_f32_16x16x32_bf16 v[112:115], v[176:179], v[184:187], v[112:115]
	v_mfma_f32_16x16x32_bf16 v[100:103], v[168:171], v[196:199], v[100:103]
	v_mfma_f32_16x16x32_bf16 v[96:99], v[176:179], v[196:199], v[96:99]
	v_mfma_f32_16x16x32_bf16 v[84:87], v[168:171], v[206:209], v[84:87]
	v_mfma_f32_16x16x32_bf16 v[80:83], v[176:179], v[206:209], v[80:83]
	v_mfma_f32_16x16x32_bf16 v[68:71], v[168:171], v[214:217], v[68:71]
	v_mfma_f32_16x16x32_bf16 v[64:67], v[176:179], v[214:217], v[64:67]
	v_mfma_f32_16x16x32_bf16 v[116:119], v[172:175], v[192:195], v[116:119]
	v_mfma_f32_16x16x32_bf16 v[112:115], v[180:183], v[192:195], v[112:115]
	v_mfma_f32_16x16x32_bf16 v[100:103], v[172:175], v[202:205], v[100:103]
	v_mfma_f32_16x16x32_bf16 v[96:99], v[180:183], v[202:205], v[96:99]
	v_mfma_f32_16x16x32_bf16 v[84:87], v[172:175], v[210:213], v[84:87]
	v_mfma_f32_16x16x32_bf16 v[80:83], v[180:183], v[210:213], v[80:83]
	v_mfma_f32_16x16x32_bf16 v[68:71], v[172:175], v[218:221], v[68:71]
	v_mfma_f32_16x16x32_bf16 v[64:67], v[180:183], v[218:221], v[64:67]
	s_setprio 0
	s_barrier
; #define PG8_STAGE(bufoff, gbase, voff) do { _Pragma("unroll") for (int _i = 0; _i < 2; ++_i) \
;         __builtin_amdgcn_global_load_lds((const unsigned*)((const char*)(gbase) + (voff)[_i]), (LAS unsigned*)(lds + (bufoff) + ldsw + _i * 8192), 16, 0, 0); } while (0)
; #define PG8_STAGEB(bufoff, gbase, perm) do { _Pragma("unroll") for (int _i = 0; _i < 2; ++_i) \
;         __builtin_amdgcn_global_load_lds((const unsigned*)((const char*)(gbase) + ((BSEL && (perm)) ? voffBp[_i] : voffB[_i])), (LAS unsigned*)(lds + (bufoff) + ldsw + _i * 8192), 16, 0, 0); } while (0)
; #define PG8_LDA(dst, b, h) do { _Pragma("unroll") for (int m = 0; m < 4; ++m) _Pragma("unroll") for (int k = 0; k < 2; ++k) dst[m][k] = *(const LAS bf16x8*)(lds + PG8_SA(b, h) + aoff + m * 2048 + k * 1024); } while (0)
; #define PG8_MMA(ai, bj, At, Bt) do { __builtin_amdgcn_s_setprio(1); _Pragma("unroll") for (int m = 0; m < 4; ++m) _Pragma("unroll") for (int n = 0; n < 2; ++n) _Pragma("unroll") for (int k = 0; k < 2; ++k) \
;         acc[ai][bj][m][n] = __builtin_amdgcn_mfma_f32_16x16x32_bf16(Bt[n][k], At[m][k], acc[ai][bj][m][n], 0, 0, 0); __builtin_amdgcn_s_setprio(0); } while (0)
; #define PG8_WAIT_V(n) asm volatile("s_waitcnt vmcnt(" #n ")" ::: "memory")
; #define PG8_WAIT_L(n) asm volatile("s_waitcnt lgkmcnt(" #n ")" ::: "memory")
; #define PG8_BAR __builtin_amdgcn_s_barrier()
; #define PG8_SCHED __builtin_amdgcn_sched_barrier(0)
; template <class Epi, bool BSEL = false>
; __device__ __forceinline__ void gemm_phase(LAS unsigned char* lds, const Gemm g, const Order& S, const Epi& E, const int tid) {
;     ...
;             PG8_LDA(At, 1, 1); PG8_STAGEB(PG8_SB(1, 0), b3, p2); PG8_STAGEB(PG8_SB(1, 1), b3 + h2, p2); PG8_STAGE(PG8_SA(1, 0), a3, voffA);
;             PG8_WAIT_V(8); PG8_WAIT_L(0); PG8_BAR; PG8_MMA(1, 0, At, B0); PG8_MMA(1, 1, At, B1); PG8_BAR; PG8_SCHED;
;         }
;         if constexpr (ALIGN_EPI) { if (wr == 0) PG8_BAR; }
	s_add_i32 s42, s56, s15
	v_lshl_add_u64 v[188:189], v[188:189], 0, s[22:23]
	s_mov_b32 m0, s42
	ds_read_b128 v[184:187], v151 offset:49152
	ds_read_b128 v[192:195], v151 offset:50176
	ds_read_b128 v[196:199], v151 offset:51200
	ds_read_b128 v[202:205], v151 offset:52224
	ds_read_b128 v[206:209], v151 offset:53248
	ds_read_b128 v[210:213], v151 offset:54272
	ds_read_b128 v[214:217], v151 offset:55296
	ds_read_b128 v[218:221], v151 offset:56320
	global_load_lds_dwordx4 v[188:189], off
	s_add_i32 m0, s42, 0x2000
	s_add_u32 s40, s40, 0x40080
	v_lshl_add_u64 v[188:189], v[222:223], 0, s[22:23]
	s_addc_u32 s41, s41, 0
	s_add_i32 s42, s57, s15
	global_load_lds_dwordx4 v[188:189], off
	v_lshl_add_u64 v[188:189], s[40:41], 0, v[132:133]
	s_mov_b32 m0, s42
	s_nop 0
	global_load_lds_dwordx4 v[188:189], off
	v_lshl_add_u64 v[188:189], s[40:41], 0, v[136:137]
	s_add_i32 m0, s42, 0x2000
	s_nop 0
	global_load_lds_dwordx4 v[188:189], off
	v_lshl_add_u64 v[188:189], v[224:225], 0, s[22:23]
	s_mov_b32 m0, s45
	s_nop 0
	global_load_lds_dwordx4 v[188:189], off
	v_lshl_add_u64 v[188:189], v[226:227], 0, s[22:23]
	s_mov_b32 m0, s46
	s_nop 0
	global_load_lds_dwordx4 v[188:189], off
	s_waitcnt vmcnt(8)
	s_waitcnt lgkmcnt(0)
	s_barrier
	s_setprio 1
	v_mfma_f32_16x16x32_bf16 v[60:63], v[152:155], v[184:187], v[60:63]
	v_mfma_f32_16x16x32_bf16 v[56:59], v[160:163], v[184:187], v[56:59]
	v_mfma_f32_16x16x32_bf16 v[44:47], v[152:155], v[196:199], v[44:47]
	v_mfma_f32_16x16x32_bf16 v[40:43], v[160:163], v[196:199], v[40:43]
	v_mfma_f32_16x16x32_bf16 v[28:31], v[152:155], v[206:209], v[28:31]
	v_mfma_f32_16x16x32_bf16 v[24:27], v[160:163], v[206:209], v[24:27]
	v_mfma_f32_16x16x32_bf16 v[12:15], v[152:155], v[214:217], v[12:15]
	v_mfma_f32_16x16x32_bf16 v[8:11], v[160:163], v[214:217], v[8:11]
	v_mfma_f32_16x16x32_bf16 v[60:63], v[156:159], v[192:195], v[60:63]
	v_mfma_f32_16x16x32_bf16 v[56:59], v[164:167], v[192:195], v[56:59]
	v_mfma_f32_16x16x32_bf16 v[44:47], v[156:159], v[202:205], v[44:47]
	v_mfma_f32_16x16x32_bf16 v[40:43], v[164:167], v[202:205], v[40:43]
	v_mfma_f32_16x16x32_bf16 v[28:31], v[156:159], v[210:213], v[28:31]
	v_mfma_f32_16x16x32_bf16 v[24:27], v[164:167], v[210:213], v[24:27]
	v_mfma_f32_16x16x32_bf16 v[12:15], v[156:159], v[218:221], v[12:15]
	v_mfma_f32_16x16x32_bf16 v[8:11], v[164:167], v[218:221], v[8:11]
	v_mfma_f32_16x16x32_bf16 v[52:55], v[168:171], v[184:187], v[52:55]
	v_mfma_f32_16x16x32_bf16 v[48:51], v[176:179], v[184:187], v[48:51]
	v_mfma_f32_16x16x32_bf16 v[36:39], v[168:171], v[196:199], v[36:39]
	v_mfma_f32_16x16x32_bf16 v[32:35], v[176:179], v[196:199], v[32:35]
	v_mfma_f32_16x16x32_bf16 v[20:23], v[168:171], v[206:209], v[20:23]
	v_mfma_f32_16x16x32_bf16 v[16:19], v[176:179], v[206:209], v[16:19]
	v_mfma_f32_16x16x32_bf16 v[4:7], v[168:171], v[214:217], v[4:7]
	v_mfma_f32_16x16x32_bf16 v[0:3], v[176:179], v[214:217], v[0:3]
	v_mfma_f32_16x16x32_bf16 v[52:55], v[172:175], v[192:195], v[52:55]
	v_mfma_f32_16x16x32_bf16 v[48:51], v[180:183], v[192:195], v[48:51]
	v_mfma_f32_16x16x32_bf16 v[36:39], v[172:175], v[202:205], v[36:39]
	v_mfma_f32_16x16x32_bf16 v[32:35], v[180:183], v[202:205], v[32:35]
	v_mfma_f32_16x16x32_bf16 v[20:23], v[172:175], v[210:213], v[20:23]
	v_mfma_f32_16x16x32_bf16 v[16:19], v[180:183], v[210:213], v[16:19]
	v_mfma_f32_16x16x32_bf16 v[4:7], v[172:175], v[218:221], v[4:7]
	v_mfma_f32_16x16x32_bf16 v[0:3], v[180:183], v[218:221], v[0:3]
	s_setprio 0
	s_barrier
	s_add_i32 s55, s55, 2
	s_add_u32 s38, s38, 0x100
	s_addc_u32 s39, s39, 0
	s_cmp_gt_u32 s55, 13
	s_cbranch_scc0 .LBB0_1101
	s_and_b64 vcc, exec, s[24:25]
	s_cbranch_vccz .LBB0_1104
	s_barrier

; #define PG8_STAGE(bufoff, gbase, voff) do { _Pragma("unroll") for (int _i = 0; _i < 2; ++_i) \
;         __builtin_amdgcn_global_load_lds((const unsigned*)((const char*)(gbase) + (voff)[_i]), (LAS unsigned*)(lds + (bufoff) + ldsw + _i * 8192), 16, 0, 0); } while (0)
; #define PG8_STAGEB(bufoff, gbase, perm) do { _Pragma("unroll") for (int _i = 0; _i < 2; ++_i) \
;         __builtin_amdgcn_global_load_lds((const unsigned*)((const char*)(gbase) + ((BSEL && (perm)) ? voffBp[_i] : voffB[_i])), (LAS unsigned*)(lds + (bufoff) + ldsw + _i * 8192), 16, 0, 0); } while (0)
; #define PG8_LDA(dst, b, h) do { _Pragma("unroll") for (int m = 0; m < 4; ++m) _Pragma("unroll") for (int k = 0; k < 2; ++k) dst[m][k] = *(const LAS bf16x8*)(lds + PG8_SA(b, h) + aoff + m * 2048 + k * 1024); } while (0)
; #define PG8_LDB(dst, b, h) do { _Pragma("unroll") for (int n = 0; n < 2; ++n) _Pragma("unroll") for (int k = 0; k < 2; ++k) dst[n][k] = *(const LAS bf16x8*)(lds + PG8_SB(b, h) + boff + n * 2048 + k * 1024); } while (0)
; #define PG8_WAIT_V(n) asm volatile("s_waitcnt vmcnt(" #n ")" ::: "memory")
; #define PG8_WAIT_L(n) asm volatile("s_waitcnt lgkmcnt(" #n ")" ::: "memory")
; #define PG8_BAR __builtin_amdgcn_s_barrier()
; #define PG8_SCHED __builtin_amdgcn_sched_barrier(0)
; template <class Epi, bool BSEL = false>
; __device__ __forceinline__ void gemm_phase(LAS unsigned char* lds, const Gemm g, const Order& S, const Epi& E, const int tid) {
;     ...
;         for (int t = 0; t < nt; t += 2) {
;             const bool last = (t == nt - 2);
;             const char* a1 = cA + (size_t)(t + 1) * kstep;
;             const char* a2 = last ? nA : cA + (size_t)(t + 2) * kstep; const char* b2 = last ? nB : cB + (size_t)(t + 2) * kstep;
;             const char* a3 = a2 + kstep; const char* b3 = b2 + kstep;
;             const bool p2 = last ? nP : cP; const size_t h2 = last ? nhB : chB;
;             PG8_LDB(B0, 0, 0); PG8_LDB(B1, 0, 1); PG8_SCHED; PG8_LDA(At, 0, 0); PG8_STAGE(PG8_SA(1, 1), a1 + hstepA, voffA);
;             PG8_WAIT_V(8); PG8_WAIT_L(0); PG8_BAR; PG8_MMA(0, 0, At, B0); PG8_MMA(0, 1, At, B1); PG8_BAR; PG8_SCHED;
;             PG8_LDA(At, 0, 1); PG8_STAGEB(PG8_SB(0, 0), b2, p2); PG8_STAGEB(PG8_SB(0, 1), b2 + h2, p2); PG8_STAGE(PG8_SA(0, 0), a2, voffA);
;             PG8_WAIT_V(8); PG8_WAIT_L(0); PG8_BAR; PG8_MMA(1, 0, At, B0); PG8_MMA(1, 1, At, B1); PG8_BAR; PG8_SCHED;
.LBB0_1271:
	v_add_u32_e32 v162, s45, v147
	v_add_u32_e32 v178, s46, v147
	s_add_u32 s2, s8, s40
	ds_read_b128 v[150:153], v162
	ds_read_b128 v[154:157], v162 offset:1024
	ds_read_b128 v[158:161], v162 offset:2048
	ds_read_b128 v[162:165], v162 offset:3072
	ds_read_b128 v[166:169], v178
	ds_read_b128 v[170:173], v178 offset:1024
	ds_read_b128 v[174:177], v178 offset:2048
	ds_read_b128 v[178:181], v178 offset:3072
	s_addc_u32 s3, s9, s41
	s_add_u32 s2, s2, 0x100
	s_addc_u32 s3, s3, 0
	s_add_u32 s57, s27, s40
	s_addc_u32 s58, s51, s41
	s_cmpk_eq_i32 s40, 0x700
	s_cselect_b32 s37, s52, s3
	s_cselect_b32 s36, s53, s2
	s_cselect_b32 s3, s54, s58
	s_cselect_b32 s2, s55, s57
	v_lshl_add_u64 v[198:199], v[142:143], 0, s[40:41]
	s_add_i32 m0, s7, 0xc000
	ds_read_b128 v[182:185], v149
	ds_read_b128 v[186:189], v149 offset:1024
	ds_read_b128 v[190:193], v149 offset:2048
	ds_read_b128 v[194:197], v149 offset:3072
	ds_read_b128 v[202:205], v149 offset:4096
	ds_read_b128 v[206:209], v149 offset:5120
	ds_read_b128 v[210:213], v149 offset:6144
	ds_read_b128 v[214:217], v149 offset:7168
	global_load_lds_dwordx4 v[198:199], off
	v_lshl_add_u64 v[198:199], v[144:145], 0, s[40:41]
	s_add_i32 m0, s7, 0xe000
	s_nop 0
	global_load_lds_dwordx4 v[198:199], off
	s_waitcnt vmcnt(8)
	s_waitcnt lgkmcnt(0)
	s_barrier
	s_setprio 1
	v_mfma_f32_16x16x32_bf16 v[124:127], v[150:153], v[182:185], v[124:127]
	v_mfma_f32_16x16x32_bf16 v[120:123], v[158:161], v[182:185], v[120:123]
	v_mfma_f32_16x16x32_bf16 v[116:119], v[150:153], v[190:193], v[116:119]
	v_mfma_f32_16x16x32_bf16 v[112:115], v[158:161], v[190:193], v[112:115]
	v_mfma_f32_16x16x32_bf16 v[108:111], v[150:153], v[202:205], v[108:111]
	v_mfma_f32_16x16x32_bf16 v[104:107], v[158:161], v[202:205], v[104:107]
	v_mfma_f32_16x16x32_bf16 v[100:103], v[150:153], v[210:213], v[100:103]
	v_mfma_f32_16x16x32_bf16 v[96:99], v[158:161], v[210:213], v[96:99]
	v_mfma_f32_16x16x32_bf16 v[124:127], v[154:157], v[186:189], v[124:127]
	v_mfma_f32_16x16x32_bf16 v[120:123], v[162:165], v[186:189], v[120:123]
	v_mfma_f32_16x16x32_bf16 v[116:119], v[154:157], v[194:197], v[116:119]
	v_mfma_f32_16x16x32_bf16 v[112:115], v[162:165], v[194:197], v[112:115]
	v_mfma_f32_16x16x32_bf16 v[108:111], v[154:157], v[206:209], v[108:111]
	v_mfma_f32_16x16x32_bf16 v[104:107], v[162:165], v[206:209], v[104:107]
	v_mfma_f32_16x16x32_bf16 v[100:103], v[154:157], v[214:217], v[100:103]
	v_mfma_f32_16x16x32_bf16 v[96:99], v[162:165], v[214:217], v[96:99]
	v_mfma_f32_16x16x32_bf16 v[92:95], v[166:169], v[182:185], v[92:95]
	v_mfma_f32_16x16x32_bf16 v[88:91], v[174:177], v[182:185], v[88:91]
	v_mfma_f32_16x16x32_bf16 v[84:87], v[166:169], v[190:193], v[84:87]
	v_mfma_f32_16x16x32_bf16 v[80:83], v[174:177], v[190:193], v[80:83]
	v_mfma_f32_16x16x32_bf16 v[76:79], v[166:169], v[202:205], v[76:79]
	v_mfma_f32_16x16x32_bf16 v[72:75], v[174:177], v[202:205], v[72:75]
	v_mfma_f32_16x16x32_bf16 v[68:71], v[166:169], v[210:213], v[68:71]
	v_mfma_f32_16x16x32_bf16 v[64:67], v[174:177], v[210:213], v[64:67]
	v_mfma_f32_16x16x32_bf16 v[92:95], v[170:173], v[186:189], v[92:95]
	v_mfma_f32_16x16x32_bf16 v[88:91], v[178:181], v[186:189], v[88:91]
	v_mfma_f32_16x16x32_bf16 v[84:87], v[170:173], v[194:197], v[84:87]
	v_mfma_f32_16x16x32_bf16 v[80:83], v[178:181], v[194:197], v[80:83]
	v_mfma_f32_16x16x32_bf16 v[76:79], v[170:173], v[206:209], v[76:79]
	v_mfma_f32_16x16x32_bf16 v[72:75], v[178:181], v[206:209], v[72:75]
	v_mfma_f32_16x16x32_bf16 v[68:71], v[170:173], v[214:217], v[68:71]
	v_mfma_f32_16x16x32_bf16 v[64:67], v[178:181], v[214:217], v[64:67]
	s_setprio 0
	s_barrier
	s_add_i32 s57, s45, s12
	v_lshl_add_u64 v[198:199], s[2:3], 0, v[132:133]
	s_mov_b32 m0, s57
	ds_read_b128 v[182:185], v149 offset:16384
	ds_read_b128 v[186:189], v149 offset:17408
	ds_read_b128 v[190:193], v149 offset:18432
	ds_read_b128 v[194:197], v149 offset:19456
	ds_read_b128 v[202:205], v149 offset:20480
	ds_read_b128 v[206:209], v149 offset:21504
	ds_read_b128 v[210:213], v149 offset:22528
	ds_read_b128 v[214:217], v149 offset:23552
	global_load_lds_dwordx4 v[198:199], off
	s_add_i32 m0, s57, 0x2000
	s_add_u32 s58, s2, 0x40000
	v_lshl_add_u64 v[218:219], s[2:3], 0, v[128:129]
	s_addc_u32 s59, s3, 0
	s_add_i32 s57, s46, s12
	global_load_lds_dwordx4 v[218:219], off
	v_lshl_add_u64 v[220:221], s[58:59], 0, v[132:133]
	s_mov_b32 m0, s57
	v_lshl_add_u64 v[222:223], s[36:37], 0, v[130:131]
	global_load_lds_dwordx4 v[220:221], off
	v_lshl_add_u64 v[220:221], s[58:59], 0, v[128:129]
	s_add_i32 m0, s57, 0x2000
	s_nop 0
	global_load_lds_dwordx4 v[220:221], off
	v_lshl_add_u64 v[220:221], s[36:37], 0, v[134:135]
	s_mov_b32 m0, s7
	s_nop 0
	global_load_lds_dwordx4 v[220:221], off
	s_mov_b32 m0, s15
	s_nop 0
	global_load_lds_dwordx4 v[222:223], off
	s_waitcnt vmcnt(8)
	s_waitcnt lgkmcnt(0)
	s_barrier
; #define PG8_STAGE(bufoff, gbase, voff) do { _Pragma("unroll") for (int _i = 0; _i < 2; ++_i) \
;         __builtin_amdgcn_global_load_lds((const unsigned*)((const char*)(gbase) + (voff)[_i]), (LAS unsigned*)(lds + (bufoff) + ldsw + _i * 8192), 16, 0, 0); } while (0)
; #define PG8_LDA(dst, b, h) do { _Pragma("unroll") for (int m = 0; m < 4; ++m) _Pragma("unroll") for (int k = 0; k < 2; ++k) dst[m][k] = *(const LAS bf16x8*)(lds + PG8_SA(b, h) + aoff + m * 2048 + k * 1024); } while (0)
; #define PG8_LDB(dst, b, h) do { _Pragma("unroll") for (int n = 0; n < 2; ++n) _Pragma("unroll") for (int k = 0; k < 2; ++k) dst[n][k] = *(const LAS bf16x8*)(lds + PG8_SB(b, h) + boff + n * 2048 + k * 1024); } while (0)
; #define PG8_MMA(ai, bj, At, Bt) do { __builtin_amdgcn_s_setprio(1); _Pragma("unroll") for (int m = 0; m < 4; ++m) _Pragma("unroll") for (int n = 0; n < 2; ++n) _Pragma("unroll") for (int k = 0; k < 2; ++k) \
;         acc[ai][bj][m][n] = __builtin_amdgcn_mfma_f32_16x16x32_bf16(Bt[n][k], At[m][k], acc[ai][bj][m][n], 0, 0, 0); __builtin_amdgcn_s_setprio(0); } while (0)
; #define PG8_WAIT_V(n) asm volatile("s_waitcnt vmcnt(" #n ")" ::: "memory")
; #define PG8_WAIT_L(n) asm volatile("s_waitcnt lgkmcnt(" #n ")" ::: "memory")
; #define PG8_BAR __builtin_amdgcn_s_barrier()
; #define PG8_SCHED __builtin_amdgcn_sched_barrier(0)
; template <class Epi, bool BSEL = false>
; __device__ __forceinline__ void gemm_phase(LAS unsigned char* lds, const Gemm g, const Order& S, const Epi& E, const int tid) {
;     ...
;             PG8_WAIT_V(8); PG8_WAIT_L(0); PG8_BAR; PG8_MMA(1, 0, At, B0); PG8_MMA(1, 1, At, B1); PG8_BAR; PG8_SCHED;
;             PG8_LDB(B0, 1, 0); PG8_LDB(B1, 1, 1); PG8_SCHED; PG8_LDA(At, 1, 0); PG8_STAGE(PG8_SA(0, 1), a2 + hstepA, voffA);
;             PG8_WAIT_V(8); PG8_WAIT_L(0); PG8_BAR; PG8_MMA(0, 0, At, B0); PG8_MMA(0, 1, At, B1); PG8_BAR; PG8_SCHED;
	s_setprio 1
	v_mfma_f32_16x16x32_bf16 v[60:63], v[150:153], v[182:185], v[60:63]
	v_mfma_f32_16x16x32_bf16 v[56:59], v[158:161], v[182:185], v[56:59]
	v_mfma_f32_16x16x32_bf16 v[52:55], v[150:153], v[190:193], v[52:55]
	v_mfma_f32_16x16x32_bf16 v[48:51], v[158:161], v[190:193], v[48:51]
	v_mfma_f32_16x16x32_bf16 v[44:47], v[150:153], v[202:205], v[44:47]
	v_mfma_f32_16x16x32_bf16 v[40:43], v[158:161], v[202:205], v[40:43]
	v_mfma_f32_16x16x32_bf16 v[36:39], v[150:153], v[210:213], v[36:39]
	v_mfma_f32_16x16x32_bf16 v[32:35], v[158:161], v[210:213], v[32:35]
	v_mfma_f32_16x16x32_bf16 v[60:63], v[154:157], v[186:189], v[60:63]
	v_mfma_f32_16x16x32_bf16 v[56:59], v[162:165], v[186:189], v[56:59]
	v_mfma_f32_16x16x32_bf16 v[52:55], v[154:157], v[194:197], v[52:55]
	v_mfma_f32_16x16x32_bf16 v[48:51], v[162:165], v[194:197], v[48:51]
	v_mfma_f32_16x16x32_bf16 v[44:47], v[154:157], v[206:209], v[44:47]
	v_mfma_f32_16x16x32_bf16 v[40:43], v[162:165], v[206:209], v[40:43]
	v_mfma_f32_16x16x32_bf16 v[36:39], v[154:157], v[214:217], v[36:39]
	v_mfma_f32_16x16x32_bf16 v[32:35], v[162:165], v[214:217], v[32:35]
	v_mfma_f32_16x16x32_bf16 v[28:31], v[166:169], v[182:185], v[28:31]
	v_mfma_f32_16x16x32_bf16 v[24:27], v[174:177], v[182:185], v[24:27]
	v_mfma_f32_16x16x32_bf16 v[20:23], v[166:169], v[190:193], v[20:23]
	v_mfma_f32_16x16x32_bf16 v[16:19], v[174:177], v[190:193], v[16:19]
	v_mfma_f32_16x16x32_bf16 v[12:15], v[166:169], v[202:205], v[12:15]
	v_mfma_f32_16x16x32_bf16 v[8:11], v[174:177], v[202:205], v[8:11]
	v_mfma_f32_16x16x32_bf16 v[4:7], v[166:169], v[210:213], v[4:7]
	v_mfma_f32_16x16x32_bf16 v[0:3], v[174:177], v[210:213], v[0:3]
	v_mfma_f32_16x16x32_bf16 v[28:31], v[170:173], v[186:189], v[28:31]
	v_mfma_f32_16x16x32_bf16 v[24:27], v[178:181], v[186:189], v[24:27]
	v_mfma_f32_16x16x32_bf16 v[20:23], v[170:173], v[194:197], v[20:23]
	v_mfma_f32_16x16x32_bf16 v[16:19], v[178:181], v[194:197], v[16:19]
	v_mfma_f32_16x16x32_bf16 v[12:15], v[170:173], v[206:209], v[12:15]
	v_mfma_f32_16x16x32_bf16 v[8:11], v[178:181], v[206:209], v[8:11]
	v_mfma_f32_16x16x32_bf16 v[4:7], v[170:173], v[214:217], v[4:7]
	v_mfma_f32_16x16x32_bf16 v[0:3], v[178:181], v[214:217], v[0:3]
	s_setprio 0
	s_barrier
	s_add_i32 s57, 0, 0x18000
	s_add_i32 s58, 0, 0x1c000
	v_add_u32_e32 v162, s57, v147
	v_add_u32_e32 v178, s58, v147
	ds_read_b128 v[150:153], v162
	ds_read_b128 v[154:157], v162 offset:1024
	ds_read_b128 v[158:161], v162 offset:2048
	ds_read_b128 v[162:165], v162 offset:3072
	ds_read_b128 v[166:169], v178
	ds_read_b128 v[170:173], v178 offset:1024
	ds_read_b128 v[174:177], v178 offset:2048
	ds_read_b128 v[178:181], v178 offset:3072
	s_add_u32 s36, s36, 0x40000
	s_addc_u32 s37, s37, 0
	s_mov_b32 m0, s20
	v_lshl_add_u64 v[224:225], s[36:37], 0, v[134:135]
	ds_read_b128 v[182:185], v149 offset:32768
	ds_read_b128 v[186:189], v149 offset:33792
	ds_read_b128 v[190:193], v149 offset:34816
	ds_read_b128 v[194:197], v149 offset:35840
	ds_read_b128 v[202:205], v149 offset:36864
	ds_read_b128 v[206:209], v149 offset:37888
	ds_read_b128 v[210:213], v149 offset:38912
	ds_read_b128 v[214:217], v149 offset:39936
	global_load_lds_dwordx4 v[224:225], off
	v_lshl_add_u64 v[224:225], s[36:37], 0, v[130:131]
	s_mov_b32 m0, s21
	s_nop 0
	global_load_lds_dwordx4 v[224:225], off
	s_waitcnt vmcnt(8)
	s_waitcnt lgkmcnt(0)
	s_barrier
	s_setprio 1
	v_mfma_f32_16x16x32_bf16 v[124:127], v[150:153], v[182:185], v[124:127]
	v_mfma_f32_16x16x32_bf16 v[120:123], v[158:161], v[182:185], v[120:123]
	v_mfma_f32_16x16x32_bf16 v[116:119], v[150:153], v[190:193], v[116:119]
	v_mfma_f32_16x16x32_bf16 v[112:115], v[158:161], v[190:193], v[112:115]
	v_mfma_f32_16x16x32_bf16 v[108:111], v[150:153], v[202:205], v[108:111]
	v_mfma_f32_16x16x32_bf16 v[104:107], v[158:161], v[202:205], v[104:107]
	v_mfma_f32_16x16x32_bf16 v[100:103], v[150:153], v[210:213], v[100:103]
	v_mfma_f32_16x16x32_bf16 v[96:99], v[158:161], v[210:213], v[96:99]
	v_mfma_f32_16x16x32_bf16 v[124:127], v[154:157], v[186:189], v[124:127]
	v_mfma_f32_16x16x32_bf16 v[120:123], v[162:165], v[186:189], v[120:123]
	v_mfma_f32_16x16x32_bf16 v[116:119], v[154:157], v[194:197], v[116:119]
	v_mfma_f32_16x16x32_bf16 v[112:115], v[162:165], v[194:197], v[112:115]
	v_mfma_f32_16x16x32_bf16 v[108:111], v[154:157], v[206:209], v[108:111]
	v_mfma_f32_16x16x32_bf16 v[104:107], v[162:165], v[206:209], v[104:107]
	v_mfma_f32_16x16x32_bf16 v[100:103], v[154:157], v[214:217], v[100:103]
	v_mfma_f32_16x16x32_bf16 v[96:99], v[162:165], v[214:217], v[96:99]
	v_mfma_f32_16x16x32_bf16 v[92:95], v[166:169], v[182:185], v[92:95]
	v_mfma_f32_16x16x32_bf16 v[88:91], v[174:177], v[182:185], v[88:91]
	v_mfma_f32_16x16x32_bf16 v[84:87], v[166:169], v[190:193], v[84:87]
	v_mfma_f32_16x16x32_bf16 v[80:83], v[174:177], v[190:193], v[80:83]
	v_mfma_f32_16x16x32_bf16 v[76:79], v[166:169], v[202:205], v[76:79]
	v_mfma_f32_16x16x32_bf16 v[72:75], v[174:177], v[202:205], v[72:75]
	v_mfma_f32_16x16x32_bf16 v[68:71], v[166:169], v[210:213], v[68:71]
	v_mfma_f32_16x16x32_bf16 v[64:67], v[174:177], v[210:213], v[64:67]
	v_mfma_f32_16x16x32_bf16 v[92:95], v[170:173], v[186:189], v[92:95]
	v_mfma_f32_16x16x32_bf16 v[88:91], v[178:181], v[186:189], v[88:91]
	v_mfma_f32_16x16x32_bf16 v[84:87], v[170:173], v[194:197], v[84:87]
	v_mfma_f32_16x16x32_bf16 v[80:83], v[178:181], v[194:197], v[80:83]
	v_mfma_f32_16x16x32_bf16 v[76:79], v[170:173], v[206:209], v[76:79]
	v_mfma_f32_16x16x32_bf16 v[72:75], v[178:181], v[206:209], v[72:75]
	v_mfma_f32_16x16x32_bf16 v[68:71], v[170:173], v[214:217], v[68:71]
	v_mfma_f32_16x16x32_bf16 v[64:67], v[178:181], v[214:217], v[64:67]
	s_setprio 0
	s_barrier
; #define PG8_STAGE(bufoff, gbase, voff) do { _Pragma("unroll") for (int _i = 0; _i < 2; ++_i) \
;         __builtin_amdgcn_global_load_lds((const unsigned*)((const char*)(gbase) + (voff)[_i]), (LAS unsigned*)(lds + (bufoff) + ldsw + _i * 8192), 16, 0, 0); } while (0)
; #define PG8_STAGEB(bufoff, gbase, perm) do { _Pragma("unroll") for (int _i = 0; _i < 2; ++_i) \
;         __builtin_amdgcn_global_load_lds((const unsigned*)((const char*)(gbase) + ((BSEL && (perm)) ? voffBp[_i] : voffB[_i])), (LAS unsigned*)(lds + (bufoff) + ldsw + _i * 8192), 16, 0, 0); } while (0)
; #define PG8_LDA(dst, b, h) do { _Pragma("unroll") for (int m = 0; m < 4; ++m) _Pragma("unroll") for (int k = 0; k < 2; ++k) dst[m][k] = *(const LAS bf16x8*)(lds + PG8_SA(b, h) + aoff + m * 2048 + k * 1024); } while (0)
; #define PG8_MMA(ai, bj, At, Bt) do { __builtin_amdgcn_s_setprio(1); _Pragma("unroll") for (int m = 0; m < 4; ++m) _Pragma("unroll") for (int n = 0; n < 2; ++n) _Pragma("unroll") for (int k = 0; k < 2; ++k) \
;         acc[ai][bj][m][n] = __builtin_amdgcn_mfma_f32_16x16x32_bf16(Bt[n][k], At[m][k], acc[ai][bj][m][n], 0, 0, 0); __builtin_amdgcn_s_setprio(0); } while (0)
; #define PG8_WAIT_V(n) asm volatile("s_waitcnt vmcnt(" #n ")" ::: "memory")
; #define PG8_WAIT_L(n) asm volatile("s_waitcnt lgkmcnt(" #n ")" ::: "memory")
; #define PG8_BAR __builtin_amdgcn_s_barrier()
; #define PG8_SCHED __builtin_amdgcn_sched_barrier(0)
; template <class Epi, bool BSEL = false>
; __device__ __forceinline__ void gemm_phase(LAS unsigned char* lds, const Gemm g, const Order& S, const Epi& E, const int tid) {
;     ...
;             PG8_LDA(At, 1, 1); PG8_STAGEB(PG8_SB(1, 0), b3, p2); PG8_STAGEB(PG8_SB(1, 1), b3 + h2, p2); PG8_STAGE(PG8_SA(1, 0), a3, voffA);
;             PG8_WAIT_V(8); PG8_WAIT_L(0); PG8_BAR; PG8_MMA(1, 0, At, B0); PG8_MMA(1, 1, At, B1); PG8_BAR; PG8_SCHED;
;         }
;         if constexpr (ALIGN_EPI) { if (wr == 0) PG8_BAR; }
	s_add_i32 s36, s57, s12
	v_lshl_add_u64 v[198:199], v[198:199], 0, s[22:23]
	s_mov_b32 m0, s36
	ds_read_b128 v[182:185], v149 offset:49152
	ds_read_b128 v[186:189], v149 offset:50176
	ds_read_b128 v[190:193], v149 offset:51200
	ds_read_b128 v[194:197], v149 offset:52224
	ds_read_b128 v[202:205], v149 offset:53248
	ds_read_b128 v[206:209], v149 offset:54272
	ds_read_b128 v[210:213], v149 offset:55296
	ds_read_b128 v[214:217], v149 offset:56320
	global_load_lds_dwordx4 v[198:199], off
	s_add_i32 m0, s36, 0x2000
	s_add_u32 s2, s2, 0x40080
	v_lshl_add_u64 v[198:199], v[218:219], 0, s[22:23]
	s_addc_u32 s3, s3, 0
	s_add_i32 s36, s58, s12
	global_load_lds_dwordx4 v[198:199], off
	v_lshl_add_u64 v[198:199], s[2:3], 0, v[132:133]
	s_mov_b32 m0, s36
	s_nop 0
	global_load_lds_dwordx4 v[198:199], off
	v_lshl_add_u64 v[198:199], s[2:3], 0, v[128:129]
	s_add_i32 m0, s36, 0x2000
	s_nop 0
	global_load_lds_dwordx4 v[198:199], off
	v_lshl_add_u64 v[198:199], v[220:221], 0, s[22:23]
	s_mov_b32 m0, s43
	s_nop 0
	global_load_lds_dwordx4 v[198:199], off
	v_lshl_add_u64 v[198:199], v[222:223], 0, s[22:23]
	s_mov_b32 m0, s44
	s_nop 0
	global_load_lds_dwordx4 v[198:199], off
	s_waitcnt vmcnt(8)
	s_waitcnt lgkmcnt(0)
	s_barrier
	s_setprio 1
	v_mfma_f32_16x16x32_bf16 v[60:63], v[150:153], v[182:185], v[60:63]
	v_mfma_f32_16x16x32_bf16 v[56:59], v[158:161], v[182:185], v[56:59]
	v_mfma_f32_16x16x32_bf16 v[52:55], v[150:153], v[190:193], v[52:55]
	v_mfma_f32_16x16x32_bf16 v[48:51], v[158:161], v[190:193], v[48:51]
	v_mfma_f32_16x16x32_bf16 v[44:47], v[150:153], v[202:205], v[44:47]
	v_mfma_f32_16x16x32_bf16 v[40:43], v[158:161], v[202:205], v[40:43]
	v_mfma_f32_16x16x32_bf16 v[36:39], v[150:153], v[210:213], v[36:39]
	v_mfma_f32_16x16x32_bf16 v[32:35], v[158:161], v[210:213], v[32:35]
	v_mfma_f32_16x16x32_bf16 v[60:63], v[154:157], v[186:189], v[60:63]
	v_mfma_f32_16x16x32_bf16 v[56:59], v[162:165], v[186:189], v[56:59]
	v_mfma_f32_16x16x32_bf16 v[52:55], v[154:157], v[194:197], v[52:55]
	v_mfma_f32_16x16x32_bf16 v[48:51], v[162:165], v[194:197], v[48:51]
	v_mfma_f32_16x16x32_bf16 v[44:47], v[154:157], v[206:209], v[44:47]
	v_mfma_f32_16x16x32_bf16 v[40:43], v[162:165], v[206:209], v[40:43]
	v_mfma_f32_16x16x32_bf16 v[36:39], v[154:157], v[214:217], v[36:39]
	v_mfma_f32_16x16x32_bf16 v[32:35], v[162:165], v[214:217], v[32:35]
	v_mfma_f32_16x16x32_bf16 v[28:31], v[166:169], v[182:185], v[28:31]
	v_mfma_f32_16x16x32_bf16 v[24:27], v[174:177], v[182:185], v[24:27]
	v_mfma_f32_16x16x32_bf16 v[20:23], v[166:169], v[190:193], v[20:23]
	v_mfma_f32_16x16x32_bf16 v[16:19], v[174:177], v[190:193], v[16:19]
	v_mfma_f32_16x16x32_bf16 v[12:15], v[166:169], v[202:205], v[12:15]
	v_mfma_f32_16x16x32_bf16 v[8:11], v[174:177], v[202:205], v[8:11]
	v_mfma_f32_16x16x32_bf16 v[4:7], v[166:169], v[210:213], v[4:7]
	v_mfma_f32_16x16x32_bf16 v[0:3], v[174:177], v[210:213], v[0:3]
	v_mfma_f32_16x16x32_bf16 v[28:31], v[170:173], v[186:189], v[28:31]
	v_mfma_f32_16x16x32_bf16 v[24:27], v[178:181], v[186:189], v[24:27]
	v_mfma_f32_16x16x32_bf16 v[20:23], v[170:173], v[194:197], v[20:23]
	v_mfma_f32_16x16x32_bf16 v[16:19], v[178:181], v[194:197], v[16:19]
	v_mfma_f32_16x16x32_bf16 v[12:15], v[170:173], v[206:209], v[12:15]
	v_mfma_f32_16x16x32_bf16 v[8:11], v[178:181], v[206:209], v[8:11]
	v_mfma_f32_16x16x32_bf16 v[4:7], v[170:173], v[214:217], v[4:7]
	v_mfma_f32_16x16x32_bf16 v[0:3], v[178:181], v[214:217], v[0:3]
	s_setprio 0
	s_barrier
	s_add_i32 s56, s56, 2
	s_add_u32 s40, s40, 0x100
	s_addc_u32 s41, s41, 0
	s_cmp_gt_u32 s56, 13
	s_cbranch_scc0 .LBB0_1271
	s_and_b64 vcc, exec, s[24:25]
	s_cbranch_vccz .LBB0_1274
	s_barrier

; #define PG8_STAGE(bufoff, gbase, voff) do { _Pragma("unroll") for (int _i = 0; _i < 2; ++_i) \
;         __builtin_amdgcn_global_load_lds((const unsigned*)((const char*)(gbase) + (voff)[_i]), (LAS unsigned*)(lds + (bufoff) + ldsw + _i * 8192), 16, 0, 0); } while (0)
; #define PG8_STAGEB(bufoff, gbase, perm) do { _Pragma("unroll") for (int _i = 0; _i < 2; ++_i) \
;         __builtin_amdgcn_global_load_lds((const unsigned*)((const char*)(gbase) + ((BSEL && (perm)) ? voffBp[_i] : voffB[_i])), (LAS unsigned*)(lds + (bufoff) + ldsw + _i * 8192), 16, 0, 0); } while (0)
; #define PG8_LDA(dst, b, h) do { _Pragma("unroll") for (int m = 0; m < 4; ++m) _Pragma("unroll") for (int k = 0; k < 2; ++k) dst[m][k] = *(const LAS bf16x8*)(lds + PG8_SA(b, h) + aoff + m * 2048 + k * 1024); } while (0)
; #define PG8_LDB(dst, b, h) do { _Pragma("unroll") for (int n = 0; n < 2; ++n) _Pragma("unroll") for (int k = 0; k < 2; ++k) dst[n][k] = *(const LAS bf16x8*)(lds + PG8_SB(b, h) + boff + n * 2048 + k * 1024); } while (0)
; #define PG8_WAIT_V(n) asm volatile("s_waitcnt vmcnt(" #n ")" ::: "memory")
; #define PG8_WAIT_L(n) asm volatile("s_waitcnt lgkmcnt(" #n ")" ::: "memory")
; #define PG8_BAR __builtin_amdgcn_s_barrier()
; #define PG8_SCHED __builtin_amdgcn_sched_barrier(0)
; template <class Epi, bool BSEL = false>
; __device__ __forceinline__ void gemm_phase(LAS unsigned char* lds, const Gemm g, const Order& S, const Epi& E, const int tid) {
;     ...
;         for (int t = 0; t < nt; t += 2) {
;             const bool last = (t == nt - 2);
;             const char* a1 = cA + (size_t)(t + 1) * kstep;
;             const char* a2 = last ? nA : cA + (size_t)(t + 2) * kstep; const char* b2 = last ? nB : cB + (size_t)(t + 2) * kstep;
;             const char* a3 = a2 + kstep; const char* b3 = b2 + kstep;
;             const bool p2 = last ? nP : cP; const size_t h2 = last ? nhB : chB;
;             PG8_LDB(B0, 0, 0); PG8_LDB(B1, 0, 1); PG8_SCHED; PG8_LDA(At, 0, 0); PG8_STAGE(PG8_SA(1, 1), a1 + hstepA, voffA);
;             PG8_WAIT_V(8); PG8_WAIT_L(0); PG8_BAR; PG8_MMA(0, 0, At, B0); PG8_MMA(0, 1, At, B1); PG8_BAR; PG8_SCHED;
;             PG8_LDA(At, 0, 1); PG8_STAGEB(PG8_SB(0, 0), b2, p2); PG8_STAGEB(PG8_SB(0, 1), b2 + h2, p2); PG8_STAGE(PG8_SA(0, 0), a2, voffA);
;             PG8_WAIT_V(8); PG8_WAIT_L(0); PG8_BAR; PG8_MMA(1, 0, At, B0); PG8_MMA(1, 1, At, B1); PG8_BAR; PG8_SCHED;
.LBB0_1364:
	v_add_u32_e32 v172, s43, v129
	ds_read_b128 v[160:163], v172
	ds_read_b128 v[164:167], v172 offset:1024
	ds_read_b128 v[168:171], v172 offset:2048
	ds_read_b128 v[176:179], v172 offset:3072
	v_add_u32_e32 v172, s44, v129
	s_add_u32 s28, s6, s2
	ds_read_b128 v[180:183], v172
	ds_read_b128 v[184:187], v172 offset:1024
	ds_read_b128 v[188:191], v172 offset:2048
	ds_read_b128 v[192:195], v172 offset:3072
	s_addc_u32 s29, s7, s3
	s_add_u32 s28, s28, 0x100
	s_addc_u32 s29, s29, 0
	s_add_u32 s55, s1, s2
	s_addc_u32 s56, s49, s3
	s_cmpk_eq_i32 s2, 0x1500
	s_cselect_b32 s35, s50, s29
	s_cselect_b32 s34, s51, s28
	s_cselect_b32 s29, s52, s56
	s_cselect_b32 s28, s53, s55
	v_lshl_add_u64 v[172:173], v[156:157], 0, s[2:3]
	s_add_i32 m0, s20, 0xc000
	ds_read_b128 v[196:199], v175
	ds_read_b128 v[202:205], v175 offset:1024
	ds_read_b128 v[206:209], v175 offset:2048
	ds_read_b128 v[210:213], v175 offset:3072
	ds_read_b128 v[214:217], v175 offset:4096
	ds_read_b128 v[218:221], v175 offset:5120
	ds_read_b128 v[222:225], v175 offset:6144
	ds_read_b128 v[226:229], v175 offset:7168
	global_load_lds_dwordx4 v[172:173], off
	v_lshl_add_u64 v[172:173], v[158:159], 0, s[2:3]
	s_add_i32 m0, s20, 0xe000
	s_nop 0
	global_load_lds_dwordx4 v[172:173], off
	s_waitcnt vmcnt(8)
	s_waitcnt lgkmcnt(0)
	s_barrier
	s_setprio 1
	v_mfma_f32_16x16x32_bf16 v[124:127], v[160:163], v[196:199], v[124:127]
	v_mfma_f32_16x16x32_bf16 v[120:123], v[168:171], v[196:199], v[120:123]
	v_mfma_f32_16x16x32_bf16 v[116:119], v[160:163], v[206:209], v[116:119]
	v_mfma_f32_16x16x32_bf16 v[112:115], v[168:171], v[206:209], v[112:115]
	v_mfma_f32_16x16x32_bf16 v[108:111], v[160:163], v[214:217], v[108:111]
	v_mfma_f32_16x16x32_bf16 v[104:107], v[168:171], v[214:217], v[104:107]
	v_mfma_f32_16x16x32_bf16 v[100:103], v[160:163], v[222:225], v[100:103]
	v_mfma_f32_16x16x32_bf16 v[96:99], v[168:171], v[222:225], v[96:99]
	v_mfma_f32_16x16x32_bf16 v[124:127], v[164:167], v[202:205], v[124:127]
	v_mfma_f32_16x16x32_bf16 v[120:123], v[176:179], v[202:205], v[120:123]
	v_mfma_f32_16x16x32_bf16 v[116:119], v[164:167], v[210:213], v[116:119]
	v_mfma_f32_16x16x32_bf16 v[112:115], v[176:179], v[210:213], v[112:115]
	v_mfma_f32_16x16x32_bf16 v[108:111], v[164:167], v[218:221], v[108:111]
	v_mfma_f32_16x16x32_bf16 v[104:107], v[176:179], v[218:221], v[104:107]
	v_mfma_f32_16x16x32_bf16 v[100:103], v[164:167], v[226:229], v[100:103]
	v_mfma_f32_16x16x32_bf16 v[96:99], v[176:179], v[226:229], v[96:99]
	v_mfma_f32_16x16x32_bf16 v[92:95], v[180:183], v[196:199], v[92:95]
	v_mfma_f32_16x16x32_bf16 v[88:91], v[188:191], v[196:199], v[88:91]
	v_mfma_f32_16x16x32_bf16 v[84:87], v[180:183], v[206:209], v[84:87]
	v_mfma_f32_16x16x32_bf16 v[80:83], v[188:191], v[206:209], v[80:83]
	v_mfma_f32_16x16x32_bf16 v[76:79], v[180:183], v[214:217], v[76:79]
	v_mfma_f32_16x16x32_bf16 v[72:75], v[188:191], v[214:217], v[72:75]
	v_mfma_f32_16x16x32_bf16 v[68:71], v[180:183], v[222:225], v[68:71]
	v_mfma_f32_16x16x32_bf16 v[64:67], v[188:191], v[222:225], v[64:67]
	v_mfma_f32_16x16x32_bf16 v[92:95], v[184:187], v[202:205], v[92:95]
	v_mfma_f32_16x16x32_bf16 v[88:91], v[192:195], v[202:205], v[88:91]
	v_mfma_f32_16x16x32_bf16 v[84:87], v[184:187], v[210:213], v[84:87]
	v_mfma_f32_16x16x32_bf16 v[80:83], v[192:195], v[210:213], v[80:83]
	v_mfma_f32_16x16x32_bf16 v[76:79], v[184:187], v[218:221], v[76:79]
	v_mfma_f32_16x16x32_bf16 v[72:75], v[192:195], v[218:221], v[72:75]
	v_mfma_f32_16x16x32_bf16 v[68:71], v[184:187], v[226:229], v[68:71]
	v_mfma_f32_16x16x32_bf16 v[64:67], v[192:195], v[226:229], v[64:67]
	s_setprio 0
	s_barrier
	s_add_i32 s55, s43, s15
	v_lshl_add_u64 v[172:173], s[28:29], 0, v[130:131]
	s_mov_b32 m0, s55
	ds_read_b128 v[196:199], v175 offset:16384
	ds_read_b128 v[202:205], v175 offset:17408
	ds_read_b128 v[206:209], v175 offset:18432
	ds_read_b128 v[210:213], v175 offset:19456
	ds_read_b128 v[214:217], v175 offset:20480
	ds_read_b128 v[218:221], v175 offset:21504
	ds_read_b128 v[222:225], v175 offset:22528
	ds_read_b128 v[226:229], v175 offset:23552
	global_load_lds_dwordx4 v[172:173], off
	s_add_i32 m0, s55, 0x2000
	s_add_u32 s56, s28, 0xb0000
	v_lshl_add_u64 v[230:231], s[28:29], 0, v[132:133]
	s_addc_u32 s57, s29, 0
	s_add_i32 s55, s44, s15
	global_load_lds_dwordx4 v[230:231], off
	v_lshl_add_u64 v[232:233], s[56:57], 0, v[130:131]
	s_mov_b32 m0, s55
	v_lshl_add_u64 v[234:235], s[34:35], 0, v[132:133]
	global_load_lds_dwordx4 v[232:233], off
	v_lshl_add_u64 v[232:233], s[56:57], 0, v[132:133]
	s_add_i32 m0, s55, 0x2000
	s_nop 0
	global_load_lds_dwordx4 v[232:233], off
	v_lshl_add_u64 v[232:233], s[34:35], 0, v[130:131]
	s_mov_b32 m0, s20
	s_nop 0
	global_load_lds_dwordx4 v[232:233], off
	s_mov_b32 m0, s21
	s_nop 0
	global_load_lds_dwordx4 v[234:235], off
	s_waitcnt vmcnt(8)
	s_waitcnt lgkmcnt(0)
	s_barrier
; #define PG8_STAGE(bufoff, gbase, voff) do { _Pragma("unroll") for (int _i = 0; _i < 2; ++_i) \
;         __builtin_amdgcn_global_load_lds((const unsigned*)((const char*)(gbase) + (voff)[_i]), (LAS unsigned*)(lds + (bufoff) + ldsw + _i * 8192), 16, 0, 0); } while (0)
; #define PG8_LDA(dst, b, h) do { _Pragma("unroll") for (int m = 0; m < 4; ++m) _Pragma("unroll") for (int k = 0; k < 2; ++k) dst[m][k] = *(const LAS bf16x8*)(lds + PG8_SA(b, h) + aoff + m * 2048 + k * 1024); } while (0)
; #define PG8_LDB(dst, b, h) do { _Pragma("unroll") for (int n = 0; n < 2; ++n) _Pragma("unroll") for (int k = 0; k < 2; ++k) dst[n][k] = *(const LAS bf16x8*)(lds + PG8_SB(b, h) + boff + n * 2048 + k * 1024); } while (0)
; #define PG8_MMA(ai, bj, At, Bt) do { __builtin_amdgcn_s_setprio(1); _Pragma("unroll") for (int m = 0; m < 4; ++m) _Pragma("unroll") for (int n = 0; n < 2; ++n) _Pragma("unroll") for (int k = 0; k < 2; ++k) \
;         acc[ai][bj][m][n] = __builtin_amdgcn_mfma_f32_16x16x32_bf16(Bt[n][k], At[m][k], acc[ai][bj][m][n], 0, 0, 0); __builtin_amdgcn_s_setprio(0); } while (0)
; #define PG8_WAIT_V(n) asm volatile("s_waitcnt vmcnt(" #n ")" ::: "memory")
; #define PG8_WAIT_L(n) asm volatile("s_waitcnt lgkmcnt(" #n ")" ::: "memory")
; #define PG8_BAR __builtin_amdgcn_s_barrier()
; #define PG8_SCHED __builtin_amdgcn_sched_barrier(0)
; template <class Epi, bool BSEL = false>
; __device__ __forceinline__ void gemm_phase(LAS unsigned char* lds, const Gemm g, const Order& S, const Epi& E, const int tid) {
;     ...
;             PG8_WAIT_V(8); PG8_WAIT_L(0); PG8_BAR; PG8_MMA(1, 0, At, B0); PG8_MMA(1, 1, At, B1); PG8_BAR; PG8_SCHED;
;             PG8_LDB(B0, 1, 0); PG8_LDB(B1, 1, 1); PG8_SCHED; PG8_LDA(At, 1, 0); PG8_STAGE(PG8_SA(0, 1), a2 + hstepA, voffA);
;             PG8_WAIT_V(8); PG8_WAIT_L(0); PG8_BAR; PG8_MMA(0, 0, At, B0); PG8_MMA(0, 1, At, B1); PG8_BAR; PG8_SCHED;
	s_setprio 1
	v_mfma_f32_16x16x32_bf16 v[60:63], v[160:163], v[196:199], v[60:63]
	v_mfma_f32_16x16x32_bf16 v[56:59], v[168:171], v[196:199], v[56:59]
	v_mfma_f32_16x16x32_bf16 v[52:55], v[160:163], v[206:209], v[52:55]
	v_mfma_f32_16x16x32_bf16 v[48:51], v[168:171], v[206:209], v[48:51]
	v_mfma_f32_16x16x32_bf16 v[44:47], v[160:163], v[214:217], v[44:47]
	v_mfma_f32_16x16x32_bf16 v[40:43], v[168:171], v[214:217], v[40:43]
	v_mfma_f32_16x16x32_bf16 v[36:39], v[160:163], v[222:225], v[36:39]
	v_mfma_f32_16x16x32_bf16 v[32:35], v[168:171], v[222:225], v[32:35]
	v_mfma_f32_16x16x32_bf16 v[60:63], v[164:167], v[202:205], v[60:63]
	v_mfma_f32_16x16x32_bf16 v[56:59], v[176:179], v[202:205], v[56:59]
	v_mfma_f32_16x16x32_bf16 v[52:55], v[164:167], v[210:213], v[52:55]
	v_mfma_f32_16x16x32_bf16 v[48:51], v[176:179], v[210:213], v[48:51]
	v_mfma_f32_16x16x32_bf16 v[44:47], v[164:167], v[218:221], v[44:47]
	v_mfma_f32_16x16x32_bf16 v[40:43], v[176:179], v[218:221], v[40:43]
	v_mfma_f32_16x16x32_bf16 v[36:39], v[164:167], v[226:229], v[36:39]
	v_mfma_f32_16x16x32_bf16 v[32:35], v[176:179], v[226:229], v[32:35]
	v_mfma_f32_16x16x32_bf16 v[28:31], v[180:183], v[196:199], v[28:31]
	v_mfma_f32_16x16x32_bf16 v[24:27], v[188:191], v[196:199], v[24:27]
	v_mfma_f32_16x16x32_bf16 v[20:23], v[180:183], v[206:209], v[20:23]
	v_mfma_f32_16x16x32_bf16 v[16:19], v[188:191], v[206:209], v[16:19]
	v_mfma_f32_16x16x32_bf16 v[12:15], v[180:183], v[214:217], v[12:15]
	v_mfma_f32_16x16x32_bf16 v[8:11], v[188:191], v[214:217], v[8:11]
	v_mfma_f32_16x16x32_bf16 v[4:7], v[180:183], v[222:225], v[4:7]
	v_mfma_f32_16x16x32_bf16 v[0:3], v[188:191], v[222:225], v[0:3]
	v_mfma_f32_16x16x32_bf16 v[28:31], v[184:187], v[202:205], v[28:31]
	v_mfma_f32_16x16x32_bf16 v[24:27], v[192:195], v[202:205], v[24:27]
	v_mfma_f32_16x16x32_bf16 v[20:23], v[184:187], v[210:213], v[20:23]
	v_mfma_f32_16x16x32_bf16 v[16:19], v[192:195], v[210:213], v[16:19]
	v_mfma_f32_16x16x32_bf16 v[12:15], v[184:187], v[218:221], v[12:15]
	v_mfma_f32_16x16x32_bf16 v[8:11], v[192:195], v[218:221], v[8:11]
	v_mfma_f32_16x16x32_bf16 v[4:7], v[184:187], v[226:229], v[4:7]
	v_mfma_f32_16x16x32_bf16 v[0:3], v[192:195], v[226:229], v[0:3]
	s_setprio 0
	s_barrier
	s_add_i32 s55, 0, 0x18000
	s_add_i32 s56, 0, 0x1c000
	v_add_u32_e32 v176, s55, v129
	v_add_u32_e32 v192, s56, v129
	ds_read_b128 v[160:163], v176
	ds_read_b128 v[164:167], v176 offset:1024
	ds_read_b128 v[168:171], v176 offset:2048
	ds_read_b128 v[176:179], v176 offset:3072
	ds_read_b128 v[180:183], v192
	ds_read_b128 v[184:187], v192 offset:1024
	ds_read_b128 v[188:191], v192 offset:2048
	ds_read_b128 v[192:195], v192 offset:3072
	s_add_u32 s34, s34, 0xb0000
	s_addc_u32 s35, s35, 0
	s_mov_b32 m0, s36
	v_lshl_add_u64 v[236:237], s[34:35], 0, v[130:131]
	ds_read_b128 v[196:199], v175 offset:32768
	ds_read_b128 v[202:205], v175 offset:33792
	ds_read_b128 v[206:209], v175 offset:34816
	ds_read_b128 v[210:213], v175 offset:35840
	ds_read_b128 v[214:217], v175 offset:36864
	ds_read_b128 v[218:221], v175 offset:37888
	ds_read_b128 v[222:225], v175 offset:38912
	ds_read_b128 v[226:229], v175 offset:39936
	global_load_lds_dwordx4 v[236:237], off
	v_lshl_add_u64 v[236:237], s[34:35], 0, v[132:133]
	s_mov_b32 m0, s37
	s_nop 0
	global_load_lds_dwordx4 v[236:237], off
	s_waitcnt vmcnt(8)
	s_waitcnt lgkmcnt(0)
	s_barrier
	s_setprio 1
	v_mfma_f32_16x16x32_bf16 v[124:127], v[160:163], v[196:199], v[124:127]
	v_mfma_f32_16x16x32_bf16 v[120:123], v[168:171], v[196:199], v[120:123]
	v_mfma_f32_16x16x32_bf16 v[116:119], v[160:163], v[206:209], v[116:119]
	v_mfma_f32_16x16x32_bf16 v[112:115], v[168:171], v[206:209], v[112:115]
	v_mfma_f32_16x16x32_bf16 v[108:111], v[160:163], v[214:217], v[108:111]
	v_mfma_f32_16x16x32_bf16 v[104:107], v[168:171], v[214:217], v[104:107]
	v_mfma_f32_16x16x32_bf16 v[100:103], v[160:163], v[222:225], v[100:103]
	v_mfma_f32_16x16x32_bf16 v[96:99], v[168:171], v[222:225], v[96:99]
	v_mfma_f32_16x16x32_bf16 v[124:127], v[164:167], v[202:205], v[124:127]
	v_mfma_f32_16x16x32_bf16 v[120:123], v[176:179], v[202:205], v[120:123]
	v_mfma_f32_16x16x32_bf16 v[116:119], v[164:167], v[210:213], v[116:119]
	v_mfma_f32_16x16x32_bf16 v[112:115], v[176:179], v[210:213], v[112:115]
	v_mfma_f32_16x16x32_bf16 v[108:111], v[164:167], v[218:221], v[108:111]
	v_mfma_f32_16x16x32_bf16 v[104:107], v[176:179], v[218:221], v[104:107]
	v_mfma_f32_16x16x32_bf16 v[100:103], v[164:167], v[226:229], v[100:103]
	v_mfma_f32_16x16x32_bf16 v[96:99], v[176:179], v[226:229], v[96:99]
	v_mfma_f32_16x16x32_bf16 v[92:95], v[180:183], v[196:199], v[92:95]
	v_mfma_f32_16x16x32_bf16 v[88:91], v[188:191], v[196:199], v[88:91]
	v_mfma_f32_16x16x32_bf16 v[84:87], v[180:183], v[206:209], v[84:87]
	v_mfma_f32_16x16x32_bf16 v[80:83], v[188:191], v[206:209], v[80:83]
	v_mfma_f32_16x16x32_bf16 v[76:79], v[180:183], v[214:217], v[76:79]
	v_mfma_f32_16x16x32_bf16 v[72:75], v[188:191], v[214:217], v[72:75]
	v_mfma_f32_16x16x32_bf16 v[68:71], v[180:183], v[222:225], v[68:71]
	v_mfma_f32_16x16x32_bf16 v[64:67], v[188:191], v[222:225], v[64:67]
	v_mfma_f32_16x16x32_bf16 v[92:95], v[184:187], v[202:205], v[92:95]
	v_mfma_f32_16x16x32_bf16 v[88:91], v[192:195], v[202:205], v[88:91]
	v_mfma_f32_16x16x32_bf16 v[84:87], v[184:187], v[210:213], v[84:87]
	v_mfma_f32_16x16x32_bf16 v[80:83], v[192:195], v[210:213], v[80:83]
	v_mfma_f32_16x16x32_bf16 v[76:79], v[184:187], v[218:221], v[76:79]
	v_mfma_f32_16x16x32_bf16 v[72:75], v[192:195], v[218:221], v[72:75]
	v_mfma_f32_16x16x32_bf16 v[68:71], v[184:187], v[226:229], v[68:71]
	v_mfma_f32_16x16x32_bf16 v[64:67], v[192:195], v[226:229], v[64:67]
	s_setprio 0
	s_barrier
; #define PG8_STAGE(bufoff, gbase, voff) do { _Pragma("unroll") for (int _i = 0; _i < 2; ++_i) \
;         __builtin_amdgcn_global_load_lds((const unsigned*)((const char*)(gbase) + (voff)[_i]), (LAS unsigned*)(lds + (bufoff) + ldsw + _i * 8192), 16, 0, 0); } while (0)
; #define PG8_STAGEB(bufoff, gbase, perm) do { _Pragma("unroll") for (int _i = 0; _i < 2; ++_i) \
;         __builtin_amdgcn_global_load_lds((const unsigned*)((const char*)(gbase) + ((BSEL && (perm)) ? voffBp[_i] : voffB[_i])), (LAS unsigned*)(lds + (bufoff) + ldsw + _i * 8192), 16, 0, 0); } while (0)
; #define PG8_LDA(dst, b, h) do { _Pragma("unroll") for (int m = 0; m < 4; ++m) _Pragma("unroll") for (int k = 0; k < 2; ++k) dst[m][k] = *(const LAS bf16x8*)(lds + PG8_SA(b, h) + aoff + m * 2048 + k * 1024); } while (0)
; #define PG8_MMA(ai, bj, At, Bt) do { __builtin_amdgcn_s_setprio(1); _Pragma("unroll") for (int m = 0; m < 4; ++m) _Pragma("unroll") for (int n = 0; n < 2; ++n) _Pragma("unroll") for (int k = 0; k < 2; ++k) \
;         acc[ai][bj][m][n] = __builtin_amdgcn_mfma_f32_16x16x32_bf16(Bt[n][k], At[m][k], acc[ai][bj][m][n], 0, 0, 0); __builtin_amdgcn_s_setprio(0); } while (0)
; #define PG8_WAIT_V(n) asm volatile("s_waitcnt vmcnt(" #n ")" ::: "memory")
; #define PG8_WAIT_L(n) asm volatile("s_waitcnt lgkmcnt(" #n ")" ::: "memory")
; #define PG8_BAR __builtin_amdgcn_s_barrier()
; #define PG8_SCHED __builtin_amdgcn_sched_barrier(0)
; template <class Epi, bool BSEL = false>
; __device__ __forceinline__ void gemm_phase(LAS unsigned char* lds, const Gemm g, const Order& S, const Epi& E, const int tid) {
;     ...
;             PG8_LDA(At, 1, 1); PG8_STAGEB(PG8_SB(1, 0), b3, p2); PG8_STAGEB(PG8_SB(1, 1), b3 + h2, p2); PG8_STAGE(PG8_SA(1, 0), a3, voffA);
;             PG8_WAIT_V(8); PG8_WAIT_L(0); PG8_BAR; PG8_MMA(1, 0, At, B0); PG8_MMA(1, 1, At, B1); PG8_BAR; PG8_SCHED;
;         }
;         if constexpr (ALIGN_EPI) { if (wr == 0) PG8_BAR; }
	s_add_i32 s34, s55, s15
	v_lshl_add_u64 v[172:173], v[172:173], 0, s[10:11]
	s_mov_b32 m0, s34
	ds_read_b128 v[196:199], v175 offset:49152
	ds_read_b128 v[202:205], v175 offset:50176
	ds_read_b128 v[206:209], v175 offset:51200
	ds_read_b128 v[210:213], v175 offset:52224
	ds_read_b128 v[214:217], v175 offset:53248
	ds_read_b128 v[218:221], v175 offset:54272
	ds_read_b128 v[222:225], v175 offset:55296
	ds_read_b128 v[226:229], v175 offset:56320
	global_load_lds_dwordx4 v[172:173], off
	s_add_i32 m0, s34, 0x2000
	s_add_u32 s28, s28, 0xb0080
	v_lshl_add_u64 v[172:173], v[230:231], 0, s[10:11]
	s_addc_u32 s29, s29, 0
	s_add_i32 s34, s56, s15
	global_load_lds_dwordx4 v[172:173], off
	v_lshl_add_u64 v[172:173], s[28:29], 0, v[130:131]
	s_mov_b32 m0, s34
	s_nop 0
	global_load_lds_dwordx4 v[172:173], off
	v_lshl_add_u64 v[172:173], s[28:29], 0, v[132:133]
	s_add_i32 m0, s34, 0x2000
	s_nop 0
	global_load_lds_dwordx4 v[172:173], off
	v_lshl_add_u64 v[172:173], v[232:233], 0, s[10:11]
	s_mov_b32 m0, s41
	s_nop 0
	global_load_lds_dwordx4 v[172:173], off
	v_lshl_add_u64 v[172:173], v[234:235], 0, s[10:11]
	s_mov_b32 m0, s42
	s_nop 0
	global_load_lds_dwordx4 v[172:173], off
	s_waitcnt vmcnt(8)
	s_waitcnt lgkmcnt(0)
	s_barrier
	s_setprio 1
	v_mfma_f32_16x16x32_bf16 v[60:63], v[160:163], v[196:199], v[60:63]
	v_mfma_f32_16x16x32_bf16 v[56:59], v[168:171], v[196:199], v[56:59]
	v_mfma_f32_16x16x32_bf16 v[52:55], v[160:163], v[206:209], v[52:55]
	v_mfma_f32_16x16x32_bf16 v[48:51], v[168:171], v[206:209], v[48:51]
	v_mfma_f32_16x16x32_bf16 v[44:47], v[160:163], v[214:217], v[44:47]
	v_mfma_f32_16x16x32_bf16 v[40:43], v[168:171], v[214:217], v[40:43]
	v_mfma_f32_16x16x32_bf16 v[36:39], v[160:163], v[222:225], v[36:39]
	v_mfma_f32_16x16x32_bf16 v[32:35], v[168:171], v[222:225], v[32:35]
	v_mfma_f32_16x16x32_bf16 v[60:63], v[164:167], v[202:205], v[60:63]
	v_mfma_f32_16x16x32_bf16 v[56:59], v[176:179], v[202:205], v[56:59]
	v_mfma_f32_16x16x32_bf16 v[52:55], v[164:167], v[210:213], v[52:55]
	v_mfma_f32_16x16x32_bf16 v[48:51], v[176:179], v[210:213], v[48:51]
	v_mfma_f32_16x16x32_bf16 v[44:47], v[164:167], v[218:221], v[44:47]
	v_mfma_f32_16x16x32_bf16 v[40:43], v[176:179], v[218:221], v[40:43]
	v_mfma_f32_16x16x32_bf16 v[36:39], v[164:167], v[226:229], v[36:39]
	v_mfma_f32_16x16x32_bf16 v[32:35], v[176:179], v[226:229], v[32:35]
	v_mfma_f32_16x16x32_bf16 v[28:31], v[180:183], v[196:199], v[28:31]
	v_mfma_f32_16x16x32_bf16 v[24:27], v[188:191], v[196:199], v[24:27]
	v_mfma_f32_16x16x32_bf16 v[20:23], v[180:183], v[206:209], v[20:23]
	v_mfma_f32_16x16x32_bf16 v[16:19], v[188:191], v[206:209], v[16:19]
	v_mfma_f32_16x16x32_bf16 v[12:15], v[180:183], v[214:217], v[12:15]
	v_mfma_f32_16x16x32_bf16 v[8:11], v[188:191], v[214:217], v[8:11]
	v_mfma_f32_16x16x32_bf16 v[4:7], v[180:183], v[222:225], v[4:7]
	v_mfma_f32_16x16x32_bf16 v[0:3], v[188:191], v[222:225], v[0:3]
	v_mfma_f32_16x16x32_bf16 v[28:31], v[184:187], v[202:205], v[28:31]
	v_mfma_f32_16x16x32_bf16 v[24:27], v[192:195], v[202:205], v[24:27]
	v_mfma_f32_16x16x32_bf16 v[20:23], v[184:187], v[210:213], v[20:23]
	v_mfma_f32_16x16x32_bf16 v[16:19], v[192:195], v[210:213], v[16:19]
	v_mfma_f32_16x16x32_bf16 v[12:15], v[184:187], v[218:221], v[12:15]
	v_mfma_f32_16x16x32_bf16 v[8:11], v[192:195], v[218:221], v[8:11]
	v_mfma_f32_16x16x32_bf16 v[4:7], v[184:187], v[226:229], v[4:7]
	v_mfma_f32_16x16x32_bf16 v[0:3], v[192:195], v[226:229], v[0:3]
	s_setprio 0
	s_barrier
	s_add_i32 s54, s54, 2
	s_add_u32 s2, s2, 0x100
	s_addc_u32 s3, s3, 0
	s_cmp_gt_u32 s54, 41
	s_cbranch_scc0 .LBB0_1364
	s_and_b64 vcc, exec, s[18:19]
	s_cbranch_vccz .LBB0_1367
	s_barrier

; #define PG8_STAGE(bufoff, gbase, voff) do { _Pragma("unroll") for (int _i = 0; _i < 2; ++_i) \
;         __builtin_amdgcn_global_load_lds((const unsigned*)((const char*)(gbase) + (voff)[_i]), (LAS unsigned*)(lds + (bufoff) + ldsw + _i * 8192), 16, 0, 0); } while (0)
; #define PG8_STAGEB(bufoff, gbase, perm) do { _Pragma("unroll") for (int _i = 0; _i < 2; ++_i) \
;         __builtin_amdgcn_global_load_lds((const unsigned*)((const char*)(gbase) + ((BSEL && (perm)) ? voffBp[_i] : voffB[_i])), (LAS unsigned*)(lds + (bufoff) + ldsw + _i * 8192), 16, 0, 0); } while (0)
; #define PG8_LDA(dst, b, h) do { _Pragma("unroll") for (int m = 0; m < 4; ++m) _Pragma("unroll") for (int k = 0; k < 2; ++k) dst[m][k] = *(const LAS bf16x8*)(lds + PG8_SA(b, h) + aoff + m * 2048 + k * 1024); } while (0)
; #define PG8_LDB(dst, b, h) do { _Pragma("unroll") for (int n = 0; n < 2; ++n) _Pragma("unroll") for (int k = 0; k < 2; ++k) dst[n][k] = *(const LAS bf16x8*)(lds + PG8_SB(b, h) + boff + n * 2048 + k * 1024); } while (0)
; #define PG8_WAIT_V(n) asm volatile("s_waitcnt vmcnt(" #n ")" ::: "memory")
; #define PG8_WAIT_L(n) asm volatile("s_waitcnt lgkmcnt(" #n ")" ::: "memory")
; #define PG8_BAR __builtin_amdgcn_s_barrier()
; #define PG8_SCHED __builtin_amdgcn_sched_barrier(0)
; template <class Epi, bool BSEL = false>
; __device__ __forceinline__ void gemm_phase(LAS unsigned char* lds, const Gemm g, const Order& S, const Epi& E, const int tid) {
;     ...
;         for (int t = 0; t < nt; t += 2) {
;             const bool last = (t == nt - 2);
;             const char* a1 = cA + (size_t)(t + 1) * kstep;
;             const char* a2 = last ? nA : cA + (size_t)(t + 2) * kstep; const char* b2 = last ? nB : cB + (size_t)(t + 2) * kstep;
;             const char* a3 = a2 + kstep; const char* b3 = b2 + kstep;
;             const bool p2 = last ? nP : cP; const size_t h2 = last ? nhB : chB;
;             PG8_LDB(B0, 0, 0); PG8_LDB(B1, 0, 1); PG8_SCHED; PG8_LDA(At, 0, 0); PG8_STAGE(PG8_SA(1, 1), a1 + hstepA, voffA);
;             PG8_WAIT_V(8); PG8_WAIT_L(0); PG8_BAR; PG8_MMA(0, 0, At, B0); PG8_MMA(0, 1, At, B1); PG8_BAR; PG8_SCHED;
;             PG8_LDA(At, 0, 1); PG8_STAGEB(PG8_SB(0, 0), b2, p2); PG8_STAGEB(PG8_SB(0, 1), b2 + h2, p2); PG8_STAGE(PG8_SA(0, 0), a2, voffA);
;             PG8_WAIT_V(8); PG8_WAIT_L(0); PG8_BAR; PG8_MMA(1, 0, At, B0); PG8_MMA(1, 1, At, B1); PG8_BAR; PG8_SCHED;
.LBB0_1393:
	v_add_u32_e32 v151, s43, v131
	ds_read_b128 v[152:155], v151
	ds_read_b128 v[156:159], v151 offset:1024
	ds_read_b128 v[168:171], v151 offset:2048
	ds_read_b128 v[172:175], v151 offset:3072
	v_add_u32_e32 v151, s44, v131
	s_add_u32 s36, s8, s34
	ds_read_b128 v[176:179], v151
	ds_read_b128 v[180:183], v151 offset:1024
	ds_read_b128 v[184:187], v151 offset:2048
	ds_read_b128 v[188:191], v151 offset:3072
	s_addc_u32 s37, s9, s35
	s_add_u32 s36, s36, 0x100
	s_addc_u32 s37, s37, 0
	s_add_u32 s54, s29, s34
	s_addc_u32 s55, s48, s35
	s_cmpk_eq_i32 s34, 0x1500
	s_cselect_b32 s39, s49, s37
	s_cselect_b32 s38, s50, s36
	s_cselect_b32 s37, s51, s55
	s_cselect_b32 s36, s52, s54
	v_lshl_add_u64 v[160:161], v[146:147], 0, s[34:35]
	s_add_i32 m0, s15, 0xc000
	ds_read_b128 v[192:195], v150
	ds_read_b128 v[196:199], v150 offset:1024
	ds_read_b128 v[202:205], v150 offset:2048
	ds_read_b128 v[206:209], v150 offset:3072
	ds_read_b128 v[210:213], v150 offset:4096
	ds_read_b128 v[214:217], v150 offset:5120
	ds_read_b128 v[218:221], v150 offset:6144
	ds_read_b128 v[222:225], v150 offset:7168
	global_load_lds_dwordx4 v[160:161], off
	v_lshl_add_u64 v[160:161], v[148:149], 0, s[34:35]
	s_add_i32 m0, s15, 0xe000
	s_nop 0
	global_load_lds_dwordx4 v[160:161], off
	s_waitcnt vmcnt(8)
	s_waitcnt lgkmcnt(0)
	s_barrier
	s_setprio 1
	v_mfma_f32_16x16x32_bf16 v[124:127], v[152:155], v[192:195], v[124:127]
	v_mfma_f32_16x16x32_bf16 v[120:123], v[168:171], v[192:195], v[120:123]
	v_mfma_f32_16x16x32_bf16 v[108:111], v[152:155], v[202:205], v[108:111]
	v_mfma_f32_16x16x32_bf16 v[104:107], v[168:171], v[202:205], v[104:107]
	v_mfma_f32_16x16x32_bf16 v[92:95], v[152:155], v[210:213], v[92:95]
	v_mfma_f32_16x16x32_bf16 v[88:91], v[168:171], v[210:213], v[88:91]
	v_mfma_f32_16x16x32_bf16 v[76:79], v[152:155], v[218:221], v[76:79]
	v_mfma_f32_16x16x32_bf16 v[72:75], v[168:171], v[218:221], v[72:75]
	v_mfma_f32_16x16x32_bf16 v[124:127], v[156:159], v[196:199], v[124:127]
	v_mfma_f32_16x16x32_bf16 v[120:123], v[172:175], v[196:199], v[120:123]
	v_mfma_f32_16x16x32_bf16 v[108:111], v[156:159], v[206:209], v[108:111]
	v_mfma_f32_16x16x32_bf16 v[104:107], v[172:175], v[206:209], v[104:107]
	v_mfma_f32_16x16x32_bf16 v[92:95], v[156:159], v[214:217], v[92:95]
	v_mfma_f32_16x16x32_bf16 v[88:91], v[172:175], v[214:217], v[88:91]
	v_mfma_f32_16x16x32_bf16 v[76:79], v[156:159], v[222:225], v[76:79]
	v_mfma_f32_16x16x32_bf16 v[72:75], v[172:175], v[222:225], v[72:75]
	v_mfma_f32_16x16x32_bf16 v[116:119], v[176:179], v[192:195], v[116:119]
	v_mfma_f32_16x16x32_bf16 v[112:115], v[184:187], v[192:195], v[112:115]
	v_mfma_f32_16x16x32_bf16 v[100:103], v[176:179], v[202:205], v[100:103]
	v_mfma_f32_16x16x32_bf16 v[96:99], v[184:187], v[202:205], v[96:99]
	v_mfma_f32_16x16x32_bf16 v[84:87], v[176:179], v[210:213], v[84:87]
	v_mfma_f32_16x16x32_bf16 v[80:83], v[184:187], v[210:213], v[80:83]
	v_mfma_f32_16x16x32_bf16 v[68:71], v[176:179], v[218:221], v[68:71]
	v_mfma_f32_16x16x32_bf16 v[64:67], v[184:187], v[218:221], v[64:67]
	v_mfma_f32_16x16x32_bf16 v[116:119], v[180:183], v[196:199], v[116:119]
	v_mfma_f32_16x16x32_bf16 v[112:115], v[188:191], v[196:199], v[112:115]
	v_mfma_f32_16x16x32_bf16 v[100:103], v[180:183], v[206:209], v[100:103]
	v_mfma_f32_16x16x32_bf16 v[96:99], v[188:191], v[206:209], v[96:99]
	v_mfma_f32_16x16x32_bf16 v[84:87], v[180:183], v[214:217], v[84:87]
	v_mfma_f32_16x16x32_bf16 v[80:83], v[188:191], v[214:217], v[80:83]
	v_mfma_f32_16x16x32_bf16 v[68:71], v[180:183], v[222:225], v[68:71]
	v_mfma_f32_16x16x32_bf16 v[64:67], v[188:191], v[222:225], v[64:67]
	s_setprio 0
	s_barrier
	s_add_i32 s54, s43, s14
	v_lshl_add_u64 v[160:161], s[36:37], 0, v[134:135]
	s_mov_b32 m0, s54
	ds_read_b128 v[192:195], v150 offset:16384
	ds_read_b128 v[196:199], v150 offset:17408
	ds_read_b128 v[202:205], v150 offset:18432
	ds_read_b128 v[206:209], v150 offset:19456
	ds_read_b128 v[210:213], v150 offset:20480
	ds_read_b128 v[214:217], v150 offset:21504
	ds_read_b128 v[218:221], v150 offset:22528
	ds_read_b128 v[222:225], v150 offset:23552
	global_load_lds_dwordx4 v[160:161], off
	s_add_i32 m0, s54, 0x2000
	s_add_u32 s54, s36, 0xb0000
	v_lshl_add_u64 v[164:165], s[36:37], 0, v[138:139]
	s_addc_u32 s55, s37, 0
	s_add_i32 s56, s44, s14
	global_load_lds_dwordx4 v[164:165], off
	v_lshl_add_u64 v[226:227], s[54:55], 0, v[134:135]
	s_mov_b32 m0, s56
	v_lshl_add_u64 v[228:229], s[38:39], 0, v[136:137]
	global_load_lds_dwordx4 v[226:227], off
	v_lshl_add_u64 v[226:227], s[54:55], 0, v[138:139]
	s_add_i32 m0, s56, 0x2000
	s_nop 0
	global_load_lds_dwordx4 v[226:227], off
	v_lshl_add_u64 v[226:227], s[38:39], 0, v[132:133]
	s_mov_b32 m0, s15
	s_nop 0
	global_load_lds_dwordx4 v[226:227], off
	s_mov_b32 m0, s20
	s_nop 0
	global_load_lds_dwordx4 v[228:229], off
	s_waitcnt vmcnt(8)
	s_waitcnt lgkmcnt(0)
	s_barrier
; #define PG8_STAGE(bufoff, gbase, voff) do { _Pragma("unroll") for (int _i = 0; _i < 2; ++_i) \
;         __builtin_amdgcn_global_load_lds((const unsigned*)((const char*)(gbase) + (voff)[_i]), (LAS unsigned*)(lds + (bufoff) + ldsw + _i * 8192), 16, 0, 0); } while (0)
; #define PG8_LDA(dst, b, h) do { _Pragma("unroll") for (int m = 0; m < 4; ++m) _Pragma("unroll") for (int k = 0; k < 2; ++k) dst[m][k] = *(const LAS bf16x8*)(lds + PG8_SA(b, h) + aoff + m * 2048 + k * 1024); } while (0)
; #define PG8_LDB(dst, b, h) do { _Pragma("unroll") for (int n = 0; n < 2; ++n) _Pragma("unroll") for (int k = 0; k < 2; ++k) dst[n][k] = *(const LAS bf16x8*)(lds + PG8_SB(b, h) + boff + n * 2048 + k * 1024); } while (0)
; #define PG8_MMA(ai, bj, At, Bt) do { __builtin_amdgcn_s_setprio(1); _Pragma("unroll") for (int m = 0; m < 4; ++m) _Pragma("unroll") for (int n = 0; n < 2; ++n) _Pragma("unroll") for (int k = 0; k < 2; ++k) \
;         acc[ai][bj][m][n] = __builtin_amdgcn_mfma_f32_16x16x32_bf16(Bt[n][k], At[m][k], acc[ai][bj][m][n], 0, 0, 0); __builtin_amdgcn_s_setprio(0); } while (0)
; #define PG8_WAIT_V(n) asm volatile("s_waitcnt vmcnt(" #n ")" ::: "memory")
; #define PG8_WAIT_L(n) asm volatile("s_waitcnt lgkmcnt(" #n ")" ::: "memory")
; #define PG8_BAR __builtin_amdgcn_s_barrier()
; #define PG8_SCHED __builtin_amdgcn_sched_barrier(0)
; template <class Epi, bool BSEL = false>
; __device__ __forceinline__ void gemm_phase(LAS unsigned char* lds, const Gemm g, const Order& S, const Epi& E, const int tid) {
;     ...
;             PG8_WAIT_V(8); PG8_WAIT_L(0); PG8_BAR; PG8_MMA(1, 0, At, B0); PG8_MMA(1, 1, At, B1); PG8_BAR; PG8_SCHED;
;             PG8_LDB(B0, 1, 0); PG8_LDB(B1, 1, 1); PG8_SCHED; PG8_LDA(At, 1, 0); PG8_STAGE(PG8_SA(0, 1), a2 + hstepA, voffA);
;             PG8_WAIT_V(8); PG8_WAIT_L(0); PG8_BAR; PG8_MMA(0, 0, At, B0); PG8_MMA(0, 1, At, B1); PG8_BAR; PG8_SCHED;
	s_setprio 1
	v_mfma_f32_16x16x32_bf16 v[60:63], v[152:155], v[192:195], v[60:63]
	v_mfma_f32_16x16x32_bf16 v[56:59], v[168:171], v[192:195], v[56:59]
	v_mfma_f32_16x16x32_bf16 v[44:47], v[152:155], v[202:205], v[44:47]
	v_mfma_f32_16x16x32_bf16 v[40:43], v[168:171], v[202:205], v[40:43]
	v_mfma_f32_16x16x32_bf16 v[28:31], v[152:155], v[210:213], v[28:31]
	v_mfma_f32_16x16x32_bf16 v[24:27], v[168:171], v[210:213], v[24:27]
	v_mfma_f32_16x16x32_bf16 v[12:15], v[152:155], v[218:221], v[12:15]
	v_mfma_f32_16x16x32_bf16 v[8:11], v[168:171], v[218:221], v[8:11]
	v_mfma_f32_16x16x32_bf16 v[60:63], v[156:159], v[196:199], v[60:63]
	v_mfma_f32_16x16x32_bf16 v[56:59], v[172:175], v[196:199], v[56:59]
	v_mfma_f32_16x16x32_bf16 v[44:47], v[156:159], v[206:209], v[44:47]
	v_mfma_f32_16x16x32_bf16 v[40:43], v[172:175], v[206:209], v[40:43]
	v_mfma_f32_16x16x32_bf16 v[28:31], v[156:159], v[214:217], v[28:31]
	v_mfma_f32_16x16x32_bf16 v[24:27], v[172:175], v[214:217], v[24:27]
	v_mfma_f32_16x16x32_bf16 v[12:15], v[156:159], v[222:225], v[12:15]
	v_mfma_f32_16x16x32_bf16 v[8:11], v[172:175], v[222:225], v[8:11]
	v_mfma_f32_16x16x32_bf16 v[52:55], v[176:179], v[192:195], v[52:55]
	v_mfma_f32_16x16x32_bf16 v[48:51], v[184:187], v[192:195], v[48:51]
	v_mfma_f32_16x16x32_bf16 v[36:39], v[176:179], v[202:205], v[36:39]
	v_mfma_f32_16x16x32_bf16 v[32:35], v[184:187], v[202:205], v[32:35]
	v_mfma_f32_16x16x32_bf16 v[20:23], v[176:179], v[210:213], v[20:23]
	v_mfma_f32_16x16x32_bf16 v[16:19], v[184:187], v[210:213], v[16:19]
	v_mfma_f32_16x16x32_bf16 v[4:7], v[176:179], v[218:221], v[4:7]
	v_mfma_f32_16x16x32_bf16 v[0:3], v[184:187], v[218:221], v[0:3]
	v_mfma_f32_16x16x32_bf16 v[52:55], v[180:183], v[196:199], v[52:55]
	v_mfma_f32_16x16x32_bf16 v[48:51], v[188:191], v[196:199], v[48:51]
	v_mfma_f32_16x16x32_bf16 v[36:39], v[180:183], v[206:209], v[36:39]
	v_mfma_f32_16x16x32_bf16 v[32:35], v[188:191], v[206:209], v[32:35]
	v_mfma_f32_16x16x32_bf16 v[20:23], v[180:183], v[214:217], v[20:23]
	v_mfma_f32_16x16x32_bf16 v[16:19], v[188:191], v[214:217], v[16:19]
	v_mfma_f32_16x16x32_bf16 v[4:7], v[180:183], v[222:225], v[4:7]
	v_mfma_f32_16x16x32_bf16 v[0:3], v[188:191], v[222:225], v[0:3]
	s_setprio 0
	s_barrier
	s_add_i32 s54, 0, 0x18000
	v_add_u32_e32 v151, s54, v131
	s_add_i32 s55, 0, 0x1c000
	ds_read_b128 v[152:155], v151
	ds_read_b128 v[156:159], v151 offset:1024
	ds_read_b128 v[168:171], v151 offset:2048
	ds_read_b128 v[172:175], v151 offset:3072
	v_add_u32_e32 v151, s55, v131
	ds_read_b128 v[176:179], v151
	ds_read_b128 v[180:183], v151 offset:1024
	ds_read_b128 v[184:187], v151 offset:2048
	ds_read_b128 v[188:191], v151 offset:3072
	s_add_u32 s38, s38, 0xb0000
	s_addc_u32 s39, s39, 0
	s_mov_b32 m0, s21
	v_lshl_add_u64 v[230:231], s[38:39], 0, v[132:133]
	ds_read_b128 v[192:195], v150 offset:32768
	ds_read_b128 v[196:199], v150 offset:33792
	ds_read_b128 v[202:205], v150 offset:34816
	ds_read_b128 v[206:209], v150 offset:35840
	ds_read_b128 v[210:213], v150 offset:36864
	ds_read_b128 v[214:217], v150 offset:37888
	ds_read_b128 v[218:221], v150 offset:38912
	ds_read_b128 v[222:225], v150 offset:39936
	global_load_lds_dwordx4 v[230:231], off
	v_lshl_add_u64 v[230:231], s[38:39], 0, v[136:137]
	s_mov_b32 m0, s40
	s_nop 0
	global_load_lds_dwordx4 v[230:231], off
	s_waitcnt vmcnt(8)
	s_waitcnt lgkmcnt(0)
	s_barrier
	s_setprio 1
	v_mfma_f32_16x16x32_bf16 v[124:127], v[152:155], v[192:195], v[124:127]
	v_mfma_f32_16x16x32_bf16 v[120:123], v[168:171], v[192:195], v[120:123]
	v_mfma_f32_16x16x32_bf16 v[108:111], v[152:155], v[202:205], v[108:111]
	v_mfma_f32_16x16x32_bf16 v[104:107], v[168:171], v[202:205], v[104:107]
	v_mfma_f32_16x16x32_bf16 v[92:95], v[152:155], v[210:213], v[92:95]
	v_mfma_f32_16x16x32_bf16 v[88:91], v[168:171], v[210:213], v[88:91]
	v_mfma_f32_16x16x32_bf16 v[76:79], v[152:155], v[218:221], v[76:79]
	v_mfma_f32_16x16x32_bf16 v[72:75], v[168:171], v[218:221], v[72:75]
	v_mfma_f32_16x16x32_bf16 v[124:127], v[156:159], v[196:199], v[124:127]
	v_mfma_f32_16x16x32_bf16 v[120:123], v[172:175], v[196:199], v[120:123]
	v_mfma_f32_16x16x32_bf16 v[108:111], v[156:159], v[206:209], v[108:111]
	v_mfma_f32_16x16x32_bf16 v[104:107], v[172:175], v[206:209], v[104:107]
	v_mfma_f32_16x16x32_bf16 v[92:95], v[156:159], v[214:217], v[92:95]
	v_mfma_f32_16x16x32_bf16 v[88:91], v[172:175], v[214:217], v[88:91]
	v_mfma_f32_16x16x32_bf16 v[76:79], v[156:159], v[222:225], v[76:79]
	v_mfma_f32_16x16x32_bf16 v[72:75], v[172:175], v[222:225], v[72:75]
	v_mfma_f32_16x16x32_bf16 v[116:119], v[176:179], v[192:195], v[116:119]
	v_mfma_f32_16x16x32_bf16 v[112:115], v[184:187], v[192:195], v[112:115]
	v_mfma_f32_16x16x32_bf16 v[100:103], v[176:179], v[202:205], v[100:103]
	v_mfma_f32_16x16x32_bf16 v[96:99], v[184:187], v[202:205], v[96:99]
	v_mfma_f32_16x16x32_bf16 v[84:87], v[176:179], v[210:213], v[84:87]
	v_mfma_f32_16x16x32_bf16 v[80:83], v[184:187], v[210:213], v[80:83]
	v_mfma_f32_16x16x32_bf16 v[68:71], v[176:179], v[218:221], v[68:71]
	v_mfma_f32_16x16x32_bf16 v[64:67], v[184:187], v[218:221], v[64:67]
	v_mfma_f32_16x16x32_bf16 v[116:119], v[180:183], v[196:199], v[116:119]
	v_mfma_f32_16x16x32_bf16 v[112:115], v[188:191], v[196:199], v[112:115]
	v_mfma_f32_16x16x32_bf16 v[100:103], v[180:183], v[206:209], v[100:103]
	v_mfma_f32_16x16x32_bf16 v[96:99], v[188:191], v[206:209], v[96:99]
	v_mfma_f32_16x16x32_bf16 v[84:87], v[180:183], v[214:217], v[84:87]
	v_mfma_f32_16x16x32_bf16 v[80:83], v[188:191], v[214:217], v[80:83]
	v_mfma_f32_16x16x32_bf16 v[68:71], v[180:183], v[222:225], v[68:71]
	v_mfma_f32_16x16x32_bf16 v[64:67], v[188:191], v[222:225], v[64:67]
	s_setprio 0
	s_barrier
; #define PG8_STAGE(bufoff, gbase, voff) do { _Pragma("unroll") for (int _i = 0; _i < 2; ++_i) \
;         __builtin_amdgcn_global_load_lds((const unsigned*)((const char*)(gbase) + (voff)[_i]), (LAS unsigned*)(lds + (bufoff) + ldsw + _i * 8192), 16, 0, 0); } while (0)
; #define PG8_STAGEB(bufoff, gbase, perm) do { _Pragma("unroll") for (int _i = 0; _i < 2; ++_i) \
;         __builtin_amdgcn_global_load_lds((const unsigned*)((const char*)(gbase) + ((BSEL && (perm)) ? voffBp[_i] : voffB[_i])), (LAS unsigned*)(lds + (bufoff) + ldsw + _i * 8192), 16, 0, 0); } while (0)
; #define PG8_LDA(dst, b, h) do { _Pragma("unroll") for (int m = 0; m < 4; ++m) _Pragma("unroll") for (int k = 0; k < 2; ++k) dst[m][k] = *(const LAS bf16x8*)(lds + PG8_SA(b, h) + aoff + m * 2048 + k * 1024); } while (0)
; #define PG8_MMA(ai, bj, At, Bt) do { __builtin_amdgcn_s_setprio(1); _Pragma("unroll") for (int m = 0; m < 4; ++m) _Pragma("unroll") for (int n = 0; n < 2; ++n) _Pragma("unroll") for (int k = 0; k < 2; ++k) \
;         acc[ai][bj][m][n] = __builtin_amdgcn_mfma_f32_16x16x32_bf16(Bt[n][k], At[m][k], acc[ai][bj][m][n], 0, 0, 0); __builtin_amdgcn_s_setprio(0); } while (0)
; #define PG8_WAIT_V(n) asm volatile("s_waitcnt vmcnt(" #n ")" ::: "memory")
; #define PG8_WAIT_L(n) asm volatile("s_waitcnt lgkmcnt(" #n ")" ::: "memory")
; #define PG8_BAR __builtin_amdgcn_s_barrier()
; #define PG8_SCHED __builtin_amdgcn_sched_barrier(0)
; template <class Epi, bool BSEL = false>
; __device__ __forceinline__ void gemm_phase(LAS unsigned char* lds, const Gemm g, const Order& S, const Epi& E, const int tid) {
;     ...
;             PG8_LDA(At, 1, 1); PG8_STAGEB(PG8_SB(1, 0), b3, p2); PG8_STAGEB(PG8_SB(1, 1), b3 + h2, p2); PG8_STAGE(PG8_SA(1, 0), a3, voffA);
;             PG8_WAIT_V(8); PG8_WAIT_L(0); PG8_BAR; PG8_MMA(1, 0, At, B0); PG8_MMA(1, 1, At, B1); PG8_BAR; PG8_SCHED;
;         }
;         if constexpr (ALIGN_EPI) { if (wr == 0) PG8_BAR; }
	s_add_i32 s38, s54, s14
	v_lshl_add_u64 v[160:161], v[160:161], 0, s[18:19]
	s_mov_b32 m0, s38
	ds_read_b128 v[192:195], v150 offset:49152
	ds_read_b128 v[196:199], v150 offset:50176
	ds_read_b128 v[202:205], v150 offset:51200
	ds_read_b128 v[206:209], v150 offset:52224
	ds_read_b128 v[210:213], v150 offset:53248
	ds_read_b128 v[214:217], v150 offset:54272
	ds_read_b128 v[218:221], v150 offset:55296
	ds_read_b128 v[222:225], v150 offset:56320
	global_load_lds_dwordx4 v[160:161], off
	s_add_i32 m0, s38, 0x2000
	s_add_u32 s36, s36, 0xb0080
	v_lshl_add_u64 v[160:161], v[164:165], 0, s[18:19]
	s_addc_u32 s37, s37, 0
	s_add_i32 s38, s55, s14
	global_load_lds_dwordx4 v[160:161], off
	v_lshl_add_u64 v[160:161], s[36:37], 0, v[134:135]
	s_mov_b32 m0, s38
	s_nop 0
	global_load_lds_dwordx4 v[160:161], off
	v_lshl_add_u64 v[160:161], s[36:37], 0, v[138:139]
	s_add_i32 m0, s38, 0x2000
	s_nop 0
	global_load_lds_dwordx4 v[160:161], off
	v_lshl_add_u64 v[160:161], v[226:227], 0, s[18:19]
	s_mov_b32 m0, s41
	s_nop 0
	global_load_lds_dwordx4 v[160:161], off
	v_lshl_add_u64 v[160:161], v[228:229], 0, s[18:19]
	s_mov_b32 m0, s42
	s_nop 0
	global_load_lds_dwordx4 v[160:161], off
	s_waitcnt vmcnt(8)
	s_waitcnt lgkmcnt(0)
	s_barrier
	s_setprio 1
	v_mfma_f32_16x16x32_bf16 v[60:63], v[152:155], v[192:195], v[60:63]
	v_mfma_f32_16x16x32_bf16 v[56:59], v[168:171], v[192:195], v[56:59]
	v_mfma_f32_16x16x32_bf16 v[44:47], v[152:155], v[202:205], v[44:47]
	v_mfma_f32_16x16x32_bf16 v[40:43], v[168:171], v[202:205], v[40:43]
	v_mfma_f32_16x16x32_bf16 v[28:31], v[152:155], v[210:213], v[28:31]
	v_mfma_f32_16x16x32_bf16 v[24:27], v[168:171], v[210:213], v[24:27]
	v_mfma_f32_16x16x32_bf16 v[12:15], v[152:155], v[218:221], v[12:15]
	v_mfma_f32_16x16x32_bf16 v[8:11], v[168:171], v[218:221], v[8:11]
	v_mfma_f32_16x16x32_bf16 v[60:63], v[156:159], v[196:199], v[60:63]
	v_mfma_f32_16x16x32_bf16 v[56:59], v[172:175], v[196:199], v[56:59]
	v_mfma_f32_16x16x32_bf16 v[44:47], v[156:159], v[206:209], v[44:47]
	v_mfma_f32_16x16x32_bf16 v[40:43], v[172:175], v[206:209], v[40:43]
	v_mfma_f32_16x16x32_bf16 v[28:31], v[156:159], v[214:217], v[28:31]
	v_mfma_f32_16x16x32_bf16 v[24:27], v[172:175], v[214:217], v[24:27]
	v_mfma_f32_16x16x32_bf16 v[12:15], v[156:159], v[222:225], v[12:15]
	v_mfma_f32_16x16x32_bf16 v[8:11], v[172:175], v[222:225], v[8:11]
	v_mfma_f32_16x16x32_bf16 v[52:55], v[176:179], v[192:195], v[52:55]
	v_mfma_f32_16x16x32_bf16 v[48:51], v[184:187], v[192:195], v[48:51]
	v_mfma_f32_16x16x32_bf16 v[36:39], v[176:179], v[202:205], v[36:39]
	v_mfma_f32_16x16x32_bf16 v[32:35], v[184:187], v[202:205], v[32:35]
	v_mfma_f32_16x16x32_bf16 v[20:23], v[176:179], v[210:213], v[20:23]
	v_mfma_f32_16x16x32_bf16 v[16:19], v[184:187], v[210:213], v[16:19]
	v_mfma_f32_16x16x32_bf16 v[4:7], v[176:179], v[218:221], v[4:7]
	v_mfma_f32_16x16x32_bf16 v[0:3], v[184:187], v[218:221], v[0:3]
	v_mfma_f32_16x16x32_bf16 v[52:55], v[180:183], v[196:199], v[52:55]
	v_mfma_f32_16x16x32_bf16 v[48:51], v[188:191], v[196:199], v[48:51]
	v_mfma_f32_16x16x32_bf16 v[36:39], v[180:183], v[206:209], v[36:39]
	v_mfma_f32_16x16x32_bf16 v[32:35], v[188:191], v[206:209], v[32:35]
	v_mfma_f32_16x16x32_bf16 v[20:23], v[180:183], v[214:217], v[20:23]
	v_mfma_f32_16x16x32_bf16 v[16:19], v[188:191], v[214:217], v[16:19]
	v_mfma_f32_16x16x32_bf16 v[4:7], v[180:183], v[222:225], v[4:7]
	v_mfma_f32_16x16x32_bf16 v[0:3], v[188:191], v[222:225], v[0:3]
	s_setprio 0
	s_barrier
	s_add_i32 s53, s53, 2
	s_add_u32 s34, s34, 0x100
	s_addc_u32 s35, s35, 0
	s_cmp_gt_u32 s53, 41
	s_cbranch_scc0 .LBB0_1393
	s_and_b64 vcc, exec, s[22:23]
	s_cbranch_vccz .LBB0_1396
	s_barrier
